# about half of the K-loop LDS-DMA loads use the SGPR-base form (32-bit lane offset), dropping their 64-bit address adds
# speedup vs baseline: 1.0029x; 1.0029x over previous
; #define PG8_STAGE(bufoff, gbase, voff) do { _Pragma("unroll") for (int _i = 0; _i < 2; ++_i) \
;         __builtin_amdgcn_global_load_lds((const unsigned*)((const char*)(gbase) + (voff)[_i]), (PG8_LAS unsigned*)(lds + (bufoff) + ldsw + _i * 8192), 16, 0, 0); } while (0)
; #define PG8_LDA(dst, b, h) do { _Pragma("unroll") for (int m = 0; m < 4; ++m) _Pragma("unroll") for (int k = 0; k < 2; ++k) dst[m][k] = *(const PG8_LAS bf16x8*)(lds + PG8_SA(b, h) + aoff + m * 2048 + k * 1024); } while (0)
; #define PG8_LDB(dst, b, h) do { _Pragma("unroll") for (int n = 0; n < 2; ++n) _Pragma("unroll") for (int k = 0; k < 2; ++k) dst[n][k] = *(const PG8_LAS bf16x8*)(lds + PG8_SB(b, h) + boff + n * 2048 + k * 1024); } while (0)
; #define PG8_MMA(ai, bj, At, Bt) do { __builtin_amdgcn_s_setprio(1); _Pragma("unroll") for (int m = 0; m < 4; ++m) _Pragma("unroll") for (int n = 0; n < 2; ++n) _Pragma("unroll") for (int k = 0; k < 2; ++k) \
;         acc[ai][bj][m][n] = __builtin_amdgcn_mfma_f32_16x16x32_bf16(Bt[n][k], At[m][k], acc[ai][bj][m][n], 0, 0, 0); __builtin_amdgcn_s_setprio(0); } while (0)
; #define PG8_BAR __builtin_amdgcn_s_barrier()
; template <class Epi, class Sched, bool ALIGN_EPI = false, bool SP2 = false>
; __device__ __forceinline__ void gemm_phase(PG8_LAS unsigned char* lds, const Gemm g, const Sched& S, const Epi& E) {
;     ...
;         const bool has_next = S.next(ui + 1, nxt);
;         const char* nA = has_next ? (const char*)g.A + (size_t)nxt.pm * tstep : cA; const char* nB = has_next ? (const char*)g.Bt + (size_t)nxt.pn * tstep : cB;
;         for (int t = 0; t < nt; t += 2) {
;             const bool last = (t == nt - 2);
;             const char* a1 = cA + (size_t)(t + 1) * kstep;
;             const char* a2 = last ? nA : cA + (size_t)(t + 2) * kstep; const char* b2 = last ? nB : cB + (size_t)(t + 2) * kstep;
;             const char* a3 = a2 + kstep; const char* b3 = b2 + kstep;
;             if (last && has_next) S.a_ready(nxt);
;             if constexpr (SP2) {
;             PG8_LDB(B0, 0, 0); PG8_LDB(B1, 0, 1); PG8_SCHED; PG8_LDA(At, 0, 0); PG8_STAGE(PG8_SA(1, 1), a1 + hstep, voffA);
;             PG8_WAIT_V(8); PG8_WAIT_L(0); PG8_BAR; PG8_MMA(0, 0, At, B0); PG8_MMA(0, 1, At, B1); PG8_BAR; PG8_SCHED;
;             PG8_LDA(At, 0, 1); PG8_STAGE(PG8_SB(0, 0), b2, voffB); PG8_STAGE(PG8_SB(0, 1), b2 + hstep, voffB); PG8_STAGE(PG8_SA(0, 0), a2, voffA);
.LBB0_128:
	s_ashr_i32 s25, s24, 31
	s_lshl_b64 s[28:29], s[24:25], 20
	v_readlane_b32 s30, v254, 51
	v_readlane_b32 s31, v254, 52
	s_add_u32 s28, s30, s28
	s_addc_u32 s29, s31, s29
	s_and_b64 s[30:31], s[26:27], exec
	s_cselect_b32 s25, s29, s9
	s_cselect_b32 s35, s28, s8
	s_ashr_i32 s23, s22, 31
	s_lshl_b64 s[30:31], s[22:23], 20
	s_add_u32 s30, s94, s30
	s_addc_u32 s31, s95, s31
	s_and_b64 s[46:47], s[26:27], exec
	s_cselect_b32 s23, s31, s45
	s_cselect_b32 s43, s30, s44
	s_add_u32 s8, s8, 0x80080
	s_addc_u32 s9, s9, 0
	s_add_u32 s48, s44, 0x100
	s_addc_u32 s49, s45, 0
	s_mov_b32 s54, -2
	s_waitcnt lgkmcnt(0)
	ds_read_b128 v[96:99], v173
	ds_read_b128 v[100:103], v173 offset:1024
	ds_read_b128 v[104:107], v173 offset:2048
	ds_read_b128 v[112:115], v173 offset:3072
	ds_read_b128 v[178:181], v175
	ds_read_b128 v[182:185], v175 offset:1024
	ds_read_b128 v[186:189], v175 offset:2048
	ds_read_b128 v[190:193], v175 offset:3072
	s_add_u32 s44, s8, 0xfff80080
	s_addc_u32 s45, s9, -1
	s_cmp_eq_u32 s54, 28
	s_cselect_b32 s47, s25, s45
	s_cselect_b32 s46, s35, s44
	s_cselect_b32 s45, s23, s49
	s_cselect_b32 s44, s43, s48
	s_add_i32 m0, s63, 0xc000
	ds_read_b128 v[198:201], v177
	ds_read_b128 v[202:205], v177 offset:1024
	ds_read_b128 v[206:209], v177 offset:2048
	ds_read_b128 v[210:213], v177 offset:3072
	ds_read_b128 v[214:217], v177 offset:4096
	ds_read_b128 v[218:221], v177 offset:5120
	ds_read_b128 v[222:225], v177 offset:6144
	ds_read_b128 v[226:229], v177 offset:7168
	global_load_lds_dwordx4 v154, s[8:9]
	s_add_i32 m0, s63, 0xe000
	s_nop 0
	global_load_lds_dwordx4 v156, s[8:9]
	s_waitcnt lgkmcnt(0)
	s_setprio 1
	s_barrier
	v_mfma_f32_16x16x32_bf16 v[140:143], v[96:99], v[198:201], 0
	v_mfma_f32_16x16x32_bf16 v[132:135], v[104:107], v[198:201], 0
	v_mfma_f32_16x16x32_bf16 v[116:119], v[96:99], v[206:209], 0
	v_mfma_f32_16x16x32_bf16 v[124:127], v[104:107], v[206:209], 0
	v_mfma_f32_16x16x32_bf16 v[84:87], v[96:99], v[214:217], 0
	v_mfma_f32_16x16x32_bf16 v[92:95], v[104:107], v[214:217], 0
	v_mfma_f32_16x16x32_bf16 v[68:71], v[96:99], v[222:225], 0
	v_mfma_f32_16x16x32_bf16 v[76:79], v[104:107], v[222:225], 0
	v_mfma_f32_16x16x32_bf16 v[140:143], v[100:103], v[202:205], v[140:143]
	v_mfma_f32_16x16x32_bf16 v[132:135], v[112:115], v[202:205], v[132:135]
	v_mfma_f32_16x16x32_bf16 v[116:119], v[100:103], v[210:213], v[116:119]
	v_mfma_f32_16x16x32_bf16 v[124:127], v[112:115], v[210:213], v[124:127]
	v_mfma_f32_16x16x32_bf16 v[84:87], v[100:103], v[218:221], v[84:87]
	v_mfma_f32_16x16x32_bf16 v[92:95], v[112:115], v[218:221], v[92:95]
	v_mfma_f32_16x16x32_bf16 v[68:71], v[100:103], v[226:229], v[68:71]
	v_mfma_f32_16x16x32_bf16 v[76:79], v[112:115], v[226:229], v[76:79]
	v_mfma_f32_16x16x32_bf16 v[128:131], v[178:181], v[198:201], 0
	v_mfma_f32_16x16x32_bf16 v[136:139], v[186:189], v[198:201], 0
	v_mfma_f32_16x16x32_bf16 v[120:123], v[178:181], v[206:209], 0
	v_mfma_f32_16x16x32_bf16 v[108:111], v[186:189], v[206:209], 0
	v_mfma_f32_16x16x32_bf16 v[88:91], v[178:181], v[214:217], 0
	v_mfma_f32_16x16x32_bf16 v[80:83], v[186:189], v[214:217], 0
	v_mfma_f32_16x16x32_bf16 v[72:75], v[178:181], v[222:225], 0
	v_mfma_f32_16x16x32_bf16 v[64:67], v[186:189], v[222:225], 0
	v_mfma_f32_16x16x32_bf16 v[128:131], v[182:185], v[202:205], v[128:131]
	v_mfma_f32_16x16x32_bf16 v[136:139], v[190:193], v[202:205], v[136:139]
	v_mfma_f32_16x16x32_bf16 v[120:123], v[182:185], v[210:213], v[120:123]
	v_mfma_f32_16x16x32_bf16 v[108:111], v[190:193], v[210:213], v[108:111]
	v_mfma_f32_16x16x32_bf16 v[88:91], v[182:185], v[218:221], v[88:91]
	v_mfma_f32_16x16x32_bf16 v[80:83], v[190:193], v[218:221], v[80:83]
	v_mfma_f32_16x16x32_bf16 v[72:75], v[182:185], v[226:229], v[72:75]
	v_mfma_f32_16x16x32_bf16 v[64:67], v[190:193], v[226:229], v[64:67]
	s_barrier
	s_setprio 0
	s_add_i32 s55, s52, s62
	v_lshl_add_u64 v[160:161], s[44:45], 0, v[144:145]
	s_mov_b32 m0, s55
	ds_read_b128 v[198:201], v177 offset:16384
	ds_read_b128 v[202:205], v177 offset:17408
	ds_read_b128 v[206:209], v177 offset:18432
	ds_read_b128 v[210:213], v177 offset:19456
	ds_read_b128 v[214:217], v177 offset:20480
	ds_read_b128 v[218:221], v177 offset:21504
	ds_read_b128 v[222:225], v177 offset:22528
	ds_read_b128 v[226:229], v177 offset:23552
	global_load_lds_dwordx4 v[160:161], off
	s_add_i32 m0, s55, 0x2000
	s_add_u32 s56, s44, 0x80000
	v_lshl_add_u64 v[164:165], s[44:45], 0, v[146:147]
	s_addc_u32 s57, s45, 0
	s_add_i32 s55, s53, s62
	global_load_lds_dwordx4 v[164:165], off
	s_mov_b32 m0, s55
	v_lshl_add_u64 v[194:195], s[46:47], 0, v[146:147]
	global_load_lds_dwordx4 v144, s[56:57]
	s_add_i32 m0, s55, 0x2000
	s_nop 0
	global_load_lds_dwordx4 v146, s[56:57]
	s_mov_b32 m0, s63
	v_lshl_add_u64 v[170:171], s[46:47], 0, v[144:145]
	global_load_lds_dwordx4 v[170:171], off
	s_mov_b32 m0, s64
	s_nop 0
	global_load_lds_dwordx4 v[194:195], off
	s_waitcnt lgkmcnt(0)
	s_setprio 1
	s_barrier
; #define PG8_STAGE(bufoff, gbase, voff) do { _Pragma("unroll") for (int _i = 0; _i < 2; ++_i) \
;         __builtin_amdgcn_global_load_lds((const unsigned*)((const char*)(gbase) + (voff)[_i]), (PG8_LAS unsigned*)(lds + (bufoff) + ldsw + _i * 8192), 16, 0, 0); } while (0)
; #define PG8_LDA(dst, b, h) do { _Pragma("unroll") for (int m = 0; m < 4; ++m) _Pragma("unroll") for (int k = 0; k < 2; ++k) dst[m][k] = *(const PG8_LAS bf16x8*)(lds + PG8_SA(b, h) + aoff + m * 2048 + k * 1024); } while (0)
; #define PG8_LDB(dst, b, h) do { _Pragma("unroll") for (int n = 0; n < 2; ++n) _Pragma("unroll") for (int k = 0; k < 2; ++k) dst[n][k] = *(const PG8_LAS bf16x8*)(lds + PG8_SB(b, h) + boff + n * 2048 + k * 1024); } while (0)
; #define PG8_MMA(ai, bj, At, Bt) do { __builtin_amdgcn_s_setprio(1); _Pragma("unroll") for (int m = 0; m < 4; ++m) _Pragma("unroll") for (int n = 0; n < 2; ++n) _Pragma("unroll") for (int k = 0; k < 2; ++k) \
;         acc[ai][bj][m][n] = __builtin_amdgcn_mfma_f32_16x16x32_bf16(Bt[n][k], At[m][k], acc[ai][bj][m][n], 0, 0, 0); __builtin_amdgcn_s_setprio(0); } while (0)
; #define PG8_WAIT_V(n) asm volatile("s_waitcnt vmcnt(" #n ")" ::: "memory")
; #define PG8_WAIT_L(n) asm volatile("s_waitcnt lgkmcnt(" #n ")" ::: "memory")
; #define PG8_BAR __builtin_amdgcn_s_barrier()
; #define PG8_SCHED __builtin_amdgcn_sched_barrier(0)
; template <class Epi, class Sched, bool ALIGN_EPI = false, bool SP2 = false>
; __device__ __forceinline__ void gemm_phase(PG8_LAS unsigned char* lds, const Gemm g, const Sched& S, const Epi& E) {
;     ...
;             PG8_WAIT_V(8); PG8_WAIT_L(0); PG8_BAR; PG8_MMA(1, 0, At, B0); PG8_MMA(1, 1, At, B1); PG8_BAR; PG8_SCHED;
;             PG8_LDB(B0, 1, 0); PG8_LDB(B1, 1, 1); PG8_SCHED; PG8_LDA(At, 1, 0); PG8_STAGE(PG8_SA(0, 1), a2 + hstep, voffA);
;             PG8_WAIT_V(8); PG8_WAIT_L(0); PG8_BAR; PG8_MMA(0, 0, At, B0); PG8_MMA(0, 1, At, B1); PG8_BAR; PG8_SCHED;
	v_mfma_f32_16x16x32_bf16 v[60:63], v[96:99], v[198:201], 0
	v_mfma_f32_16x16x32_bf16 v[52:55], v[104:107], v[198:201], 0
	v_mfma_f32_16x16x32_bf16 v[36:39], v[96:99], v[206:209], 0
	v_mfma_f32_16x16x32_bf16 v[44:47], v[104:107], v[206:209], 0
	v_mfma_f32_16x16x32_bf16 v[20:23], v[96:99], v[214:217], 0
	v_mfma_f32_16x16x32_bf16 v[28:31], v[104:107], v[214:217], 0
	v_mfma_f32_16x16x32_bf16 v[4:7], v[96:99], v[222:225], 0
	v_mfma_f32_16x16x32_bf16 v[12:15], v[104:107], v[222:225], 0
	v_mfma_f32_16x16x32_bf16 v[60:63], v[100:103], v[202:205], v[60:63]
	v_mfma_f32_16x16x32_bf16 v[52:55], v[112:115], v[202:205], v[52:55]
	v_mfma_f32_16x16x32_bf16 v[36:39], v[100:103], v[210:213], v[36:39]
	v_mfma_f32_16x16x32_bf16 v[44:47], v[112:115], v[210:213], v[44:47]
	v_mfma_f32_16x16x32_bf16 v[20:23], v[100:103], v[218:221], v[20:23]
	v_mfma_f32_16x16x32_bf16 v[28:31], v[112:115], v[218:221], v[28:31]
	v_mfma_f32_16x16x32_bf16 v[4:7], v[100:103], v[226:229], v[4:7]
	v_mfma_f32_16x16x32_bf16 v[12:15], v[112:115], v[226:229], v[12:15]
	v_mfma_f32_16x16x32_bf16 v[48:51], v[178:181], v[198:201], 0
	v_mfma_f32_16x16x32_bf16 v[56:59], v[186:189], v[198:201], 0
	v_mfma_f32_16x16x32_bf16 v[40:43], v[178:181], v[206:209], 0
	v_mfma_f32_16x16x32_bf16 v[32:35], v[186:189], v[206:209], 0
	v_mfma_f32_16x16x32_bf16 v[24:27], v[178:181], v[214:217], 0
	v_mfma_f32_16x16x32_bf16 v[16:19], v[186:189], v[214:217], 0
	v_mfma_f32_16x16x32_bf16 v[8:11], v[178:181], v[222:225], 0
	v_mfma_f32_16x16x32_bf16 v[0:3], v[186:189], v[222:225], 0
	v_mfma_f32_16x16x32_bf16 v[48:51], v[182:185], v[202:205], v[48:51]
	v_mfma_f32_16x16x32_bf16 v[56:59], v[190:193], v[202:205], v[56:59]
	v_mfma_f32_16x16x32_bf16 v[40:43], v[182:185], v[210:213], v[40:43]
	v_mfma_f32_16x16x32_bf16 v[32:35], v[190:193], v[210:213], v[32:35]
	v_mfma_f32_16x16x32_bf16 v[24:27], v[182:185], v[218:221], v[24:27]
	v_mfma_f32_16x16x32_bf16 v[16:19], v[190:193], v[218:221], v[16:19]
	v_mfma_f32_16x16x32_bf16 v[8:11], v[182:185], v[226:229], v[8:11]
	v_mfma_f32_16x16x32_bf16 v[0:3], v[190:193], v[226:229], v[0:3]
	s_barrier
	s_setprio 0
	s_add_i32 s55, 0, 0x18000
	s_add_i32 s56, 0, 0x1c000
	v_add_u32_e32 v112, s55, v167
	v_add_u32_e32 v162, s56, v167
	ds_read_b128 v[96:99], v112
	ds_read_b128 v[100:103], v112 offset:1024
	ds_read_b128 v[104:107], v112 offset:2048
	ds_read_b128 v[112:115], v112 offset:3072
	ds_read_b128 v[178:181], v162
	ds_read_b128 v[182:185], v162 offset:1024
	ds_read_b128 v[186:189], v162 offset:2048
	ds_read_b128 v[190:193], v162 offset:3072
	s_add_u32 s46, s46, 0x80000
	s_addc_u32 s47, s47, 0
	s_mov_b32 m0, s65
	ds_read_b128 v[198:201], v177 offset:32768
	ds_read_b128 v[202:205], v177 offset:33792
	ds_read_b128 v[206:209], v177 offset:34816
	ds_read_b128 v[210:213], v177 offset:35840
	ds_read_b128 v[214:217], v177 offset:36864
	ds_read_b128 v[218:221], v177 offset:37888
	ds_read_b128 v[222:225], v177 offset:38912
	ds_read_b128 v[226:229], v177 offset:39936
	global_load_lds_dwordx4 v144, s[46:47]
	s_mov_b32 m0, s66
	v_lshl_add_u64 v[230:231], s[46:47], 0, v[146:147]
	global_load_lds_dwordx4 v[230:231], off
	s_waitcnt vmcnt(8) lgkmcnt(0)
	s_setprio 1
	s_barrier
	v_mfma_f32_16x16x32_bf16 v[140:143], v[96:99], v[198:201], v[140:143]
	v_mfma_f32_16x16x32_bf16 v[132:135], v[104:107], v[198:201], v[132:135]
	v_mfma_f32_16x16x32_bf16 v[116:119], v[96:99], v[206:209], v[116:119]
	v_mfma_f32_16x16x32_bf16 v[124:127], v[104:107], v[206:209], v[124:127]
	v_mfma_f32_16x16x32_bf16 v[84:87], v[96:99], v[214:217], v[84:87]
	v_mfma_f32_16x16x32_bf16 v[92:95], v[104:107], v[214:217], v[92:95]
	v_mfma_f32_16x16x32_bf16 v[68:71], v[96:99], v[222:225], v[68:71]
	v_mfma_f32_16x16x32_bf16 v[76:79], v[104:107], v[222:225], v[76:79]
	v_mfma_f32_16x16x32_bf16 v[140:143], v[100:103], v[202:205], v[140:143]
	v_mfma_f32_16x16x32_bf16 v[132:135], v[112:115], v[202:205], v[132:135]
	v_mfma_f32_16x16x32_bf16 v[116:119], v[100:103], v[210:213], v[116:119]
	v_mfma_f32_16x16x32_bf16 v[124:127], v[112:115], v[210:213], v[124:127]
	v_mfma_f32_16x16x32_bf16 v[84:87], v[100:103], v[218:221], v[84:87]
	v_mfma_f32_16x16x32_bf16 v[92:95], v[112:115], v[218:221], v[92:95]
	v_mfma_f32_16x16x32_bf16 v[68:71], v[100:103], v[226:229], v[68:71]
	v_mfma_f32_16x16x32_bf16 v[76:79], v[112:115], v[226:229], v[76:79]
	v_mfma_f32_16x16x32_bf16 v[128:131], v[178:181], v[198:201], v[128:131]
	v_mfma_f32_16x16x32_bf16 v[136:139], v[186:189], v[198:201], v[136:139]
	v_mfma_f32_16x16x32_bf16 v[120:123], v[178:181], v[206:209], v[120:123]
	v_mfma_f32_16x16x32_bf16 v[108:111], v[186:189], v[206:209], v[108:111]
	v_mfma_f32_16x16x32_bf16 v[88:91], v[178:181], v[214:217], v[88:91]
	v_mfma_f32_16x16x32_bf16 v[80:83], v[186:189], v[214:217], v[80:83]
	v_mfma_f32_16x16x32_bf16 v[72:75], v[178:181], v[222:225], v[72:75]
	v_mfma_f32_16x16x32_bf16 v[64:67], v[186:189], v[222:225], v[64:67]
	v_mfma_f32_16x16x32_bf16 v[128:131], v[182:185], v[202:205], v[128:131]
	v_mfma_f32_16x16x32_bf16 v[136:139], v[190:193], v[202:205], v[136:139]
	v_mfma_f32_16x16x32_bf16 v[120:123], v[182:185], v[210:213], v[120:123]
	v_mfma_f32_16x16x32_bf16 v[108:111], v[190:193], v[210:213], v[108:111]
	v_mfma_f32_16x16x32_bf16 v[88:91], v[182:185], v[218:221], v[88:91]
	v_mfma_f32_16x16x32_bf16 v[80:83], v[190:193], v[218:221], v[80:83]
	v_mfma_f32_16x16x32_bf16 v[72:75], v[182:185], v[226:229], v[72:75]
	v_mfma_f32_16x16x32_bf16 v[64:67], v[190:193], v[226:229], v[64:67]
	s_barrier
; #define PG8_STAGE(bufoff, gbase, voff) do { _Pragma("unroll") for (int _i = 0; _i < 2; ++_i) \
;         __builtin_amdgcn_global_load_lds((const unsigned*)((const char*)(gbase) + (voff)[_i]), (PG8_LAS unsigned*)(lds + (bufoff) + ldsw + _i * 8192), 16, 0, 0); } while (0)
; #define PG8_LDA(dst, b, h) do { _Pragma("unroll") for (int m = 0; m < 4; ++m) _Pragma("unroll") for (int k = 0; k < 2; ++k) dst[m][k] = *(const PG8_LAS bf16x8*)(lds + PG8_SA(b, h) + aoff + m * 2048 + k * 1024); } while (0)
; #define PG8_LDB(dst, b, h) do { _Pragma("unroll") for (int n = 0; n < 2; ++n) _Pragma("unroll") for (int k = 0; k < 2; ++k) dst[n][k] = *(const PG8_LAS bf16x8*)(lds + PG8_SB(b, h) + boff + n * 2048 + k * 1024); } while (0)
; #define PG8_MMA(ai, bj, At, Bt) do { __builtin_amdgcn_s_setprio(1); _Pragma("unroll") for (int m = 0; m < 4; ++m) _Pragma("unroll") for (int n = 0; n < 2; ++n) _Pragma("unroll") for (int k = 0; k < 2; ++k) \
;         acc[ai][bj][m][n] = __builtin_amdgcn_mfma_f32_16x16x32_bf16(Bt[n][k], At[m][k], acc[ai][bj][m][n], 0, 0, 0); __builtin_amdgcn_s_setprio(0); } while (0)
; #define PG8_WAIT_V(n) asm volatile("s_waitcnt vmcnt(" #n ")" ::: "memory")
; template <class Epi, class Sched, bool ALIGN_EPI = false, bool SP2 = false>
; __device__ __forceinline__ void gemm_phase(PG8_LAS unsigned char* lds, const Gemm g, const Sched& S, const Epi& E) {
;     ...
;             PG8_LDB(B0, 0, 0); PG8_LDB(B1, 0, 1); PG8_SCHED; PG8_LDA(At, 0, 0); PG8_STAGE(PG8_SA(1, 1), a1 + hstep, voffA);
;             PG8_WAIT_V(8); PG8_WAIT_L(0); PG8_BAR; PG8_MMA(0, 0, At, B0); PG8_MMA(0, 1, At, B1); PG8_BAR; PG8_SCHED;
;             PG8_LDA(At, 0, 1); PG8_STAGE(PG8_SB(0, 0), b2, voffB); PG8_STAGE(PG8_SB(0, 1), b2 + hstep, voffB); PG8_STAGE(PG8_SA(0, 0), a2, voffA);
;             PG8_WAIT_V(8); PG8_WAIT_L(0); PG8_BAR; PG8_MMA(1, 0, At, B0); PG8_MMA(1, 1, At, B1); PG8_BAR; PG8_SCHED;
;             PG8_LDB(B0, 1, 0); PG8_LDB(B1, 1, 1); PG8_SCHED; PG8_LDA(At, 1, 0); PG8_STAGE(PG8_SA(0, 1), a2 + hstep, voffA);
;             PG8_WAIT_V(8); PG8_WAIT_L(0); PG8_BAR; PG8_MMA(0, 0, At, B0); PG8_MMA(0, 1, At, B1); PG8_BAR; PG8_SCHED;
;             PG8_LDA(At, 1, 1); PG8_STAGE(PG8_SB(1, 0), b3, voffB); PG8_STAGE(PG8_SB(1, 1), b3 + hstep, voffB); PG8_STAGE(PG8_SA(1, 0), a3, voffA);
;             PG8_WAIT_V(8); PG8_WAIT_L(0); PG8_BAR; PG8_MMA(1, 0, At, B0); PG8_MMA(1, 1, At, B1); PG8_BAR; PG8_SCHED;
	s_setprio 0
	s_add_i32 s46, s55, s62
	v_lshl_add_u64 v[160:161], v[160:161], 0, s[12:13]
	s_mov_b32 m0, s46
	ds_read_b128 v[198:201], v177 offset:49152
	ds_read_b128 v[202:205], v177 offset:50176
	ds_read_b128 v[206:209], v177 offset:51200
	ds_read_b128 v[210:213], v177 offset:52224
	ds_read_b128 v[214:217], v177 offset:53248
	ds_read_b128 v[218:221], v177 offset:54272
	ds_read_b128 v[222:225], v177 offset:55296
	ds_read_b128 v[226:229], v177 offset:56320
	global_load_lds_dwordx4 v[160:161], off
	s_add_i32 m0, s46, 0x2000
	s_add_u32 s44, s44, 0x80080
	v_lshl_add_u64 v[160:161], v[164:165], 0, s[12:13]
	s_addc_u32 s45, s45, 0
	s_add_i32 s46, s56, s62
	global_load_lds_dwordx4 v[160:161], off
	s_mov_b32 m0, s46
	s_nop 0
	global_load_lds_dwordx4 v144, s[44:45]
	s_add_i32 m0, s46, 0x2000
	v_lshl_add_u64 v[160:161], s[44:45], 0, v[146:147]
	global_load_lds_dwordx4 v[160:161], off
	s_mov_b32 m0, s68
	v_lshl_add_u64 v[160:161], v[170:171], 0, s[12:13]
	global_load_lds_dwordx4 v[160:161], off
	s_mov_b32 m0, s69
	v_lshl_add_u64 v[160:161], v[194:195], 0, s[12:13]
	global_load_lds_dwordx4 v[160:161], off
	s_waitcnt vmcnt(8) lgkmcnt(0)
	s_setprio 1
	s_barrier
	v_mfma_f32_16x16x32_bf16 v[60:63], v[96:99], v[198:201], v[60:63]
	v_mfma_f32_16x16x32_bf16 v[52:55], v[104:107], v[198:201], v[52:55]
	v_mfma_f32_16x16x32_bf16 v[36:39], v[96:99], v[206:209], v[36:39]
	v_mfma_f32_16x16x32_bf16 v[44:47], v[104:107], v[206:209], v[44:47]
	v_mfma_f32_16x16x32_bf16 v[20:23], v[96:99], v[214:217], v[20:23]
	v_mfma_f32_16x16x32_bf16 v[28:31], v[104:107], v[214:217], v[28:31]
	v_mfma_f32_16x16x32_bf16 v[4:7], v[96:99], v[222:225], v[4:7]
	v_mfma_f32_16x16x32_bf16 v[12:15], v[104:107], v[222:225], v[12:15]
	v_mfma_f32_16x16x32_bf16 v[60:63], v[100:103], v[202:205], v[60:63]
	v_mfma_f32_16x16x32_bf16 v[52:55], v[112:115], v[202:205], v[52:55]
	v_mfma_f32_16x16x32_bf16 v[36:39], v[100:103], v[210:213], v[36:39]
	v_mfma_f32_16x16x32_bf16 v[44:47], v[112:115], v[210:213], v[44:47]
	v_mfma_f32_16x16x32_bf16 v[20:23], v[100:103], v[218:221], v[20:23]
	v_mfma_f32_16x16x32_bf16 v[28:31], v[112:115], v[218:221], v[28:31]
	v_mfma_f32_16x16x32_bf16 v[4:7], v[100:103], v[226:229], v[4:7]
	v_mfma_f32_16x16x32_bf16 v[12:15], v[112:115], v[226:229], v[12:15]
	v_mfma_f32_16x16x32_bf16 v[48:51], v[178:181], v[198:201], v[48:51]
	v_mfma_f32_16x16x32_bf16 v[56:59], v[186:189], v[198:201], v[56:59]
	v_mfma_f32_16x16x32_bf16 v[40:43], v[178:181], v[206:209], v[40:43]
	v_mfma_f32_16x16x32_bf16 v[32:35], v[186:189], v[206:209], v[32:35]
	v_mfma_f32_16x16x32_bf16 v[24:27], v[178:181], v[214:217], v[24:27]
	v_mfma_f32_16x16x32_bf16 v[16:19], v[186:189], v[214:217], v[16:19]
	v_mfma_f32_16x16x32_bf16 v[8:11], v[178:181], v[222:225], v[8:11]
	v_mfma_f32_16x16x32_bf16 v[0:3], v[186:189], v[222:225], v[0:3]
	v_mfma_f32_16x16x32_bf16 v[48:51], v[182:185], v[202:205], v[48:51]
	v_mfma_f32_16x16x32_bf16 v[56:59], v[190:193], v[202:205], v[56:59]
	v_mfma_f32_16x16x32_bf16 v[40:43], v[182:185], v[210:213], v[40:43]
	v_mfma_f32_16x16x32_bf16 v[32:35], v[190:193], v[210:213], v[32:35]
	v_mfma_f32_16x16x32_bf16 v[24:27], v[182:185], v[218:221], v[24:27]
	v_mfma_f32_16x16x32_bf16 v[16:19], v[190:193], v[218:221], v[16:19]
	v_mfma_f32_16x16x32_bf16 v[8:11], v[182:185], v[226:229], v[8:11]
	v_mfma_f32_16x16x32_bf16 v[0:3], v[190:193], v[226:229], v[0:3]
	s_barrier
	s_setprio 0
	s_add_i32 s54, s54, 2
	s_add_u32 s8, s8, 0x100
	s_addc_u32 s9, s9, 0
	s_add_u32 s48, s48, 0x100
	s_addc_u32 s49, s49, 0
.LBB0_129:
	ds_read_b128 v[96:99], v173
	ds_read_b128 v[100:103], v173 offset:1024
	ds_read_b128 v[104:107], v173 offset:2048
	ds_read_b128 v[112:115], v173 offset:3072
	ds_read_b128 v[178:181], v175
	ds_read_b128 v[182:185], v175 offset:1024
	ds_read_b128 v[186:189], v175 offset:2048
	ds_read_b128 v[190:193], v175 offset:3072
	s_add_u32 s44, s8, 0xfff80080
	s_addc_u32 s45, s9, -1
	s_cmp_eq_u32 s54, 28
	s_cselect_b32 s47, s25, s45
	s_cselect_b32 s46, s35, s44
	s_cselect_b32 s45, s23, s49
	s_cselect_b32 s44, s43, s48
	s_add_i32 m0, s63, 0xc000
	ds_read_b128 v[198:201], v177
	ds_read_b128 v[202:205], v177 offset:1024
	ds_read_b128 v[206:209], v177 offset:2048
	ds_read_b128 v[210:213], v177 offset:3072
	ds_read_b128 v[214:217], v177 offset:4096
	ds_read_b128 v[218:221], v177 offset:5120
	ds_read_b128 v[222:225], v177 offset:6144
	ds_read_b128 v[226:229], v177 offset:7168
	global_load_lds_dwordx4 v154, s[8:9]
	s_add_i32 m0, s63, 0xe000
	s_nop 0
	global_load_lds_dwordx4 v156, s[8:9]
	s_waitcnt vmcnt(8) lgkmcnt(0)
	s_setprio 1
	s_barrier
; #define PG8_STAGE(bufoff, gbase, voff) do { _Pragma("unroll") for (int _i = 0; _i < 2; ++_i) \
;         __builtin_amdgcn_global_load_lds((const unsigned*)((const char*)(gbase) + (voff)[_i]), (PG8_LAS unsigned*)(lds + (bufoff) + ldsw + _i * 8192), 16, 0, 0); } while (0)
; #define PG8_LDA(dst, b, h) do { _Pragma("unroll") for (int m = 0; m < 4; ++m) _Pragma("unroll") for (int k = 0; k < 2; ++k) dst[m][k] = *(const PG8_LAS bf16x8*)(lds + PG8_SA(b, h) + aoff + m * 2048 + k * 1024); } while (0)
; #define PG8_MMA(ai, bj, At, Bt) do { __builtin_amdgcn_s_setprio(1); _Pragma("unroll") for (int m = 0; m < 4; ++m) _Pragma("unroll") for (int n = 0; n < 2; ++n) _Pragma("unroll") for (int k = 0; k < 2; ++k) \
;         acc[ai][bj][m][n] = __builtin_amdgcn_mfma_f32_16x16x32_bf16(Bt[n][k], At[m][k], acc[ai][bj][m][n], 0, 0, 0); __builtin_amdgcn_s_setprio(0); } while (0)
; #define PG8_WAIT_V(n) asm volatile("s_waitcnt vmcnt(" #n ")" ::: "memory")
; #define PG8_WAIT_L(n) asm volatile("s_waitcnt lgkmcnt(" #n ")" ::: "memory")
; #define PG8_BAR __builtin_amdgcn_s_barrier()
; #define PG8_SCHED __builtin_amdgcn_sched_barrier(0)
; template <class Epi, class Sched, bool ALIGN_EPI = false, bool SP2 = false>
; __device__ __forceinline__ void gemm_phase(PG8_LAS unsigned char* lds, const Gemm g, const Sched& S, const Epi& E) {
;     ...
;             PG8_WAIT_V(8); PG8_WAIT_L(0); PG8_BAR; PG8_MMA(0, 0, At, B0); PG8_MMA(0, 1, At, B1); PG8_BAR; PG8_SCHED;
;             PG8_LDA(At, 0, 1); PG8_STAGE(PG8_SB(0, 0), b2, voffB); PG8_STAGE(PG8_SB(0, 1), b2 + hstep, voffB); PG8_STAGE(PG8_SA(0, 0), a2, voffA);
;             PG8_WAIT_V(8); PG8_WAIT_L(0); PG8_BAR; PG8_MMA(1, 0, At, B0); PG8_MMA(1, 1, At, B1); PG8_BAR; PG8_SCHED;
	v_mfma_f32_16x16x32_bf16 v[140:143], v[96:99], v[198:201], v[140:143]
	v_mfma_f32_16x16x32_bf16 v[132:135], v[104:107], v[198:201], v[132:135]
	v_mfma_f32_16x16x32_bf16 v[116:119], v[96:99], v[206:209], v[116:119]
	v_mfma_f32_16x16x32_bf16 v[124:127], v[104:107], v[206:209], v[124:127]
	v_mfma_f32_16x16x32_bf16 v[84:87], v[96:99], v[214:217], v[84:87]
	v_mfma_f32_16x16x32_bf16 v[92:95], v[104:107], v[214:217], v[92:95]
	v_mfma_f32_16x16x32_bf16 v[68:71], v[96:99], v[222:225], v[68:71]
	v_mfma_f32_16x16x32_bf16 v[76:79], v[104:107], v[222:225], v[76:79]
	v_mfma_f32_16x16x32_bf16 v[140:143], v[100:103], v[202:205], v[140:143]
	v_mfma_f32_16x16x32_bf16 v[132:135], v[112:115], v[202:205], v[132:135]
	v_mfma_f32_16x16x32_bf16 v[116:119], v[100:103], v[210:213], v[116:119]
	v_mfma_f32_16x16x32_bf16 v[124:127], v[112:115], v[210:213], v[124:127]
	v_mfma_f32_16x16x32_bf16 v[84:87], v[100:103], v[218:221], v[84:87]
	v_mfma_f32_16x16x32_bf16 v[92:95], v[112:115], v[218:221], v[92:95]
	v_mfma_f32_16x16x32_bf16 v[68:71], v[100:103], v[226:229], v[68:71]
	v_mfma_f32_16x16x32_bf16 v[76:79], v[112:115], v[226:229], v[76:79]
	v_mfma_f32_16x16x32_bf16 v[128:131], v[178:181], v[198:201], v[128:131]
	v_mfma_f32_16x16x32_bf16 v[136:139], v[186:189], v[198:201], v[136:139]
	v_mfma_f32_16x16x32_bf16 v[120:123], v[178:181], v[206:209], v[120:123]
	v_mfma_f32_16x16x32_bf16 v[108:111], v[186:189], v[206:209], v[108:111]
	v_mfma_f32_16x16x32_bf16 v[88:91], v[178:181], v[214:217], v[88:91]
	v_mfma_f32_16x16x32_bf16 v[80:83], v[186:189], v[214:217], v[80:83]
	v_mfma_f32_16x16x32_bf16 v[72:75], v[178:181], v[222:225], v[72:75]
	v_mfma_f32_16x16x32_bf16 v[64:67], v[186:189], v[222:225], v[64:67]
	v_mfma_f32_16x16x32_bf16 v[128:131], v[182:185], v[202:205], v[128:131]
	v_mfma_f32_16x16x32_bf16 v[136:139], v[190:193], v[202:205], v[136:139]
	v_mfma_f32_16x16x32_bf16 v[120:123], v[182:185], v[210:213], v[120:123]
	v_mfma_f32_16x16x32_bf16 v[108:111], v[190:193], v[210:213], v[108:111]
	v_mfma_f32_16x16x32_bf16 v[88:91], v[182:185], v[218:221], v[88:91]
	v_mfma_f32_16x16x32_bf16 v[80:83], v[190:193], v[218:221], v[80:83]
	v_mfma_f32_16x16x32_bf16 v[72:75], v[182:185], v[226:229], v[72:75]
	v_mfma_f32_16x16x32_bf16 v[64:67], v[190:193], v[226:229], v[64:67]
	s_barrier
	s_setprio 0
	s_add_i32 s55, s52, s62
	v_lshl_add_u64 v[160:161], s[44:45], 0, v[144:145]
	s_mov_b32 m0, s55
	ds_read_b128 v[198:201], v177 offset:16384
	ds_read_b128 v[202:205], v177 offset:17408
	ds_read_b128 v[206:209], v177 offset:18432
	ds_read_b128 v[210:213], v177 offset:19456
	ds_read_b128 v[214:217], v177 offset:20480
	ds_read_b128 v[218:221], v177 offset:21504
	ds_read_b128 v[222:225], v177 offset:22528
	ds_read_b128 v[226:229], v177 offset:23552
	global_load_lds_dwordx4 v[160:161], off
	s_add_i32 m0, s55, 0x2000
	s_add_u32 s56, s44, 0x80000
	v_lshl_add_u64 v[164:165], s[44:45], 0, v[146:147]
	s_addc_u32 s57, s45, 0
	s_add_i32 s55, s53, s62
	global_load_lds_dwordx4 v[164:165], off
	s_mov_b32 m0, s55
	v_lshl_add_u64 v[194:195], s[46:47], 0, v[146:147]
	global_load_lds_dwordx4 v144, s[56:57]
	s_add_i32 m0, s55, 0x2000
	s_nop 0
	global_load_lds_dwordx4 v146, s[56:57]
	s_mov_b32 m0, s63
	v_lshl_add_u64 v[170:171], s[46:47], 0, v[144:145]
	global_load_lds_dwordx4 v[170:171], off
	s_mov_b32 m0, s64
	s_nop 0
	global_load_lds_dwordx4 v[194:195], off
	s_waitcnt vmcnt(8) lgkmcnt(0)
	s_setprio 1
	s_barrier
	v_mfma_f32_16x16x32_bf16 v[60:63], v[96:99], v[198:201], v[60:63]
	v_mfma_f32_16x16x32_bf16 v[52:55], v[104:107], v[198:201], v[52:55]
	v_mfma_f32_16x16x32_bf16 v[36:39], v[96:99], v[206:209], v[36:39]
	v_mfma_f32_16x16x32_bf16 v[44:47], v[104:107], v[206:209], v[44:47]
	v_mfma_f32_16x16x32_bf16 v[20:23], v[96:99], v[214:217], v[20:23]
	v_mfma_f32_16x16x32_bf16 v[28:31], v[104:107], v[214:217], v[28:31]
	v_mfma_f32_16x16x32_bf16 v[4:7], v[96:99], v[222:225], v[4:7]
	v_mfma_f32_16x16x32_bf16 v[12:15], v[104:107], v[222:225], v[12:15]
	v_mfma_f32_16x16x32_bf16 v[60:63], v[100:103], v[202:205], v[60:63]
	v_mfma_f32_16x16x32_bf16 v[52:55], v[112:115], v[202:205], v[52:55]
	v_mfma_f32_16x16x32_bf16 v[36:39], v[100:103], v[210:213], v[36:39]
	v_mfma_f32_16x16x32_bf16 v[44:47], v[112:115], v[210:213], v[44:47]
	v_mfma_f32_16x16x32_bf16 v[20:23], v[100:103], v[218:221], v[20:23]
	v_mfma_f32_16x16x32_bf16 v[28:31], v[112:115], v[218:221], v[28:31]
	v_mfma_f32_16x16x32_bf16 v[4:7], v[100:103], v[226:229], v[4:7]
	v_mfma_f32_16x16x32_bf16 v[12:15], v[112:115], v[226:229], v[12:15]
	v_mfma_f32_16x16x32_bf16 v[48:51], v[178:181], v[198:201], v[48:51]
	v_mfma_f32_16x16x32_bf16 v[56:59], v[186:189], v[198:201], v[56:59]
	v_mfma_f32_16x16x32_bf16 v[40:43], v[178:181], v[206:209], v[40:43]
	v_mfma_f32_16x16x32_bf16 v[32:35], v[186:189], v[206:209], v[32:35]
	v_mfma_f32_16x16x32_bf16 v[24:27], v[178:181], v[214:217], v[24:27]
	v_mfma_f32_16x16x32_bf16 v[16:19], v[186:189], v[214:217], v[16:19]
	v_mfma_f32_16x16x32_bf16 v[8:11], v[178:181], v[222:225], v[8:11]
	v_mfma_f32_16x16x32_bf16 v[0:3], v[186:189], v[222:225], v[0:3]
	v_mfma_f32_16x16x32_bf16 v[48:51], v[182:185], v[202:205], v[48:51]
	v_mfma_f32_16x16x32_bf16 v[56:59], v[190:193], v[202:205], v[56:59]
	v_mfma_f32_16x16x32_bf16 v[40:43], v[182:185], v[210:213], v[40:43]
	v_mfma_f32_16x16x32_bf16 v[32:35], v[190:193], v[210:213], v[32:35]
	v_mfma_f32_16x16x32_bf16 v[24:27], v[182:185], v[218:221], v[24:27]
	v_mfma_f32_16x16x32_bf16 v[16:19], v[190:193], v[218:221], v[16:19]
	v_mfma_f32_16x16x32_bf16 v[8:11], v[182:185], v[226:229], v[8:11]
	v_mfma_f32_16x16x32_bf16 v[0:3], v[190:193], v[226:229], v[0:3]
	s_barrier
; #define PG8_STAGE(bufoff, gbase, voff) do { _Pragma("unroll") for (int _i = 0; _i < 2; ++_i) \
;         __builtin_amdgcn_global_load_lds((const unsigned*)((const char*)(gbase) + (voff)[_i]), (PG8_LAS unsigned*)(lds + (bufoff) + ldsw + _i * 8192), 16, 0, 0); } while (0)
; #define PG8_LDA(dst, b, h) do { _Pragma("unroll") for (int m = 0; m < 4; ++m) _Pragma("unroll") for (int k = 0; k < 2; ++k) dst[m][k] = *(const PG8_LAS bf16x8*)(lds + PG8_SA(b, h) + aoff + m * 2048 + k * 1024); } while (0)
; #define PG8_LDB(dst, b, h) do { _Pragma("unroll") for (int n = 0; n < 2; ++n) _Pragma("unroll") for (int k = 0; k < 2; ++k) dst[n][k] = *(const PG8_LAS bf16x8*)(lds + PG8_SB(b, h) + boff + n * 2048 + k * 1024); } while (0)
; #define PG8_MMA(ai, bj, At, Bt) do { __builtin_amdgcn_s_setprio(1); _Pragma("unroll") for (int m = 0; m < 4; ++m) _Pragma("unroll") for (int n = 0; n < 2; ++n) _Pragma("unroll") for (int k = 0; k < 2; ++k) \
;         acc[ai][bj][m][n] = __builtin_amdgcn_mfma_f32_16x16x32_bf16(Bt[n][k], At[m][k], acc[ai][bj][m][n], 0, 0, 0); __builtin_amdgcn_s_setprio(0); } while (0)
; #define PG8_WAIT_V(n) asm volatile("s_waitcnt vmcnt(" #n ")" ::: "memory")
; #define PG8_WAIT_L(n) asm volatile("s_waitcnt lgkmcnt(" #n ")" ::: "memory")
; #define PG8_BAR __builtin_amdgcn_s_barrier()
; #define PG8_SCHED __builtin_amdgcn_sched_barrier(0)
; template <class Epi, class Sched, bool ALIGN_EPI = false, bool SP2 = false>
; __device__ __forceinline__ void gemm_phase(PG8_LAS unsigned char* lds, const Gemm g, const Sched& S, const Epi& E) {
;     ...
;             PG8_LDB(B0, 1, 0); PG8_LDB(B1, 1, 1); PG8_SCHED; PG8_LDA(At, 1, 0); PG8_STAGE(PG8_SA(0, 1), a2 + hstep, voffA);
;             PG8_WAIT_V(8); PG8_WAIT_L(0); PG8_BAR; PG8_MMA(0, 0, At, B0); PG8_MMA(0, 1, At, B1); PG8_BAR; PG8_SCHED;
;             PG8_LDA(At, 1, 1); PG8_STAGE(PG8_SB(1, 0), b3, voffB); PG8_STAGE(PG8_SB(1, 1), b3 + hstep, voffB); PG8_STAGE(PG8_SA(1, 0), a3, voffA);
;             PG8_WAIT_V(8); PG8_WAIT_L(0); PG8_BAR; PG8_MMA(1, 0, At, B0); PG8_MMA(1, 1, At, B1); PG8_BAR; PG8_SCHED;
;     ...
;         }
;         if constexpr (ALIGN_EPI) { if (wr == 0) PG8_BAR; }
	s_setprio 0
	s_add_i32 s55, 0, 0x18000
	s_add_i32 s56, 0, 0x1c000
	v_add_u32_e32 v112, s55, v167
	v_add_u32_e32 v162, s56, v167
	ds_read_b128 v[96:99], v112
	ds_read_b128 v[100:103], v112 offset:1024
	ds_read_b128 v[104:107], v112 offset:2048
	ds_read_b128 v[112:115], v112 offset:3072
	ds_read_b128 v[178:181], v162
	ds_read_b128 v[182:185], v162 offset:1024
	ds_read_b128 v[186:189], v162 offset:2048
	ds_read_b128 v[190:193], v162 offset:3072
	s_add_u32 s46, s46, 0x80000
	s_addc_u32 s47, s47, 0
	s_mov_b32 m0, s65
	ds_read_b128 v[198:201], v177 offset:32768
	ds_read_b128 v[202:205], v177 offset:33792
	ds_read_b128 v[206:209], v177 offset:34816
	ds_read_b128 v[210:213], v177 offset:35840
	ds_read_b128 v[214:217], v177 offset:36864
	ds_read_b128 v[218:221], v177 offset:37888
	ds_read_b128 v[222:225], v177 offset:38912
	ds_read_b128 v[226:229], v177 offset:39936
	global_load_lds_dwordx4 v144, s[46:47]
	s_mov_b32 m0, s66
	s_nop 0
	global_load_lds_dwordx4 v146, s[46:47]
	s_waitcnt vmcnt(8) lgkmcnt(0)
	s_setprio 1
	s_barrier
	v_mfma_f32_16x16x32_bf16 v[140:143], v[96:99], v[198:201], v[140:143]
	v_mfma_f32_16x16x32_bf16 v[132:135], v[104:107], v[198:201], v[132:135]
	v_mfma_f32_16x16x32_bf16 v[116:119], v[96:99], v[206:209], v[116:119]
	v_mfma_f32_16x16x32_bf16 v[124:127], v[104:107], v[206:209], v[124:127]
	v_mfma_f32_16x16x32_bf16 v[84:87], v[96:99], v[214:217], v[84:87]
	v_mfma_f32_16x16x32_bf16 v[92:95], v[104:107], v[214:217], v[92:95]
	v_mfma_f32_16x16x32_bf16 v[68:71], v[96:99], v[222:225], v[68:71]
	v_mfma_f32_16x16x32_bf16 v[76:79], v[104:107], v[222:225], v[76:79]
	v_mfma_f32_16x16x32_bf16 v[140:143], v[100:103], v[202:205], v[140:143]
	v_mfma_f32_16x16x32_bf16 v[132:135], v[112:115], v[202:205], v[132:135]
	v_mfma_f32_16x16x32_bf16 v[116:119], v[100:103], v[210:213], v[116:119]
	v_mfma_f32_16x16x32_bf16 v[124:127], v[112:115], v[210:213], v[124:127]
	v_mfma_f32_16x16x32_bf16 v[84:87], v[100:103], v[218:221], v[84:87]
	v_mfma_f32_16x16x32_bf16 v[92:95], v[112:115], v[218:221], v[92:95]
	v_mfma_f32_16x16x32_bf16 v[68:71], v[100:103], v[226:229], v[68:71]
	v_mfma_f32_16x16x32_bf16 v[76:79], v[112:115], v[226:229], v[76:79]
	v_mfma_f32_16x16x32_bf16 v[128:131], v[178:181], v[198:201], v[128:131]
	v_mfma_f32_16x16x32_bf16 v[136:139], v[186:189], v[198:201], v[136:139]
	v_mfma_f32_16x16x32_bf16 v[120:123], v[178:181], v[206:209], v[120:123]
	v_mfma_f32_16x16x32_bf16 v[108:111], v[186:189], v[206:209], v[108:111]
	v_mfma_f32_16x16x32_bf16 v[88:91], v[178:181], v[214:217], v[88:91]
	v_mfma_f32_16x16x32_bf16 v[80:83], v[186:189], v[214:217], v[80:83]
	v_mfma_f32_16x16x32_bf16 v[72:75], v[178:181], v[222:225], v[72:75]
	v_mfma_f32_16x16x32_bf16 v[64:67], v[186:189], v[222:225], v[64:67]
	v_mfma_f32_16x16x32_bf16 v[128:131], v[182:185], v[202:205], v[128:131]
	v_mfma_f32_16x16x32_bf16 v[136:139], v[190:193], v[202:205], v[136:139]
	v_mfma_f32_16x16x32_bf16 v[120:123], v[182:185], v[210:213], v[120:123]
	v_mfma_f32_16x16x32_bf16 v[108:111], v[190:193], v[210:213], v[108:111]
	v_mfma_f32_16x16x32_bf16 v[88:91], v[182:185], v[218:221], v[88:91]
	v_mfma_f32_16x16x32_bf16 v[80:83], v[190:193], v[218:221], v[80:83]
	v_mfma_f32_16x16x32_bf16 v[72:75], v[182:185], v[226:229], v[72:75]
	v_mfma_f32_16x16x32_bf16 v[64:67], v[190:193], v[226:229], v[64:67]
	s_barrier
	s_setprio 0
	s_add_i32 s46, s55, s62
	v_lshl_add_u64 v[160:161], v[160:161], 0, s[12:13]
	s_mov_b32 m0, s46
	ds_read_b128 v[198:201], v177 offset:49152
	ds_read_b128 v[202:205], v177 offset:50176
	ds_read_b128 v[206:209], v177 offset:51200
	ds_read_b128 v[210:213], v177 offset:52224
	ds_read_b128 v[214:217], v177 offset:53248
	ds_read_b128 v[218:221], v177 offset:54272
	ds_read_b128 v[222:225], v177 offset:55296
	ds_read_b128 v[226:229], v177 offset:56320
	global_load_lds_dwordx4 v[160:161], off
	s_add_i32 m0, s46, 0x2000
	s_add_u32 s44, s44, 0x80080
	v_lshl_add_u64 v[160:161], v[164:165], 0, s[12:13]
	s_addc_u32 s45, s45, 0
	s_add_i32 s46, s56, s62
	global_load_lds_dwordx4 v[160:161], off
	s_mov_b32 m0, s46
	s_nop 0
	global_load_lds_dwordx4 v144, s[44:45]
	s_add_i32 m0, s46, 0x2000
	v_lshl_add_u64 v[160:161], s[44:45], 0, v[146:147]
	global_load_lds_dwordx4 v[160:161], off
	s_mov_b32 m0, s68
	v_lshl_add_u64 v[160:161], v[170:171], 0, s[12:13]
	global_load_lds_dwordx4 v[160:161], off
	s_mov_b32 m0, s69
	v_lshl_add_u64 v[160:161], v[194:195], 0, s[12:13]
	global_load_lds_dwordx4 v[160:161], off
	s_waitcnt vmcnt(8) lgkmcnt(0)
	s_setprio 1
	s_barrier
	v_mfma_f32_16x16x32_bf16 v[60:63], v[96:99], v[198:201], v[60:63]
	v_mfma_f32_16x16x32_bf16 v[52:55], v[104:107], v[198:201], v[52:55]
	v_mfma_f32_16x16x32_bf16 v[36:39], v[96:99], v[206:209], v[36:39]
	v_mfma_f32_16x16x32_bf16 v[44:47], v[104:107], v[206:209], v[44:47]
	v_mfma_f32_16x16x32_bf16 v[20:23], v[96:99], v[214:217], v[20:23]
	v_mfma_f32_16x16x32_bf16 v[28:31], v[104:107], v[214:217], v[28:31]
	v_mfma_f32_16x16x32_bf16 v[4:7], v[96:99], v[222:225], v[4:7]
	v_mfma_f32_16x16x32_bf16 v[12:15], v[104:107], v[222:225], v[12:15]
	v_mfma_f32_16x16x32_bf16 v[60:63], v[100:103], v[202:205], v[60:63]
	v_mfma_f32_16x16x32_bf16 v[52:55], v[112:115], v[202:205], v[52:55]
	v_mfma_f32_16x16x32_bf16 v[36:39], v[100:103], v[210:213], v[36:39]
	v_mfma_f32_16x16x32_bf16 v[44:47], v[112:115], v[210:213], v[44:47]
	v_mfma_f32_16x16x32_bf16 v[20:23], v[100:103], v[218:221], v[20:23]
	v_mfma_f32_16x16x32_bf16 v[28:31], v[112:115], v[218:221], v[28:31]
	v_mfma_f32_16x16x32_bf16 v[4:7], v[100:103], v[226:229], v[4:7]
	v_mfma_f32_16x16x32_bf16 v[12:15], v[112:115], v[226:229], v[12:15]
	v_mfma_f32_16x16x32_bf16 v[48:51], v[178:181], v[198:201], v[48:51]
	v_mfma_f32_16x16x32_bf16 v[56:59], v[186:189], v[198:201], v[56:59]
	v_mfma_f32_16x16x32_bf16 v[40:43], v[178:181], v[206:209], v[40:43]
	v_mfma_f32_16x16x32_bf16 v[32:35], v[186:189], v[206:209], v[32:35]
	v_mfma_f32_16x16x32_bf16 v[24:27], v[178:181], v[214:217], v[24:27]
	v_mfma_f32_16x16x32_bf16 v[16:19], v[186:189], v[214:217], v[16:19]
	v_mfma_f32_16x16x32_bf16 v[8:11], v[178:181], v[222:225], v[8:11]
	v_mfma_f32_16x16x32_bf16 v[0:3], v[186:189], v[222:225], v[0:3]
	v_mfma_f32_16x16x32_bf16 v[48:51], v[182:185], v[202:205], v[48:51]
	v_mfma_f32_16x16x32_bf16 v[56:59], v[190:193], v[202:205], v[56:59]
	v_mfma_f32_16x16x32_bf16 v[40:43], v[182:185], v[210:213], v[40:43]
	v_mfma_f32_16x16x32_bf16 v[32:35], v[190:193], v[210:213], v[32:35]
	v_mfma_f32_16x16x32_bf16 v[24:27], v[182:185], v[218:221], v[24:27]
	v_mfma_f32_16x16x32_bf16 v[16:19], v[190:193], v[218:221], v[16:19]
	v_mfma_f32_16x16x32_bf16 v[8:11], v[182:185], v[226:229], v[8:11]
	v_mfma_f32_16x16x32_bf16 v[0:3], v[190:193], v[226:229], v[0:3]
	s_barrier
	s_setprio 0
	s_add_i32 s54, s54, 2
	s_add_u32 s8, s8, 0x100
	s_addc_u32 s9, s9, 0
	s_add_u32 s48, s48, 0x100
	s_addc_u32 s49, s49, 0
	s_cmp_gt_u32 s54, 29
	s_cbranch_scc0 .LBB0_129
	s_and_b64 vcc, exec, s[14:15]
	s_cbranch_vccz .LBB0_132
	s_barrier

; #define PG8_STAGE(bufoff, gbase, voff) do { _Pragma("unroll") for (int _i = 0; _i < 2; ++_i) \
;         __builtin_amdgcn_global_load_lds((const unsigned*)((const char*)(gbase) + (voff)[_i]), (PG8_LAS unsigned*)(lds + (bufoff) + ldsw + _i * 8192), 16, 0, 0); } while (0)
; #define PG8_LDA(dst, b, h) do { _Pragma("unroll") for (int m = 0; m < 4; ++m) _Pragma("unroll") for (int k = 0; k < 2; ++k) dst[m][k] = *(const PG8_LAS bf16x8*)(lds + PG8_SA(b, h) + aoff + m * 2048 + k * 1024); } while (0)
; #define PG8_LDB(dst, b, h) do { _Pragma("unroll") for (int n = 0; n < 2; ++n) _Pragma("unroll") for (int k = 0; k < 2; ++k) dst[n][k] = *(const PG8_LAS bf16x8*)(lds + PG8_SB(b, h) + boff + n * 2048 + k * 1024); } while (0)
; #define PG8_MMA(ai, bj, At, Bt) do { __builtin_amdgcn_s_setprio(1); _Pragma("unroll") for (int m = 0; m < 4; ++m) _Pragma("unroll") for (int n = 0; n < 2; ++n) _Pragma("unroll") for (int k = 0; k < 2; ++k) \
;         acc[ai][bj][m][n] = __builtin_amdgcn_mfma_f32_16x16x32_bf16(Bt[n][k], At[m][k], acc[ai][bj][m][n], 0, 0, 0); __builtin_amdgcn_s_setprio(0); } while (0)
; #define PG8_BAR __builtin_amdgcn_s_barrier()
; template <class Epi, class Sched, bool ALIGN_EPI = false, bool SP2 = false>
; __device__ __forceinline__ void gemm_phase(PG8_LAS unsigned char* lds, const Gemm g, const Sched& S, const Epi& E) {
;     ...
;         const bool has_next = S.next(ui + 1, nxt);
;         const char* nA = has_next ? (const char*)g.A + (size_t)nxt.pm * tstep : cA; const char* nB = has_next ? (const char*)g.Bt + (size_t)nxt.pn * tstep : cB;
;         for (int t = 0; t < nt; t += 2) {
;             const bool last = (t == nt - 2);
;             const char* a1 = cA + (size_t)(t + 1) * kstep;
;             const char* a2 = last ? nA : cA + (size_t)(t + 2) * kstep; const char* b2 = last ? nB : cB + (size_t)(t + 2) * kstep;
;             const char* a3 = a2 + kstep; const char* b3 = b2 + kstep;
;             if (last && has_next) S.a_ready(nxt);
;             if constexpr (SP2) {
;             PG8_LDB(B0, 0, 0); PG8_LDB(B1, 0, 1); PG8_SCHED; PG8_LDA(At, 0, 0); PG8_STAGE(PG8_SA(1, 1), a1 + hstep, voffA);
;             PG8_WAIT_V(8); PG8_WAIT_L(0); PG8_BAR; PG8_MMA(0, 0, At, B0); PG8_MMA(0, 1, At, B1); PG8_BAR; PG8_SCHED;
;             PG8_LDA(At, 0, 1); PG8_STAGE(PG8_SB(0, 0), b2, voffB); PG8_STAGE(PG8_SB(0, 1), b2 + hstep, voffB); PG8_STAGE(PG8_SA(0, 0), a2, voffA);
.LBB0_306:
	s_ashr_i32 s21, s20, 31
	s_lshl_b64 s[22:23], s[20:21], 20
	s_add_u32 s22, s60, s22
	s_addc_u32 s23, s61, s23
	s_and_b64 s[24:25], s[4:5], exec
	s_cselect_b32 s7, s23, s27
	s_cselect_b32 s21, s22, s26
	s_ashr_i32 s19, s18, 31
	s_lshl_b64 s[24:25], s[18:19], 20
	s_add_u32 s24, s68, s24
	s_addc_u32 s25, s69, s25
	s_and_b64 s[30:31], s[4:5], exec
	s_cselect_b32 s19, s25, s29
	s_cselect_b32 s33, s24, s28
	s_add_u32 s26, s26, 0x80080
	s_addc_u32 s27, s27, 0
	s_add_u32 s48, s28, 0x100
	s_addc_u32 s49, s29, 0
	s_mov_b32 s50, -2
	s_waitcnt lgkmcnt(0)
	s_waitcnt lgkmcnt(0)
	ds_read_b128 v[128:131], v181
	ds_read_b128 v[132:135], v181 offset:1024
	ds_read_b128 v[136:139], v181 offset:2048
	ds_read_b128 v[140:143], v181 offset:3072
	ds_read_b128 v[144:147], v182
	ds_read_b128 v[148:151], v182 offset:1024
	ds_read_b128 v[168:171], v182 offset:2048
	ds_read_b128 v[172:175], v182 offset:3072
	s_add_u32 s28, s26, 0xfff80080
	s_addc_u32 s29, s27, -1
	s_cmp_eq_u32 s50, 28
	s_cselect_b32 s31, s7, s29
	s_cselect_b32 s30, s21, s28
	s_cselect_b32 s29, s19, s49
	s_cselect_b32 s28, s33, s48
	s_add_i32 m0, s35, 0xc000
	ds_read_b128 v[186:189], v183
	ds_read_b128 v[190:193], v183 offset:1024
	ds_read_b128 v[198:201], v183 offset:2048
	ds_read_b128 v[202:205], v183 offset:3072
	ds_read_b128 v[206:209], v183 offset:4096
	ds_read_b128 v[210:213], v183 offset:5120
	ds_read_b128 v[214:217], v183 offset:6144
	ds_read_b128 v[218:221], v183 offset:7168
	global_load_lds_dwordx4 v160, s[26:27]
	s_add_i32 m0, s35, 0xe000
	s_nop 0
	global_load_lds_dwordx4 v162, s[26:27]
	s_waitcnt lgkmcnt(0)
	s_setprio 1
	s_barrier
	v_mfma_f32_16x16x32_bf16 v[124:127], v[128:131], v[186:189], 0
	v_mfma_f32_16x16x32_bf16 v[120:123], v[136:139], v[186:189], 0
	v_mfma_f32_16x16x32_bf16 v[104:107], v[128:131], v[198:201], 0
	v_mfma_f32_16x16x32_bf16 v[108:111], v[136:139], v[198:201], 0
	v_mfma_f32_16x16x32_bf16 v[88:91], v[128:131], v[206:209], 0
	v_mfma_f32_16x16x32_bf16 v[92:95], v[136:139], v[206:209], 0
	v_mfma_f32_16x16x32_bf16 v[72:75], v[128:131], v[214:217], 0
	v_mfma_f32_16x16x32_bf16 v[76:79], v[136:139], v[214:217], 0
	v_mfma_f32_16x16x32_bf16 v[124:127], v[132:135], v[190:193], v[124:127]
	v_mfma_f32_16x16x32_bf16 v[120:123], v[140:143], v[190:193], v[120:123]
	v_mfma_f32_16x16x32_bf16 v[104:107], v[132:135], v[202:205], v[104:107]
	v_mfma_f32_16x16x32_bf16 v[108:111], v[140:143], v[202:205], v[108:111]
	v_mfma_f32_16x16x32_bf16 v[88:91], v[132:135], v[210:213], v[88:91]
	v_mfma_f32_16x16x32_bf16 v[92:95], v[140:143], v[210:213], v[92:95]
	v_mfma_f32_16x16x32_bf16 v[72:75], v[132:135], v[218:221], v[72:75]
	v_mfma_f32_16x16x32_bf16 v[76:79], v[140:143], v[218:221], v[76:79]
	v_mfma_f32_16x16x32_bf16 v[116:119], v[144:147], v[186:189], 0
	v_mfma_f32_16x16x32_bf16 v[112:115], v[168:171], v[186:189], 0
	v_mfma_f32_16x16x32_bf16 v[100:103], v[144:147], v[198:201], 0
	v_mfma_f32_16x16x32_bf16 v[96:99], v[168:171], v[198:201], 0
	v_mfma_f32_16x16x32_bf16 v[84:87], v[144:147], v[206:209], 0
	v_mfma_f32_16x16x32_bf16 v[80:83], v[168:171], v[206:209], 0
	v_mfma_f32_16x16x32_bf16 v[68:71], v[144:147], v[214:217], 0
	v_mfma_f32_16x16x32_bf16 v[64:67], v[168:171], v[214:217], 0
	v_mfma_f32_16x16x32_bf16 v[116:119], v[148:151], v[190:193], v[116:119]
	v_mfma_f32_16x16x32_bf16 v[112:115], v[172:175], v[190:193], v[112:115]
	v_mfma_f32_16x16x32_bf16 v[100:103], v[148:151], v[202:205], v[100:103]
	v_mfma_f32_16x16x32_bf16 v[96:99], v[172:175], v[202:205], v[96:99]
	v_mfma_f32_16x16x32_bf16 v[84:87], v[148:151], v[210:213], v[84:87]
	v_mfma_f32_16x16x32_bf16 v[80:83], v[172:175], v[210:213], v[80:83]
	v_mfma_f32_16x16x32_bf16 v[68:71], v[148:151], v[218:221], v[68:71]
	v_mfma_f32_16x16x32_bf16 v[64:67], v[172:175], v[218:221], v[64:67]
	s_barrier
	s_setprio 0
	s_add_i32 s51, s62, s34
	v_lshl_add_u64 v[176:177], s[28:29], 0, v[154:155]
	s_mov_b32 m0, s51
	ds_read_b128 v[186:189], v183 offset:16384
	ds_read_b128 v[190:193], v183 offset:17408
	ds_read_b128 v[198:201], v183 offset:18432
	ds_read_b128 v[202:205], v183 offset:19456
	ds_read_b128 v[206:209], v183 offset:20480
	ds_read_b128 v[210:213], v183 offset:21504
	ds_read_b128 v[214:217], v183 offset:22528
	ds_read_b128 v[218:221], v183 offset:23552
	global_load_lds_dwordx4 v[176:177], off
	s_add_i32 m0, s51, 0x2000
	s_add_u32 s52, s28, 0x80000
	v_lshl_add_u64 v[194:195], s[28:29], 0, v[158:159]
	s_addc_u32 s53, s29, 0
	s_add_i32 s51, s63, s34
	global_load_lds_dwordx4 v[194:195], off
	s_mov_b32 m0, s51
	v_lshl_add_u64 v[224:225], s[30:31], 0, v[156:157]
	global_load_lds_dwordx4 v154, s[52:53]
	s_add_i32 m0, s51, 0x2000
	s_nop 0
	global_load_lds_dwordx4 v158, s[52:53]
	s_mov_b32 m0, s35
	v_lshl_add_u64 v[222:223], s[30:31], 0, v[152:153]
	global_load_lds_dwordx4 v[222:223], off
	s_mov_b32 m0, s37
	s_nop 0
	global_load_lds_dwordx4 v[224:225], off
	s_waitcnt lgkmcnt(0)
	s_setprio 1
	s_barrier
; #define PG8_STAGE(bufoff, gbase, voff) do { _Pragma("unroll") for (int _i = 0; _i < 2; ++_i) \
;         __builtin_amdgcn_global_load_lds((const unsigned*)((const char*)(gbase) + (voff)[_i]), (PG8_LAS unsigned*)(lds + (bufoff) + ldsw + _i * 8192), 16, 0, 0); } while (0)
; #define PG8_LDA(dst, b, h) do { _Pragma("unroll") for (int m = 0; m < 4; ++m) _Pragma("unroll") for (int k = 0; k < 2; ++k) dst[m][k] = *(const PG8_LAS bf16x8*)(lds + PG8_SA(b, h) + aoff + m * 2048 + k * 1024); } while (0)
; #define PG8_LDB(dst, b, h) do { _Pragma("unroll") for (int n = 0; n < 2; ++n) _Pragma("unroll") for (int k = 0; k < 2; ++k) dst[n][k] = *(const PG8_LAS bf16x8*)(lds + PG8_SB(b, h) + boff + n * 2048 + k * 1024); } while (0)
; #define PG8_MMA(ai, bj, At, Bt) do { __builtin_amdgcn_s_setprio(1); _Pragma("unroll") for (int m = 0; m < 4; ++m) _Pragma("unroll") for (int n = 0; n < 2; ++n) _Pragma("unroll") for (int k = 0; k < 2; ++k) \
;         acc[ai][bj][m][n] = __builtin_amdgcn_mfma_f32_16x16x32_bf16(Bt[n][k], At[m][k], acc[ai][bj][m][n], 0, 0, 0); __builtin_amdgcn_s_setprio(0); } while (0)
; #define PG8_WAIT_V(n) asm volatile("s_waitcnt vmcnt(" #n ")" ::: "memory")
; #define PG8_WAIT_L(n) asm volatile("s_waitcnt lgkmcnt(" #n ")" ::: "memory")
; #define PG8_BAR __builtin_amdgcn_s_barrier()
; #define PG8_SCHED __builtin_amdgcn_sched_barrier(0)
; template <class Epi, class Sched, bool ALIGN_EPI = false, bool SP2 = false>
; __device__ __forceinline__ void gemm_phase(PG8_LAS unsigned char* lds, const Gemm g, const Sched& S, const Epi& E) {
;     ...
;             PG8_WAIT_V(8); PG8_WAIT_L(0); PG8_BAR; PG8_MMA(1, 0, At, B0); PG8_MMA(1, 1, At, B1); PG8_BAR; PG8_SCHED;
;             PG8_LDB(B0, 1, 0); PG8_LDB(B1, 1, 1); PG8_SCHED; PG8_LDA(At, 1, 0); PG8_STAGE(PG8_SA(0, 1), a2 + hstep, voffA);
;             PG8_WAIT_V(8); PG8_WAIT_L(0); PG8_BAR; PG8_MMA(0, 0, At, B0); PG8_MMA(0, 1, At, B1); PG8_BAR; PG8_SCHED;
	v_mfma_f32_16x16x32_bf16 v[56:59], v[128:131], v[186:189], 0
	v_mfma_f32_16x16x32_bf16 v[60:63], v[136:139], v[186:189], 0
	v_mfma_f32_16x16x32_bf16 v[40:43], v[128:131], v[198:201], 0
	v_mfma_f32_16x16x32_bf16 v[44:47], v[136:139], v[198:201], 0
	v_mfma_f32_16x16x32_bf16 v[24:27], v[128:131], v[206:209], 0
	v_mfma_f32_16x16x32_bf16 v[28:31], v[136:139], v[206:209], 0
	v_mfma_f32_16x16x32_bf16 v[8:11], v[128:131], v[214:217], 0
	v_mfma_f32_16x16x32_bf16 v[12:15], v[136:139], v[214:217], 0
	v_mfma_f32_16x16x32_bf16 v[56:59], v[132:135], v[190:193], v[56:59]
	v_mfma_f32_16x16x32_bf16 v[60:63], v[140:143], v[190:193], v[60:63]
	v_mfma_f32_16x16x32_bf16 v[40:43], v[132:135], v[202:205], v[40:43]
	v_mfma_f32_16x16x32_bf16 v[44:47], v[140:143], v[202:205], v[44:47]
	v_mfma_f32_16x16x32_bf16 v[24:27], v[132:135], v[210:213], v[24:27]
	v_mfma_f32_16x16x32_bf16 v[28:31], v[140:143], v[210:213], v[28:31]
	v_mfma_f32_16x16x32_bf16 v[8:11], v[132:135], v[218:221], v[8:11]
	v_mfma_f32_16x16x32_bf16 v[12:15], v[140:143], v[218:221], v[12:15]
	v_mfma_f32_16x16x32_bf16 v[52:55], v[144:147], v[186:189], 0
	v_mfma_f32_16x16x32_bf16 v[48:51], v[168:171], v[186:189], 0
	v_mfma_f32_16x16x32_bf16 v[36:39], v[144:147], v[198:201], 0
	v_mfma_f32_16x16x32_bf16 v[32:35], v[168:171], v[198:201], 0
	v_mfma_f32_16x16x32_bf16 v[20:23], v[144:147], v[206:209], 0
	v_mfma_f32_16x16x32_bf16 v[16:19], v[168:171], v[206:209], 0
	v_mfma_f32_16x16x32_bf16 v[4:7], v[144:147], v[214:217], 0
	v_mfma_f32_16x16x32_bf16 v[0:3], v[168:171], v[214:217], 0
	v_mfma_f32_16x16x32_bf16 v[52:55], v[148:151], v[190:193], v[52:55]
	v_mfma_f32_16x16x32_bf16 v[48:51], v[172:175], v[190:193], v[48:51]
	v_mfma_f32_16x16x32_bf16 v[36:39], v[148:151], v[202:205], v[36:39]
	v_mfma_f32_16x16x32_bf16 v[32:35], v[172:175], v[202:205], v[32:35]
	v_mfma_f32_16x16x32_bf16 v[20:23], v[148:151], v[210:213], v[20:23]
	v_mfma_f32_16x16x32_bf16 v[16:19], v[172:175], v[210:213], v[16:19]
	v_mfma_f32_16x16x32_bf16 v[4:7], v[148:151], v[218:221], v[4:7]
	v_mfma_f32_16x16x32_bf16 v[0:3], v[172:175], v[218:221], v[0:3]
	s_barrier
	s_setprio 0
	s_add_i32 s51, 0, 0x18000
	s_add_i32 s52, 0, 0x1c000
	v_add_u32_e32 v140, s51, v179
	v_add_u32_e32 v172, s52, v179
	ds_read_b128 v[128:131], v140
	ds_read_b128 v[132:135], v140 offset:1024
	ds_read_b128 v[136:139], v140 offset:2048
	ds_read_b128 v[140:143], v140 offset:3072
	ds_read_b128 v[144:147], v172
	ds_read_b128 v[148:151], v172 offset:1024
	ds_read_b128 v[168:171], v172 offset:2048
	ds_read_b128 v[172:175], v172 offset:3072
	s_add_u32 s30, s30, 0x80000
	s_addc_u32 s31, s31, 0
	s_mov_b32 m0, s39
	ds_read_b128 v[186:189], v183 offset:32768
	ds_read_b128 v[190:193], v183 offset:33792
	ds_read_b128 v[198:201], v183 offset:34816
	ds_read_b128 v[202:205], v183 offset:35840
	ds_read_b128 v[206:209], v183 offset:36864
	ds_read_b128 v[210:213], v183 offset:37888
	ds_read_b128 v[214:217], v183 offset:38912
	ds_read_b128 v[218:221], v183 offset:39936
	global_load_lds_dwordx4 v152, s[30:31]
	s_mov_b32 m0, s42
	v_lshl_add_u64 v[226:227], s[30:31], 0, v[156:157]
	global_load_lds_dwordx4 v[226:227], off
	s_waitcnt vmcnt(8) lgkmcnt(0)
	s_setprio 1
	s_barrier
	v_mfma_f32_16x16x32_bf16 v[124:127], v[128:131], v[186:189], v[124:127]
	v_mfma_f32_16x16x32_bf16 v[120:123], v[136:139], v[186:189], v[120:123]
	v_mfma_f32_16x16x32_bf16 v[104:107], v[128:131], v[198:201], v[104:107]
	v_mfma_f32_16x16x32_bf16 v[108:111], v[136:139], v[198:201], v[108:111]
	v_mfma_f32_16x16x32_bf16 v[88:91], v[128:131], v[206:209], v[88:91]
	v_mfma_f32_16x16x32_bf16 v[92:95], v[136:139], v[206:209], v[92:95]
	v_mfma_f32_16x16x32_bf16 v[72:75], v[128:131], v[214:217], v[72:75]
	v_mfma_f32_16x16x32_bf16 v[76:79], v[136:139], v[214:217], v[76:79]
	v_mfma_f32_16x16x32_bf16 v[124:127], v[132:135], v[190:193], v[124:127]
	v_mfma_f32_16x16x32_bf16 v[120:123], v[140:143], v[190:193], v[120:123]
	v_mfma_f32_16x16x32_bf16 v[104:107], v[132:135], v[202:205], v[104:107]
	v_mfma_f32_16x16x32_bf16 v[108:111], v[140:143], v[202:205], v[108:111]
	v_mfma_f32_16x16x32_bf16 v[88:91], v[132:135], v[210:213], v[88:91]
	v_mfma_f32_16x16x32_bf16 v[92:95], v[140:143], v[210:213], v[92:95]
	v_mfma_f32_16x16x32_bf16 v[72:75], v[132:135], v[218:221], v[72:75]
	v_mfma_f32_16x16x32_bf16 v[76:79], v[140:143], v[218:221], v[76:79]
	v_mfma_f32_16x16x32_bf16 v[116:119], v[144:147], v[186:189], v[116:119]
	v_mfma_f32_16x16x32_bf16 v[112:115], v[168:171], v[186:189], v[112:115]
	v_mfma_f32_16x16x32_bf16 v[100:103], v[144:147], v[198:201], v[100:103]
	v_mfma_f32_16x16x32_bf16 v[96:99], v[168:171], v[198:201], v[96:99]
	v_mfma_f32_16x16x32_bf16 v[84:87], v[144:147], v[206:209], v[84:87]
	v_mfma_f32_16x16x32_bf16 v[80:83], v[168:171], v[206:209], v[80:83]
	v_mfma_f32_16x16x32_bf16 v[68:71], v[144:147], v[214:217], v[68:71]
	v_mfma_f32_16x16x32_bf16 v[64:67], v[168:171], v[214:217], v[64:67]
	v_mfma_f32_16x16x32_bf16 v[116:119], v[148:151], v[190:193], v[116:119]
	v_mfma_f32_16x16x32_bf16 v[112:115], v[172:175], v[190:193], v[112:115]
	v_mfma_f32_16x16x32_bf16 v[100:103], v[148:151], v[202:205], v[100:103]
	v_mfma_f32_16x16x32_bf16 v[96:99], v[172:175], v[202:205], v[96:99]
	v_mfma_f32_16x16x32_bf16 v[84:87], v[148:151], v[210:213], v[84:87]
	v_mfma_f32_16x16x32_bf16 v[80:83], v[172:175], v[210:213], v[80:83]
	v_mfma_f32_16x16x32_bf16 v[68:71], v[148:151], v[218:221], v[68:71]
	v_mfma_f32_16x16x32_bf16 v[64:67], v[172:175], v[218:221], v[64:67]
	s_barrier
; #define PG8_STAGE(bufoff, gbase, voff) do { _Pragma("unroll") for (int _i = 0; _i < 2; ++_i) \
;         __builtin_amdgcn_global_load_lds((const unsigned*)((const char*)(gbase) + (voff)[_i]), (PG8_LAS unsigned*)(lds + (bufoff) + ldsw + _i * 8192), 16, 0, 0); } while (0)
; #define PG8_LDA(dst, b, h) do { _Pragma("unroll") for (int m = 0; m < 4; ++m) _Pragma("unroll") for (int k = 0; k < 2; ++k) dst[m][k] = *(const PG8_LAS bf16x8*)(lds + PG8_SA(b, h) + aoff + m * 2048 + k * 1024); } while (0)
; #define PG8_LDB(dst, b, h) do { _Pragma("unroll") for (int n = 0; n < 2; ++n) _Pragma("unroll") for (int k = 0; k < 2; ++k) dst[n][k] = *(const PG8_LAS bf16x8*)(lds + PG8_SB(b, h) + boff + n * 2048 + k * 1024); } while (0)
; #define PG8_MMA(ai, bj, At, Bt) do { __builtin_amdgcn_s_setprio(1); _Pragma("unroll") for (int m = 0; m < 4; ++m) _Pragma("unroll") for (int n = 0; n < 2; ++n) _Pragma("unroll") for (int k = 0; k < 2; ++k) \
;         acc[ai][bj][m][n] = __builtin_amdgcn_mfma_f32_16x16x32_bf16(Bt[n][k], At[m][k], acc[ai][bj][m][n], 0, 0, 0); __builtin_amdgcn_s_setprio(0); } while (0)
; #define PG8_WAIT_V(n) asm volatile("s_waitcnt vmcnt(" #n ")" ::: "memory")
; template <class Epi, class Sched, bool ALIGN_EPI = false, bool SP2 = false>
; __device__ __forceinline__ void gemm_phase(PG8_LAS unsigned char* lds, const Gemm g, const Sched& S, const Epi& E) {
;     ...
;             PG8_LDB(B0, 0, 0); PG8_LDB(B1, 0, 1); PG8_SCHED; PG8_LDA(At, 0, 0); PG8_STAGE(PG8_SA(1, 1), a1 + hstep, voffA);
;             PG8_WAIT_V(8); PG8_WAIT_L(0); PG8_BAR; PG8_MMA(0, 0, At, B0); PG8_MMA(0, 1, At, B1); PG8_BAR; PG8_SCHED;
;             PG8_LDA(At, 0, 1); PG8_STAGE(PG8_SB(0, 0), b2, voffB); PG8_STAGE(PG8_SB(0, 1), b2 + hstep, voffB); PG8_STAGE(PG8_SA(0, 0), a2, voffA);
;             PG8_WAIT_V(8); PG8_WAIT_L(0); PG8_BAR; PG8_MMA(1, 0, At, B0); PG8_MMA(1, 1, At, B1); PG8_BAR; PG8_SCHED;
;             PG8_LDB(B0, 1, 0); PG8_LDB(B1, 1, 1); PG8_SCHED; PG8_LDA(At, 1, 0); PG8_STAGE(PG8_SA(0, 1), a2 + hstep, voffA);
;             PG8_WAIT_V(8); PG8_WAIT_L(0); PG8_BAR; PG8_MMA(0, 0, At, B0); PG8_MMA(0, 1, At, B1); PG8_BAR; PG8_SCHED;
;             PG8_LDA(At, 1, 1); PG8_STAGE(PG8_SB(1, 0), b3, voffB); PG8_STAGE(PG8_SB(1, 1), b3 + hstep, voffB); PG8_STAGE(PG8_SA(1, 0), a3, voffA);
;             PG8_WAIT_V(8); PG8_WAIT_L(0); PG8_BAR; PG8_MMA(1, 0, At, B0); PG8_MMA(1, 1, At, B1); PG8_BAR; PG8_SCHED;
	s_setprio 0
	s_add_i32 s30, s51, s34
	v_lshl_add_u64 v[176:177], v[176:177], 0, s[12:13]
	s_mov_b32 m0, s30
	ds_read_b128 v[186:189], v183 offset:49152
	ds_read_b128 v[190:193], v183 offset:50176
	ds_read_b128 v[198:201], v183 offset:51200
	ds_read_b128 v[202:205], v183 offset:52224
	ds_read_b128 v[206:209], v183 offset:53248
	ds_read_b128 v[210:213], v183 offset:54272
	ds_read_b128 v[214:217], v183 offset:55296
	ds_read_b128 v[218:221], v183 offset:56320
	global_load_lds_dwordx4 v[176:177], off
	s_add_i32 m0, s30, 0x2000
	s_add_u32 s28, s28, 0x80080
	v_lshl_add_u64 v[176:177], v[194:195], 0, s[12:13]
	s_addc_u32 s29, s29, 0
	s_add_i32 s30, s52, s34
	global_load_lds_dwordx4 v[176:177], off
	s_mov_b32 m0, s30
	s_nop 0
	global_load_lds_dwordx4 v154, s[28:29]
	s_add_i32 m0, s30, 0x2000
	v_lshl_add_u64 v[176:177], s[28:29], 0, v[158:159]
	global_load_lds_dwordx4 v[176:177], off
	s_mov_b32 m0, s44
	v_lshl_add_u64 v[176:177], v[222:223], 0, s[12:13]
	global_load_lds_dwordx4 v[176:177], off
	s_mov_b32 m0, s45
	v_lshl_add_u64 v[176:177], v[224:225], 0, s[12:13]
	global_load_lds_dwordx4 v[176:177], off
	s_waitcnt vmcnt(8) lgkmcnt(0)
	s_setprio 1
	s_barrier
	v_mfma_f32_16x16x32_bf16 v[56:59], v[128:131], v[186:189], v[56:59]
	v_mfma_f32_16x16x32_bf16 v[60:63], v[136:139], v[186:189], v[60:63]
	v_mfma_f32_16x16x32_bf16 v[40:43], v[128:131], v[198:201], v[40:43]
	v_mfma_f32_16x16x32_bf16 v[44:47], v[136:139], v[198:201], v[44:47]
	v_mfma_f32_16x16x32_bf16 v[24:27], v[128:131], v[206:209], v[24:27]
	v_mfma_f32_16x16x32_bf16 v[28:31], v[136:139], v[206:209], v[28:31]
	v_mfma_f32_16x16x32_bf16 v[8:11], v[128:131], v[214:217], v[8:11]
	v_mfma_f32_16x16x32_bf16 v[12:15], v[136:139], v[214:217], v[12:15]
	v_mfma_f32_16x16x32_bf16 v[56:59], v[132:135], v[190:193], v[56:59]
	v_mfma_f32_16x16x32_bf16 v[60:63], v[140:143], v[190:193], v[60:63]
	v_mfma_f32_16x16x32_bf16 v[40:43], v[132:135], v[202:205], v[40:43]
	v_mfma_f32_16x16x32_bf16 v[44:47], v[140:143], v[202:205], v[44:47]
	v_mfma_f32_16x16x32_bf16 v[24:27], v[132:135], v[210:213], v[24:27]
	v_mfma_f32_16x16x32_bf16 v[28:31], v[140:143], v[210:213], v[28:31]
	v_mfma_f32_16x16x32_bf16 v[8:11], v[132:135], v[218:221], v[8:11]
	v_mfma_f32_16x16x32_bf16 v[12:15], v[140:143], v[218:221], v[12:15]
	v_mfma_f32_16x16x32_bf16 v[52:55], v[144:147], v[186:189], v[52:55]
	v_mfma_f32_16x16x32_bf16 v[48:51], v[168:171], v[186:189], v[48:51]
	v_mfma_f32_16x16x32_bf16 v[36:39], v[144:147], v[198:201], v[36:39]
	v_mfma_f32_16x16x32_bf16 v[32:35], v[168:171], v[198:201], v[32:35]
	v_mfma_f32_16x16x32_bf16 v[20:23], v[144:147], v[206:209], v[20:23]
	v_mfma_f32_16x16x32_bf16 v[16:19], v[168:171], v[206:209], v[16:19]
	v_mfma_f32_16x16x32_bf16 v[4:7], v[144:147], v[214:217], v[4:7]
	v_mfma_f32_16x16x32_bf16 v[0:3], v[168:171], v[214:217], v[0:3]
	v_mfma_f32_16x16x32_bf16 v[52:55], v[148:151], v[190:193], v[52:55]
	v_mfma_f32_16x16x32_bf16 v[48:51], v[172:175], v[190:193], v[48:51]
	v_mfma_f32_16x16x32_bf16 v[36:39], v[148:151], v[202:205], v[36:39]
	v_mfma_f32_16x16x32_bf16 v[32:35], v[172:175], v[202:205], v[32:35]
	v_mfma_f32_16x16x32_bf16 v[20:23], v[148:151], v[210:213], v[20:23]
	v_mfma_f32_16x16x32_bf16 v[16:19], v[172:175], v[210:213], v[16:19]
	v_mfma_f32_16x16x32_bf16 v[4:7], v[148:151], v[218:221], v[4:7]
	v_mfma_f32_16x16x32_bf16 v[0:3], v[172:175], v[218:221], v[0:3]
	s_barrier
	s_setprio 0
	s_add_i32 s50, s50, 2
	s_add_u32 s26, s26, 0x100
	s_addc_u32 s27, s27, 0
	s_add_u32 s48, s48, 0x100
	s_addc_u32 s49, s49, 0
.LBB0_307:
	ds_read_b128 v[128:131], v181
	ds_read_b128 v[132:135], v181 offset:1024
	ds_read_b128 v[136:139], v181 offset:2048
	ds_read_b128 v[140:143], v181 offset:3072
	ds_read_b128 v[144:147], v182
	ds_read_b128 v[148:151], v182 offset:1024
	ds_read_b128 v[168:171], v182 offset:2048
	ds_read_b128 v[172:175], v182 offset:3072
	s_add_u32 s28, s26, 0xfff80080
	s_addc_u32 s29, s27, -1
	s_cmp_eq_u32 s50, 28
	s_cselect_b32 s31, s7, s29
	s_cselect_b32 s30, s21, s28
	s_cselect_b32 s29, s19, s49
	s_cselect_b32 s28, s33, s48
	s_add_i32 m0, s35, 0xc000
	ds_read_b128 v[186:189], v183
	ds_read_b128 v[190:193], v183 offset:1024
	ds_read_b128 v[198:201], v183 offset:2048
	ds_read_b128 v[202:205], v183 offset:3072
	ds_read_b128 v[206:209], v183 offset:4096
	ds_read_b128 v[210:213], v183 offset:5120
	ds_read_b128 v[214:217], v183 offset:6144
	ds_read_b128 v[218:221], v183 offset:7168
	global_load_lds_dwordx4 v160, s[26:27]
	s_add_i32 m0, s35, 0xe000
	s_nop 0
	global_load_lds_dwordx4 v162, s[26:27]
	s_waitcnt vmcnt(8) lgkmcnt(0)
	s_setprio 1
	s_barrier
; #define PG8_STAGE(bufoff, gbase, voff) do { _Pragma("unroll") for (int _i = 0; _i < 2; ++_i) \
;         __builtin_amdgcn_global_load_lds((const unsigned*)((const char*)(gbase) + (voff)[_i]), (PG8_LAS unsigned*)(lds + (bufoff) + ldsw + _i * 8192), 16, 0, 0); } while (0)
; #define PG8_LDA(dst, b, h) do { _Pragma("unroll") for (int m = 0; m < 4; ++m) _Pragma("unroll") for (int k = 0; k < 2; ++k) dst[m][k] = *(const PG8_LAS bf16x8*)(lds + PG8_SA(b, h) + aoff + m * 2048 + k * 1024); } while (0)
; #define PG8_MMA(ai, bj, At, Bt) do { __builtin_amdgcn_s_setprio(1); _Pragma("unroll") for (int m = 0; m < 4; ++m) _Pragma("unroll") for (int n = 0; n < 2; ++n) _Pragma("unroll") for (int k = 0; k < 2; ++k) \
;         acc[ai][bj][m][n] = __builtin_amdgcn_mfma_f32_16x16x32_bf16(Bt[n][k], At[m][k], acc[ai][bj][m][n], 0, 0, 0); __builtin_amdgcn_s_setprio(0); } while (0)
; #define PG8_WAIT_V(n) asm volatile("s_waitcnt vmcnt(" #n ")" ::: "memory")
; #define PG8_WAIT_L(n) asm volatile("s_waitcnt lgkmcnt(" #n ")" ::: "memory")
; #define PG8_BAR __builtin_amdgcn_s_barrier()
; #define PG8_SCHED __builtin_amdgcn_sched_barrier(0)
; template <class Epi, class Sched, bool ALIGN_EPI = false, bool SP2 = false>
; __device__ __forceinline__ void gemm_phase(PG8_LAS unsigned char* lds, const Gemm g, const Sched& S, const Epi& E) {
;     ...
;             PG8_WAIT_V(8); PG8_WAIT_L(0); PG8_BAR; PG8_MMA(0, 0, At, B0); PG8_MMA(0, 1, At, B1); PG8_BAR; PG8_SCHED;
;             PG8_LDA(At, 0, 1); PG8_STAGE(PG8_SB(0, 0), b2, voffB); PG8_STAGE(PG8_SB(0, 1), b2 + hstep, voffB); PG8_STAGE(PG8_SA(0, 0), a2, voffA);
;             PG8_WAIT_V(8); PG8_WAIT_L(0); PG8_BAR; PG8_MMA(1, 0, At, B0); PG8_MMA(1, 1, At, B1); PG8_BAR; PG8_SCHED;
	v_mfma_f32_16x16x32_bf16 v[124:127], v[128:131], v[186:189], v[124:127]
	v_mfma_f32_16x16x32_bf16 v[120:123], v[136:139], v[186:189], v[120:123]
	v_mfma_f32_16x16x32_bf16 v[104:107], v[128:131], v[198:201], v[104:107]
	v_mfma_f32_16x16x32_bf16 v[108:111], v[136:139], v[198:201], v[108:111]
	v_mfma_f32_16x16x32_bf16 v[88:91], v[128:131], v[206:209], v[88:91]
	v_mfma_f32_16x16x32_bf16 v[92:95], v[136:139], v[206:209], v[92:95]
	v_mfma_f32_16x16x32_bf16 v[72:75], v[128:131], v[214:217], v[72:75]
	v_mfma_f32_16x16x32_bf16 v[76:79], v[136:139], v[214:217], v[76:79]
	v_mfma_f32_16x16x32_bf16 v[124:127], v[132:135], v[190:193], v[124:127]
	v_mfma_f32_16x16x32_bf16 v[120:123], v[140:143], v[190:193], v[120:123]
	v_mfma_f32_16x16x32_bf16 v[104:107], v[132:135], v[202:205], v[104:107]
	v_mfma_f32_16x16x32_bf16 v[108:111], v[140:143], v[202:205], v[108:111]
	v_mfma_f32_16x16x32_bf16 v[88:91], v[132:135], v[210:213], v[88:91]
	v_mfma_f32_16x16x32_bf16 v[92:95], v[140:143], v[210:213], v[92:95]
	v_mfma_f32_16x16x32_bf16 v[72:75], v[132:135], v[218:221], v[72:75]
	v_mfma_f32_16x16x32_bf16 v[76:79], v[140:143], v[218:221], v[76:79]
	v_mfma_f32_16x16x32_bf16 v[116:119], v[144:147], v[186:189], v[116:119]
	v_mfma_f32_16x16x32_bf16 v[112:115], v[168:171], v[186:189], v[112:115]
	v_mfma_f32_16x16x32_bf16 v[100:103], v[144:147], v[198:201], v[100:103]
	v_mfma_f32_16x16x32_bf16 v[96:99], v[168:171], v[198:201], v[96:99]
	v_mfma_f32_16x16x32_bf16 v[84:87], v[144:147], v[206:209], v[84:87]
	v_mfma_f32_16x16x32_bf16 v[80:83], v[168:171], v[206:209], v[80:83]
	v_mfma_f32_16x16x32_bf16 v[68:71], v[144:147], v[214:217], v[68:71]
	v_mfma_f32_16x16x32_bf16 v[64:67], v[168:171], v[214:217], v[64:67]
	v_mfma_f32_16x16x32_bf16 v[116:119], v[148:151], v[190:193], v[116:119]
	v_mfma_f32_16x16x32_bf16 v[112:115], v[172:175], v[190:193], v[112:115]
	v_mfma_f32_16x16x32_bf16 v[100:103], v[148:151], v[202:205], v[100:103]
	v_mfma_f32_16x16x32_bf16 v[96:99], v[172:175], v[202:205], v[96:99]
	v_mfma_f32_16x16x32_bf16 v[84:87], v[148:151], v[210:213], v[84:87]
	v_mfma_f32_16x16x32_bf16 v[80:83], v[172:175], v[210:213], v[80:83]
	v_mfma_f32_16x16x32_bf16 v[68:71], v[148:151], v[218:221], v[68:71]
	v_mfma_f32_16x16x32_bf16 v[64:67], v[172:175], v[218:221], v[64:67]
	s_barrier
	s_setprio 0
	s_add_i32 s51, s62, s34
	v_lshl_add_u64 v[176:177], s[28:29], 0, v[154:155]
	s_mov_b32 m0, s51
	ds_read_b128 v[186:189], v183 offset:16384
	ds_read_b128 v[190:193], v183 offset:17408
	ds_read_b128 v[198:201], v183 offset:18432
	ds_read_b128 v[202:205], v183 offset:19456
	ds_read_b128 v[206:209], v183 offset:20480
	ds_read_b128 v[210:213], v183 offset:21504
	ds_read_b128 v[214:217], v183 offset:22528
	ds_read_b128 v[218:221], v183 offset:23552
	global_load_lds_dwordx4 v[176:177], off
	s_add_i32 m0, s51, 0x2000
	s_add_u32 s52, s28, 0x80000
	v_lshl_add_u64 v[194:195], s[28:29], 0, v[158:159]
	s_addc_u32 s53, s29, 0
	s_add_i32 s51, s63, s34
	global_load_lds_dwordx4 v[194:195], off
	s_mov_b32 m0, s51
	v_lshl_add_u64 v[224:225], s[30:31], 0, v[156:157]
	global_load_lds_dwordx4 v154, s[52:53]
	s_add_i32 m0, s51, 0x2000
	s_nop 0
	global_load_lds_dwordx4 v158, s[52:53]
	s_mov_b32 m0, s35
	v_lshl_add_u64 v[222:223], s[30:31], 0, v[152:153]
	global_load_lds_dwordx4 v[222:223], off
	s_mov_b32 m0, s37
	s_nop 0
	global_load_lds_dwordx4 v[224:225], off
	s_waitcnt vmcnt(8) lgkmcnt(0)
	s_setprio 1
	s_barrier
	v_mfma_f32_16x16x32_bf16 v[56:59], v[128:131], v[186:189], v[56:59]
	v_mfma_f32_16x16x32_bf16 v[60:63], v[136:139], v[186:189], v[60:63]
	v_mfma_f32_16x16x32_bf16 v[40:43], v[128:131], v[198:201], v[40:43]
	v_mfma_f32_16x16x32_bf16 v[44:47], v[136:139], v[198:201], v[44:47]
	v_mfma_f32_16x16x32_bf16 v[24:27], v[128:131], v[206:209], v[24:27]
	v_mfma_f32_16x16x32_bf16 v[28:31], v[136:139], v[206:209], v[28:31]
	v_mfma_f32_16x16x32_bf16 v[8:11], v[128:131], v[214:217], v[8:11]
	v_mfma_f32_16x16x32_bf16 v[12:15], v[136:139], v[214:217], v[12:15]
	v_mfma_f32_16x16x32_bf16 v[56:59], v[132:135], v[190:193], v[56:59]
	v_mfma_f32_16x16x32_bf16 v[60:63], v[140:143], v[190:193], v[60:63]
	v_mfma_f32_16x16x32_bf16 v[40:43], v[132:135], v[202:205], v[40:43]
	v_mfma_f32_16x16x32_bf16 v[44:47], v[140:143], v[202:205], v[44:47]
	v_mfma_f32_16x16x32_bf16 v[24:27], v[132:135], v[210:213], v[24:27]
	v_mfma_f32_16x16x32_bf16 v[28:31], v[140:143], v[210:213], v[28:31]
	v_mfma_f32_16x16x32_bf16 v[8:11], v[132:135], v[218:221], v[8:11]
	v_mfma_f32_16x16x32_bf16 v[12:15], v[140:143], v[218:221], v[12:15]
	v_mfma_f32_16x16x32_bf16 v[52:55], v[144:147], v[186:189], v[52:55]
	v_mfma_f32_16x16x32_bf16 v[48:51], v[168:171], v[186:189], v[48:51]
	v_mfma_f32_16x16x32_bf16 v[36:39], v[144:147], v[198:201], v[36:39]
	v_mfma_f32_16x16x32_bf16 v[32:35], v[168:171], v[198:201], v[32:35]
	v_mfma_f32_16x16x32_bf16 v[20:23], v[144:147], v[206:209], v[20:23]
	v_mfma_f32_16x16x32_bf16 v[16:19], v[168:171], v[206:209], v[16:19]
	v_mfma_f32_16x16x32_bf16 v[4:7], v[144:147], v[214:217], v[4:7]
	v_mfma_f32_16x16x32_bf16 v[0:3], v[168:171], v[214:217], v[0:3]
	v_mfma_f32_16x16x32_bf16 v[52:55], v[148:151], v[190:193], v[52:55]
	v_mfma_f32_16x16x32_bf16 v[48:51], v[172:175], v[190:193], v[48:51]
	v_mfma_f32_16x16x32_bf16 v[36:39], v[148:151], v[202:205], v[36:39]
	v_mfma_f32_16x16x32_bf16 v[32:35], v[172:175], v[202:205], v[32:35]
	v_mfma_f32_16x16x32_bf16 v[20:23], v[148:151], v[210:213], v[20:23]
	v_mfma_f32_16x16x32_bf16 v[16:19], v[172:175], v[210:213], v[16:19]
	v_mfma_f32_16x16x32_bf16 v[4:7], v[148:151], v[218:221], v[4:7]
	v_mfma_f32_16x16x32_bf16 v[0:3], v[172:175], v[218:221], v[0:3]
	s_barrier
; #define PG8_STAGE(bufoff, gbase, voff) do { _Pragma("unroll") for (int _i = 0; _i < 2; ++_i) \
;         __builtin_amdgcn_global_load_lds((const unsigned*)((const char*)(gbase) + (voff)[_i]), (PG8_LAS unsigned*)(lds + (bufoff) + ldsw + _i * 8192), 16, 0, 0); } while (0)
; #define PG8_LDA(dst, b, h) do { _Pragma("unroll") for (int m = 0; m < 4; ++m) _Pragma("unroll") for (int k = 0; k < 2; ++k) dst[m][k] = *(const PG8_LAS bf16x8*)(lds + PG8_SA(b, h) + aoff + m * 2048 + k * 1024); } while (0)
; #define PG8_LDB(dst, b, h) do { _Pragma("unroll") for (int n = 0; n < 2; ++n) _Pragma("unroll") for (int k = 0; k < 2; ++k) dst[n][k] = *(const PG8_LAS bf16x8*)(lds + PG8_SB(b, h) + boff + n * 2048 + k * 1024); } while (0)
; #define PG8_MMA(ai, bj, At, Bt) do { __builtin_amdgcn_s_setprio(1); _Pragma("unroll") for (int m = 0; m < 4; ++m) _Pragma("unroll") for (int n = 0; n < 2; ++n) _Pragma("unroll") for (int k = 0; k < 2; ++k) \
;         acc[ai][bj][m][n] = __builtin_amdgcn_mfma_f32_16x16x32_bf16(Bt[n][k], At[m][k], acc[ai][bj][m][n], 0, 0, 0); __builtin_amdgcn_s_setprio(0); } while (0)
; #define PG8_WAIT_V(n) asm volatile("s_waitcnt vmcnt(" #n ")" ::: "memory")
; #define PG8_WAIT_L(n) asm volatile("s_waitcnt lgkmcnt(" #n ")" ::: "memory")
; #define PG8_BAR __builtin_amdgcn_s_barrier()
; #define PG8_SCHED __builtin_amdgcn_sched_barrier(0)
; template <class Epi, class Sched, bool ALIGN_EPI = false, bool SP2 = false>
; __device__ __forceinline__ void gemm_phase(PG8_LAS unsigned char* lds, const Gemm g, const Sched& S, const Epi& E) {
;     ...
;             PG8_LDB(B0, 1, 0); PG8_LDB(B1, 1, 1); PG8_SCHED; PG8_LDA(At, 1, 0); PG8_STAGE(PG8_SA(0, 1), a2 + hstep, voffA);
;             PG8_WAIT_V(8); PG8_WAIT_L(0); PG8_BAR; PG8_MMA(0, 0, At, B0); PG8_MMA(0, 1, At, B1); PG8_BAR; PG8_SCHED;
;             PG8_LDA(At, 1, 1); PG8_STAGE(PG8_SB(1, 0), b3, voffB); PG8_STAGE(PG8_SB(1, 1), b3 + hstep, voffB); PG8_STAGE(PG8_SA(1, 0), a3, voffA);
;             PG8_WAIT_V(8); PG8_WAIT_L(0); PG8_BAR; PG8_MMA(1, 0, At, B0); PG8_MMA(1, 1, At, B1); PG8_BAR; PG8_SCHED;
;     ...
;         }
;         if constexpr (ALIGN_EPI) { if (wr == 0) PG8_BAR; }
	s_setprio 0
	s_add_i32 s51, 0, 0x18000
	s_add_i32 s52, 0, 0x1c000
	v_add_u32_e32 v140, s51, v179
	v_add_u32_e32 v172, s52, v179
	ds_read_b128 v[128:131], v140
	ds_read_b128 v[132:135], v140 offset:1024
	ds_read_b128 v[136:139], v140 offset:2048
	ds_read_b128 v[140:143], v140 offset:3072
	ds_read_b128 v[144:147], v172
	ds_read_b128 v[148:151], v172 offset:1024
	ds_read_b128 v[168:171], v172 offset:2048
	ds_read_b128 v[172:175], v172 offset:3072
	s_add_u32 s30, s30, 0x80000
	s_addc_u32 s31, s31, 0
	s_mov_b32 m0, s39
	ds_read_b128 v[186:189], v183 offset:32768
	ds_read_b128 v[190:193], v183 offset:33792
	ds_read_b128 v[198:201], v183 offset:34816
	ds_read_b128 v[202:205], v183 offset:35840
	ds_read_b128 v[206:209], v183 offset:36864
	ds_read_b128 v[210:213], v183 offset:37888
	ds_read_b128 v[214:217], v183 offset:38912
	ds_read_b128 v[218:221], v183 offset:39936
	global_load_lds_dwordx4 v152, s[30:31]
	s_mov_b32 m0, s42
	s_nop 0
	global_load_lds_dwordx4 v156, s[30:31]
	s_waitcnt vmcnt(8) lgkmcnt(0)
	s_setprio 1
	s_barrier
	v_mfma_f32_16x16x32_bf16 v[124:127], v[128:131], v[186:189], v[124:127]
	v_mfma_f32_16x16x32_bf16 v[120:123], v[136:139], v[186:189], v[120:123]
	v_mfma_f32_16x16x32_bf16 v[104:107], v[128:131], v[198:201], v[104:107]
	v_mfma_f32_16x16x32_bf16 v[108:111], v[136:139], v[198:201], v[108:111]
	v_mfma_f32_16x16x32_bf16 v[88:91], v[128:131], v[206:209], v[88:91]
	v_mfma_f32_16x16x32_bf16 v[92:95], v[136:139], v[206:209], v[92:95]
	v_mfma_f32_16x16x32_bf16 v[72:75], v[128:131], v[214:217], v[72:75]
	v_mfma_f32_16x16x32_bf16 v[76:79], v[136:139], v[214:217], v[76:79]
	v_mfma_f32_16x16x32_bf16 v[124:127], v[132:135], v[190:193], v[124:127]
	v_mfma_f32_16x16x32_bf16 v[120:123], v[140:143], v[190:193], v[120:123]
	v_mfma_f32_16x16x32_bf16 v[104:107], v[132:135], v[202:205], v[104:107]
	v_mfma_f32_16x16x32_bf16 v[108:111], v[140:143], v[202:205], v[108:111]
	v_mfma_f32_16x16x32_bf16 v[88:91], v[132:135], v[210:213], v[88:91]
	v_mfma_f32_16x16x32_bf16 v[92:95], v[140:143], v[210:213], v[92:95]
	v_mfma_f32_16x16x32_bf16 v[72:75], v[132:135], v[218:221], v[72:75]
	v_mfma_f32_16x16x32_bf16 v[76:79], v[140:143], v[218:221], v[76:79]
	v_mfma_f32_16x16x32_bf16 v[116:119], v[144:147], v[186:189], v[116:119]
	v_mfma_f32_16x16x32_bf16 v[112:115], v[168:171], v[186:189], v[112:115]
	v_mfma_f32_16x16x32_bf16 v[100:103], v[144:147], v[198:201], v[100:103]
	v_mfma_f32_16x16x32_bf16 v[96:99], v[168:171], v[198:201], v[96:99]
	v_mfma_f32_16x16x32_bf16 v[84:87], v[144:147], v[206:209], v[84:87]
	v_mfma_f32_16x16x32_bf16 v[80:83], v[168:171], v[206:209], v[80:83]
	v_mfma_f32_16x16x32_bf16 v[68:71], v[144:147], v[214:217], v[68:71]
	v_mfma_f32_16x16x32_bf16 v[64:67], v[168:171], v[214:217], v[64:67]
	v_mfma_f32_16x16x32_bf16 v[116:119], v[148:151], v[190:193], v[116:119]
	v_mfma_f32_16x16x32_bf16 v[112:115], v[172:175], v[190:193], v[112:115]
	v_mfma_f32_16x16x32_bf16 v[100:103], v[148:151], v[202:205], v[100:103]
	v_mfma_f32_16x16x32_bf16 v[96:99], v[172:175], v[202:205], v[96:99]
	v_mfma_f32_16x16x32_bf16 v[84:87], v[148:151], v[210:213], v[84:87]
	v_mfma_f32_16x16x32_bf16 v[80:83], v[172:175], v[210:213], v[80:83]
	v_mfma_f32_16x16x32_bf16 v[68:71], v[148:151], v[218:221], v[68:71]
	v_mfma_f32_16x16x32_bf16 v[64:67], v[172:175], v[218:221], v[64:67]
	s_barrier
	s_setprio 0
	s_add_i32 s30, s51, s34
	v_lshl_add_u64 v[176:177], v[176:177], 0, s[12:13]
	s_mov_b32 m0, s30
	ds_read_b128 v[186:189], v183 offset:49152
	ds_read_b128 v[190:193], v183 offset:50176
	ds_read_b128 v[198:201], v183 offset:51200
	ds_read_b128 v[202:205], v183 offset:52224
	ds_read_b128 v[206:209], v183 offset:53248
	ds_read_b128 v[210:213], v183 offset:54272
	ds_read_b128 v[214:217], v183 offset:55296
	ds_read_b128 v[218:221], v183 offset:56320
	global_load_lds_dwordx4 v[176:177], off
	s_add_i32 m0, s30, 0x2000
	s_add_u32 s28, s28, 0x80080
	v_lshl_add_u64 v[176:177], v[194:195], 0, s[12:13]
	s_addc_u32 s29, s29, 0
	s_add_i32 s30, s52, s34
	global_load_lds_dwordx4 v[176:177], off
	s_mov_b32 m0, s30
	s_nop 0
	global_load_lds_dwordx4 v154, s[28:29]
	s_add_i32 m0, s30, 0x2000
	v_lshl_add_u64 v[176:177], s[28:29], 0, v[158:159]
	global_load_lds_dwordx4 v[176:177], off
	s_mov_b32 m0, s44
	v_lshl_add_u64 v[176:177], v[222:223], 0, s[12:13]
	global_load_lds_dwordx4 v[176:177], off
	s_mov_b32 m0, s45
	v_lshl_add_u64 v[176:177], v[224:225], 0, s[12:13]
	global_load_lds_dwordx4 v[176:177], off
	s_waitcnt vmcnt(8) lgkmcnt(0)
	s_setprio 1
	s_barrier
	v_mfma_f32_16x16x32_bf16 v[56:59], v[128:131], v[186:189], v[56:59]
	v_mfma_f32_16x16x32_bf16 v[60:63], v[136:139], v[186:189], v[60:63]
	v_mfma_f32_16x16x32_bf16 v[40:43], v[128:131], v[198:201], v[40:43]
	v_mfma_f32_16x16x32_bf16 v[44:47], v[136:139], v[198:201], v[44:47]
	v_mfma_f32_16x16x32_bf16 v[24:27], v[128:131], v[206:209], v[24:27]
	v_mfma_f32_16x16x32_bf16 v[28:31], v[136:139], v[206:209], v[28:31]
	v_mfma_f32_16x16x32_bf16 v[8:11], v[128:131], v[214:217], v[8:11]
	v_mfma_f32_16x16x32_bf16 v[12:15], v[136:139], v[214:217], v[12:15]
	v_mfma_f32_16x16x32_bf16 v[56:59], v[132:135], v[190:193], v[56:59]
	v_mfma_f32_16x16x32_bf16 v[60:63], v[140:143], v[190:193], v[60:63]
	v_mfma_f32_16x16x32_bf16 v[40:43], v[132:135], v[202:205], v[40:43]
	v_mfma_f32_16x16x32_bf16 v[44:47], v[140:143], v[202:205], v[44:47]
	v_mfma_f32_16x16x32_bf16 v[24:27], v[132:135], v[210:213], v[24:27]
	v_mfma_f32_16x16x32_bf16 v[28:31], v[140:143], v[210:213], v[28:31]
	v_mfma_f32_16x16x32_bf16 v[8:11], v[132:135], v[218:221], v[8:11]
	v_mfma_f32_16x16x32_bf16 v[12:15], v[140:143], v[218:221], v[12:15]
	v_mfma_f32_16x16x32_bf16 v[52:55], v[144:147], v[186:189], v[52:55]
	v_mfma_f32_16x16x32_bf16 v[48:51], v[168:171], v[186:189], v[48:51]
	v_mfma_f32_16x16x32_bf16 v[36:39], v[144:147], v[198:201], v[36:39]
	v_mfma_f32_16x16x32_bf16 v[32:35], v[168:171], v[198:201], v[32:35]
	v_mfma_f32_16x16x32_bf16 v[20:23], v[144:147], v[206:209], v[20:23]
	v_mfma_f32_16x16x32_bf16 v[16:19], v[168:171], v[206:209], v[16:19]
	v_mfma_f32_16x16x32_bf16 v[4:7], v[144:147], v[214:217], v[4:7]
	v_mfma_f32_16x16x32_bf16 v[0:3], v[168:171], v[214:217], v[0:3]
	v_mfma_f32_16x16x32_bf16 v[52:55], v[148:151], v[190:193], v[52:55]
	v_mfma_f32_16x16x32_bf16 v[48:51], v[172:175], v[190:193], v[48:51]
	v_mfma_f32_16x16x32_bf16 v[36:39], v[148:151], v[202:205], v[36:39]
	v_mfma_f32_16x16x32_bf16 v[32:35], v[172:175], v[202:205], v[32:35]
	v_mfma_f32_16x16x32_bf16 v[20:23], v[148:151], v[210:213], v[20:23]
	v_mfma_f32_16x16x32_bf16 v[16:19], v[172:175], v[210:213], v[16:19]
	v_mfma_f32_16x16x32_bf16 v[4:7], v[148:151], v[218:221], v[4:7]
	v_mfma_f32_16x16x32_bf16 v[0:3], v[172:175], v[218:221], v[0:3]
	s_barrier
	s_setprio 0
	s_add_i32 s50, s50, 2
	s_add_u32 s26, s26, 0x100
	s_addc_u32 s27, s27, 0
	s_add_u32 s48, s48, 0x100
	s_addc_u32 s49, s49, 0
	s_cmp_gt_u32 s50, 29
	s_cbranch_scc0 .LBB0_307
	s_and_b64 vcc, exec, s[14:15]
	s_cbranch_vccz .LBB0_310
	s_barrier

; #define PG8_STAGE(bufoff, gbase, voff) do { _Pragma("unroll") for (int _i = 0; _i < 2; ++_i) \
;         __builtin_amdgcn_global_load_lds((const unsigned*)((const char*)(gbase) + (voff)[_i]), (PG8_LAS unsigned*)(lds + (bufoff) + ldsw + _i * 8192), 16, 0, 0); } while (0)
; #define PG8_LDA(dst, b, h) do { _Pragma("unroll") for (int m = 0; m < 4; ++m) _Pragma("unroll") for (int k = 0; k < 2; ++k) dst[m][k] = *(const PG8_LAS bf16x8*)(lds + PG8_SA(b, h) + aoff + m * 2048 + k * 1024); } while (0)
; #define PG8_LDB(dst, b, h) do { _Pragma("unroll") for (int n = 0; n < 2; ++n) _Pragma("unroll") for (int k = 0; k < 2; ++k) dst[n][k] = *(const PG8_LAS bf16x8*)(lds + PG8_SB(b, h) + boff + n * 2048 + k * 1024); } while (0)
; #define PG8_MMA(ai, bj, At, Bt) do { __builtin_amdgcn_s_setprio(1); _Pragma("unroll") for (int m = 0; m < 4; ++m) _Pragma("unroll") for (int n = 0; n < 2; ++n) _Pragma("unroll") for (int k = 0; k < 2; ++k) \
;         acc[ai][bj][m][n] = __builtin_amdgcn_mfma_f32_16x16x32_bf16(Bt[n][k], At[m][k], acc[ai][bj][m][n], 0, 0, 0); __builtin_amdgcn_s_setprio(0); } while (0)
; #define PG8_BAR __builtin_amdgcn_s_barrier()
; template <class Epi, class Sched, bool ALIGN_EPI = false, bool SP2 = false>
; __device__ __forceinline__ void gemm_phase(PG8_LAS unsigned char* lds, const Gemm g, const Sched& S, const Epi& E) {
;     ...
;         const bool has_next = S.next(ui + 1, nxt);
;         const char* nA = has_next ? (const char*)g.A + (size_t)nxt.pm * tstep : cA; const char* nB = has_next ? (const char*)g.Bt + (size_t)nxt.pn * tstep : cB;
;         for (int t = 0; t < nt; t += 2) {
;             const bool last = (t == nt - 2);
;             const char* a1 = cA + (size_t)(t + 1) * kstep;
;             const char* a2 = last ? nA : cA + (size_t)(t + 2) * kstep; const char* b2 = last ? nB : cB + (size_t)(t + 2) * kstep;
;             const char* a3 = a2 + kstep; const char* b3 = b2 + kstep;
;             if (last && has_next) S.a_ready(nxt);
;             if constexpr (SP2) {
;             PG8_LDB(B0, 0, 0); PG8_LDB(B1, 0, 1); PG8_SCHED; PG8_LDA(At, 0, 0); PG8_STAGE(PG8_SA(1, 1), a1 + hstep, voffA);
;             PG8_WAIT_V(8); PG8_WAIT_L(0); PG8_BAR; PG8_MMA(0, 0, At, B0); PG8_MMA(0, 1, At, B1); PG8_BAR; PG8_SCHED;
;             PG8_LDA(At, 0, 1); PG8_STAGE(PG8_SB(0, 0), b2, voffB); PG8_STAGE(PG8_SB(0, 1), b2 + hstep, voffB); PG8_STAGE(PG8_SA(0, 0), a2, voffA);
.LBB0_490:
	s_ashr_i32 s21, s20, 31
	s_lshl_b64 s[0:1], s[20:21], 20
	v_readlane_b32 s24, v254, 51
	v_readlane_b32 s25, v254, 52
	s_add_u32 s24, s24, s0
	s_addc_u32 s25, s25, s1
	s_and_b64 s[0:1], s[22:23], exec
	s_cselect_b32 s5, s25, s31
	s_cselect_b32 s21, s24, s30
	s_ashr_i32 s19, s18, 31
	s_lshl_b64 s[0:1], s[18:19], 20
	v_readlane_b32 s26, v254, 22
	v_readlane_b32 s27, v254, 23
	s_add_u32 s26, s26, s0
	s_addc_u32 s27, s27, s1
	s_and_b64 s[0:1], s[22:23], exec
	s_cselect_b32 s19, s27, s29
	s_cselect_b32 s33, s26, s28
	s_add_u32 s0, s30, 0x80080
	s_addc_u32 s1, s31, 0
	s_add_u32 s44, s28, 0x100
	s_addc_u32 s45, s29, 0
	s_mov_b32 s48, -2
	v_add_u32_e32 v140, s68, v163
	v_add_u32_e32 v152, s69, v163
	ds_read_b128 v[128:131], v140
	ds_read_b128 v[132:135], v140 offset:1024
	ds_read_b128 v[136:139], v140 offset:2048
	ds_read_b128 v[140:143], v140 offset:3072
	ds_read_b128 v[184:187], v152
	ds_read_b128 v[218:221], v152 offset:1024
	ds_read_b128 v[222:225], v152 offset:2048
	ds_read_b128 v[226:229], v152 offset:3072
	s_add_u32 s28, s0, 0xfff80080
	s_addc_u32 s29, s1, -1
	s_cmp_eq_u32 s48, 28
	s_cselect_b32 s31, s5, s29
	s_cselect_b32 s30, s21, s28
	s_cselect_b32 s29, s19, s45
	s_cselect_b32 s28, s33, s44
	s_add_i32 m0, s17, 0xc000
	ds_read_b128 v[230:233], v214
	ds_read_b128 v[234:237], v214 offset:1024
	ds_read_b128 v[238:241], v214 offset:2048
	ds_read_b128 v[242:245], v214 offset:3072
	ds_read_b128 v[246:249], v214 offset:4096
	ds_read_b128 v[250:253], v214 offset:5120
	ds_read_b128 v[206:209], v214 offset:6144
	ds_read_b128 v[210:213], v214 offset:7168
	global_load_lds_dwordx4 v156, s[0:1]
	s_add_i32 m0, s17, 0xe000
	s_nop 0
	global_load_lds_dwordx4 v158, s[0:1]
	s_waitcnt lgkmcnt(0)
	s_setprio 1
	s_barrier
	v_mfma_f32_16x16x32_bf16 v[124:127], v[128:131], v[230:233], 0
	v_mfma_f32_16x16x32_bf16 v[120:123], v[136:139], v[230:233], 0
	v_mfma_f32_16x16x32_bf16 v[116:119], v[128:131], v[238:241], 0
	v_mfma_f32_16x16x32_bf16 v[108:111], v[136:139], v[238:241], 0
	v_mfma_f32_16x16x32_bf16 v[100:103], v[128:131], v[246:249], 0
	v_mfma_f32_16x16x32_bf16 v[92:95], v[136:139], v[246:249], 0
	v_mfma_f32_16x16x32_bf16 v[84:87], v[128:131], v[206:209], 0
	v_mfma_f32_16x16x32_bf16 v[76:79], v[136:139], v[206:209], 0
	v_mfma_f32_16x16x32_bf16 v[124:127], v[132:135], v[234:237], v[124:127]
	v_mfma_f32_16x16x32_bf16 v[120:123], v[140:143], v[234:237], v[120:123]
	v_mfma_f32_16x16x32_bf16 v[116:119], v[132:135], v[242:245], v[116:119]
	v_mfma_f32_16x16x32_bf16 v[108:111], v[140:143], v[242:245], v[108:111]
	v_mfma_f32_16x16x32_bf16 v[100:103], v[132:135], v[250:253], v[100:103]
	v_mfma_f32_16x16x32_bf16 v[92:95], v[140:143], v[250:253], v[92:95]
	v_mfma_f32_16x16x32_bf16 v[84:87], v[132:135], v[210:213], v[84:87]
	v_mfma_f32_16x16x32_bf16 v[76:79], v[140:143], v[210:213], v[76:79]
	v_mfma_f32_16x16x32_bf16 v[112:115], v[184:187], v[230:233], 0
	v_mfma_f32_16x16x32_bf16 v[104:107], v[222:225], v[230:233], 0
	v_mfma_f32_16x16x32_bf16 v[96:99], v[184:187], v[238:241], 0
	v_mfma_f32_16x16x32_bf16 v[88:91], v[222:225], v[238:241], 0
	v_mfma_f32_16x16x32_bf16 v[80:83], v[184:187], v[246:249], 0
	v_mfma_f32_16x16x32_bf16 v[72:75], v[222:225], v[246:249], 0
	v_mfma_f32_16x16x32_bf16 v[68:71], v[184:187], v[206:209], 0
	v_mfma_f32_16x16x32_bf16 v[64:67], v[222:225], v[206:209], 0
	v_mfma_f32_16x16x32_bf16 v[112:115], v[218:221], v[234:237], v[112:115]
	v_mfma_f32_16x16x32_bf16 v[104:107], v[226:229], v[234:237], v[104:107]
	v_mfma_f32_16x16x32_bf16 v[96:99], v[218:221], v[242:245], v[96:99]
	v_mfma_f32_16x16x32_bf16 v[88:91], v[226:229], v[242:245], v[88:91]
	v_mfma_f32_16x16x32_bf16 v[80:83], v[218:221], v[250:253], v[80:83]
	v_mfma_f32_16x16x32_bf16 v[72:75], v[226:229], v[250:253], v[72:75]
	v_mfma_f32_16x16x32_bf16 v[68:71], v[218:221], v[210:213], v[68:71]
	v_mfma_f32_16x16x32_bf16 v[64:67], v[226:229], v[210:213], v[64:67]
	s_barrier
	s_setprio 0
	s_add_i32 s49, s68, s34
	v_lshl_add_u64 v[172:173], s[28:29], 0, v[146:147]
	s_mov_b32 m0, s49
	ds_read_b128 v[206:209], v214 offset:16384
	ds_read_b128 v[210:213], v214 offset:17408
	ds_read_b128 v[230:233], v214 offset:18432
	ds_read_b128 v[234:237], v214 offset:19456
	ds_read_b128 v[238:241], v214 offset:20480
	ds_read_b128 v[242:245], v214 offset:21504
	ds_read_b128 v[246:249], v214 offset:22528
	ds_read_b128 v[250:253], v214 offset:23552
	global_load_lds_dwordx4 v[172:173], off
	s_add_i32 m0, s49, 0x2000
	s_add_u32 s50, s28, 0x80000
	v_lshl_add_u64 v[176:177], s[28:29], 0, v[150:151]
	s_addc_u32 s51, s29, 0
	s_add_i32 s49, s69, s34
	global_load_lds_dwordx4 v[176:177], off
	s_mov_b32 m0, s49
	v_lshl_add_u64 v[188:189], s[30:31], 0, v[148:149]
	global_load_lds_dwordx4 v146, s[50:51]
	s_add_i32 m0, s49, 0x2000
	s_nop 0
	global_load_lds_dwordx4 v150, s[50:51]
	s_mov_b32 m0, s17
	v_lshl_add_u64 v[180:181], s[30:31], 0, v[144:145]
	global_load_lds_dwordx4 v[180:181], off
	s_mov_b32 m0, s35
	s_nop 0
	global_load_lds_dwordx4 v[188:189], off
	s_waitcnt lgkmcnt(0)
	s_setprio 1
	s_barrier
; #define PG8_STAGE(bufoff, gbase, voff) do { _Pragma("unroll") for (int _i = 0; _i < 2; ++_i) \
;         __builtin_amdgcn_global_load_lds((const unsigned*)((const char*)(gbase) + (voff)[_i]), (PG8_LAS unsigned*)(lds + (bufoff) + ldsw + _i * 8192), 16, 0, 0); } while (0)
; #define PG8_LDA(dst, b, h) do { _Pragma("unroll") for (int m = 0; m < 4; ++m) _Pragma("unroll") for (int k = 0; k < 2; ++k) dst[m][k] = *(const PG8_LAS bf16x8*)(lds + PG8_SA(b, h) + aoff + m * 2048 + k * 1024); } while (0)
; #define PG8_LDB(dst, b, h) do { _Pragma("unroll") for (int n = 0; n < 2; ++n) _Pragma("unroll") for (int k = 0; k < 2; ++k) dst[n][k] = *(const PG8_LAS bf16x8*)(lds + PG8_SB(b, h) + boff + n * 2048 + k * 1024); } while (0)
; #define PG8_MMA(ai, bj, At, Bt) do { __builtin_amdgcn_s_setprio(1); _Pragma("unroll") for (int m = 0; m < 4; ++m) _Pragma("unroll") for (int n = 0; n < 2; ++n) _Pragma("unroll") for (int k = 0; k < 2; ++k) \
;         acc[ai][bj][m][n] = __builtin_amdgcn_mfma_f32_16x16x32_bf16(Bt[n][k], At[m][k], acc[ai][bj][m][n], 0, 0, 0); __builtin_amdgcn_s_setprio(0); } while (0)
; #define PG8_WAIT_V(n) asm volatile("s_waitcnt vmcnt(" #n ")" ::: "memory")
; #define PG8_WAIT_L(n) asm volatile("s_waitcnt lgkmcnt(" #n ")" ::: "memory")
; #define PG8_BAR __builtin_amdgcn_s_barrier()
; #define PG8_SCHED __builtin_amdgcn_sched_barrier(0)
; template <class Epi, class Sched, bool ALIGN_EPI = false, bool SP2 = false>
; __device__ __forceinline__ void gemm_phase(PG8_LAS unsigned char* lds, const Gemm g, const Sched& S, const Epi& E) {
;     ...
;             PG8_WAIT_V(8); PG8_WAIT_L(0); PG8_BAR; PG8_MMA(1, 0, At, B0); PG8_MMA(1, 1, At, B1); PG8_BAR; PG8_SCHED;
;             PG8_LDB(B0, 1, 0); PG8_LDB(B1, 1, 1); PG8_SCHED; PG8_LDA(At, 1, 0); PG8_STAGE(PG8_SA(0, 1), a2 + hstep, voffA);
;             PG8_WAIT_V(8); PG8_WAIT_L(0); PG8_BAR; PG8_MMA(0, 0, At, B0); PG8_MMA(0, 1, At, B1); PG8_BAR; PG8_SCHED;
	v_mfma_f32_16x16x32_bf16 v[60:63], v[128:131], v[206:209], 0
	v_mfma_f32_16x16x32_bf16 v[56:59], v[136:139], v[206:209], 0
	v_mfma_f32_16x16x32_bf16 v[52:55], v[128:131], v[230:233], 0
	v_mfma_f32_16x16x32_bf16 v[44:47], v[136:139], v[230:233], 0
	v_mfma_f32_16x16x32_bf16 v[36:39], v[128:131], v[238:241], 0
	v_mfma_f32_16x16x32_bf16 v[28:31], v[136:139], v[238:241], 0
	v_mfma_f32_16x16x32_bf16 v[20:23], v[128:131], v[246:249], 0
	v_mfma_f32_16x16x32_bf16 v[12:15], v[136:139], v[246:249], 0
	v_mfma_f32_16x16x32_bf16 v[60:63], v[132:135], v[210:213], v[60:63]
	v_mfma_f32_16x16x32_bf16 v[56:59], v[140:143], v[210:213], v[56:59]
	v_mfma_f32_16x16x32_bf16 v[52:55], v[132:135], v[234:237], v[52:55]
	v_mfma_f32_16x16x32_bf16 v[44:47], v[140:143], v[234:237], v[44:47]
	v_mfma_f32_16x16x32_bf16 v[36:39], v[132:135], v[242:245], v[36:39]
	v_mfma_f32_16x16x32_bf16 v[28:31], v[140:143], v[242:245], v[28:31]
	v_mfma_f32_16x16x32_bf16 v[20:23], v[132:135], v[250:253], v[20:23]
	v_mfma_f32_16x16x32_bf16 v[12:15], v[140:143], v[250:253], v[12:15]
	v_mfma_f32_16x16x32_bf16 v[48:51], v[184:187], v[206:209], 0
	v_mfma_f32_16x16x32_bf16 v[40:43], v[222:225], v[206:209], 0
	v_mfma_f32_16x16x32_bf16 v[32:35], v[184:187], v[230:233], 0
	v_mfma_f32_16x16x32_bf16 v[24:27], v[222:225], v[230:233], 0
	v_mfma_f32_16x16x32_bf16 v[16:19], v[184:187], v[238:241], 0
	v_mfma_f32_16x16x32_bf16 v[8:11], v[222:225], v[238:241], 0
	v_mfma_f32_16x16x32_bf16 v[4:7], v[184:187], v[246:249], 0
	v_mfma_f32_16x16x32_bf16 v[0:3], v[222:225], v[246:249], 0
	v_mfma_f32_16x16x32_bf16 v[48:51], v[218:221], v[210:213], v[48:51]
	v_mfma_f32_16x16x32_bf16 v[40:43], v[226:229], v[210:213], v[40:43]
	v_mfma_f32_16x16x32_bf16 v[32:35], v[218:221], v[234:237], v[32:35]
	v_mfma_f32_16x16x32_bf16 v[24:27], v[226:229], v[234:237], v[24:27]
	v_mfma_f32_16x16x32_bf16 v[16:19], v[218:221], v[242:245], v[16:19]
	v_mfma_f32_16x16x32_bf16 v[8:11], v[226:229], v[242:245], v[8:11]
	v_mfma_f32_16x16x32_bf16 v[4:7], v[218:221], v[250:253], v[4:7]
	v_mfma_f32_16x16x32_bf16 v[0:3], v[226:229], v[250:253], v[0:3]
	s_barrier
	s_setprio 0
	s_add_i32 s49, 0, 0x18000
	s_add_i32 s50, 0, 0x1c000
	v_add_u32_e32 v140, s49, v163
	v_add_u32_e32 v152, s50, v163
	ds_read_b128 v[128:131], v140
	ds_read_b128 v[132:135], v140 offset:1024
	ds_read_b128 v[136:139], v140 offset:2048
	ds_read_b128 v[140:143], v140 offset:3072
	ds_read_b128 v[184:187], v152
	ds_read_b128 v[206:209], v152 offset:1024
	ds_read_b128 v[210:213], v152 offset:2048
	ds_read_b128 v[218:221], v152 offset:3072
	s_add_u32 s30, s30, 0x80000
	s_addc_u32 s31, s31, 0
	s_mov_b32 m0, s37
	ds_read_b128 v[222:225], v214 offset:32768
	ds_read_b128 v[226:229], v214 offset:33792
	ds_read_b128 v[230:233], v214 offset:34816
	ds_read_b128 v[234:237], v214 offset:35840
	ds_read_b128 v[238:241], v214 offset:36864
	ds_read_b128 v[242:245], v214 offset:37888
	ds_read_b128 v[246:249], v214 offset:38912
	ds_read_b128 v[250:253], v214 offset:39936
	global_load_lds_dwordx4 v144, s[30:31]
	s_mov_b32 m0, s39
	v_lshl_add_u64 v[216:217], s[30:31], 0, v[148:149]
	global_load_lds_dwordx4 v[216:217], off
	s_waitcnt vmcnt(8) lgkmcnt(0)
	s_setprio 1
	s_barrier
	v_mfma_f32_16x16x32_bf16 v[124:127], v[128:131], v[222:225], v[124:127]
	v_mfma_f32_16x16x32_bf16 v[120:123], v[136:139], v[222:225], v[120:123]
	v_mfma_f32_16x16x32_bf16 v[116:119], v[128:131], v[230:233], v[116:119]
	v_mfma_f32_16x16x32_bf16 v[108:111], v[136:139], v[230:233], v[108:111]
	v_mfma_f32_16x16x32_bf16 v[100:103], v[128:131], v[238:241], v[100:103]
	v_mfma_f32_16x16x32_bf16 v[92:95], v[136:139], v[238:241], v[92:95]
	v_mfma_f32_16x16x32_bf16 v[84:87], v[128:131], v[246:249], v[84:87]
	v_mfma_f32_16x16x32_bf16 v[76:79], v[136:139], v[246:249], v[76:79]
	v_mfma_f32_16x16x32_bf16 v[124:127], v[132:135], v[226:229], v[124:127]
	v_mfma_f32_16x16x32_bf16 v[120:123], v[140:143], v[226:229], v[120:123]
	v_mfma_f32_16x16x32_bf16 v[116:119], v[132:135], v[234:237], v[116:119]
	v_mfma_f32_16x16x32_bf16 v[108:111], v[140:143], v[234:237], v[108:111]
	v_mfma_f32_16x16x32_bf16 v[100:103], v[132:135], v[242:245], v[100:103]
	v_mfma_f32_16x16x32_bf16 v[92:95], v[140:143], v[242:245], v[92:95]
	v_mfma_f32_16x16x32_bf16 v[84:87], v[132:135], v[250:253], v[84:87]
	v_mfma_f32_16x16x32_bf16 v[76:79], v[140:143], v[250:253], v[76:79]
	v_mfma_f32_16x16x32_bf16 v[112:115], v[184:187], v[222:225], v[112:115]
	v_mfma_f32_16x16x32_bf16 v[104:107], v[210:213], v[222:225], v[104:107]
	v_mfma_f32_16x16x32_bf16 v[96:99], v[184:187], v[230:233], v[96:99]
	v_mfma_f32_16x16x32_bf16 v[88:91], v[210:213], v[230:233], v[88:91]
	v_mfma_f32_16x16x32_bf16 v[80:83], v[184:187], v[238:241], v[80:83]
	v_mfma_f32_16x16x32_bf16 v[72:75], v[210:213], v[238:241], v[72:75]
	v_mfma_f32_16x16x32_bf16 v[68:71], v[184:187], v[246:249], v[68:71]
	v_mfma_f32_16x16x32_bf16 v[64:67], v[210:213], v[246:249], v[64:67]
	v_mfma_f32_16x16x32_bf16 v[112:115], v[206:209], v[226:229], v[112:115]
	v_mfma_f32_16x16x32_bf16 v[104:107], v[218:221], v[226:229], v[104:107]
	v_mfma_f32_16x16x32_bf16 v[96:99], v[206:209], v[234:237], v[96:99]
	v_mfma_f32_16x16x32_bf16 v[88:91], v[218:221], v[234:237], v[88:91]
	v_mfma_f32_16x16x32_bf16 v[80:83], v[206:209], v[242:245], v[80:83]
	v_mfma_f32_16x16x32_bf16 v[72:75], v[218:221], v[242:245], v[72:75]
	v_mfma_f32_16x16x32_bf16 v[68:71], v[206:209], v[250:253], v[68:71]
	v_mfma_f32_16x16x32_bf16 v[64:67], v[218:221], v[250:253], v[64:67]
	s_barrier
; #define PG8_STAGE(bufoff, gbase, voff) do { _Pragma("unroll") for (int _i = 0; _i < 2; ++_i) \
;         __builtin_amdgcn_global_load_lds((const unsigned*)((const char*)(gbase) + (voff)[_i]), (PG8_LAS unsigned*)(lds + (bufoff) + ldsw + _i * 8192), 16, 0, 0); } while (0)
; #define PG8_LDA(dst, b, h) do { _Pragma("unroll") for (int m = 0; m < 4; ++m) _Pragma("unroll") for (int k = 0; k < 2; ++k) dst[m][k] = *(const PG8_LAS bf16x8*)(lds + PG8_SA(b, h) + aoff + m * 2048 + k * 1024); } while (0)
; #define PG8_LDB(dst, b, h) do { _Pragma("unroll") for (int n = 0; n < 2; ++n) _Pragma("unroll") for (int k = 0; k < 2; ++k) dst[n][k] = *(const PG8_LAS bf16x8*)(lds + PG8_SB(b, h) + boff + n * 2048 + k * 1024); } while (0)
; #define PG8_MMA(ai, bj, At, Bt) do { __builtin_amdgcn_s_setprio(1); _Pragma("unroll") for (int m = 0; m < 4; ++m) _Pragma("unroll") for (int n = 0; n < 2; ++n) _Pragma("unroll") for (int k = 0; k < 2; ++k) \
;         acc[ai][bj][m][n] = __builtin_amdgcn_mfma_f32_16x16x32_bf16(Bt[n][k], At[m][k], acc[ai][bj][m][n], 0, 0, 0); __builtin_amdgcn_s_setprio(0); } while (0)
; #define PG8_WAIT_V(n) asm volatile("s_waitcnt vmcnt(" #n ")" ::: "memory")
; template <class Epi, class Sched, bool ALIGN_EPI = false, bool SP2 = false>
; __device__ __forceinline__ void gemm_phase(PG8_LAS unsigned char* lds, const Gemm g, const Sched& S, const Epi& E) {
;     ...
;             PG8_LDB(B0, 0, 0); PG8_LDB(B1, 0, 1); PG8_SCHED; PG8_LDA(At, 0, 0); PG8_STAGE(PG8_SA(1, 1), a1 + hstep, voffA);
;             PG8_WAIT_V(8); PG8_WAIT_L(0); PG8_BAR; PG8_MMA(0, 0, At, B0); PG8_MMA(0, 1, At, B1); PG8_BAR; PG8_SCHED;
;             PG8_LDA(At, 0, 1); PG8_STAGE(PG8_SB(0, 0), b2, voffB); PG8_STAGE(PG8_SB(0, 1), b2 + hstep, voffB); PG8_STAGE(PG8_SA(0, 0), a2, voffA);
;             PG8_WAIT_V(8); PG8_WAIT_L(0); PG8_BAR; PG8_MMA(1, 0, At, B0); PG8_MMA(1, 1, At, B1); PG8_BAR; PG8_SCHED;
;             PG8_LDB(B0, 1, 0); PG8_LDB(B1, 1, 1); PG8_SCHED; PG8_LDA(At, 1, 0); PG8_STAGE(PG8_SA(0, 1), a2 + hstep, voffA);
;             PG8_WAIT_V(8); PG8_WAIT_L(0); PG8_BAR; PG8_MMA(0, 0, At, B0); PG8_MMA(0, 1, At, B1); PG8_BAR; PG8_SCHED;
;             PG8_LDA(At, 1, 1); PG8_STAGE(PG8_SB(1, 0), b3, voffB); PG8_STAGE(PG8_SB(1, 1), b3 + hstep, voffB); PG8_STAGE(PG8_SA(1, 0), a3, voffA);
;             PG8_WAIT_V(8); PG8_WAIT_L(0); PG8_BAR; PG8_MMA(1, 0, At, B0); PG8_MMA(1, 1, At, B1); PG8_BAR; PG8_SCHED;
	s_setprio 0
	s_add_i32 s30, s49, s34
	v_lshl_add_u64 v[172:173], v[172:173], 0, s[10:11]
	s_mov_b32 m0, s30
	ds_read_b128 v[222:225], v214 offset:49152
	ds_read_b128 v[226:229], v214 offset:50176
	ds_read_b128 v[230:233], v214 offset:51200
	ds_read_b128 v[234:237], v214 offset:52224
	ds_read_b128 v[238:241], v214 offset:53248
	ds_read_b128 v[242:245], v214 offset:54272
	ds_read_b128 v[246:249], v214 offset:55296
	ds_read_b128 v[250:253], v214 offset:56320
	global_load_lds_dwordx4 v[172:173], off
	s_add_i32 m0, s30, 0x2000
	s_add_u32 s28, s28, 0x80080
	v_lshl_add_u64 v[172:173], v[176:177], 0, s[10:11]
	s_addc_u32 s29, s29, 0
	s_add_i32 s30, s50, s34
	global_load_lds_dwordx4 v[172:173], off
	s_mov_b32 m0, s30
	s_nop 0
	global_load_lds_dwordx4 v146, s[28:29]
	s_add_i32 m0, s30, 0x2000
	v_lshl_add_u64 v[172:173], s[28:29], 0, v[150:151]
	global_load_lds_dwordx4 v[172:173], off
	s_mov_b32 m0, s43
	v_lshl_add_u64 v[172:173], v[180:181], 0, s[10:11]
	global_load_lds_dwordx4 v[172:173], off
	s_mov_b32 m0, s46
	v_lshl_add_u64 v[172:173], v[188:189], 0, s[10:11]
	global_load_lds_dwordx4 v[172:173], off
	s_waitcnt vmcnt(8) lgkmcnt(0)
	s_setprio 1
	s_barrier
	v_mfma_f32_16x16x32_bf16 v[60:63], v[128:131], v[222:225], v[60:63]
	v_mfma_f32_16x16x32_bf16 v[56:59], v[136:139], v[222:225], v[56:59]
	v_mfma_f32_16x16x32_bf16 v[52:55], v[128:131], v[230:233], v[52:55]
	v_mfma_f32_16x16x32_bf16 v[44:47], v[136:139], v[230:233], v[44:47]
	v_mfma_f32_16x16x32_bf16 v[36:39], v[128:131], v[238:241], v[36:39]
	v_mfma_f32_16x16x32_bf16 v[28:31], v[136:139], v[238:241], v[28:31]
	v_mfma_f32_16x16x32_bf16 v[20:23], v[128:131], v[246:249], v[20:23]
	v_mfma_f32_16x16x32_bf16 v[12:15], v[136:139], v[246:249], v[12:15]
	v_mfma_f32_16x16x32_bf16 v[60:63], v[132:135], v[226:229], v[60:63]
	v_mfma_f32_16x16x32_bf16 v[56:59], v[140:143], v[226:229], v[56:59]
	v_mfma_f32_16x16x32_bf16 v[52:55], v[132:135], v[234:237], v[52:55]
	v_mfma_f32_16x16x32_bf16 v[44:47], v[140:143], v[234:237], v[44:47]
	v_mfma_f32_16x16x32_bf16 v[36:39], v[132:135], v[242:245], v[36:39]
	v_mfma_f32_16x16x32_bf16 v[28:31], v[140:143], v[242:245], v[28:31]
	v_mfma_f32_16x16x32_bf16 v[20:23], v[132:135], v[250:253], v[20:23]
	v_mfma_f32_16x16x32_bf16 v[12:15], v[140:143], v[250:253], v[12:15]
	v_mfma_f32_16x16x32_bf16 v[48:51], v[184:187], v[222:225], v[48:51]
	v_mfma_f32_16x16x32_bf16 v[40:43], v[210:213], v[222:225], v[40:43]
	v_mfma_f32_16x16x32_bf16 v[32:35], v[184:187], v[230:233], v[32:35]
	v_mfma_f32_16x16x32_bf16 v[24:27], v[210:213], v[230:233], v[24:27]
	v_mfma_f32_16x16x32_bf16 v[16:19], v[184:187], v[238:241], v[16:19]
	v_mfma_f32_16x16x32_bf16 v[8:11], v[210:213], v[238:241], v[8:11]
	v_mfma_f32_16x16x32_bf16 v[4:7], v[184:187], v[246:249], v[4:7]
	v_mfma_f32_16x16x32_bf16 v[0:3], v[210:213], v[246:249], v[0:3]
	v_mfma_f32_16x16x32_bf16 v[48:51], v[206:209], v[226:229], v[48:51]
	v_mfma_f32_16x16x32_bf16 v[40:43], v[218:221], v[226:229], v[40:43]
	v_mfma_f32_16x16x32_bf16 v[32:35], v[206:209], v[234:237], v[32:35]
	v_mfma_f32_16x16x32_bf16 v[24:27], v[218:221], v[234:237], v[24:27]
	v_mfma_f32_16x16x32_bf16 v[16:19], v[206:209], v[242:245], v[16:19]
	v_mfma_f32_16x16x32_bf16 v[8:11], v[218:221], v[242:245], v[8:11]
	v_mfma_f32_16x16x32_bf16 v[4:7], v[206:209], v[250:253], v[4:7]
	v_mfma_f32_16x16x32_bf16 v[0:3], v[218:221], v[250:253], v[0:3]
	s_barrier
	s_setprio 0
	s_add_i32 s48, s48, 2
	s_add_u32 s0, s0, 0x100
	s_addc_u32 s1, s1, 0
	s_add_u32 s44, s44, 0x100
	s_addc_u32 s45, s45, 0
.LBB0_491:
	v_add_u32_e32 v140, s68, v163
	v_add_u32_e32 v152, s69, v163
	ds_read_b128 v[128:131], v140
	ds_read_b128 v[132:135], v140 offset:1024
	ds_read_b128 v[136:139], v140 offset:2048
	ds_read_b128 v[140:143], v140 offset:3072
	ds_read_b128 v[184:187], v152
	ds_read_b128 v[218:221], v152 offset:1024
	ds_read_b128 v[222:225], v152 offset:2048
	ds_read_b128 v[226:229], v152 offset:3072
	s_add_u32 s28, s0, 0xfff80080
	s_addc_u32 s29, s1, -1
	s_cmp_eq_u32 s48, 28
	s_cselect_b32 s31, s5, s29
	s_cselect_b32 s30, s21, s28
	s_cselect_b32 s29, s19, s45
	s_cselect_b32 s28, s33, s44
	s_add_i32 m0, s17, 0xc000
	ds_read_b128 v[230:233], v214
	ds_read_b128 v[234:237], v214 offset:1024
	ds_read_b128 v[238:241], v214 offset:2048
	ds_read_b128 v[242:245], v214 offset:3072
	ds_read_b128 v[246:249], v214 offset:4096
	ds_read_b128 v[250:253], v214 offset:5120
	ds_read_b128 v[206:209], v214 offset:6144
	ds_read_b128 v[210:213], v214 offset:7168
	global_load_lds_dwordx4 v156, s[0:1]
	s_add_i32 m0, s17, 0xe000
	s_nop 0
	global_load_lds_dwordx4 v158, s[0:1]
	s_waitcnt vmcnt(8) lgkmcnt(0)
	s_setprio 1
	s_barrier
; #define PG8_STAGE(bufoff, gbase, voff) do { _Pragma("unroll") for (int _i = 0; _i < 2; ++_i) \
;         __builtin_amdgcn_global_load_lds((const unsigned*)((const char*)(gbase) + (voff)[_i]), (PG8_LAS unsigned*)(lds + (bufoff) + ldsw + _i * 8192), 16, 0, 0); } while (0)
; #define PG8_LDA(dst, b, h) do { _Pragma("unroll") for (int m = 0; m < 4; ++m) _Pragma("unroll") for (int k = 0; k < 2; ++k) dst[m][k] = *(const PG8_LAS bf16x8*)(lds + PG8_SA(b, h) + aoff + m * 2048 + k * 1024); } while (0)
; #define PG8_MMA(ai, bj, At, Bt) do { __builtin_amdgcn_s_setprio(1); _Pragma("unroll") for (int m = 0; m < 4; ++m) _Pragma("unroll") for (int n = 0; n < 2; ++n) _Pragma("unroll") for (int k = 0; k < 2; ++k) \
;         acc[ai][bj][m][n] = __builtin_amdgcn_mfma_f32_16x16x32_bf16(Bt[n][k], At[m][k], acc[ai][bj][m][n], 0, 0, 0); __builtin_amdgcn_s_setprio(0); } while (0)
; #define PG8_WAIT_V(n) asm volatile("s_waitcnt vmcnt(" #n ")" ::: "memory")
; #define PG8_WAIT_L(n) asm volatile("s_waitcnt lgkmcnt(" #n ")" ::: "memory")
; #define PG8_BAR __builtin_amdgcn_s_barrier()
; #define PG8_SCHED __builtin_amdgcn_sched_barrier(0)
; template <class Epi, class Sched, bool ALIGN_EPI = false, bool SP2 = false>
; __device__ __forceinline__ void gemm_phase(PG8_LAS unsigned char* lds, const Gemm g, const Sched& S, const Epi& E) {
;     ...
;             PG8_WAIT_V(8); PG8_WAIT_L(0); PG8_BAR; PG8_MMA(0, 0, At, B0); PG8_MMA(0, 1, At, B1); PG8_BAR; PG8_SCHED;
;             PG8_LDA(At, 0, 1); PG8_STAGE(PG8_SB(0, 0), b2, voffB); PG8_STAGE(PG8_SB(0, 1), b2 + hstep, voffB); PG8_STAGE(PG8_SA(0, 0), a2, voffA);
;             PG8_WAIT_V(8); PG8_WAIT_L(0); PG8_BAR; PG8_MMA(1, 0, At, B0); PG8_MMA(1, 1, At, B1); PG8_BAR; PG8_SCHED;
	v_mfma_f32_16x16x32_bf16 v[124:127], v[128:131], v[230:233], v[124:127]
	v_mfma_f32_16x16x32_bf16 v[120:123], v[136:139], v[230:233], v[120:123]
	v_mfma_f32_16x16x32_bf16 v[116:119], v[128:131], v[238:241], v[116:119]
	v_mfma_f32_16x16x32_bf16 v[108:111], v[136:139], v[238:241], v[108:111]
	v_mfma_f32_16x16x32_bf16 v[100:103], v[128:131], v[246:249], v[100:103]
	v_mfma_f32_16x16x32_bf16 v[92:95], v[136:139], v[246:249], v[92:95]
	v_mfma_f32_16x16x32_bf16 v[84:87], v[128:131], v[206:209], v[84:87]
	v_mfma_f32_16x16x32_bf16 v[76:79], v[136:139], v[206:209], v[76:79]
	v_mfma_f32_16x16x32_bf16 v[124:127], v[132:135], v[234:237], v[124:127]
	v_mfma_f32_16x16x32_bf16 v[120:123], v[140:143], v[234:237], v[120:123]
	v_mfma_f32_16x16x32_bf16 v[116:119], v[132:135], v[242:245], v[116:119]
	v_mfma_f32_16x16x32_bf16 v[108:111], v[140:143], v[242:245], v[108:111]
	v_mfma_f32_16x16x32_bf16 v[100:103], v[132:135], v[250:253], v[100:103]
	v_mfma_f32_16x16x32_bf16 v[92:95], v[140:143], v[250:253], v[92:95]
	v_mfma_f32_16x16x32_bf16 v[84:87], v[132:135], v[210:213], v[84:87]
	v_mfma_f32_16x16x32_bf16 v[76:79], v[140:143], v[210:213], v[76:79]
	v_mfma_f32_16x16x32_bf16 v[112:115], v[184:187], v[230:233], v[112:115]
	v_mfma_f32_16x16x32_bf16 v[104:107], v[222:225], v[230:233], v[104:107]
	v_mfma_f32_16x16x32_bf16 v[96:99], v[184:187], v[238:241], v[96:99]
	v_mfma_f32_16x16x32_bf16 v[88:91], v[222:225], v[238:241], v[88:91]
	v_mfma_f32_16x16x32_bf16 v[80:83], v[184:187], v[246:249], v[80:83]
	v_mfma_f32_16x16x32_bf16 v[72:75], v[222:225], v[246:249], v[72:75]
	v_mfma_f32_16x16x32_bf16 v[68:71], v[184:187], v[206:209], v[68:71]
	v_mfma_f32_16x16x32_bf16 v[64:67], v[222:225], v[206:209], v[64:67]
	v_mfma_f32_16x16x32_bf16 v[112:115], v[218:221], v[234:237], v[112:115]
	v_mfma_f32_16x16x32_bf16 v[104:107], v[226:229], v[234:237], v[104:107]
	v_mfma_f32_16x16x32_bf16 v[96:99], v[218:221], v[242:245], v[96:99]
	v_mfma_f32_16x16x32_bf16 v[88:91], v[226:229], v[242:245], v[88:91]
	v_mfma_f32_16x16x32_bf16 v[80:83], v[218:221], v[250:253], v[80:83]
	v_mfma_f32_16x16x32_bf16 v[72:75], v[226:229], v[250:253], v[72:75]
	v_mfma_f32_16x16x32_bf16 v[68:71], v[218:221], v[210:213], v[68:71]
	v_mfma_f32_16x16x32_bf16 v[64:67], v[226:229], v[210:213], v[64:67]
	s_barrier
	s_setprio 0
	s_add_i32 s49, s68, s34
	v_lshl_add_u64 v[172:173], s[28:29], 0, v[146:147]
	s_mov_b32 m0, s49
	ds_read_b128 v[206:209], v214 offset:16384
	ds_read_b128 v[210:213], v214 offset:17408
	ds_read_b128 v[230:233], v214 offset:18432
	ds_read_b128 v[234:237], v214 offset:19456
	ds_read_b128 v[238:241], v214 offset:20480
	ds_read_b128 v[242:245], v214 offset:21504
	ds_read_b128 v[246:249], v214 offset:22528
	ds_read_b128 v[250:253], v214 offset:23552
	global_load_lds_dwordx4 v[172:173], off
	s_add_i32 m0, s49, 0x2000
	s_add_u32 s50, s28, 0x80000
	v_lshl_add_u64 v[176:177], s[28:29], 0, v[150:151]
	s_addc_u32 s51, s29, 0
	s_add_i32 s49, s69, s34
	global_load_lds_dwordx4 v[176:177], off
	s_mov_b32 m0, s49
	v_lshl_add_u64 v[188:189], s[30:31], 0, v[148:149]
	global_load_lds_dwordx4 v146, s[50:51]
	s_add_i32 m0, s49, 0x2000
	s_nop 0
	global_load_lds_dwordx4 v150, s[50:51]
	s_mov_b32 m0, s17
	v_lshl_add_u64 v[180:181], s[30:31], 0, v[144:145]
	global_load_lds_dwordx4 v[180:181], off
	s_mov_b32 m0, s35
	s_nop 0
	global_load_lds_dwordx4 v[188:189], off
	s_waitcnt vmcnt(8) lgkmcnt(0)
	s_setprio 1
	s_barrier
	v_mfma_f32_16x16x32_bf16 v[60:63], v[128:131], v[206:209], v[60:63]
	v_mfma_f32_16x16x32_bf16 v[56:59], v[136:139], v[206:209], v[56:59]
	v_mfma_f32_16x16x32_bf16 v[52:55], v[128:131], v[230:233], v[52:55]
	v_mfma_f32_16x16x32_bf16 v[44:47], v[136:139], v[230:233], v[44:47]
	v_mfma_f32_16x16x32_bf16 v[36:39], v[128:131], v[238:241], v[36:39]
	v_mfma_f32_16x16x32_bf16 v[28:31], v[136:139], v[238:241], v[28:31]
	v_mfma_f32_16x16x32_bf16 v[20:23], v[128:131], v[246:249], v[20:23]
	v_mfma_f32_16x16x32_bf16 v[12:15], v[136:139], v[246:249], v[12:15]
	v_mfma_f32_16x16x32_bf16 v[60:63], v[132:135], v[210:213], v[60:63]
	v_mfma_f32_16x16x32_bf16 v[56:59], v[140:143], v[210:213], v[56:59]
	v_mfma_f32_16x16x32_bf16 v[52:55], v[132:135], v[234:237], v[52:55]
	v_mfma_f32_16x16x32_bf16 v[44:47], v[140:143], v[234:237], v[44:47]
	v_mfma_f32_16x16x32_bf16 v[36:39], v[132:135], v[242:245], v[36:39]
	v_mfma_f32_16x16x32_bf16 v[28:31], v[140:143], v[242:245], v[28:31]
	v_mfma_f32_16x16x32_bf16 v[20:23], v[132:135], v[250:253], v[20:23]
	v_mfma_f32_16x16x32_bf16 v[12:15], v[140:143], v[250:253], v[12:15]
	v_mfma_f32_16x16x32_bf16 v[48:51], v[184:187], v[206:209], v[48:51]
	v_mfma_f32_16x16x32_bf16 v[40:43], v[222:225], v[206:209], v[40:43]
	v_mfma_f32_16x16x32_bf16 v[32:35], v[184:187], v[230:233], v[32:35]
	v_mfma_f32_16x16x32_bf16 v[24:27], v[222:225], v[230:233], v[24:27]
	v_mfma_f32_16x16x32_bf16 v[16:19], v[184:187], v[238:241], v[16:19]
	v_mfma_f32_16x16x32_bf16 v[8:11], v[222:225], v[238:241], v[8:11]
	v_mfma_f32_16x16x32_bf16 v[4:7], v[184:187], v[246:249], v[4:7]
	v_mfma_f32_16x16x32_bf16 v[0:3], v[222:225], v[246:249], v[0:3]
	v_mfma_f32_16x16x32_bf16 v[48:51], v[218:221], v[210:213], v[48:51]
	v_mfma_f32_16x16x32_bf16 v[40:43], v[226:229], v[210:213], v[40:43]
	v_mfma_f32_16x16x32_bf16 v[32:35], v[218:221], v[234:237], v[32:35]
	v_mfma_f32_16x16x32_bf16 v[24:27], v[226:229], v[234:237], v[24:27]
	v_mfma_f32_16x16x32_bf16 v[16:19], v[218:221], v[242:245], v[16:19]
	v_mfma_f32_16x16x32_bf16 v[8:11], v[226:229], v[242:245], v[8:11]
	v_mfma_f32_16x16x32_bf16 v[4:7], v[218:221], v[250:253], v[4:7]
	v_mfma_f32_16x16x32_bf16 v[0:3], v[226:229], v[250:253], v[0:3]
	s_barrier
; #define PG8_STAGE(bufoff, gbase, voff) do { _Pragma("unroll") for (int _i = 0; _i < 2; ++_i) \
;         __builtin_amdgcn_global_load_lds((const unsigned*)((const char*)(gbase) + (voff)[_i]), (PG8_LAS unsigned*)(lds + (bufoff) + ldsw + _i * 8192), 16, 0, 0); } while (0)
; #define PG8_LDA(dst, b, h) do { _Pragma("unroll") for (int m = 0; m < 4; ++m) _Pragma("unroll") for (int k = 0; k < 2; ++k) dst[m][k] = *(const PG8_LAS bf16x8*)(lds + PG8_SA(b, h) + aoff + m * 2048 + k * 1024); } while (0)
; #define PG8_LDB(dst, b, h) do { _Pragma("unroll") for (int n = 0; n < 2; ++n) _Pragma("unroll") for (int k = 0; k < 2; ++k) dst[n][k] = *(const PG8_LAS bf16x8*)(lds + PG8_SB(b, h) + boff + n * 2048 + k * 1024); } while (0)
; #define PG8_MMA(ai, bj, At, Bt) do { __builtin_amdgcn_s_setprio(1); _Pragma("unroll") for (int m = 0; m < 4; ++m) _Pragma("unroll") for (int n = 0; n < 2; ++n) _Pragma("unroll") for (int k = 0; k < 2; ++k) \
;         acc[ai][bj][m][n] = __builtin_amdgcn_mfma_f32_16x16x32_bf16(Bt[n][k], At[m][k], acc[ai][bj][m][n], 0, 0, 0); __builtin_amdgcn_s_setprio(0); } while (0)
; #define PG8_WAIT_V(n) asm volatile("s_waitcnt vmcnt(" #n ")" ::: "memory")
; #define PG8_WAIT_L(n) asm volatile("s_waitcnt lgkmcnt(" #n ")" ::: "memory")
; #define PG8_BAR __builtin_amdgcn_s_barrier()
; #define PG8_SCHED __builtin_amdgcn_sched_barrier(0)
; template <class Epi, class Sched, bool ALIGN_EPI = false, bool SP2 = false>
; __device__ __forceinline__ void gemm_phase(PG8_LAS unsigned char* lds, const Gemm g, const Sched& S, const Epi& E) {
;     ...
;             PG8_LDB(B0, 1, 0); PG8_LDB(B1, 1, 1); PG8_SCHED; PG8_LDA(At, 1, 0); PG8_STAGE(PG8_SA(0, 1), a2 + hstep, voffA);
;             PG8_WAIT_V(8); PG8_WAIT_L(0); PG8_BAR; PG8_MMA(0, 0, At, B0); PG8_MMA(0, 1, At, B1); PG8_BAR; PG8_SCHED;
;             PG8_LDA(At, 1, 1); PG8_STAGE(PG8_SB(1, 0), b3, voffB); PG8_STAGE(PG8_SB(1, 1), b3 + hstep, voffB); PG8_STAGE(PG8_SA(1, 0), a3, voffA);
;             PG8_WAIT_V(8); PG8_WAIT_L(0); PG8_BAR; PG8_MMA(1, 0, At, B0); PG8_MMA(1, 1, At, B1); PG8_BAR; PG8_SCHED;
;     ...
;         }
;         if constexpr (ALIGN_EPI) { if (wr == 0) PG8_BAR; }
	s_setprio 0
	s_add_i32 s49, 0, 0x18000
	s_add_i32 s50, 0, 0x1c000
	v_add_u32_e32 v140, s49, v163
	v_add_u32_e32 v152, s50, v163
	ds_read_b128 v[128:131], v140
	ds_read_b128 v[132:135], v140 offset:1024
	ds_read_b128 v[136:139], v140 offset:2048
	ds_read_b128 v[140:143], v140 offset:3072
	ds_read_b128 v[184:187], v152
	ds_read_b128 v[206:209], v152 offset:1024
	ds_read_b128 v[210:213], v152 offset:2048
	ds_read_b128 v[218:221], v152 offset:3072
	s_add_u32 s30, s30, 0x80000
	s_addc_u32 s31, s31, 0
	s_mov_b32 m0, s37
	ds_read_b128 v[222:225], v214 offset:32768
	ds_read_b128 v[226:229], v214 offset:33792
	ds_read_b128 v[230:233], v214 offset:34816
	ds_read_b128 v[234:237], v214 offset:35840
	ds_read_b128 v[238:241], v214 offset:36864
	ds_read_b128 v[242:245], v214 offset:37888
	ds_read_b128 v[246:249], v214 offset:38912
	ds_read_b128 v[250:253], v214 offset:39936
	global_load_lds_dwordx4 v144, s[30:31]
	s_mov_b32 m0, s39
	s_nop 0
	global_load_lds_dwordx4 v148, s[30:31]
	s_waitcnt vmcnt(8) lgkmcnt(0)
	s_setprio 1
	s_barrier
	v_mfma_f32_16x16x32_bf16 v[124:127], v[128:131], v[222:225], v[124:127]
	v_mfma_f32_16x16x32_bf16 v[120:123], v[136:139], v[222:225], v[120:123]
	v_mfma_f32_16x16x32_bf16 v[116:119], v[128:131], v[230:233], v[116:119]
	v_mfma_f32_16x16x32_bf16 v[108:111], v[136:139], v[230:233], v[108:111]
	v_mfma_f32_16x16x32_bf16 v[100:103], v[128:131], v[238:241], v[100:103]
	v_mfma_f32_16x16x32_bf16 v[92:95], v[136:139], v[238:241], v[92:95]
	v_mfma_f32_16x16x32_bf16 v[84:87], v[128:131], v[246:249], v[84:87]
	v_mfma_f32_16x16x32_bf16 v[76:79], v[136:139], v[246:249], v[76:79]
	v_mfma_f32_16x16x32_bf16 v[124:127], v[132:135], v[226:229], v[124:127]
	v_mfma_f32_16x16x32_bf16 v[120:123], v[140:143], v[226:229], v[120:123]
	v_mfma_f32_16x16x32_bf16 v[116:119], v[132:135], v[234:237], v[116:119]
	v_mfma_f32_16x16x32_bf16 v[108:111], v[140:143], v[234:237], v[108:111]
	v_mfma_f32_16x16x32_bf16 v[100:103], v[132:135], v[242:245], v[100:103]
	v_mfma_f32_16x16x32_bf16 v[92:95], v[140:143], v[242:245], v[92:95]
	v_mfma_f32_16x16x32_bf16 v[84:87], v[132:135], v[250:253], v[84:87]
	v_mfma_f32_16x16x32_bf16 v[76:79], v[140:143], v[250:253], v[76:79]
	v_mfma_f32_16x16x32_bf16 v[112:115], v[184:187], v[222:225], v[112:115]
	v_mfma_f32_16x16x32_bf16 v[104:107], v[210:213], v[222:225], v[104:107]
	v_mfma_f32_16x16x32_bf16 v[96:99], v[184:187], v[230:233], v[96:99]
	v_mfma_f32_16x16x32_bf16 v[88:91], v[210:213], v[230:233], v[88:91]
	v_mfma_f32_16x16x32_bf16 v[80:83], v[184:187], v[238:241], v[80:83]
	v_mfma_f32_16x16x32_bf16 v[72:75], v[210:213], v[238:241], v[72:75]
	v_mfma_f32_16x16x32_bf16 v[68:71], v[184:187], v[246:249], v[68:71]
	v_mfma_f32_16x16x32_bf16 v[64:67], v[210:213], v[246:249], v[64:67]
	v_mfma_f32_16x16x32_bf16 v[112:115], v[206:209], v[226:229], v[112:115]
	v_mfma_f32_16x16x32_bf16 v[104:107], v[218:221], v[226:229], v[104:107]
	v_mfma_f32_16x16x32_bf16 v[96:99], v[206:209], v[234:237], v[96:99]
	v_mfma_f32_16x16x32_bf16 v[88:91], v[218:221], v[234:237], v[88:91]
	v_mfma_f32_16x16x32_bf16 v[80:83], v[206:209], v[242:245], v[80:83]
	v_mfma_f32_16x16x32_bf16 v[72:75], v[218:221], v[242:245], v[72:75]
	v_mfma_f32_16x16x32_bf16 v[68:71], v[206:209], v[250:253], v[68:71]
	v_mfma_f32_16x16x32_bf16 v[64:67], v[218:221], v[250:253], v[64:67]
	s_barrier
	s_setprio 0
	s_add_i32 s30, s49, s34
	v_lshl_add_u64 v[172:173], v[172:173], 0, s[10:11]
	s_mov_b32 m0, s30
	ds_read_b128 v[222:225], v214 offset:49152
	ds_read_b128 v[226:229], v214 offset:50176
	ds_read_b128 v[230:233], v214 offset:51200
	ds_read_b128 v[234:237], v214 offset:52224
	ds_read_b128 v[238:241], v214 offset:53248
	ds_read_b128 v[242:245], v214 offset:54272
	ds_read_b128 v[246:249], v214 offset:55296
	ds_read_b128 v[250:253], v214 offset:56320
	global_load_lds_dwordx4 v[172:173], off
	s_add_i32 m0, s30, 0x2000
	s_add_u32 s28, s28, 0x80080
	v_lshl_add_u64 v[172:173], v[176:177], 0, s[10:11]
	s_addc_u32 s29, s29, 0
	s_add_i32 s30, s50, s34
	global_load_lds_dwordx4 v[172:173], off
	s_mov_b32 m0, s30
	s_nop 0
	global_load_lds_dwordx4 v146, s[28:29]
	s_add_i32 m0, s30, 0x2000
	v_lshl_add_u64 v[172:173], s[28:29], 0, v[150:151]
	global_load_lds_dwordx4 v[172:173], off
	s_mov_b32 m0, s43
	v_lshl_add_u64 v[172:173], v[180:181], 0, s[10:11]
	global_load_lds_dwordx4 v[172:173], off
	s_mov_b32 m0, s46
	v_lshl_add_u64 v[172:173], v[188:189], 0, s[10:11]
	global_load_lds_dwordx4 v[172:173], off
	s_waitcnt vmcnt(8) lgkmcnt(0)
	s_setprio 1
	s_barrier
	v_mfma_f32_16x16x32_bf16 v[60:63], v[128:131], v[222:225], v[60:63]
	v_mfma_f32_16x16x32_bf16 v[56:59], v[136:139], v[222:225], v[56:59]
	v_mfma_f32_16x16x32_bf16 v[52:55], v[128:131], v[230:233], v[52:55]
	v_mfma_f32_16x16x32_bf16 v[44:47], v[136:139], v[230:233], v[44:47]
	v_mfma_f32_16x16x32_bf16 v[36:39], v[128:131], v[238:241], v[36:39]
	v_mfma_f32_16x16x32_bf16 v[28:31], v[136:139], v[238:241], v[28:31]
	v_mfma_f32_16x16x32_bf16 v[20:23], v[128:131], v[246:249], v[20:23]
	v_mfma_f32_16x16x32_bf16 v[12:15], v[136:139], v[246:249], v[12:15]
	v_mfma_f32_16x16x32_bf16 v[60:63], v[132:135], v[226:229], v[60:63]
	v_mfma_f32_16x16x32_bf16 v[56:59], v[140:143], v[226:229], v[56:59]
	v_mfma_f32_16x16x32_bf16 v[52:55], v[132:135], v[234:237], v[52:55]
	v_mfma_f32_16x16x32_bf16 v[44:47], v[140:143], v[234:237], v[44:47]
	v_mfma_f32_16x16x32_bf16 v[36:39], v[132:135], v[242:245], v[36:39]
	v_mfma_f32_16x16x32_bf16 v[28:31], v[140:143], v[242:245], v[28:31]
	v_mfma_f32_16x16x32_bf16 v[20:23], v[132:135], v[250:253], v[20:23]
	v_mfma_f32_16x16x32_bf16 v[12:15], v[140:143], v[250:253], v[12:15]
	v_mfma_f32_16x16x32_bf16 v[48:51], v[184:187], v[222:225], v[48:51]
	v_mfma_f32_16x16x32_bf16 v[40:43], v[210:213], v[222:225], v[40:43]
	v_mfma_f32_16x16x32_bf16 v[32:35], v[184:187], v[230:233], v[32:35]
	v_mfma_f32_16x16x32_bf16 v[24:27], v[210:213], v[230:233], v[24:27]
	v_mfma_f32_16x16x32_bf16 v[16:19], v[184:187], v[238:241], v[16:19]
	v_mfma_f32_16x16x32_bf16 v[8:11], v[210:213], v[238:241], v[8:11]
	v_mfma_f32_16x16x32_bf16 v[4:7], v[184:187], v[246:249], v[4:7]
	v_mfma_f32_16x16x32_bf16 v[0:3], v[210:213], v[246:249], v[0:3]
	v_mfma_f32_16x16x32_bf16 v[48:51], v[206:209], v[226:229], v[48:51]
	v_mfma_f32_16x16x32_bf16 v[40:43], v[218:221], v[226:229], v[40:43]
	v_mfma_f32_16x16x32_bf16 v[32:35], v[206:209], v[234:237], v[32:35]
	v_mfma_f32_16x16x32_bf16 v[24:27], v[218:221], v[234:237], v[24:27]
	v_mfma_f32_16x16x32_bf16 v[16:19], v[206:209], v[242:245], v[16:19]
	v_mfma_f32_16x16x32_bf16 v[8:11], v[218:221], v[242:245], v[8:11]
	v_mfma_f32_16x16x32_bf16 v[4:7], v[206:209], v[250:253], v[4:7]
	v_mfma_f32_16x16x32_bf16 v[0:3], v[218:221], v[250:253], v[0:3]
	s_barrier
	s_setprio 0
	s_add_i32 s48, s48, 2
	s_add_u32 s0, s0, 0x100
	s_addc_u32 s1, s1, 0
	s_add_u32 s44, s44, 0x100
	s_addc_u32 s45, s45, 0
	s_cmp_gt_u32 s48, 29
	s_cbranch_scc0 .LBB0_491
	s_and_b64 vcc, exec, s[12:13]
	s_cbranch_vccz .LBB0_494
	s_barrier

; #define PG8_STAGE(bufoff, gbase, voff) do { _Pragma("unroll") for (int _i = 0; _i < 2; ++_i) \
;         __builtin_amdgcn_global_load_lds((const unsigned*)((const char*)(gbase) + (voff)[_i]), (PG8_LAS unsigned*)(lds + (bufoff) + ldsw + _i * 8192), 16, 0, 0); } while (0)
; #define PG8_LDA(dst, b, h) do { _Pragma("unroll") for (int m = 0; m < 4; ++m) _Pragma("unroll") for (int k = 0; k < 2; ++k) dst[m][k] = *(const PG8_LAS bf16x8*)(lds + PG8_SA(b, h) + aoff + m * 2048 + k * 1024); } while (0)
; #define PG8_LDB(dst, b, h) do { _Pragma("unroll") for (int n = 0; n < 2; ++n) _Pragma("unroll") for (int k = 0; k < 2; ++k) dst[n][k] = *(const PG8_LAS bf16x8*)(lds + PG8_SB(b, h) + boff + n * 2048 + k * 1024); } while (0)
; #define PG8_MMA(ai, bj, At, Bt) do { __builtin_amdgcn_s_setprio(1); _Pragma("unroll") for (int m = 0; m < 4; ++m) _Pragma("unroll") for (int n = 0; n < 2; ++n) _Pragma("unroll") for (int k = 0; k < 2; ++k) \
;         acc[ai][bj][m][n] = __builtin_amdgcn_mfma_f32_16x16x32_bf16(Bt[n][k], At[m][k], acc[ai][bj][m][n], 0, 0, 0); __builtin_amdgcn_s_setprio(0); } while (0)
; #define PG8_WAIT_V(n) asm volatile("s_waitcnt vmcnt(" #n ")" ::: "memory")
; template <class Epi, class Sched, bool ALIGN_EPI = false, bool SP2 = false>
; __device__ __forceinline__ void gemm_phase(PG8_LAS unsigned char* lds, const Gemm g, const Sched& S, const Epi& E) {
;     ...
;         const char* nA = has_next ? (const char*)g.A + (size_t)nxt.pm * tstep : cA; const char* nB = has_next ? (const char*)g.Bt + (size_t)nxt.pn * tstep : cB;
;         for (int t = 0; t < nt; t += 2) {
;             const bool last = (t == nt - 2);
;             const char* a1 = cA + (size_t)(t + 1) * kstep;
;             const char* a2 = last ? nA : cA + (size_t)(t + 2) * kstep; const char* b2 = last ? nB : cB + (size_t)(t + 2) * kstep;
;             const char* a3 = a2 + kstep; const char* b3 = b2 + kstep;
;             if (last && has_next) S.a_ready(nxt);
;             if constexpr (SP2) {
;             PG8_LDB(B0, 0, 0); PG8_LDB(B1, 0, 1); PG8_SCHED; PG8_LDA(At, 0, 0); PG8_STAGE(PG8_SA(1, 1), a1 + hstep, voffA);
;             PG8_WAIT_V(8); PG8_WAIT_L(0); PG8_BAR; PG8_MMA(0, 0, At, B0); PG8_MMA(0, 1, At, B1); PG8_BAR; PG8_SCHED;
;             PG8_LDA(At, 0, 1); PG8_STAGE(PG8_SB(0, 0), b2, voffB); PG8_STAGE(PG8_SB(0, 1), b2 + hstep, voffB); PG8_STAGE(PG8_SA(0, 0), a2, voffA);
.LBB0_762:
	s_ashr_i32 s21, s20, 31
	s_lshl_b64 s[22:23], s[20:21], 21
	s_add_u32 s22, s60, s22
	s_addc_u32 s23, s61, s23
	s_and_b64 s[24:25], s[4:5], exec
	s_cselect_b32 s7, s23, s27
	s_cselect_b32 s21, s22, s26
	s_ashr_i32 s19, s18, 31
	s_lshl_b64 s[24:25], s[18:19], 21
	v_readlane_b32 s30, v254, 32
	v_readlane_b32 s31, v254, 33
	s_add_u32 s24, s30, s24
	s_addc_u32 s25, s31, s25
	s_and_b64 s[30:31], s[4:5], exec
	s_cselect_b32 s19, s25, s29
	s_cselect_b32 s48, s24, s28
	s_add_u32 s26, s26, 0x100080
	s_addc_u32 s27, s27, 0
	s_add_u32 s49, s28, 0x100
	s_addc_u32 s52, s29, 0
	s_mov_b32 s53, -2
	s_waitcnt lgkmcnt(0)
	ds_read_b128 v[128:131], v181
	ds_read_b128 v[132:135], v181 offset:1024
	ds_read_b128 v[136:139], v181 offset:2048
	ds_read_b128 v[140:143], v181 offset:3072
	ds_read_b128 v[144:147], v182
	ds_read_b128 v[148:151], v182 offset:1024
	ds_read_b128 v[168:171], v182 offset:2048
	ds_read_b128 v[172:175], v182 offset:3072
	s_add_u32 s28, s26, 0xfff00080
	s_addc_u32 s29, s27, -1
	s_cmp_eq_u32 s53, 60
	s_cselect_b32 s31, s7, s29
	s_cselect_b32 s30, s21, s28
	s_cselect_b32 s29, s19, s52
	s_cselect_b32 s28, s48, s49
	s_add_i32 m0, s35, 0xc000
	ds_read_b128 v[186:189], v183
	ds_read_b128 v[190:193], v183 offset:1024
	ds_read_b128 v[198:201], v183 offset:2048
	ds_read_b128 v[202:205], v183 offset:3072
	ds_read_b128 v[206:209], v183 offset:4096
	ds_read_b128 v[210:213], v183 offset:5120
	ds_read_b128 v[214:217], v183 offset:6144
	ds_read_b128 v[218:221], v183 offset:7168
	global_load_lds_dwordx4 v160, s[26:27]
	s_add_i32 m0, s35, 0xe000
	s_nop 0
	global_load_lds_dwordx4 v162, s[26:27]
	s_waitcnt lgkmcnt(0)
	s_setprio 1
	s_barrier
	v_mfma_f32_16x16x32_bf16 v[124:127], v[128:131], v[186:189], 0
	v_mfma_f32_16x16x32_bf16 v[120:123], v[136:139], v[186:189], 0
	v_mfma_f32_16x16x32_bf16 v[104:107], v[128:131], v[198:201], 0
	v_mfma_f32_16x16x32_bf16 v[108:111], v[136:139], v[198:201], 0
	v_mfma_f32_16x16x32_bf16 v[88:91], v[128:131], v[206:209], 0
	v_mfma_f32_16x16x32_bf16 v[92:95], v[136:139], v[206:209], 0
	v_mfma_f32_16x16x32_bf16 v[72:75], v[128:131], v[214:217], 0
	v_mfma_f32_16x16x32_bf16 v[76:79], v[136:139], v[214:217], 0
	v_mfma_f32_16x16x32_bf16 v[124:127], v[132:135], v[190:193], v[124:127]
	v_mfma_f32_16x16x32_bf16 v[120:123], v[140:143], v[190:193], v[120:123]
	v_mfma_f32_16x16x32_bf16 v[104:107], v[132:135], v[202:205], v[104:107]
	v_mfma_f32_16x16x32_bf16 v[108:111], v[140:143], v[202:205], v[108:111]
	v_mfma_f32_16x16x32_bf16 v[88:91], v[132:135], v[210:213], v[88:91]
	v_mfma_f32_16x16x32_bf16 v[92:95], v[140:143], v[210:213], v[92:95]
	v_mfma_f32_16x16x32_bf16 v[72:75], v[132:135], v[218:221], v[72:75]
	v_mfma_f32_16x16x32_bf16 v[76:79], v[140:143], v[218:221], v[76:79]
	v_mfma_f32_16x16x32_bf16 v[116:119], v[144:147], v[186:189], 0
	v_mfma_f32_16x16x32_bf16 v[112:115], v[168:171], v[186:189], 0
	v_mfma_f32_16x16x32_bf16 v[100:103], v[144:147], v[198:201], 0
	v_mfma_f32_16x16x32_bf16 v[96:99], v[168:171], v[198:201], 0
	v_mfma_f32_16x16x32_bf16 v[84:87], v[144:147], v[206:209], 0
	v_mfma_f32_16x16x32_bf16 v[80:83], v[168:171], v[206:209], 0
	v_mfma_f32_16x16x32_bf16 v[68:71], v[144:147], v[214:217], 0
	v_mfma_f32_16x16x32_bf16 v[64:67], v[168:171], v[214:217], 0
	v_mfma_f32_16x16x32_bf16 v[116:119], v[148:151], v[190:193], v[116:119]
	v_mfma_f32_16x16x32_bf16 v[112:115], v[172:175], v[190:193], v[112:115]
	v_mfma_f32_16x16x32_bf16 v[100:103], v[148:151], v[202:205], v[100:103]
	v_mfma_f32_16x16x32_bf16 v[96:99], v[172:175], v[202:205], v[96:99]
	v_mfma_f32_16x16x32_bf16 v[84:87], v[148:151], v[210:213], v[84:87]
	v_mfma_f32_16x16x32_bf16 v[80:83], v[172:175], v[210:213], v[80:83]
	v_mfma_f32_16x16x32_bf16 v[68:71], v[148:151], v[218:221], v[68:71]
	v_mfma_f32_16x16x32_bf16 v[64:67], v[172:175], v[218:221], v[64:67]
	s_barrier
	s_setprio 0
	s_add_i32 s54, s47, s34
	v_lshl_add_u64 v[176:177], s[28:29], 0, v[154:155]
	s_mov_b32 m0, s54
	ds_read_b128 v[186:189], v183 offset:16384
	ds_read_b128 v[190:193], v183 offset:17408
	ds_read_b128 v[198:201], v183 offset:18432
	ds_read_b128 v[202:205], v183 offset:19456
	ds_read_b128 v[206:209], v183 offset:20480
	ds_read_b128 v[210:213], v183 offset:21504
	ds_read_b128 v[214:217], v183 offset:22528
	ds_read_b128 v[218:221], v183 offset:23552
	global_load_lds_dwordx4 v[176:177], off
	s_add_i32 m0, s54, 0x2000
	s_add_u32 s54, s28, 0x100000
	v_lshl_add_u64 v[194:195], s[28:29], 0, v[158:159]
	s_addc_u32 s55, s29, 0
	s_add_i32 s56, s50, s34
	global_load_lds_dwordx4 v[194:195], off
	s_mov_b32 m0, s56
	v_lshl_add_u64 v[224:225], s[30:31], 0, v[156:157]
	global_load_lds_dwordx4 v154, s[54:55]
	s_add_i32 m0, s56, 0x2000
	s_nop 0
	global_load_lds_dwordx4 v158, s[54:55]
	s_mov_b32 m0, s35
	v_lshl_add_u64 v[222:223], s[30:31], 0, v[152:153]
	global_load_lds_dwordx4 v[222:223], off
	s_mov_b32 m0, s33
	s_nop 0
	global_load_lds_dwordx4 v[224:225], off
	s_waitcnt lgkmcnt(0)
	s_setprio 1
	s_barrier
; #define PG8_STAGE(bufoff, gbase, voff) do { _Pragma("unroll") for (int _i = 0; _i < 2; ++_i) \
;         __builtin_amdgcn_global_load_lds((const unsigned*)((const char*)(gbase) + (voff)[_i]), (PG8_LAS unsigned*)(lds + (bufoff) + ldsw + _i * 8192), 16, 0, 0); } while (0)
; #define PG8_LDA(dst, b, h) do { _Pragma("unroll") for (int m = 0; m < 4; ++m) _Pragma("unroll") for (int k = 0; k < 2; ++k) dst[m][k] = *(const PG8_LAS bf16x8*)(lds + PG8_SA(b, h) + aoff + m * 2048 + k * 1024); } while (0)
; #define PG8_LDB(dst, b, h) do { _Pragma("unroll") for (int n = 0; n < 2; ++n) _Pragma("unroll") for (int k = 0; k < 2; ++k) dst[n][k] = *(const PG8_LAS bf16x8*)(lds + PG8_SB(b, h) + boff + n * 2048 + k * 1024); } while (0)
; #define PG8_MMA(ai, bj, At, Bt) do { __builtin_amdgcn_s_setprio(1); _Pragma("unroll") for (int m = 0; m < 4; ++m) _Pragma("unroll") for (int n = 0; n < 2; ++n) _Pragma("unroll") for (int k = 0; k < 2; ++k) \
;         acc[ai][bj][m][n] = __builtin_amdgcn_mfma_f32_16x16x32_bf16(Bt[n][k], At[m][k], acc[ai][bj][m][n], 0, 0, 0); __builtin_amdgcn_s_setprio(0); } while (0)
; #define PG8_WAIT_V(n) asm volatile("s_waitcnt vmcnt(" #n ")" ::: "memory")
; #define PG8_WAIT_L(n) asm volatile("s_waitcnt lgkmcnt(" #n ")" ::: "memory")
; #define PG8_BAR __builtin_amdgcn_s_barrier()
; #define PG8_SCHED __builtin_amdgcn_sched_barrier(0)
; template <class Epi, class Sched, bool ALIGN_EPI = false, bool SP2 = false>
; __device__ __forceinline__ void gemm_phase(PG8_LAS unsigned char* lds, const Gemm g, const Sched& S, const Epi& E) {
;     ...
;             PG8_WAIT_V(8); PG8_WAIT_L(0); PG8_BAR; PG8_MMA(1, 0, At, B0); PG8_MMA(1, 1, At, B1); PG8_BAR; PG8_SCHED;
;             PG8_LDB(B0, 1, 0); PG8_LDB(B1, 1, 1); PG8_SCHED; PG8_LDA(At, 1, 0); PG8_STAGE(PG8_SA(0, 1), a2 + hstep, voffA);
;             PG8_WAIT_V(8); PG8_WAIT_L(0); PG8_BAR; PG8_MMA(0, 0, At, B0); PG8_MMA(0, 1, At, B1); PG8_BAR; PG8_SCHED;
	v_mfma_f32_16x16x32_bf16 v[56:59], v[128:131], v[186:189], 0
	v_mfma_f32_16x16x32_bf16 v[60:63], v[136:139], v[186:189], 0
	v_mfma_f32_16x16x32_bf16 v[40:43], v[128:131], v[198:201], 0
	v_mfma_f32_16x16x32_bf16 v[44:47], v[136:139], v[198:201], 0
	v_mfma_f32_16x16x32_bf16 v[24:27], v[128:131], v[206:209], 0
	v_mfma_f32_16x16x32_bf16 v[28:31], v[136:139], v[206:209], 0
	v_mfma_f32_16x16x32_bf16 v[8:11], v[128:131], v[214:217], 0
	v_mfma_f32_16x16x32_bf16 v[12:15], v[136:139], v[214:217], 0
	v_mfma_f32_16x16x32_bf16 v[56:59], v[132:135], v[190:193], v[56:59]
	v_mfma_f32_16x16x32_bf16 v[60:63], v[140:143], v[190:193], v[60:63]
	v_mfma_f32_16x16x32_bf16 v[40:43], v[132:135], v[202:205], v[40:43]
	v_mfma_f32_16x16x32_bf16 v[44:47], v[140:143], v[202:205], v[44:47]
	v_mfma_f32_16x16x32_bf16 v[24:27], v[132:135], v[210:213], v[24:27]
	v_mfma_f32_16x16x32_bf16 v[28:31], v[140:143], v[210:213], v[28:31]
	v_mfma_f32_16x16x32_bf16 v[8:11], v[132:135], v[218:221], v[8:11]
	v_mfma_f32_16x16x32_bf16 v[12:15], v[140:143], v[218:221], v[12:15]
	v_mfma_f32_16x16x32_bf16 v[52:55], v[144:147], v[186:189], 0
	v_mfma_f32_16x16x32_bf16 v[48:51], v[168:171], v[186:189], 0
	v_mfma_f32_16x16x32_bf16 v[36:39], v[144:147], v[198:201], 0
	v_mfma_f32_16x16x32_bf16 v[32:35], v[168:171], v[198:201], 0
	v_mfma_f32_16x16x32_bf16 v[20:23], v[144:147], v[206:209], 0
	v_mfma_f32_16x16x32_bf16 v[16:19], v[168:171], v[206:209], 0
	v_mfma_f32_16x16x32_bf16 v[4:7], v[144:147], v[214:217], 0
	v_mfma_f32_16x16x32_bf16 v[0:3], v[168:171], v[214:217], 0
	v_mfma_f32_16x16x32_bf16 v[52:55], v[148:151], v[190:193], v[52:55]
	v_mfma_f32_16x16x32_bf16 v[48:51], v[172:175], v[190:193], v[48:51]
	v_mfma_f32_16x16x32_bf16 v[36:39], v[148:151], v[202:205], v[36:39]
	v_mfma_f32_16x16x32_bf16 v[32:35], v[172:175], v[202:205], v[32:35]
	v_mfma_f32_16x16x32_bf16 v[20:23], v[148:151], v[210:213], v[20:23]
	v_mfma_f32_16x16x32_bf16 v[16:19], v[172:175], v[210:213], v[16:19]
	v_mfma_f32_16x16x32_bf16 v[4:7], v[148:151], v[218:221], v[4:7]
	v_mfma_f32_16x16x32_bf16 v[0:3], v[172:175], v[218:221], v[0:3]
	s_barrier
	s_setprio 0
	s_add_i32 s54, 0, 0x18000
	s_add_i32 s55, 0, 0x1c000
	v_add_u32_e32 v140, s54, v179
	v_add_u32_e32 v172, s55, v179
	ds_read_b128 v[128:131], v140
	ds_read_b128 v[132:135], v140 offset:1024
	ds_read_b128 v[136:139], v140 offset:2048
	ds_read_b128 v[140:143], v140 offset:3072
	ds_read_b128 v[144:147], v172
	ds_read_b128 v[148:151], v172 offset:1024
	ds_read_b128 v[168:171], v172 offset:2048
	ds_read_b128 v[172:175], v172 offset:3072
	s_add_u32 s30, s30, 0x100000
	s_addc_u32 s31, s31, 0
	s_mov_b32 m0, s37
	ds_read_b128 v[186:189], v183 offset:32768
	ds_read_b128 v[190:193], v183 offset:33792
	ds_read_b128 v[198:201], v183 offset:34816
	ds_read_b128 v[202:205], v183 offset:35840
	ds_read_b128 v[206:209], v183 offset:36864
	ds_read_b128 v[210:213], v183 offset:37888
	ds_read_b128 v[214:217], v183 offset:38912
	ds_read_b128 v[218:221], v183 offset:39936
	global_load_lds_dwordx4 v152, s[30:31]
	s_mov_b32 m0, s39
	v_lshl_add_u64 v[226:227], s[30:31], 0, v[156:157]
	global_load_lds_dwordx4 v[226:227], off
	s_waitcnt vmcnt(8) lgkmcnt(0)
	s_setprio 1
	s_barrier
	v_mfma_f32_16x16x32_bf16 v[124:127], v[128:131], v[186:189], v[124:127]
	v_mfma_f32_16x16x32_bf16 v[120:123], v[136:139], v[186:189], v[120:123]
	v_mfma_f32_16x16x32_bf16 v[104:107], v[128:131], v[198:201], v[104:107]
	v_mfma_f32_16x16x32_bf16 v[108:111], v[136:139], v[198:201], v[108:111]
	v_mfma_f32_16x16x32_bf16 v[88:91], v[128:131], v[206:209], v[88:91]
	v_mfma_f32_16x16x32_bf16 v[92:95], v[136:139], v[206:209], v[92:95]
	v_mfma_f32_16x16x32_bf16 v[72:75], v[128:131], v[214:217], v[72:75]
	v_mfma_f32_16x16x32_bf16 v[76:79], v[136:139], v[214:217], v[76:79]
	v_mfma_f32_16x16x32_bf16 v[124:127], v[132:135], v[190:193], v[124:127]
	v_mfma_f32_16x16x32_bf16 v[120:123], v[140:143], v[190:193], v[120:123]
	v_mfma_f32_16x16x32_bf16 v[104:107], v[132:135], v[202:205], v[104:107]
	v_mfma_f32_16x16x32_bf16 v[108:111], v[140:143], v[202:205], v[108:111]
	v_mfma_f32_16x16x32_bf16 v[88:91], v[132:135], v[210:213], v[88:91]
	v_mfma_f32_16x16x32_bf16 v[92:95], v[140:143], v[210:213], v[92:95]
	v_mfma_f32_16x16x32_bf16 v[72:75], v[132:135], v[218:221], v[72:75]
	v_mfma_f32_16x16x32_bf16 v[76:79], v[140:143], v[218:221], v[76:79]
	v_mfma_f32_16x16x32_bf16 v[116:119], v[144:147], v[186:189], v[116:119]
	v_mfma_f32_16x16x32_bf16 v[112:115], v[168:171], v[186:189], v[112:115]
	v_mfma_f32_16x16x32_bf16 v[100:103], v[144:147], v[198:201], v[100:103]
	v_mfma_f32_16x16x32_bf16 v[96:99], v[168:171], v[198:201], v[96:99]
	v_mfma_f32_16x16x32_bf16 v[84:87], v[144:147], v[206:209], v[84:87]
	v_mfma_f32_16x16x32_bf16 v[80:83], v[168:171], v[206:209], v[80:83]
	v_mfma_f32_16x16x32_bf16 v[68:71], v[144:147], v[214:217], v[68:71]
	v_mfma_f32_16x16x32_bf16 v[64:67], v[168:171], v[214:217], v[64:67]
	v_mfma_f32_16x16x32_bf16 v[116:119], v[148:151], v[190:193], v[116:119]
	v_mfma_f32_16x16x32_bf16 v[112:115], v[172:175], v[190:193], v[112:115]
	v_mfma_f32_16x16x32_bf16 v[100:103], v[148:151], v[202:205], v[100:103]
	v_mfma_f32_16x16x32_bf16 v[96:99], v[172:175], v[202:205], v[96:99]
	v_mfma_f32_16x16x32_bf16 v[84:87], v[148:151], v[210:213], v[84:87]
	v_mfma_f32_16x16x32_bf16 v[80:83], v[172:175], v[210:213], v[80:83]
	v_mfma_f32_16x16x32_bf16 v[68:71], v[148:151], v[218:221], v[68:71]
	v_mfma_f32_16x16x32_bf16 v[64:67], v[172:175], v[218:221], v[64:67]
	s_barrier
; #define PG8_STAGE(bufoff, gbase, voff) do { _Pragma("unroll") for (int _i = 0; _i < 2; ++_i) \
;         __builtin_amdgcn_global_load_lds((const unsigned*)((const char*)(gbase) + (voff)[_i]), (PG8_LAS unsigned*)(lds + (bufoff) + ldsw + _i * 8192), 16, 0, 0); } while (0)
; #define PG8_LDA(dst, b, h) do { _Pragma("unroll") for (int m = 0; m < 4; ++m) _Pragma("unroll") for (int k = 0; k < 2; ++k) dst[m][k] = *(const PG8_LAS bf16x8*)(lds + PG8_SA(b, h) + aoff + m * 2048 + k * 1024); } while (0)
; #define PG8_LDB(dst, b, h) do { _Pragma("unroll") for (int n = 0; n < 2; ++n) _Pragma("unroll") for (int k = 0; k < 2; ++k) dst[n][k] = *(const PG8_LAS bf16x8*)(lds + PG8_SB(b, h) + boff + n * 2048 + k * 1024); } while (0)
; #define PG8_MMA(ai, bj, At, Bt) do { __builtin_amdgcn_s_setprio(1); _Pragma("unroll") for (int m = 0; m < 4; ++m) _Pragma("unroll") for (int n = 0; n < 2; ++n) _Pragma("unroll") for (int k = 0; k < 2; ++k) \
;         acc[ai][bj][m][n] = __builtin_amdgcn_mfma_f32_16x16x32_bf16(Bt[n][k], At[m][k], acc[ai][bj][m][n], 0, 0, 0); __builtin_amdgcn_s_setprio(0); } while (0)
; #define PG8_WAIT_V(n) asm volatile("s_waitcnt vmcnt(" #n ")" ::: "memory")
; template <class Epi, class Sched, bool ALIGN_EPI = false, bool SP2 = false>
; __device__ __forceinline__ void gemm_phase(PG8_LAS unsigned char* lds, const Gemm g, const Sched& S, const Epi& E) {
;     ...
;             PG8_LDB(B0, 0, 0); PG8_LDB(B1, 0, 1); PG8_SCHED; PG8_LDA(At, 0, 0); PG8_STAGE(PG8_SA(1, 1), a1 + hstep, voffA);
;             PG8_WAIT_V(8); PG8_WAIT_L(0); PG8_BAR; PG8_MMA(0, 0, At, B0); PG8_MMA(0, 1, At, B1); PG8_BAR; PG8_SCHED;
;             PG8_LDA(At, 0, 1); PG8_STAGE(PG8_SB(0, 0), b2, voffB); PG8_STAGE(PG8_SB(0, 1), b2 + hstep, voffB); PG8_STAGE(PG8_SA(0, 0), a2, voffA);
;             PG8_WAIT_V(8); PG8_WAIT_L(0); PG8_BAR; PG8_MMA(1, 0, At, B0); PG8_MMA(1, 1, At, B1); PG8_BAR; PG8_SCHED;
;             PG8_LDB(B0, 1, 0); PG8_LDB(B1, 1, 1); PG8_SCHED; PG8_LDA(At, 1, 0); PG8_STAGE(PG8_SA(0, 1), a2 + hstep, voffA);
;             PG8_WAIT_V(8); PG8_WAIT_L(0); PG8_BAR; PG8_MMA(0, 0, At, B0); PG8_MMA(0, 1, At, B1); PG8_BAR; PG8_SCHED;
;             PG8_LDA(At, 1, 1); PG8_STAGE(PG8_SB(1, 0), b3, voffB); PG8_STAGE(PG8_SB(1, 1), b3 + hstep, voffB); PG8_STAGE(PG8_SA(1, 0), a3, voffA);
;             PG8_WAIT_V(8); PG8_WAIT_L(0); PG8_BAR; PG8_MMA(1, 0, At, B0); PG8_MMA(1, 1, At, B1); PG8_BAR; PG8_SCHED;
	s_setprio 0
	s_add_i32 s30, s54, s34
	v_lshl_add_u64 v[176:177], v[176:177], 0, s[12:13]
	s_mov_b32 m0, s30
	ds_read_b128 v[186:189], v183 offset:49152
	ds_read_b128 v[190:193], v183 offset:50176
	ds_read_b128 v[198:201], v183 offset:51200
	ds_read_b128 v[202:205], v183 offset:52224
	ds_read_b128 v[206:209], v183 offset:53248
	ds_read_b128 v[210:213], v183 offset:54272
	ds_read_b128 v[214:217], v183 offset:55296
	ds_read_b128 v[218:221], v183 offset:56320
	global_load_lds_dwordx4 v[176:177], off
	s_add_i32 m0, s30, 0x2000
	s_add_u32 s28, s28, 0x100080
	v_lshl_add_u64 v[176:177], v[194:195], 0, s[12:13]
	s_addc_u32 s29, s29, 0
	s_add_i32 s30, s55, s34
	global_load_lds_dwordx4 v[176:177], off
	s_mov_b32 m0, s30
	s_nop 0
	global_load_lds_dwordx4 v154, s[28:29]
	s_add_i32 m0, s30, 0x2000
	v_lshl_add_u64 v[176:177], s[28:29], 0, v[158:159]
	global_load_lds_dwordx4 v[176:177], off
	s_mov_b32 m0, s43
	v_lshl_add_u64 v[176:177], v[222:223], 0, s[12:13]
	global_load_lds_dwordx4 v[176:177], off
	s_mov_b32 m0, s44
	v_lshl_add_u64 v[176:177], v[224:225], 0, s[12:13]
	global_load_lds_dwordx4 v[176:177], off
	s_waitcnt vmcnt(8) lgkmcnt(0)
	s_setprio 1
	s_barrier
	v_mfma_f32_16x16x32_bf16 v[56:59], v[128:131], v[186:189], v[56:59]
	v_mfma_f32_16x16x32_bf16 v[60:63], v[136:139], v[186:189], v[60:63]
	v_mfma_f32_16x16x32_bf16 v[40:43], v[128:131], v[198:201], v[40:43]
	v_mfma_f32_16x16x32_bf16 v[44:47], v[136:139], v[198:201], v[44:47]
	v_mfma_f32_16x16x32_bf16 v[24:27], v[128:131], v[206:209], v[24:27]
	v_mfma_f32_16x16x32_bf16 v[28:31], v[136:139], v[206:209], v[28:31]
	v_mfma_f32_16x16x32_bf16 v[8:11], v[128:131], v[214:217], v[8:11]
	v_mfma_f32_16x16x32_bf16 v[12:15], v[136:139], v[214:217], v[12:15]
	v_mfma_f32_16x16x32_bf16 v[56:59], v[132:135], v[190:193], v[56:59]
	v_mfma_f32_16x16x32_bf16 v[60:63], v[140:143], v[190:193], v[60:63]
	v_mfma_f32_16x16x32_bf16 v[40:43], v[132:135], v[202:205], v[40:43]
	v_mfma_f32_16x16x32_bf16 v[44:47], v[140:143], v[202:205], v[44:47]
	v_mfma_f32_16x16x32_bf16 v[24:27], v[132:135], v[210:213], v[24:27]
	v_mfma_f32_16x16x32_bf16 v[28:31], v[140:143], v[210:213], v[28:31]
	v_mfma_f32_16x16x32_bf16 v[8:11], v[132:135], v[218:221], v[8:11]
	v_mfma_f32_16x16x32_bf16 v[12:15], v[140:143], v[218:221], v[12:15]
	v_mfma_f32_16x16x32_bf16 v[52:55], v[144:147], v[186:189], v[52:55]
	v_mfma_f32_16x16x32_bf16 v[48:51], v[168:171], v[186:189], v[48:51]
	v_mfma_f32_16x16x32_bf16 v[36:39], v[144:147], v[198:201], v[36:39]
	v_mfma_f32_16x16x32_bf16 v[32:35], v[168:171], v[198:201], v[32:35]
	v_mfma_f32_16x16x32_bf16 v[20:23], v[144:147], v[206:209], v[20:23]
	v_mfma_f32_16x16x32_bf16 v[16:19], v[168:171], v[206:209], v[16:19]
	v_mfma_f32_16x16x32_bf16 v[4:7], v[144:147], v[214:217], v[4:7]
	v_mfma_f32_16x16x32_bf16 v[0:3], v[168:171], v[214:217], v[0:3]
	v_mfma_f32_16x16x32_bf16 v[52:55], v[148:151], v[190:193], v[52:55]
	v_mfma_f32_16x16x32_bf16 v[48:51], v[172:175], v[190:193], v[48:51]
	v_mfma_f32_16x16x32_bf16 v[36:39], v[148:151], v[202:205], v[36:39]
	v_mfma_f32_16x16x32_bf16 v[32:35], v[172:175], v[202:205], v[32:35]
	v_mfma_f32_16x16x32_bf16 v[20:23], v[148:151], v[210:213], v[20:23]
	v_mfma_f32_16x16x32_bf16 v[16:19], v[172:175], v[210:213], v[16:19]
	v_mfma_f32_16x16x32_bf16 v[4:7], v[148:151], v[218:221], v[4:7]
	v_mfma_f32_16x16x32_bf16 v[0:3], v[172:175], v[218:221], v[0:3]
	s_barrier
	s_setprio 0
	s_add_i32 s53, s53, 2
	s_add_u32 s26, s26, 0x100
	s_addc_u32 s27, s27, 0
	s_add_u32 s49, s49, 0x100
	s_addc_u32 s52, s52, 0
.LBB0_763:
	ds_read_b128 v[128:131], v181
	ds_read_b128 v[132:135], v181 offset:1024
	ds_read_b128 v[136:139], v181 offset:2048
	ds_read_b128 v[140:143], v181 offset:3072
	ds_read_b128 v[144:147], v182
	ds_read_b128 v[148:151], v182 offset:1024
	ds_read_b128 v[168:171], v182 offset:2048
	ds_read_b128 v[172:175], v182 offset:3072
	s_add_u32 s28, s26, 0xfff00080
	s_addc_u32 s29, s27, -1
	s_cmp_eq_u32 s53, 60
	s_cselect_b32 s31, s7, s29
	s_cselect_b32 s30, s21, s28
	s_cselect_b32 s29, s19, s52
	s_cselect_b32 s28, s48, s49
	s_add_i32 m0, s35, 0xc000
	ds_read_b128 v[186:189], v183
	ds_read_b128 v[190:193], v183 offset:1024
	ds_read_b128 v[198:201], v183 offset:2048
	ds_read_b128 v[202:205], v183 offset:3072
	ds_read_b128 v[206:209], v183 offset:4096
	ds_read_b128 v[210:213], v183 offset:5120
	ds_read_b128 v[214:217], v183 offset:6144
	ds_read_b128 v[218:221], v183 offset:7168
	global_load_lds_dwordx4 v160, s[26:27]
	s_add_i32 m0, s35, 0xe000
	s_nop 0
	global_load_lds_dwordx4 v162, s[26:27]
	s_waitcnt vmcnt(8) lgkmcnt(0)
	s_setprio 1
	s_barrier
; #define PG8_STAGE(bufoff, gbase, voff) do { _Pragma("unroll") for (int _i = 0; _i < 2; ++_i) \
;         __builtin_amdgcn_global_load_lds((const unsigned*)((const char*)(gbase) + (voff)[_i]), (PG8_LAS unsigned*)(lds + (bufoff) + ldsw + _i * 8192), 16, 0, 0); } while (0)
; #define PG8_LDA(dst, b, h) do { _Pragma("unroll") for (int m = 0; m < 4; ++m) _Pragma("unroll") for (int k = 0; k < 2; ++k) dst[m][k] = *(const PG8_LAS bf16x8*)(lds + PG8_SA(b, h) + aoff + m * 2048 + k * 1024); } while (0)
; #define PG8_MMA(ai, bj, At, Bt) do { __builtin_amdgcn_s_setprio(1); _Pragma("unroll") for (int m = 0; m < 4; ++m) _Pragma("unroll") for (int n = 0; n < 2; ++n) _Pragma("unroll") for (int k = 0; k < 2; ++k) \
;         acc[ai][bj][m][n] = __builtin_amdgcn_mfma_f32_16x16x32_bf16(Bt[n][k], At[m][k], acc[ai][bj][m][n], 0, 0, 0); __builtin_amdgcn_s_setprio(0); } while (0)
; #define PG8_WAIT_V(n) asm volatile("s_waitcnt vmcnt(" #n ")" ::: "memory")
; #define PG8_WAIT_L(n) asm volatile("s_waitcnt lgkmcnt(" #n ")" ::: "memory")
; #define PG8_BAR __builtin_amdgcn_s_barrier()
; #define PG8_SCHED __builtin_amdgcn_sched_barrier(0)
; template <class Epi, class Sched, bool ALIGN_EPI = false, bool SP2 = false>
; __device__ __forceinline__ void gemm_phase(PG8_LAS unsigned char* lds, const Gemm g, const Sched& S, const Epi& E) {
;     ...
;             PG8_WAIT_V(8); PG8_WAIT_L(0); PG8_BAR; PG8_MMA(0, 0, At, B0); PG8_MMA(0, 1, At, B1); PG8_BAR; PG8_SCHED;
;             PG8_LDA(At, 0, 1); PG8_STAGE(PG8_SB(0, 0), b2, voffB); PG8_STAGE(PG8_SB(0, 1), b2 + hstep, voffB); PG8_STAGE(PG8_SA(0, 0), a2, voffA);
;             PG8_WAIT_V(8); PG8_WAIT_L(0); PG8_BAR; PG8_MMA(1, 0, At, B0); PG8_MMA(1, 1, At, B1); PG8_BAR; PG8_SCHED;
	v_mfma_f32_16x16x32_bf16 v[124:127], v[128:131], v[186:189], v[124:127]
	v_mfma_f32_16x16x32_bf16 v[120:123], v[136:139], v[186:189], v[120:123]
	v_mfma_f32_16x16x32_bf16 v[104:107], v[128:131], v[198:201], v[104:107]
	v_mfma_f32_16x16x32_bf16 v[108:111], v[136:139], v[198:201], v[108:111]
	v_mfma_f32_16x16x32_bf16 v[88:91], v[128:131], v[206:209], v[88:91]
	v_mfma_f32_16x16x32_bf16 v[92:95], v[136:139], v[206:209], v[92:95]
	v_mfma_f32_16x16x32_bf16 v[72:75], v[128:131], v[214:217], v[72:75]
	v_mfma_f32_16x16x32_bf16 v[76:79], v[136:139], v[214:217], v[76:79]
	v_mfma_f32_16x16x32_bf16 v[124:127], v[132:135], v[190:193], v[124:127]
	v_mfma_f32_16x16x32_bf16 v[120:123], v[140:143], v[190:193], v[120:123]
	v_mfma_f32_16x16x32_bf16 v[104:107], v[132:135], v[202:205], v[104:107]
	v_mfma_f32_16x16x32_bf16 v[108:111], v[140:143], v[202:205], v[108:111]
	v_mfma_f32_16x16x32_bf16 v[88:91], v[132:135], v[210:213], v[88:91]
	v_mfma_f32_16x16x32_bf16 v[92:95], v[140:143], v[210:213], v[92:95]
	v_mfma_f32_16x16x32_bf16 v[72:75], v[132:135], v[218:221], v[72:75]
	v_mfma_f32_16x16x32_bf16 v[76:79], v[140:143], v[218:221], v[76:79]
	v_mfma_f32_16x16x32_bf16 v[116:119], v[144:147], v[186:189], v[116:119]
	v_mfma_f32_16x16x32_bf16 v[112:115], v[168:171], v[186:189], v[112:115]
	v_mfma_f32_16x16x32_bf16 v[100:103], v[144:147], v[198:201], v[100:103]
	v_mfma_f32_16x16x32_bf16 v[96:99], v[168:171], v[198:201], v[96:99]
	v_mfma_f32_16x16x32_bf16 v[84:87], v[144:147], v[206:209], v[84:87]
	v_mfma_f32_16x16x32_bf16 v[80:83], v[168:171], v[206:209], v[80:83]
	v_mfma_f32_16x16x32_bf16 v[68:71], v[144:147], v[214:217], v[68:71]
	v_mfma_f32_16x16x32_bf16 v[64:67], v[168:171], v[214:217], v[64:67]
	v_mfma_f32_16x16x32_bf16 v[116:119], v[148:151], v[190:193], v[116:119]
	v_mfma_f32_16x16x32_bf16 v[112:115], v[172:175], v[190:193], v[112:115]
	v_mfma_f32_16x16x32_bf16 v[100:103], v[148:151], v[202:205], v[100:103]
	v_mfma_f32_16x16x32_bf16 v[96:99], v[172:175], v[202:205], v[96:99]
	v_mfma_f32_16x16x32_bf16 v[84:87], v[148:151], v[210:213], v[84:87]
	v_mfma_f32_16x16x32_bf16 v[80:83], v[172:175], v[210:213], v[80:83]
	v_mfma_f32_16x16x32_bf16 v[68:71], v[148:151], v[218:221], v[68:71]
	v_mfma_f32_16x16x32_bf16 v[64:67], v[172:175], v[218:221], v[64:67]
	s_barrier
	s_setprio 0
	s_add_i32 s54, s47, s34
	v_lshl_add_u64 v[176:177], s[28:29], 0, v[154:155]
	s_mov_b32 m0, s54
	ds_read_b128 v[186:189], v183 offset:16384
	ds_read_b128 v[190:193], v183 offset:17408
	ds_read_b128 v[198:201], v183 offset:18432
	ds_read_b128 v[202:205], v183 offset:19456
	ds_read_b128 v[206:209], v183 offset:20480
	ds_read_b128 v[210:213], v183 offset:21504
	ds_read_b128 v[214:217], v183 offset:22528
	ds_read_b128 v[218:221], v183 offset:23552
	global_load_lds_dwordx4 v[176:177], off
	s_add_i32 m0, s54, 0x2000
	s_add_u32 s54, s28, 0x100000
	v_lshl_add_u64 v[194:195], s[28:29], 0, v[158:159]
	s_addc_u32 s55, s29, 0
	s_add_i32 s56, s50, s34
	global_load_lds_dwordx4 v[194:195], off
	s_mov_b32 m0, s56
	v_lshl_add_u64 v[224:225], s[30:31], 0, v[156:157]
	global_load_lds_dwordx4 v154, s[54:55]
	s_add_i32 m0, s56, 0x2000
	s_nop 0
	global_load_lds_dwordx4 v158, s[54:55]
	s_mov_b32 m0, s35
	v_lshl_add_u64 v[222:223], s[30:31], 0, v[152:153]
	global_load_lds_dwordx4 v[222:223], off
	s_mov_b32 m0, s33
	s_nop 0
	global_load_lds_dwordx4 v[224:225], off
	s_waitcnt vmcnt(8) lgkmcnt(0)
	s_setprio 1
	s_barrier
	v_mfma_f32_16x16x32_bf16 v[56:59], v[128:131], v[186:189], v[56:59]
	v_mfma_f32_16x16x32_bf16 v[60:63], v[136:139], v[186:189], v[60:63]
	v_mfma_f32_16x16x32_bf16 v[40:43], v[128:131], v[198:201], v[40:43]
	v_mfma_f32_16x16x32_bf16 v[44:47], v[136:139], v[198:201], v[44:47]
	v_mfma_f32_16x16x32_bf16 v[24:27], v[128:131], v[206:209], v[24:27]
	v_mfma_f32_16x16x32_bf16 v[28:31], v[136:139], v[206:209], v[28:31]
	v_mfma_f32_16x16x32_bf16 v[8:11], v[128:131], v[214:217], v[8:11]
	v_mfma_f32_16x16x32_bf16 v[12:15], v[136:139], v[214:217], v[12:15]
	v_mfma_f32_16x16x32_bf16 v[56:59], v[132:135], v[190:193], v[56:59]
	v_mfma_f32_16x16x32_bf16 v[60:63], v[140:143], v[190:193], v[60:63]
	v_mfma_f32_16x16x32_bf16 v[40:43], v[132:135], v[202:205], v[40:43]
	v_mfma_f32_16x16x32_bf16 v[44:47], v[140:143], v[202:205], v[44:47]
	v_mfma_f32_16x16x32_bf16 v[24:27], v[132:135], v[210:213], v[24:27]
	v_mfma_f32_16x16x32_bf16 v[28:31], v[140:143], v[210:213], v[28:31]
	v_mfma_f32_16x16x32_bf16 v[8:11], v[132:135], v[218:221], v[8:11]
	v_mfma_f32_16x16x32_bf16 v[12:15], v[140:143], v[218:221], v[12:15]
	v_mfma_f32_16x16x32_bf16 v[52:55], v[144:147], v[186:189], v[52:55]
	v_mfma_f32_16x16x32_bf16 v[48:51], v[168:171], v[186:189], v[48:51]
	v_mfma_f32_16x16x32_bf16 v[36:39], v[144:147], v[198:201], v[36:39]
	v_mfma_f32_16x16x32_bf16 v[32:35], v[168:171], v[198:201], v[32:35]
	v_mfma_f32_16x16x32_bf16 v[20:23], v[144:147], v[206:209], v[20:23]
	v_mfma_f32_16x16x32_bf16 v[16:19], v[168:171], v[206:209], v[16:19]
	v_mfma_f32_16x16x32_bf16 v[4:7], v[144:147], v[214:217], v[4:7]
	v_mfma_f32_16x16x32_bf16 v[0:3], v[168:171], v[214:217], v[0:3]
	v_mfma_f32_16x16x32_bf16 v[52:55], v[148:151], v[190:193], v[52:55]
	v_mfma_f32_16x16x32_bf16 v[48:51], v[172:175], v[190:193], v[48:51]
	v_mfma_f32_16x16x32_bf16 v[36:39], v[148:151], v[202:205], v[36:39]
	v_mfma_f32_16x16x32_bf16 v[32:35], v[172:175], v[202:205], v[32:35]
	v_mfma_f32_16x16x32_bf16 v[20:23], v[148:151], v[210:213], v[20:23]
	v_mfma_f32_16x16x32_bf16 v[16:19], v[172:175], v[210:213], v[16:19]
	v_mfma_f32_16x16x32_bf16 v[4:7], v[148:151], v[218:221], v[4:7]
	v_mfma_f32_16x16x32_bf16 v[0:3], v[172:175], v[218:221], v[0:3]
	s_barrier
; #define PG8_STAGE(bufoff, gbase, voff) do { _Pragma("unroll") for (int _i = 0; _i < 2; ++_i) \
;         __builtin_amdgcn_global_load_lds((const unsigned*)((const char*)(gbase) + (voff)[_i]), (PG8_LAS unsigned*)(lds + (bufoff) + ldsw + _i * 8192), 16, 0, 0); } while (0)
; #define PG8_LDA(dst, b, h) do { _Pragma("unroll") for (int m = 0; m < 4; ++m) _Pragma("unroll") for (int k = 0; k < 2; ++k) dst[m][k] = *(const PG8_LAS bf16x8*)(lds + PG8_SA(b, h) + aoff + m * 2048 + k * 1024); } while (0)
; #define PG8_LDB(dst, b, h) do { _Pragma("unroll") for (int n = 0; n < 2; ++n) _Pragma("unroll") for (int k = 0; k < 2; ++k) dst[n][k] = *(const PG8_LAS bf16x8*)(lds + PG8_SB(b, h) + boff + n * 2048 + k * 1024); } while (0)
; #define PG8_MMA(ai, bj, At, Bt) do { __builtin_amdgcn_s_setprio(1); _Pragma("unroll") for (int m = 0; m < 4; ++m) _Pragma("unroll") for (int n = 0; n < 2; ++n) _Pragma("unroll") for (int k = 0; k < 2; ++k) \
;         acc[ai][bj][m][n] = __builtin_amdgcn_mfma_f32_16x16x32_bf16(Bt[n][k], At[m][k], acc[ai][bj][m][n], 0, 0, 0); __builtin_amdgcn_s_setprio(0); } while (0)
; #define PG8_WAIT_V(n) asm volatile("s_waitcnt vmcnt(" #n ")" ::: "memory")
; #define PG8_WAIT_L(n) asm volatile("s_waitcnt lgkmcnt(" #n ")" ::: "memory")
; #define PG8_BAR __builtin_amdgcn_s_barrier()
; #define PG8_SCHED __builtin_amdgcn_sched_barrier(0)
; template <class Epi, class Sched, bool ALIGN_EPI = false, bool SP2 = false>
; __device__ __forceinline__ void gemm_phase(PG8_LAS unsigned char* lds, const Gemm g, const Sched& S, const Epi& E) {
;     ...
;             PG8_LDB(B0, 1, 0); PG8_LDB(B1, 1, 1); PG8_SCHED; PG8_LDA(At, 1, 0); PG8_STAGE(PG8_SA(0, 1), a2 + hstep, voffA);
;             PG8_WAIT_V(8); PG8_WAIT_L(0); PG8_BAR; PG8_MMA(0, 0, At, B0); PG8_MMA(0, 1, At, B1); PG8_BAR; PG8_SCHED;
;             PG8_LDA(At, 1, 1); PG8_STAGE(PG8_SB(1, 0), b3, voffB); PG8_STAGE(PG8_SB(1, 1), b3 + hstep, voffB); PG8_STAGE(PG8_SA(1, 0), a3, voffA);
;             PG8_WAIT_V(8); PG8_WAIT_L(0); PG8_BAR; PG8_MMA(1, 0, At, B0); PG8_MMA(1, 1, At, B1); PG8_BAR; PG8_SCHED;
;     ...
;         if constexpr (ALIGN_EPI) { if (wr == 0) PG8_BAR; }
	s_setprio 0
	s_add_i32 s54, 0, 0x18000
	s_add_i32 s55, 0, 0x1c000
	v_add_u32_e32 v140, s54, v179
	v_add_u32_e32 v172, s55, v179
	ds_read_b128 v[128:131], v140
	ds_read_b128 v[132:135], v140 offset:1024
	ds_read_b128 v[136:139], v140 offset:2048
	ds_read_b128 v[140:143], v140 offset:3072
	ds_read_b128 v[144:147], v172
	ds_read_b128 v[148:151], v172 offset:1024
	ds_read_b128 v[168:171], v172 offset:2048
	ds_read_b128 v[172:175], v172 offset:3072
	s_add_u32 s30, s30, 0x100000
	s_addc_u32 s31, s31, 0
	s_mov_b32 m0, s37
	ds_read_b128 v[186:189], v183 offset:32768
	ds_read_b128 v[190:193], v183 offset:33792
	ds_read_b128 v[198:201], v183 offset:34816
	ds_read_b128 v[202:205], v183 offset:35840
	ds_read_b128 v[206:209], v183 offset:36864
	ds_read_b128 v[210:213], v183 offset:37888
	ds_read_b128 v[214:217], v183 offset:38912
	ds_read_b128 v[218:221], v183 offset:39936
	global_load_lds_dwordx4 v152, s[30:31]
	s_mov_b32 m0, s39
	s_nop 0
	global_load_lds_dwordx4 v156, s[30:31]
	s_waitcnt vmcnt(8) lgkmcnt(0)
	s_setprio 1
	s_barrier
	v_mfma_f32_16x16x32_bf16 v[124:127], v[128:131], v[186:189], v[124:127]
	v_mfma_f32_16x16x32_bf16 v[120:123], v[136:139], v[186:189], v[120:123]
	v_mfma_f32_16x16x32_bf16 v[104:107], v[128:131], v[198:201], v[104:107]
	v_mfma_f32_16x16x32_bf16 v[108:111], v[136:139], v[198:201], v[108:111]
	v_mfma_f32_16x16x32_bf16 v[88:91], v[128:131], v[206:209], v[88:91]
	v_mfma_f32_16x16x32_bf16 v[92:95], v[136:139], v[206:209], v[92:95]
	v_mfma_f32_16x16x32_bf16 v[72:75], v[128:131], v[214:217], v[72:75]
	v_mfma_f32_16x16x32_bf16 v[76:79], v[136:139], v[214:217], v[76:79]
	v_mfma_f32_16x16x32_bf16 v[124:127], v[132:135], v[190:193], v[124:127]
	v_mfma_f32_16x16x32_bf16 v[120:123], v[140:143], v[190:193], v[120:123]
	v_mfma_f32_16x16x32_bf16 v[104:107], v[132:135], v[202:205], v[104:107]
	v_mfma_f32_16x16x32_bf16 v[108:111], v[140:143], v[202:205], v[108:111]
	v_mfma_f32_16x16x32_bf16 v[88:91], v[132:135], v[210:213], v[88:91]
	v_mfma_f32_16x16x32_bf16 v[92:95], v[140:143], v[210:213], v[92:95]
	v_mfma_f32_16x16x32_bf16 v[72:75], v[132:135], v[218:221], v[72:75]
	v_mfma_f32_16x16x32_bf16 v[76:79], v[140:143], v[218:221], v[76:79]
	v_mfma_f32_16x16x32_bf16 v[116:119], v[144:147], v[186:189], v[116:119]
	v_mfma_f32_16x16x32_bf16 v[112:115], v[168:171], v[186:189], v[112:115]
	v_mfma_f32_16x16x32_bf16 v[100:103], v[144:147], v[198:201], v[100:103]
	v_mfma_f32_16x16x32_bf16 v[96:99], v[168:171], v[198:201], v[96:99]
	v_mfma_f32_16x16x32_bf16 v[84:87], v[144:147], v[206:209], v[84:87]
	v_mfma_f32_16x16x32_bf16 v[80:83], v[168:171], v[206:209], v[80:83]
	v_mfma_f32_16x16x32_bf16 v[68:71], v[144:147], v[214:217], v[68:71]
	v_mfma_f32_16x16x32_bf16 v[64:67], v[168:171], v[214:217], v[64:67]
	v_mfma_f32_16x16x32_bf16 v[116:119], v[148:151], v[190:193], v[116:119]
	v_mfma_f32_16x16x32_bf16 v[112:115], v[172:175], v[190:193], v[112:115]
	v_mfma_f32_16x16x32_bf16 v[100:103], v[148:151], v[202:205], v[100:103]
	v_mfma_f32_16x16x32_bf16 v[96:99], v[172:175], v[202:205], v[96:99]
	v_mfma_f32_16x16x32_bf16 v[84:87], v[148:151], v[210:213], v[84:87]
	v_mfma_f32_16x16x32_bf16 v[80:83], v[172:175], v[210:213], v[80:83]
	v_mfma_f32_16x16x32_bf16 v[68:71], v[148:151], v[218:221], v[68:71]
	v_mfma_f32_16x16x32_bf16 v[64:67], v[172:175], v[218:221], v[64:67]
	s_barrier
	s_setprio 0
	s_add_i32 s30, s54, s34
	v_lshl_add_u64 v[176:177], v[176:177], 0, s[12:13]
	s_mov_b32 m0, s30
	ds_read_b128 v[186:189], v183 offset:49152
	ds_read_b128 v[190:193], v183 offset:50176
	ds_read_b128 v[198:201], v183 offset:51200
	ds_read_b128 v[202:205], v183 offset:52224
	ds_read_b128 v[206:209], v183 offset:53248
	ds_read_b128 v[210:213], v183 offset:54272
	ds_read_b128 v[214:217], v183 offset:55296
	ds_read_b128 v[218:221], v183 offset:56320
	global_load_lds_dwordx4 v[176:177], off
	s_add_i32 m0, s30, 0x2000
	s_add_u32 s28, s28, 0x100080
	v_lshl_add_u64 v[176:177], v[194:195], 0, s[12:13]
	s_addc_u32 s29, s29, 0
	s_add_i32 s30, s55, s34
	global_load_lds_dwordx4 v[176:177], off
	s_mov_b32 m0, s30
	s_nop 0
	global_load_lds_dwordx4 v154, s[28:29]
	s_add_i32 m0, s30, 0x2000
	v_lshl_add_u64 v[176:177], s[28:29], 0, v[158:159]
	global_load_lds_dwordx4 v[176:177], off
	s_mov_b32 m0, s43
	v_lshl_add_u64 v[176:177], v[222:223], 0, s[12:13]
	global_load_lds_dwordx4 v[176:177], off
	s_mov_b32 m0, s44
	v_lshl_add_u64 v[176:177], v[224:225], 0, s[12:13]
	global_load_lds_dwordx4 v[176:177], off
	s_waitcnt vmcnt(8) lgkmcnt(0)
	s_setprio 1
	s_barrier
	v_mfma_f32_16x16x32_bf16 v[56:59], v[128:131], v[186:189], v[56:59]
	v_mfma_f32_16x16x32_bf16 v[60:63], v[136:139], v[186:189], v[60:63]
	v_mfma_f32_16x16x32_bf16 v[40:43], v[128:131], v[198:201], v[40:43]
	v_mfma_f32_16x16x32_bf16 v[44:47], v[136:139], v[198:201], v[44:47]
	v_mfma_f32_16x16x32_bf16 v[24:27], v[128:131], v[206:209], v[24:27]
	v_mfma_f32_16x16x32_bf16 v[28:31], v[136:139], v[206:209], v[28:31]
	v_mfma_f32_16x16x32_bf16 v[8:11], v[128:131], v[214:217], v[8:11]
	v_mfma_f32_16x16x32_bf16 v[12:15], v[136:139], v[214:217], v[12:15]
	v_mfma_f32_16x16x32_bf16 v[56:59], v[132:135], v[190:193], v[56:59]
	v_mfma_f32_16x16x32_bf16 v[60:63], v[140:143], v[190:193], v[60:63]
	v_mfma_f32_16x16x32_bf16 v[40:43], v[132:135], v[202:205], v[40:43]
	v_mfma_f32_16x16x32_bf16 v[44:47], v[140:143], v[202:205], v[44:47]
	v_mfma_f32_16x16x32_bf16 v[24:27], v[132:135], v[210:213], v[24:27]
	v_mfma_f32_16x16x32_bf16 v[28:31], v[140:143], v[210:213], v[28:31]
	v_mfma_f32_16x16x32_bf16 v[8:11], v[132:135], v[218:221], v[8:11]
	v_mfma_f32_16x16x32_bf16 v[12:15], v[140:143], v[218:221], v[12:15]
	v_mfma_f32_16x16x32_bf16 v[52:55], v[144:147], v[186:189], v[52:55]
	v_mfma_f32_16x16x32_bf16 v[48:51], v[168:171], v[186:189], v[48:51]
	v_mfma_f32_16x16x32_bf16 v[36:39], v[144:147], v[198:201], v[36:39]
	v_mfma_f32_16x16x32_bf16 v[32:35], v[168:171], v[198:201], v[32:35]
	v_mfma_f32_16x16x32_bf16 v[20:23], v[144:147], v[206:209], v[20:23]
	v_mfma_f32_16x16x32_bf16 v[16:19], v[168:171], v[206:209], v[16:19]
	v_mfma_f32_16x16x32_bf16 v[4:7], v[144:147], v[214:217], v[4:7]
	v_mfma_f32_16x16x32_bf16 v[0:3], v[168:171], v[214:217], v[0:3]
	v_mfma_f32_16x16x32_bf16 v[52:55], v[148:151], v[190:193], v[52:55]
	v_mfma_f32_16x16x32_bf16 v[48:51], v[172:175], v[190:193], v[48:51]
	v_mfma_f32_16x16x32_bf16 v[36:39], v[148:151], v[202:205], v[36:39]
	v_mfma_f32_16x16x32_bf16 v[32:35], v[172:175], v[202:205], v[32:35]
	v_mfma_f32_16x16x32_bf16 v[20:23], v[148:151], v[210:213], v[20:23]
	v_mfma_f32_16x16x32_bf16 v[16:19], v[172:175], v[210:213], v[16:19]
	v_mfma_f32_16x16x32_bf16 v[4:7], v[148:151], v[218:221], v[4:7]
	v_mfma_f32_16x16x32_bf16 v[0:3], v[172:175], v[218:221], v[0:3]
	s_barrier
	s_setprio 0
	s_add_i32 s53, s53, 2
	s_add_u32 s26, s26, 0x100
	s_addc_u32 s27, s27, 0
	s_add_u32 s49, s49, 0x100
	s_addc_u32 s52, s52, 0
	s_cmp_gt_u32 s53, 61
	s_cbranch_scc0 .LBB0_763
	s_and_b64 vcc, exec, s[14:15]
	s_cbranch_vccz .LBB0_766
	s_barrier

; #define PG8_STAGE(bufoff, gbase, voff) do { _Pragma("unroll") for (int _i = 0; _i < 2; ++_i) \
;         __builtin_amdgcn_global_load_lds((const unsigned*)((const char*)(gbase) + (voff)[_i]), (PG8_LAS unsigned*)(lds + (bufoff) + ldsw + _i * 8192), 16, 0, 0); } while (0)
; #define PG8_LDA(dst, b, h) do { _Pragma("unroll") for (int m = 0; m < 4; ++m) _Pragma("unroll") for (int k = 0; k < 2; ++k) dst[m][k] = *(const PG8_LAS bf16x8*)(lds + PG8_SA(b, h) + aoff + m * 2048 + k * 1024); } while (0)
; #define PG8_LDB(dst, b, h) do { _Pragma("unroll") for (int n = 0; n < 2; ++n) _Pragma("unroll") for (int k = 0; k < 2; ++k) dst[n][k] = *(const PG8_LAS bf16x8*)(lds + PG8_SB(b, h) + boff + n * 2048 + k * 1024); } while (0)
; #define PG8_MMA(ai, bj, At, Bt) do { __builtin_amdgcn_s_setprio(1); _Pragma("unroll") for (int m = 0; m < 4; ++m) _Pragma("unroll") for (int n = 0; n < 2; ++n) _Pragma("unroll") for (int k = 0; k < 2; ++k) \
;         acc[ai][bj][m][n] = __builtin_amdgcn_mfma_f32_16x16x32_bf16(Bt[n][k], At[m][k], acc[ai][bj][m][n], 0, 0, 0); __builtin_amdgcn_s_setprio(0); } while (0)
; #define PG8_WAIT_V(n) asm volatile("s_waitcnt vmcnt(" #n ")" ::: "memory")
; template <class Epi, class Sched, bool ALIGN_EPI = false, bool SP2 = false>
; __device__ __forceinline__ void gemm_phase(PG8_LAS unsigned char* lds, const Gemm g, const Sched& S, const Epi& E) {
;     ...
;         const char* nA = has_next ? (const char*)g.A + (size_t)nxt.pm * tstep : cA; const char* nB = has_next ? (const char*)g.Bt + (size_t)nxt.pn * tstep : cB;
;         for (int t = 0; t < nt; t += 2) {
;             const bool last = (t == nt - 2);
;             const char* a1 = cA + (size_t)(t + 1) * kstep;
;             const char* a2 = last ? nA : cA + (size_t)(t + 2) * kstep; const char* b2 = last ? nB : cB + (size_t)(t + 2) * kstep;
;             const char* a3 = a2 + kstep; const char* b3 = b2 + kstep;
;             if (last && has_next) S.a_ready(nxt);
;             if constexpr (SP2) {
;             PG8_LDB(B0, 0, 0); PG8_LDB(B1, 0, 1); PG8_SCHED; PG8_LDA(At, 0, 0); PG8_STAGE(PG8_SA(1, 1), a1 + hstep, voffA);
;             PG8_WAIT_V(8); PG8_WAIT_L(0); PG8_BAR; PG8_MMA(0, 0, At, B0); PG8_MMA(0, 1, At, B1); PG8_BAR; PG8_SCHED;
;             PG8_LDA(At, 0, 1); PG8_STAGE(PG8_SB(0, 0), b2, voffB); PG8_STAGE(PG8_SB(0, 1), b2 + hstep, voffB); PG8_STAGE(PG8_SA(0, 0), a2, voffA);
.LBB0_954:
	s_ashr_i32 s53, s52, 31
	s_lshl_b64 s[22:23], s[52:53], 20
	s_add_u32 s54, s74, s22
	s_addc_u32 s55, s75, s23
	s_and_b64 s[24:25], s[62:63], exec
	s_cselect_b32 s1, s55, s27
	s_cselect_b32 s5, s54, s26
	s_ashr_i32 s41, s40, 31
	s_lshl_b64 s[24:25], s[40:41], 20
	s_add_u32 s56, s94, s24
	s_addc_u32 s57, s95, s25
	s_and_b64 s[30:31], s[62:63], exec
	s_cselect_b32 s17, s57, s29
	s_cselect_b32 s19, s56, s28
	s_add_u32 s26, s26, 0x80080
	s_addc_u32 s27, s27, 0
	s_add_u32 s33, s28, 0x100
	s_addc_u32 s44, s29, 0
	s_mov_b32 s45, -2
	s_waitcnt vmcnt(0)
	ds_read_b128 v[128:131], v209
	ds_read_b128 v[132:135], v209 offset:1024
	ds_read_b128 v[136:139], v209 offset:2048
	ds_read_b128 v[178:181], v209 offset:3072
	ds_read_b128 v[182:185], v210
	ds_read_b128 v[186:189], v210 offset:1024
	ds_read_b128 v[190:193], v210 offset:2048
	ds_read_b128 v[222:225], v210 offset:3072
	s_add_u32 s28, s26, 0xfff80080
	s_addc_u32 s29, s27, -1
	s_cmp_eq_u32 s45, 28
	s_cselect_b32 s31, s1, s29
	s_cselect_b32 s30, s5, s28
	s_cselect_b32 s29, s17, s44
	s_cselect_b32 s28, s19, s33
	s_add_i32 m0, s35, 0xc000
	ds_read_b128 v[226:229], v211
	ds_read_b128 v[230:233], v211 offset:1024
	ds_read_b128 v[234:237], v211 offset:2048
	ds_read_b128 v[238:241], v211 offset:3072
	ds_read_b128 v[242:245], v211 offset:4096
	ds_read_b128 v[246:249], v211 offset:5120
	ds_read_b128 v[250:253], v211 offset:6144
	ds_read_b128 v[160:163], v211 offset:7168
	global_load_lds_dwordx4 v150, s[26:27]
	s_add_i32 m0, s35, 0xe000
	s_nop 0
	global_load_lds_dwordx4 v152, s[26:27]
	s_waitcnt lgkmcnt(0)
	s_setprio 1
	s_barrier
	v_mfma_f32_16x16x32_bf16 v[124:127], v[128:131], v[226:229], 0
	v_mfma_f32_16x16x32_bf16 v[120:123], v[136:139], v[226:229], 0
	v_mfma_f32_16x16x32_bf16 v[116:119], v[128:131], v[234:237], 0
	v_mfma_f32_16x16x32_bf16 v[108:111], v[136:139], v[234:237], 0
	v_mfma_f32_16x16x32_bf16 v[100:103], v[128:131], v[242:245], 0
	v_mfma_f32_16x16x32_bf16 v[92:95], v[136:139], v[242:245], 0
	v_mfma_f32_16x16x32_bf16 v[84:87], v[128:131], v[250:253], 0
	v_mfma_f32_16x16x32_bf16 v[76:79], v[136:139], v[250:253], 0
	v_mfma_f32_16x16x32_bf16 v[124:127], v[132:135], v[230:233], v[124:127]
	v_mfma_f32_16x16x32_bf16 v[120:123], v[178:181], v[230:233], v[120:123]
	v_mfma_f32_16x16x32_bf16 v[116:119], v[132:135], v[238:241], v[116:119]
	v_mfma_f32_16x16x32_bf16 v[108:111], v[178:181], v[238:241], v[108:111]
	v_mfma_f32_16x16x32_bf16 v[100:103], v[132:135], v[246:249], v[100:103]
	v_mfma_f32_16x16x32_bf16 v[92:95], v[178:181], v[246:249], v[92:95]
	v_mfma_f32_16x16x32_bf16 v[84:87], v[132:135], v[160:163], v[84:87]
	v_mfma_f32_16x16x32_bf16 v[76:79], v[178:181], v[160:163], v[76:79]
	v_mfma_f32_16x16x32_bf16 v[112:115], v[182:185], v[226:229], 0
	v_mfma_f32_16x16x32_bf16 v[104:107], v[190:193], v[226:229], 0
	v_mfma_f32_16x16x32_bf16 v[96:99], v[182:185], v[234:237], 0
	v_mfma_f32_16x16x32_bf16 v[88:91], v[190:193], v[234:237], 0
	v_mfma_f32_16x16x32_bf16 v[80:83], v[182:185], v[242:245], 0
	v_mfma_f32_16x16x32_bf16 v[72:75], v[190:193], v[242:245], 0
	v_mfma_f32_16x16x32_bf16 v[68:71], v[182:185], v[250:253], 0
	v_mfma_f32_16x16x32_bf16 v[64:67], v[190:193], v[250:253], 0
	v_mfma_f32_16x16x32_bf16 v[112:115], v[186:189], v[230:233], v[112:115]
	v_mfma_f32_16x16x32_bf16 v[104:107], v[222:225], v[230:233], v[104:107]
	v_mfma_f32_16x16x32_bf16 v[96:99], v[186:189], v[238:241], v[96:99]
	v_mfma_f32_16x16x32_bf16 v[88:91], v[222:225], v[238:241], v[88:91]
	v_mfma_f32_16x16x32_bf16 v[80:83], v[186:189], v[246:249], v[80:83]
	v_mfma_f32_16x16x32_bf16 v[72:75], v[222:225], v[246:249], v[72:75]
	v_mfma_f32_16x16x32_bf16 v[68:71], v[186:189], v[160:163], v[68:71]
	v_mfma_f32_16x16x32_bf16 v[64:67], v[222:225], v[160:163], v[64:67]
	s_barrier
	s_setprio 0
	s_add_i32 s48, s69, s34
	v_lshl_add_u64 v[166:167], s[28:29], 0, v[142:143]
	s_mov_b32 m0, s48
	ds_read_b128 v[160:163], v211 offset:16384
	ds_read_b128 v[226:229], v211 offset:17408
	ds_read_b128 v[230:233], v211 offset:18432
	ds_read_b128 v[234:237], v211 offset:19456
	ds_read_b128 v[238:241], v211 offset:20480
	ds_read_b128 v[242:245], v211 offset:21504
	ds_read_b128 v[246:249], v211 offset:22528
	ds_read_b128 v[250:253], v211 offset:23552
	global_load_lds_dwordx4 v[166:167], off
	s_add_i32 m0, s48, 0x2000
	s_add_u32 s48, s28, 0x80000
	v_lshl_add_u64 v[170:171], s[28:29], 0, v[146:147]
	s_addc_u32 s49, s29, 0
	s_add_i32 s50, s70, s34
	global_load_lds_dwordx4 v[170:171], off
	s_mov_b32 m0, s50
	v_lshl_add_u64 v[194:195], s[30:31], 0, v[144:145]
	global_load_lds_dwordx4 v142, s[48:49]
	s_add_i32 m0, s50, 0x2000
	s_nop 0
	global_load_lds_dwordx4 v146, s[48:49]
	s_mov_b32 m0, s35
	v_lshl_add_u64 v[174:175], s[30:31], 0, v[140:141]
	global_load_lds_dwordx4 v[174:175], off
	s_mov_b32 m0, s37
	s_nop 0
	global_load_lds_dwordx4 v[194:195], off
	s_waitcnt lgkmcnt(0)
	s_setprio 1
	s_barrier
; #define PG8_STAGE(bufoff, gbase, voff) do { _Pragma("unroll") for (int _i = 0; _i < 2; ++_i) \
;         __builtin_amdgcn_global_load_lds((const unsigned*)((const char*)(gbase) + (voff)[_i]), (PG8_LAS unsigned*)(lds + (bufoff) + ldsw + _i * 8192), 16, 0, 0); } while (0)
; #define PG8_LDA(dst, b, h) do { _Pragma("unroll") for (int m = 0; m < 4; ++m) _Pragma("unroll") for (int k = 0; k < 2; ++k) dst[m][k] = *(const PG8_LAS bf16x8*)(lds + PG8_SA(b, h) + aoff + m * 2048 + k * 1024); } while (0)
; #define PG8_LDB(dst, b, h) do { _Pragma("unroll") for (int n = 0; n < 2; ++n) _Pragma("unroll") for (int k = 0; k < 2; ++k) dst[n][k] = *(const PG8_LAS bf16x8*)(lds + PG8_SB(b, h) + boff + n * 2048 + k * 1024); } while (0)
; #define PG8_MMA(ai, bj, At, Bt) do { __builtin_amdgcn_s_setprio(1); _Pragma("unroll") for (int m = 0; m < 4; ++m) _Pragma("unroll") for (int n = 0; n < 2; ++n) _Pragma("unroll") for (int k = 0; k < 2; ++k) \
;         acc[ai][bj][m][n] = __builtin_amdgcn_mfma_f32_16x16x32_bf16(Bt[n][k], At[m][k], acc[ai][bj][m][n], 0, 0, 0); __builtin_amdgcn_s_setprio(0); } while (0)
; #define PG8_WAIT_V(n) asm volatile("s_waitcnt vmcnt(" #n ")" ::: "memory")
; #define PG8_WAIT_L(n) asm volatile("s_waitcnt lgkmcnt(" #n ")" ::: "memory")
; #define PG8_BAR __builtin_amdgcn_s_barrier()
; #define PG8_SCHED __builtin_amdgcn_sched_barrier(0)
; template <class Epi, class Sched, bool ALIGN_EPI = false, bool SP2 = false>
; __device__ __forceinline__ void gemm_phase(PG8_LAS unsigned char* lds, const Gemm g, const Sched& S, const Epi& E) {
;     ...
;             PG8_WAIT_V(8); PG8_WAIT_L(0); PG8_BAR; PG8_MMA(1, 0, At, B0); PG8_MMA(1, 1, At, B1); PG8_BAR; PG8_SCHED;
;             PG8_LDB(B0, 1, 0); PG8_LDB(B1, 1, 1); PG8_SCHED; PG8_LDA(At, 1, 0); PG8_STAGE(PG8_SA(0, 1), a2 + hstep, voffA);
;             PG8_WAIT_V(8); PG8_WAIT_L(0); PG8_BAR; PG8_MMA(0, 0, At, B0); PG8_MMA(0, 1, At, B1); PG8_BAR; PG8_SCHED;
	v_mfma_f32_16x16x32_bf16 v[60:63], v[128:131], v[160:163], 0
	v_mfma_f32_16x16x32_bf16 v[56:59], v[136:139], v[160:163], 0
	v_mfma_f32_16x16x32_bf16 v[52:55], v[128:131], v[230:233], 0
	v_mfma_f32_16x16x32_bf16 v[44:47], v[136:139], v[230:233], 0
	v_mfma_f32_16x16x32_bf16 v[36:39], v[128:131], v[238:241], 0
	v_mfma_f32_16x16x32_bf16 v[28:31], v[136:139], v[238:241], 0
	v_mfma_f32_16x16x32_bf16 v[20:23], v[128:131], v[246:249], 0
	v_mfma_f32_16x16x32_bf16 v[12:15], v[136:139], v[246:249], 0
	v_mfma_f32_16x16x32_bf16 v[60:63], v[132:135], v[226:229], v[60:63]
	v_mfma_f32_16x16x32_bf16 v[56:59], v[178:181], v[226:229], v[56:59]
	v_mfma_f32_16x16x32_bf16 v[52:55], v[132:135], v[234:237], v[52:55]
	v_mfma_f32_16x16x32_bf16 v[44:47], v[178:181], v[234:237], v[44:47]
	v_mfma_f32_16x16x32_bf16 v[36:39], v[132:135], v[242:245], v[36:39]
	v_mfma_f32_16x16x32_bf16 v[28:31], v[178:181], v[242:245], v[28:31]
	v_mfma_f32_16x16x32_bf16 v[20:23], v[132:135], v[250:253], v[20:23]
	v_mfma_f32_16x16x32_bf16 v[12:15], v[178:181], v[250:253], v[12:15]
	v_mfma_f32_16x16x32_bf16 v[48:51], v[182:185], v[160:163], 0
	v_mfma_f32_16x16x32_bf16 v[40:43], v[190:193], v[160:163], 0
	v_mfma_f32_16x16x32_bf16 v[32:35], v[182:185], v[230:233], 0
	v_mfma_f32_16x16x32_bf16 v[24:27], v[190:193], v[230:233], 0
	v_mfma_f32_16x16x32_bf16 v[16:19], v[182:185], v[238:241], 0
	v_mfma_f32_16x16x32_bf16 v[8:11], v[190:193], v[238:241], 0
	v_mfma_f32_16x16x32_bf16 v[4:7], v[182:185], v[246:249], 0
	v_mfma_f32_16x16x32_bf16 v[0:3], v[190:193], v[246:249], 0
	v_mfma_f32_16x16x32_bf16 v[48:51], v[186:189], v[226:229], v[48:51]
	v_mfma_f32_16x16x32_bf16 v[40:43], v[222:225], v[226:229], v[40:43]
	v_mfma_f32_16x16x32_bf16 v[32:35], v[186:189], v[234:237], v[32:35]
	v_mfma_f32_16x16x32_bf16 v[24:27], v[222:225], v[234:237], v[24:27]
	v_mfma_f32_16x16x32_bf16 v[16:19], v[186:189], v[242:245], v[16:19]
	v_mfma_f32_16x16x32_bf16 v[8:11], v[222:225], v[242:245], v[8:11]
	v_mfma_f32_16x16x32_bf16 v[4:7], v[186:189], v[250:253], v[4:7]
	v_mfma_f32_16x16x32_bf16 v[0:3], v[222:225], v[250:253], v[0:3]
	s_barrier
	s_setprio 0
	s_add_i32 s48, 0, 0x18000
	v_add_u32_e32 v148, s48, v159
	s_add_i32 s49, 0, 0x1c000
	ds_read_b128 v[128:131], v148
	ds_read_b128 v[132:135], v148 offset:1024
	ds_read_b128 v[136:139], v148 offset:2048
	ds_read_b128 v[160:163], v148 offset:3072
	v_add_u32_e32 v148, s49, v159
	ds_read_b128 v[178:181], v148
	ds_read_b128 v[182:185], v148 offset:1024
	ds_read_b128 v[186:189], v148 offset:2048
	ds_read_b128 v[190:193], v148 offset:3072
	s_add_u32 s30, s30, 0x80000
	s_addc_u32 s31, s31, 0
	s_mov_b32 m0, s39
	ds_read_b128 v[222:225], v211 offset:32768
	ds_read_b128 v[226:229], v211 offset:33792
	ds_read_b128 v[230:233], v211 offset:34816
	ds_read_b128 v[234:237], v211 offset:35840
	ds_read_b128 v[238:241], v211 offset:36864
	ds_read_b128 v[242:245], v211 offset:37888
	ds_read_b128 v[246:249], v211 offset:38912
	ds_read_b128 v[250:253], v211 offset:39936
	global_load_lds_dwordx4 v140, s[30:31]
	s_mov_b32 m0, s42
	v_lshl_add_u64 v[154:155], s[30:31], 0, v[144:145]
	global_load_lds_dwordx4 v[154:155], off
	s_waitcnt vmcnt(8) lgkmcnt(0)
	s_setprio 1
	s_barrier
	v_mfma_f32_16x16x32_bf16 v[124:127], v[128:131], v[222:225], v[124:127]
	v_mfma_f32_16x16x32_bf16 v[120:123], v[136:139], v[222:225], v[120:123]
	v_mfma_f32_16x16x32_bf16 v[116:119], v[128:131], v[230:233], v[116:119]
	v_mfma_f32_16x16x32_bf16 v[108:111], v[136:139], v[230:233], v[108:111]
	v_mfma_f32_16x16x32_bf16 v[100:103], v[128:131], v[238:241], v[100:103]
	v_mfma_f32_16x16x32_bf16 v[92:95], v[136:139], v[238:241], v[92:95]
	v_mfma_f32_16x16x32_bf16 v[84:87], v[128:131], v[246:249], v[84:87]
	v_mfma_f32_16x16x32_bf16 v[76:79], v[136:139], v[246:249], v[76:79]
	v_mfma_f32_16x16x32_bf16 v[124:127], v[132:135], v[226:229], v[124:127]
	v_mfma_f32_16x16x32_bf16 v[120:123], v[160:163], v[226:229], v[120:123]
	v_mfma_f32_16x16x32_bf16 v[116:119], v[132:135], v[234:237], v[116:119]
	v_mfma_f32_16x16x32_bf16 v[108:111], v[160:163], v[234:237], v[108:111]
	v_mfma_f32_16x16x32_bf16 v[100:103], v[132:135], v[242:245], v[100:103]
	v_mfma_f32_16x16x32_bf16 v[92:95], v[160:163], v[242:245], v[92:95]
	v_mfma_f32_16x16x32_bf16 v[84:87], v[132:135], v[250:253], v[84:87]
	v_mfma_f32_16x16x32_bf16 v[76:79], v[160:163], v[250:253], v[76:79]
	v_mfma_f32_16x16x32_bf16 v[112:115], v[178:181], v[222:225], v[112:115]
	v_mfma_f32_16x16x32_bf16 v[104:107], v[186:189], v[222:225], v[104:107]
	v_mfma_f32_16x16x32_bf16 v[96:99], v[178:181], v[230:233], v[96:99]
	v_mfma_f32_16x16x32_bf16 v[88:91], v[186:189], v[230:233], v[88:91]
	v_mfma_f32_16x16x32_bf16 v[80:83], v[178:181], v[238:241], v[80:83]
	v_mfma_f32_16x16x32_bf16 v[72:75], v[186:189], v[238:241], v[72:75]
	v_mfma_f32_16x16x32_bf16 v[68:71], v[178:181], v[246:249], v[68:71]
	v_mfma_f32_16x16x32_bf16 v[64:67], v[186:189], v[246:249], v[64:67]
	v_mfma_f32_16x16x32_bf16 v[112:115], v[182:185], v[226:229], v[112:115]
	v_mfma_f32_16x16x32_bf16 v[104:107], v[190:193], v[226:229], v[104:107]
	v_mfma_f32_16x16x32_bf16 v[96:99], v[182:185], v[234:237], v[96:99]
	v_mfma_f32_16x16x32_bf16 v[88:91], v[190:193], v[234:237], v[88:91]
	v_mfma_f32_16x16x32_bf16 v[80:83], v[182:185], v[242:245], v[80:83]
	v_mfma_f32_16x16x32_bf16 v[72:75], v[190:193], v[242:245], v[72:75]
	v_mfma_f32_16x16x32_bf16 v[68:71], v[182:185], v[250:253], v[68:71]
	v_mfma_f32_16x16x32_bf16 v[64:67], v[190:193], v[250:253], v[64:67]
	s_barrier
; #define PG8_STAGE(bufoff, gbase, voff) do { _Pragma("unroll") for (int _i = 0; _i < 2; ++_i) \
;         __builtin_amdgcn_global_load_lds((const unsigned*)((const char*)(gbase) + (voff)[_i]), (PG8_LAS unsigned*)(lds + (bufoff) + ldsw + _i * 8192), 16, 0, 0); } while (0)
; #define PG8_LDA(dst, b, h) do { _Pragma("unroll") for (int m = 0; m < 4; ++m) _Pragma("unroll") for (int k = 0; k < 2; ++k) dst[m][k] = *(const PG8_LAS bf16x8*)(lds + PG8_SA(b, h) + aoff + m * 2048 + k * 1024); } while (0)
; #define PG8_LDB(dst, b, h) do { _Pragma("unroll") for (int n = 0; n < 2; ++n) _Pragma("unroll") for (int k = 0; k < 2; ++k) dst[n][k] = *(const PG8_LAS bf16x8*)(lds + PG8_SB(b, h) + boff + n * 2048 + k * 1024); } while (0)
; #define PG8_MMA(ai, bj, At, Bt) do { __builtin_amdgcn_s_setprio(1); _Pragma("unroll") for (int m = 0; m < 4; ++m) _Pragma("unroll") for (int n = 0; n < 2; ++n) _Pragma("unroll") for (int k = 0; k < 2; ++k) \
;         acc[ai][bj][m][n] = __builtin_amdgcn_mfma_f32_16x16x32_bf16(Bt[n][k], At[m][k], acc[ai][bj][m][n], 0, 0, 0); __builtin_amdgcn_s_setprio(0); } while (0)
; #define PG8_WAIT_V(n) asm volatile("s_waitcnt vmcnt(" #n ")" ::: "memory")
; template <class Epi, class Sched, bool ALIGN_EPI = false, bool SP2 = false>
; __device__ __forceinline__ void gemm_phase(PG8_LAS unsigned char* lds, const Gemm g, const Sched& S, const Epi& E) {
;     ...
;             PG8_LDB(B0, 0, 0); PG8_LDB(B1, 0, 1); PG8_SCHED; PG8_LDA(At, 0, 0); PG8_STAGE(PG8_SA(1, 1), a1 + hstep, voffA);
;             PG8_WAIT_V(8); PG8_WAIT_L(0); PG8_BAR; PG8_MMA(0, 0, At, B0); PG8_MMA(0, 1, At, B1); PG8_BAR; PG8_SCHED;
;             PG8_LDA(At, 0, 1); PG8_STAGE(PG8_SB(0, 0), b2, voffB); PG8_STAGE(PG8_SB(0, 1), b2 + hstep, voffB); PG8_STAGE(PG8_SA(0, 0), a2, voffA);
;             PG8_WAIT_V(8); PG8_WAIT_L(0); PG8_BAR; PG8_MMA(1, 0, At, B0); PG8_MMA(1, 1, At, B1); PG8_BAR; PG8_SCHED;
;             PG8_LDB(B0, 1, 0); PG8_LDB(B1, 1, 1); PG8_SCHED; PG8_LDA(At, 1, 0); PG8_STAGE(PG8_SA(0, 1), a2 + hstep, voffA);
;             PG8_WAIT_V(8); PG8_WAIT_L(0); PG8_BAR; PG8_MMA(0, 0, At, B0); PG8_MMA(0, 1, At, B1); PG8_BAR; PG8_SCHED;
;             PG8_LDA(At, 1, 1); PG8_STAGE(PG8_SB(1, 0), b3, voffB); PG8_STAGE(PG8_SB(1, 1), b3 + hstep, voffB); PG8_STAGE(PG8_SA(1, 0), a3, voffA);
;             PG8_WAIT_V(8); PG8_WAIT_L(0); PG8_BAR; PG8_MMA(1, 0, At, B0); PG8_MMA(1, 1, At, B1); PG8_BAR; PG8_SCHED;
	s_setprio 0
	s_add_i32 s30, s48, s34
	v_lshl_add_u64 v[154:155], v[166:167], 0, s[10:11]
	s_mov_b32 m0, s30
	ds_read_b128 v[222:225], v211 offset:49152
	ds_read_b128 v[226:229], v211 offset:50176
	ds_read_b128 v[230:233], v211 offset:51200
	ds_read_b128 v[234:237], v211 offset:52224
	ds_read_b128 v[238:241], v211 offset:53248
	ds_read_b128 v[242:245], v211 offset:54272
	ds_read_b128 v[246:249], v211 offset:55296
	ds_read_b128 v[250:253], v211 offset:56320
	global_load_lds_dwordx4 v[154:155], off
	s_add_i32 m0, s30, 0x2000
	s_add_u32 s28, s28, 0x80080
	v_lshl_add_u64 v[154:155], v[170:171], 0, s[10:11]
	s_addc_u32 s29, s29, 0
	s_add_i32 s30, s49, s34
	global_load_lds_dwordx4 v[154:155], off
	s_mov_b32 m0, s30
	s_nop 0
	global_load_lds_dwordx4 v142, s[28:29]
	s_add_i32 m0, s30, 0x2000
	v_lshl_add_u64 v[154:155], s[28:29], 0, v[146:147]
	global_load_lds_dwordx4 v[154:155], off
	s_mov_b32 m0, s46
	v_lshl_add_u64 v[154:155], v[174:175], 0, s[10:11]
	global_load_lds_dwordx4 v[154:155], off
	s_mov_b32 m0, s47
	v_lshl_add_u64 v[154:155], v[194:195], 0, s[10:11]
	global_load_lds_dwordx4 v[154:155], off
	s_waitcnt vmcnt(8) lgkmcnt(0)
	s_setprio 1
	s_barrier
	v_mfma_f32_16x16x32_bf16 v[60:63], v[128:131], v[222:225], v[60:63]
	v_mfma_f32_16x16x32_bf16 v[56:59], v[136:139], v[222:225], v[56:59]
	v_mfma_f32_16x16x32_bf16 v[52:55], v[128:131], v[230:233], v[52:55]
	v_mfma_f32_16x16x32_bf16 v[44:47], v[136:139], v[230:233], v[44:47]
	v_mfma_f32_16x16x32_bf16 v[36:39], v[128:131], v[238:241], v[36:39]
	v_mfma_f32_16x16x32_bf16 v[28:31], v[136:139], v[238:241], v[28:31]
	v_mfma_f32_16x16x32_bf16 v[20:23], v[128:131], v[246:249], v[20:23]
	v_mfma_f32_16x16x32_bf16 v[12:15], v[136:139], v[246:249], v[12:15]
	v_mfma_f32_16x16x32_bf16 v[60:63], v[132:135], v[226:229], v[60:63]
	v_mfma_f32_16x16x32_bf16 v[56:59], v[160:163], v[226:229], v[56:59]
	v_mfma_f32_16x16x32_bf16 v[52:55], v[132:135], v[234:237], v[52:55]
	v_mfma_f32_16x16x32_bf16 v[44:47], v[160:163], v[234:237], v[44:47]
	v_mfma_f32_16x16x32_bf16 v[36:39], v[132:135], v[242:245], v[36:39]
	v_mfma_f32_16x16x32_bf16 v[28:31], v[160:163], v[242:245], v[28:31]
	v_mfma_f32_16x16x32_bf16 v[20:23], v[132:135], v[250:253], v[20:23]
	v_mfma_f32_16x16x32_bf16 v[12:15], v[160:163], v[250:253], v[12:15]
	v_mfma_f32_16x16x32_bf16 v[48:51], v[178:181], v[222:225], v[48:51]
	v_mfma_f32_16x16x32_bf16 v[40:43], v[186:189], v[222:225], v[40:43]
	v_mfma_f32_16x16x32_bf16 v[32:35], v[178:181], v[230:233], v[32:35]
	v_mfma_f32_16x16x32_bf16 v[24:27], v[186:189], v[230:233], v[24:27]
	v_mfma_f32_16x16x32_bf16 v[16:19], v[178:181], v[238:241], v[16:19]
	v_mfma_f32_16x16x32_bf16 v[8:11], v[186:189], v[238:241], v[8:11]
	v_mfma_f32_16x16x32_bf16 v[4:7], v[178:181], v[246:249], v[4:7]
	v_mfma_f32_16x16x32_bf16 v[0:3], v[186:189], v[246:249], v[0:3]
	v_mfma_f32_16x16x32_bf16 v[48:51], v[182:185], v[226:229], v[48:51]
	v_mfma_f32_16x16x32_bf16 v[40:43], v[190:193], v[226:229], v[40:43]
	v_mfma_f32_16x16x32_bf16 v[32:35], v[182:185], v[234:237], v[32:35]
	v_mfma_f32_16x16x32_bf16 v[24:27], v[190:193], v[234:237], v[24:27]
	v_mfma_f32_16x16x32_bf16 v[16:19], v[182:185], v[242:245], v[16:19]
	v_mfma_f32_16x16x32_bf16 v[8:11], v[190:193], v[242:245], v[8:11]
	v_mfma_f32_16x16x32_bf16 v[4:7], v[182:185], v[250:253], v[4:7]
	v_mfma_f32_16x16x32_bf16 v[0:3], v[190:193], v[250:253], v[0:3]
	s_barrier
	s_setprio 0
	s_add_i32 s45, s45, 2
	s_add_u32 s26, s26, 0x100
	s_addc_u32 s27, s27, 0
	s_add_u32 s33, s33, 0x100
	s_addc_u32 s44, s44, 0
.LBB0_955:
	ds_read_b128 v[128:131], v209
	ds_read_b128 v[132:135], v209 offset:1024
	ds_read_b128 v[136:139], v209 offset:2048
	ds_read_b128 v[178:181], v209 offset:3072
	ds_read_b128 v[182:185], v210
	ds_read_b128 v[186:189], v210 offset:1024
	ds_read_b128 v[190:193], v210 offset:2048
	ds_read_b128 v[222:225], v210 offset:3072
	s_add_u32 s28, s26, 0xfff80080
	s_addc_u32 s29, s27, -1
	s_cmp_eq_u32 s45, 28
	s_cselect_b32 s31, s1, s29
	s_cselect_b32 s30, s5, s28
	s_cselect_b32 s29, s17, s44
	s_cselect_b32 s28, s19, s33
	s_add_i32 m0, s35, 0xc000
	ds_read_b128 v[226:229], v211
	ds_read_b128 v[230:233], v211 offset:1024
	ds_read_b128 v[234:237], v211 offset:2048
	ds_read_b128 v[238:241], v211 offset:3072
	ds_read_b128 v[242:245], v211 offset:4096
	ds_read_b128 v[246:249], v211 offset:5120
	ds_read_b128 v[250:253], v211 offset:6144
	ds_read_b128 v[160:163], v211 offset:7168
	global_load_lds_dwordx4 v150, s[26:27]
	s_add_i32 m0, s35, 0xe000
	s_nop 0
	global_load_lds_dwordx4 v152, s[26:27]
	s_waitcnt vmcnt(8) lgkmcnt(0)
	s_setprio 1
	s_barrier
; #define PG8_STAGE(bufoff, gbase, voff) do { _Pragma("unroll") for (int _i = 0; _i < 2; ++_i) \
;         __builtin_amdgcn_global_load_lds((const unsigned*)((const char*)(gbase) + (voff)[_i]), (PG8_LAS unsigned*)(lds + (bufoff) + ldsw + _i * 8192), 16, 0, 0); } while (0)
; #define PG8_LDA(dst, b, h) do { _Pragma("unroll") for (int m = 0; m < 4; ++m) _Pragma("unroll") for (int k = 0; k < 2; ++k) dst[m][k] = *(const PG8_LAS bf16x8*)(lds + PG8_SA(b, h) + aoff + m * 2048 + k * 1024); } while (0)
; #define PG8_MMA(ai, bj, At, Bt) do { __builtin_amdgcn_s_setprio(1); _Pragma("unroll") for (int m = 0; m < 4; ++m) _Pragma("unroll") for (int n = 0; n < 2; ++n) _Pragma("unroll") for (int k = 0; k < 2; ++k) \
;         acc[ai][bj][m][n] = __builtin_amdgcn_mfma_f32_16x16x32_bf16(Bt[n][k], At[m][k], acc[ai][bj][m][n], 0, 0, 0); __builtin_amdgcn_s_setprio(0); } while (0)
; #define PG8_WAIT_V(n) asm volatile("s_waitcnt vmcnt(" #n ")" ::: "memory")
; #define PG8_WAIT_L(n) asm volatile("s_waitcnt lgkmcnt(" #n ")" ::: "memory")
; #define PG8_BAR __builtin_amdgcn_s_barrier()
; #define PG8_SCHED __builtin_amdgcn_sched_barrier(0)
; template <class Epi, class Sched, bool ALIGN_EPI = false, bool SP2 = false>
; __device__ __forceinline__ void gemm_phase(PG8_LAS unsigned char* lds, const Gemm g, const Sched& S, const Epi& E) {
;     ...
;             PG8_WAIT_V(8); PG8_WAIT_L(0); PG8_BAR; PG8_MMA(0, 0, At, B0); PG8_MMA(0, 1, At, B1); PG8_BAR; PG8_SCHED;
;             PG8_LDA(At, 0, 1); PG8_STAGE(PG8_SB(0, 0), b2, voffB); PG8_STAGE(PG8_SB(0, 1), b2 + hstep, voffB); PG8_STAGE(PG8_SA(0, 0), a2, voffA);
;             PG8_WAIT_V(8); PG8_WAIT_L(0); PG8_BAR; PG8_MMA(1, 0, At, B0); PG8_MMA(1, 1, At, B1); PG8_BAR; PG8_SCHED;
	v_mfma_f32_16x16x32_bf16 v[124:127], v[128:131], v[226:229], v[124:127]
	v_mfma_f32_16x16x32_bf16 v[120:123], v[136:139], v[226:229], v[120:123]
	v_mfma_f32_16x16x32_bf16 v[116:119], v[128:131], v[234:237], v[116:119]
	v_mfma_f32_16x16x32_bf16 v[108:111], v[136:139], v[234:237], v[108:111]
	v_mfma_f32_16x16x32_bf16 v[100:103], v[128:131], v[242:245], v[100:103]
	v_mfma_f32_16x16x32_bf16 v[92:95], v[136:139], v[242:245], v[92:95]
	v_mfma_f32_16x16x32_bf16 v[84:87], v[128:131], v[250:253], v[84:87]
	v_mfma_f32_16x16x32_bf16 v[76:79], v[136:139], v[250:253], v[76:79]
	v_mfma_f32_16x16x32_bf16 v[124:127], v[132:135], v[230:233], v[124:127]
	v_mfma_f32_16x16x32_bf16 v[120:123], v[178:181], v[230:233], v[120:123]
	v_mfma_f32_16x16x32_bf16 v[116:119], v[132:135], v[238:241], v[116:119]
	v_mfma_f32_16x16x32_bf16 v[108:111], v[178:181], v[238:241], v[108:111]
	v_mfma_f32_16x16x32_bf16 v[100:103], v[132:135], v[246:249], v[100:103]
	v_mfma_f32_16x16x32_bf16 v[92:95], v[178:181], v[246:249], v[92:95]
	v_mfma_f32_16x16x32_bf16 v[84:87], v[132:135], v[160:163], v[84:87]
	v_mfma_f32_16x16x32_bf16 v[76:79], v[178:181], v[160:163], v[76:79]
	v_mfma_f32_16x16x32_bf16 v[112:115], v[182:185], v[226:229], v[112:115]
	v_mfma_f32_16x16x32_bf16 v[104:107], v[190:193], v[226:229], v[104:107]
	v_mfma_f32_16x16x32_bf16 v[96:99], v[182:185], v[234:237], v[96:99]
	v_mfma_f32_16x16x32_bf16 v[88:91], v[190:193], v[234:237], v[88:91]
	v_mfma_f32_16x16x32_bf16 v[80:83], v[182:185], v[242:245], v[80:83]
	v_mfma_f32_16x16x32_bf16 v[72:75], v[190:193], v[242:245], v[72:75]
	v_mfma_f32_16x16x32_bf16 v[68:71], v[182:185], v[250:253], v[68:71]
	v_mfma_f32_16x16x32_bf16 v[64:67], v[190:193], v[250:253], v[64:67]
	v_mfma_f32_16x16x32_bf16 v[112:115], v[186:189], v[230:233], v[112:115]
	v_mfma_f32_16x16x32_bf16 v[104:107], v[222:225], v[230:233], v[104:107]
	v_mfma_f32_16x16x32_bf16 v[96:99], v[186:189], v[238:241], v[96:99]
	v_mfma_f32_16x16x32_bf16 v[88:91], v[222:225], v[238:241], v[88:91]
	v_mfma_f32_16x16x32_bf16 v[80:83], v[186:189], v[246:249], v[80:83]
	v_mfma_f32_16x16x32_bf16 v[72:75], v[222:225], v[246:249], v[72:75]
	v_mfma_f32_16x16x32_bf16 v[68:71], v[186:189], v[160:163], v[68:71]
	v_mfma_f32_16x16x32_bf16 v[64:67], v[222:225], v[160:163], v[64:67]
	s_barrier
	s_setprio 0
	s_add_i32 s48, s69, s34
	v_lshl_add_u64 v[166:167], s[28:29], 0, v[142:143]
	s_mov_b32 m0, s48
	ds_read_b128 v[160:163], v211 offset:16384
	ds_read_b128 v[226:229], v211 offset:17408
	ds_read_b128 v[230:233], v211 offset:18432
	ds_read_b128 v[234:237], v211 offset:19456
	ds_read_b128 v[238:241], v211 offset:20480
	ds_read_b128 v[242:245], v211 offset:21504
	ds_read_b128 v[246:249], v211 offset:22528
	ds_read_b128 v[250:253], v211 offset:23552
	global_load_lds_dwordx4 v[166:167], off
	s_add_i32 m0, s48, 0x2000
	s_add_u32 s48, s28, 0x80000
	v_lshl_add_u64 v[170:171], s[28:29], 0, v[146:147]
	s_addc_u32 s49, s29, 0
	s_add_i32 s50, s70, s34
	global_load_lds_dwordx4 v[170:171], off
	s_mov_b32 m0, s50
	v_lshl_add_u64 v[194:195], s[30:31], 0, v[144:145]
	global_load_lds_dwordx4 v142, s[48:49]
	s_add_i32 m0, s50, 0x2000
	s_nop 0
	global_load_lds_dwordx4 v146, s[48:49]
	s_mov_b32 m0, s35
	v_lshl_add_u64 v[174:175], s[30:31], 0, v[140:141]
	global_load_lds_dwordx4 v[174:175], off
	s_mov_b32 m0, s37
	s_nop 0
	global_load_lds_dwordx4 v[194:195], off
	s_waitcnt vmcnt(8) lgkmcnt(0)
	s_setprio 1
	s_barrier
	v_mfma_f32_16x16x32_bf16 v[60:63], v[128:131], v[160:163], v[60:63]
	v_mfma_f32_16x16x32_bf16 v[56:59], v[136:139], v[160:163], v[56:59]
	v_mfma_f32_16x16x32_bf16 v[52:55], v[128:131], v[230:233], v[52:55]
	v_mfma_f32_16x16x32_bf16 v[44:47], v[136:139], v[230:233], v[44:47]
	v_mfma_f32_16x16x32_bf16 v[36:39], v[128:131], v[238:241], v[36:39]
	v_mfma_f32_16x16x32_bf16 v[28:31], v[136:139], v[238:241], v[28:31]
	v_mfma_f32_16x16x32_bf16 v[20:23], v[128:131], v[246:249], v[20:23]
	v_mfma_f32_16x16x32_bf16 v[12:15], v[136:139], v[246:249], v[12:15]
	v_mfma_f32_16x16x32_bf16 v[60:63], v[132:135], v[226:229], v[60:63]
	v_mfma_f32_16x16x32_bf16 v[56:59], v[178:181], v[226:229], v[56:59]
	v_mfma_f32_16x16x32_bf16 v[52:55], v[132:135], v[234:237], v[52:55]
	v_mfma_f32_16x16x32_bf16 v[44:47], v[178:181], v[234:237], v[44:47]
	v_mfma_f32_16x16x32_bf16 v[36:39], v[132:135], v[242:245], v[36:39]
	v_mfma_f32_16x16x32_bf16 v[28:31], v[178:181], v[242:245], v[28:31]
	v_mfma_f32_16x16x32_bf16 v[20:23], v[132:135], v[250:253], v[20:23]
	v_mfma_f32_16x16x32_bf16 v[12:15], v[178:181], v[250:253], v[12:15]
	v_mfma_f32_16x16x32_bf16 v[48:51], v[182:185], v[160:163], v[48:51]
	v_mfma_f32_16x16x32_bf16 v[40:43], v[190:193], v[160:163], v[40:43]
	v_mfma_f32_16x16x32_bf16 v[32:35], v[182:185], v[230:233], v[32:35]
	v_mfma_f32_16x16x32_bf16 v[24:27], v[190:193], v[230:233], v[24:27]
	v_mfma_f32_16x16x32_bf16 v[16:19], v[182:185], v[238:241], v[16:19]
	v_mfma_f32_16x16x32_bf16 v[8:11], v[190:193], v[238:241], v[8:11]
	v_mfma_f32_16x16x32_bf16 v[4:7], v[182:185], v[246:249], v[4:7]
	v_mfma_f32_16x16x32_bf16 v[0:3], v[190:193], v[246:249], v[0:3]
	v_mfma_f32_16x16x32_bf16 v[48:51], v[186:189], v[226:229], v[48:51]
	v_mfma_f32_16x16x32_bf16 v[40:43], v[222:225], v[226:229], v[40:43]
	v_mfma_f32_16x16x32_bf16 v[32:35], v[186:189], v[234:237], v[32:35]
	v_mfma_f32_16x16x32_bf16 v[24:27], v[222:225], v[234:237], v[24:27]
	v_mfma_f32_16x16x32_bf16 v[16:19], v[186:189], v[242:245], v[16:19]
	v_mfma_f32_16x16x32_bf16 v[8:11], v[222:225], v[242:245], v[8:11]
	v_mfma_f32_16x16x32_bf16 v[4:7], v[186:189], v[250:253], v[4:7]
	v_mfma_f32_16x16x32_bf16 v[0:3], v[222:225], v[250:253], v[0:3]
	s_barrier
; #define PG8_STAGE(bufoff, gbase, voff) do { _Pragma("unroll") for (int _i = 0; _i < 2; ++_i) \
;         __builtin_amdgcn_global_load_lds((const unsigned*)((const char*)(gbase) + (voff)[_i]), (PG8_LAS unsigned*)(lds + (bufoff) + ldsw + _i * 8192), 16, 0, 0); } while (0)
; #define PG8_LDA(dst, b, h) do { _Pragma("unroll") for (int m = 0; m < 4; ++m) _Pragma("unroll") for (int k = 0; k < 2; ++k) dst[m][k] = *(const PG8_LAS bf16x8*)(lds + PG8_SA(b, h) + aoff + m * 2048 + k * 1024); } while (0)
; #define PG8_LDB(dst, b, h) do { _Pragma("unroll") for (int n = 0; n < 2; ++n) _Pragma("unroll") for (int k = 0; k < 2; ++k) dst[n][k] = *(const PG8_LAS bf16x8*)(lds + PG8_SB(b, h) + boff + n * 2048 + k * 1024); } while (0)
; #define PG8_MMA(ai, bj, At, Bt) do { __builtin_amdgcn_s_setprio(1); _Pragma("unroll") for (int m = 0; m < 4; ++m) _Pragma("unroll") for (int n = 0; n < 2; ++n) _Pragma("unroll") for (int k = 0; k < 2; ++k) \
;         acc[ai][bj][m][n] = __builtin_amdgcn_mfma_f32_16x16x32_bf16(Bt[n][k], At[m][k], acc[ai][bj][m][n], 0, 0, 0); __builtin_amdgcn_s_setprio(0); } while (0)
; #define PG8_WAIT_V(n) asm volatile("s_waitcnt vmcnt(" #n ")" ::: "memory")
; #define PG8_WAIT_L(n) asm volatile("s_waitcnt lgkmcnt(" #n ")" ::: "memory")
; #define PG8_BAR __builtin_amdgcn_s_barrier()
; #define PG8_SCHED __builtin_amdgcn_sched_barrier(0)
; template <class Epi, class Sched, bool ALIGN_EPI = false, bool SP2 = false>
; __device__ __forceinline__ void gemm_phase(PG8_LAS unsigned char* lds, const Gemm g, const Sched& S, const Epi& E) {
;     ...
;             PG8_LDB(B0, 1, 0); PG8_LDB(B1, 1, 1); PG8_SCHED; PG8_LDA(At, 1, 0); PG8_STAGE(PG8_SA(0, 1), a2 + hstep, voffA);
;             PG8_WAIT_V(8); PG8_WAIT_L(0); PG8_BAR; PG8_MMA(0, 0, At, B0); PG8_MMA(0, 1, At, B1); PG8_BAR; PG8_SCHED;
;             PG8_LDA(At, 1, 1); PG8_STAGE(PG8_SB(1, 0), b3, voffB); PG8_STAGE(PG8_SB(1, 1), b3 + hstep, voffB); PG8_STAGE(PG8_SA(1, 0), a3, voffA);
;             PG8_WAIT_V(8); PG8_WAIT_L(0); PG8_BAR; PG8_MMA(1, 0, At, B0); PG8_MMA(1, 1, At, B1); PG8_BAR; PG8_SCHED;
;     ...
;         if constexpr (ALIGN_EPI) { if (wr == 0) PG8_BAR; }
	s_setprio 0
	s_add_i32 s48, 0, 0x18000
	v_add_u32_e32 v148, s48, v159
	s_add_i32 s49, 0, 0x1c000
	ds_read_b128 v[128:131], v148
	ds_read_b128 v[132:135], v148 offset:1024
	ds_read_b128 v[136:139], v148 offset:2048
	ds_read_b128 v[160:163], v148 offset:3072
	v_add_u32_e32 v148, s49, v159
	ds_read_b128 v[178:181], v148
	ds_read_b128 v[182:185], v148 offset:1024
	ds_read_b128 v[186:189], v148 offset:2048
	ds_read_b128 v[190:193], v148 offset:3072
	s_add_u32 s30, s30, 0x80000
	s_addc_u32 s31, s31, 0
	s_mov_b32 m0, s39
	ds_read_b128 v[222:225], v211 offset:32768
	ds_read_b128 v[226:229], v211 offset:33792
	ds_read_b128 v[230:233], v211 offset:34816
	ds_read_b128 v[234:237], v211 offset:35840
	ds_read_b128 v[238:241], v211 offset:36864
	ds_read_b128 v[242:245], v211 offset:37888
	ds_read_b128 v[246:249], v211 offset:38912
	ds_read_b128 v[250:253], v211 offset:39936
	global_load_lds_dwordx4 v140, s[30:31]
	s_mov_b32 m0, s42
	v_lshl_add_u64 v[154:155], s[30:31], 0, v[144:145]
	global_load_lds_dwordx4 v[154:155], off
	s_waitcnt vmcnt(8) lgkmcnt(0)
	s_setprio 1
	s_barrier
	v_mfma_f32_16x16x32_bf16 v[124:127], v[128:131], v[222:225], v[124:127]
	v_mfma_f32_16x16x32_bf16 v[120:123], v[136:139], v[222:225], v[120:123]
	v_mfma_f32_16x16x32_bf16 v[116:119], v[128:131], v[230:233], v[116:119]
	v_mfma_f32_16x16x32_bf16 v[108:111], v[136:139], v[230:233], v[108:111]
	v_mfma_f32_16x16x32_bf16 v[100:103], v[128:131], v[238:241], v[100:103]
	v_mfma_f32_16x16x32_bf16 v[92:95], v[136:139], v[238:241], v[92:95]
	v_mfma_f32_16x16x32_bf16 v[84:87], v[128:131], v[246:249], v[84:87]
	v_mfma_f32_16x16x32_bf16 v[76:79], v[136:139], v[246:249], v[76:79]
	v_mfma_f32_16x16x32_bf16 v[124:127], v[132:135], v[226:229], v[124:127]
	v_mfma_f32_16x16x32_bf16 v[120:123], v[160:163], v[226:229], v[120:123]
	v_mfma_f32_16x16x32_bf16 v[116:119], v[132:135], v[234:237], v[116:119]
	v_mfma_f32_16x16x32_bf16 v[108:111], v[160:163], v[234:237], v[108:111]
	v_mfma_f32_16x16x32_bf16 v[100:103], v[132:135], v[242:245], v[100:103]
	v_mfma_f32_16x16x32_bf16 v[92:95], v[160:163], v[242:245], v[92:95]
	v_mfma_f32_16x16x32_bf16 v[84:87], v[132:135], v[250:253], v[84:87]
	v_mfma_f32_16x16x32_bf16 v[76:79], v[160:163], v[250:253], v[76:79]
	v_mfma_f32_16x16x32_bf16 v[112:115], v[178:181], v[222:225], v[112:115]
	v_mfma_f32_16x16x32_bf16 v[104:107], v[186:189], v[222:225], v[104:107]
	v_mfma_f32_16x16x32_bf16 v[96:99], v[178:181], v[230:233], v[96:99]
	v_mfma_f32_16x16x32_bf16 v[88:91], v[186:189], v[230:233], v[88:91]
	v_mfma_f32_16x16x32_bf16 v[80:83], v[178:181], v[238:241], v[80:83]
	v_mfma_f32_16x16x32_bf16 v[72:75], v[186:189], v[238:241], v[72:75]
	v_mfma_f32_16x16x32_bf16 v[68:71], v[178:181], v[246:249], v[68:71]
	v_mfma_f32_16x16x32_bf16 v[64:67], v[186:189], v[246:249], v[64:67]
	v_mfma_f32_16x16x32_bf16 v[112:115], v[182:185], v[226:229], v[112:115]
	v_mfma_f32_16x16x32_bf16 v[104:107], v[190:193], v[226:229], v[104:107]
	v_mfma_f32_16x16x32_bf16 v[96:99], v[182:185], v[234:237], v[96:99]
	v_mfma_f32_16x16x32_bf16 v[88:91], v[190:193], v[234:237], v[88:91]
	v_mfma_f32_16x16x32_bf16 v[80:83], v[182:185], v[242:245], v[80:83]
	v_mfma_f32_16x16x32_bf16 v[72:75], v[190:193], v[242:245], v[72:75]
	v_mfma_f32_16x16x32_bf16 v[68:71], v[182:185], v[250:253], v[68:71]
	v_mfma_f32_16x16x32_bf16 v[64:67], v[190:193], v[250:253], v[64:67]
	s_barrier
	s_setprio 0
	s_add_i32 s30, s48, s34
	v_lshl_add_u64 v[154:155], v[166:167], 0, s[10:11]
	s_mov_b32 m0, s30
	ds_read_b128 v[222:225], v211 offset:49152
	ds_read_b128 v[226:229], v211 offset:50176
	ds_read_b128 v[230:233], v211 offset:51200
	ds_read_b128 v[234:237], v211 offset:52224
	ds_read_b128 v[238:241], v211 offset:53248
	ds_read_b128 v[242:245], v211 offset:54272
	ds_read_b128 v[246:249], v211 offset:55296
	ds_read_b128 v[250:253], v211 offset:56320
	global_load_lds_dwordx4 v[154:155], off
	s_add_i32 m0, s30, 0x2000
	s_add_u32 s28, s28, 0x80080
	v_lshl_add_u64 v[154:155], v[170:171], 0, s[10:11]
	s_addc_u32 s29, s29, 0
	s_add_i32 s30, s49, s34
	global_load_lds_dwordx4 v[154:155], off
	s_mov_b32 m0, s30
	s_nop 0
	global_load_lds_dwordx4 v142, s[28:29]
	s_add_i32 m0, s30, 0x2000
	v_lshl_add_u64 v[154:155], s[28:29], 0, v[146:147]
	global_load_lds_dwordx4 v[154:155], off
	s_mov_b32 m0, s46
	v_lshl_add_u64 v[154:155], v[174:175], 0, s[10:11]
	global_load_lds_dwordx4 v[154:155], off
	s_mov_b32 m0, s47
	v_lshl_add_u64 v[154:155], v[194:195], 0, s[10:11]
	global_load_lds_dwordx4 v[154:155], off
	s_waitcnt vmcnt(8) lgkmcnt(0)
	s_setprio 1
	s_barrier
	v_mfma_f32_16x16x32_bf16 v[60:63], v[128:131], v[222:225], v[60:63]
	v_mfma_f32_16x16x32_bf16 v[56:59], v[136:139], v[222:225], v[56:59]
	v_mfma_f32_16x16x32_bf16 v[52:55], v[128:131], v[230:233], v[52:55]
	v_mfma_f32_16x16x32_bf16 v[44:47], v[136:139], v[230:233], v[44:47]
	v_mfma_f32_16x16x32_bf16 v[36:39], v[128:131], v[238:241], v[36:39]
	v_mfma_f32_16x16x32_bf16 v[28:31], v[136:139], v[238:241], v[28:31]
	v_mfma_f32_16x16x32_bf16 v[20:23], v[128:131], v[246:249], v[20:23]
	v_mfma_f32_16x16x32_bf16 v[12:15], v[136:139], v[246:249], v[12:15]
	v_mfma_f32_16x16x32_bf16 v[60:63], v[132:135], v[226:229], v[60:63]
	v_mfma_f32_16x16x32_bf16 v[56:59], v[160:163], v[226:229], v[56:59]
	v_mfma_f32_16x16x32_bf16 v[52:55], v[132:135], v[234:237], v[52:55]
	v_mfma_f32_16x16x32_bf16 v[44:47], v[160:163], v[234:237], v[44:47]
	v_mfma_f32_16x16x32_bf16 v[36:39], v[132:135], v[242:245], v[36:39]
	v_mfma_f32_16x16x32_bf16 v[28:31], v[160:163], v[242:245], v[28:31]
	v_mfma_f32_16x16x32_bf16 v[20:23], v[132:135], v[250:253], v[20:23]
	v_mfma_f32_16x16x32_bf16 v[12:15], v[160:163], v[250:253], v[12:15]
	v_mfma_f32_16x16x32_bf16 v[48:51], v[178:181], v[222:225], v[48:51]
	v_mfma_f32_16x16x32_bf16 v[40:43], v[186:189], v[222:225], v[40:43]
	v_mfma_f32_16x16x32_bf16 v[32:35], v[178:181], v[230:233], v[32:35]
	v_mfma_f32_16x16x32_bf16 v[24:27], v[186:189], v[230:233], v[24:27]
	v_mfma_f32_16x16x32_bf16 v[16:19], v[178:181], v[238:241], v[16:19]
	v_mfma_f32_16x16x32_bf16 v[8:11], v[186:189], v[238:241], v[8:11]
	v_mfma_f32_16x16x32_bf16 v[4:7], v[178:181], v[246:249], v[4:7]
	v_mfma_f32_16x16x32_bf16 v[0:3], v[186:189], v[246:249], v[0:3]
	v_mfma_f32_16x16x32_bf16 v[48:51], v[182:185], v[226:229], v[48:51]
	v_mfma_f32_16x16x32_bf16 v[40:43], v[190:193], v[226:229], v[40:43]
	v_mfma_f32_16x16x32_bf16 v[32:35], v[182:185], v[234:237], v[32:35]
	v_mfma_f32_16x16x32_bf16 v[24:27], v[190:193], v[234:237], v[24:27]
	v_mfma_f32_16x16x32_bf16 v[16:19], v[182:185], v[242:245], v[16:19]
	v_mfma_f32_16x16x32_bf16 v[8:11], v[190:193], v[242:245], v[8:11]
	v_mfma_f32_16x16x32_bf16 v[4:7], v[182:185], v[250:253], v[4:7]
	v_mfma_f32_16x16x32_bf16 v[0:3], v[190:193], v[250:253], v[0:3]
	s_barrier
	s_setprio 0
	s_add_i32 s45, s45, 2
	s_add_u32 s26, s26, 0x100
	s_addc_u32 s27, s27, 0
	s_add_u32 s33, s33, 0x100
	s_addc_u32 s44, s44, 0
	s_cmp_gt_u32 s45, 29
	s_cbranch_scc0 .LBB0_955
	s_and_b64 vcc, exec, s[12:13]
	s_cbranch_vccz .LBB0_958
	s_barrier

; #define PG8_STAGE(bufoff, gbase, voff) do { _Pragma("unroll") for (int _i = 0; _i < 2; ++_i) \
;         __builtin_amdgcn_global_load_lds((const unsigned*)((const char*)(gbase) + (voff)[_i]), (PG8_LAS unsigned*)(lds + (bufoff) + ldsw + _i * 8192), 16, 0, 0); } while (0)
; #define PG8_LDA(dst, b, h) do { _Pragma("unroll") for (int m = 0; m < 4; ++m) _Pragma("unroll") for (int k = 0; k < 2; ++k) dst[m][k] = *(const PG8_LAS bf16x8*)(lds + PG8_SA(b, h) + aoff + m * 2048 + k * 1024); } while (0)
; #define PG8_LDB(dst, b, h) do { _Pragma("unroll") for (int n = 0; n < 2; ++n) _Pragma("unroll") for (int k = 0; k < 2; ++k) dst[n][k] = *(const PG8_LAS bf16x8*)(lds + PG8_SB(b, h) + boff + n * 2048 + k * 1024); } while (0)
; #define PG8_MMA(ai, bj, At, Bt) do { __builtin_amdgcn_s_setprio(1); _Pragma("unroll") for (int m = 0; m < 4; ++m) _Pragma("unroll") for (int n = 0; n < 2; ++n) _Pragma("unroll") for (int k = 0; k < 2; ++k) \
;         acc[ai][bj][m][n] = __builtin_amdgcn_mfma_f32_16x16x32_bf16(Bt[n][k], At[m][k], acc[ai][bj][m][n], 0, 0, 0); __builtin_amdgcn_s_setprio(0); } while (0)
; #define PG8_WAIT_V(n) asm volatile("s_waitcnt vmcnt(" #n ")" ::: "memory")
; template <class Epi, class Sched, bool ALIGN_EPI = false, bool SP2 = false>
; __device__ __forceinline__ void gemm_phase(PG8_LAS unsigned char* lds, const Gemm g, const Sched& S, const Epi& E) {
;     ...
;         const char* nA = has_next ? (const char*)g.A + (size_t)nxt.pm * tstep : cA; const char* nB = has_next ? (const char*)g.Bt + (size_t)nxt.pn * tstep : cB;
;         for (int t = 0; t < nt; t += 2) {
;             const bool last = (t == nt - 2);
;             const char* a1 = cA + (size_t)(t + 1) * kstep;
;             const char* a2 = last ? nA : cA + (size_t)(t + 2) * kstep; const char* b2 = last ? nB : cB + (size_t)(t + 2) * kstep;
;             const char* a3 = a2 + kstep; const char* b3 = b2 + kstep;
;             if (last && has_next) S.a_ready(nxt);
;             if constexpr (SP2) {
;             PG8_LDB(B0, 0, 0); PG8_LDB(B1, 0, 1); PG8_SCHED; PG8_LDA(At, 0, 0); PG8_STAGE(PG8_SA(1, 1), a1 + hstep, voffA);
;             PG8_WAIT_V(8); PG8_WAIT_L(0); PG8_BAR; PG8_MMA(0, 0, At, B0); PG8_MMA(0, 1, At, B1); PG8_BAR; PG8_SCHED;
;             PG8_LDA(At, 0, 1); PG8_STAGE(PG8_SB(0, 0), b2, voffB); PG8_STAGE(PG8_SB(0, 1), b2 + hstep, voffB); PG8_STAGE(PG8_SA(0, 0), a2, voffA);
.LBB0_1179:
	s_ashr_i32 s21, s20, 31
	s_lshl_b64 s[22:23], s[20:21], 20
	s_add_u32 s22, s56, s22
	s_addc_u32 s23, s57, s23
	s_and_b64 s[24:25], s[4:5], exec
	s_cselect_b32 s7, s23, s27
	s_cselect_b32 s21, s22, s26
	s_ashr_i32 s19, s18, 31
	s_lshl_b64 s[24:25], s[18:19], 20
	s_add_u32 s24, s68, s24
	s_addc_u32 s25, s69, s25
	s_and_b64 s[30:31], s[4:5], exec
	s_cselect_b32 s19, s25, s29
	s_cselect_b32 s46, s24, s28
	s_add_u32 s26, s26, 0x80080
	s_addc_u32 s27, s27, 0
	s_add_u32 s47, s28, 0x100
	s_addc_u32 s48, s29, 0
	s_mov_b32 s49, -2
	s_waitcnt lgkmcnt(0)
	ds_read_b128 v[128:131], v181
	ds_read_b128 v[132:135], v181 offset:1024
	ds_read_b128 v[136:139], v181 offset:2048
	ds_read_b128 v[140:143], v181 offset:3072
	ds_read_b128 v[144:147], v182
	ds_read_b128 v[148:151], v182 offset:1024
	ds_read_b128 v[168:171], v182 offset:2048
	ds_read_b128 v[172:175], v182 offset:3072
	s_add_u32 s28, s26, 0xfff80080
	s_addc_u32 s29, s27, -1
	s_cmp_eq_u32 s49, 28
	s_cselect_b32 s31, s7, s29
	s_cselect_b32 s30, s21, s28
	s_cselect_b32 s29, s19, s48
	s_cselect_b32 s28, s46, s47
	s_add_i32 m0, s35, 0xc000
	ds_read_b128 v[186:189], v183
	ds_read_b128 v[190:193], v183 offset:1024
	ds_read_b128 v[198:201], v183 offset:2048
	ds_read_b128 v[202:205], v183 offset:3072
	ds_read_b128 v[206:209], v183 offset:4096
	ds_read_b128 v[210:213], v183 offset:5120
	ds_read_b128 v[214:217], v183 offset:6144
	ds_read_b128 v[218:221], v183 offset:7168
	global_load_lds_dwordx4 v160, s[26:27]
	s_add_i32 m0, s35, 0xe000
	s_nop 0
	global_load_lds_dwordx4 v162, s[26:27]
	s_waitcnt lgkmcnt(0)
	s_setprio 1
	s_barrier
	v_mfma_f32_16x16x32_bf16 v[124:127], v[128:131], v[186:189], 0
	v_mfma_f32_16x16x32_bf16 v[120:123], v[136:139], v[186:189], 0
	v_mfma_f32_16x16x32_bf16 v[104:107], v[128:131], v[198:201], 0
	v_mfma_f32_16x16x32_bf16 v[108:111], v[136:139], v[198:201], 0
	v_mfma_f32_16x16x32_bf16 v[88:91], v[128:131], v[206:209], 0
	v_mfma_f32_16x16x32_bf16 v[92:95], v[136:139], v[206:209], 0
	v_mfma_f32_16x16x32_bf16 v[72:75], v[128:131], v[214:217], 0
	v_mfma_f32_16x16x32_bf16 v[76:79], v[136:139], v[214:217], 0
	v_mfma_f32_16x16x32_bf16 v[124:127], v[132:135], v[190:193], v[124:127]
	v_mfma_f32_16x16x32_bf16 v[120:123], v[140:143], v[190:193], v[120:123]
	v_mfma_f32_16x16x32_bf16 v[104:107], v[132:135], v[202:205], v[104:107]
	v_mfma_f32_16x16x32_bf16 v[108:111], v[140:143], v[202:205], v[108:111]
	v_mfma_f32_16x16x32_bf16 v[88:91], v[132:135], v[210:213], v[88:91]
	v_mfma_f32_16x16x32_bf16 v[92:95], v[140:143], v[210:213], v[92:95]
	v_mfma_f32_16x16x32_bf16 v[72:75], v[132:135], v[218:221], v[72:75]
	v_mfma_f32_16x16x32_bf16 v[76:79], v[140:143], v[218:221], v[76:79]
	v_mfma_f32_16x16x32_bf16 v[116:119], v[144:147], v[186:189], 0
	v_mfma_f32_16x16x32_bf16 v[112:115], v[168:171], v[186:189], 0
	v_mfma_f32_16x16x32_bf16 v[100:103], v[144:147], v[198:201], 0
	v_mfma_f32_16x16x32_bf16 v[96:99], v[168:171], v[198:201], 0
	v_mfma_f32_16x16x32_bf16 v[84:87], v[144:147], v[206:209], 0
	v_mfma_f32_16x16x32_bf16 v[80:83], v[168:171], v[206:209], 0
	v_mfma_f32_16x16x32_bf16 v[68:71], v[144:147], v[214:217], 0
	v_mfma_f32_16x16x32_bf16 v[64:67], v[168:171], v[214:217], 0
	v_mfma_f32_16x16x32_bf16 v[116:119], v[148:151], v[190:193], v[116:119]
	v_mfma_f32_16x16x32_bf16 v[112:115], v[172:175], v[190:193], v[112:115]
	v_mfma_f32_16x16x32_bf16 v[100:103], v[148:151], v[202:205], v[100:103]
	v_mfma_f32_16x16x32_bf16 v[96:99], v[172:175], v[202:205], v[96:99]
	v_mfma_f32_16x16x32_bf16 v[84:87], v[148:151], v[210:213], v[84:87]
	v_mfma_f32_16x16x32_bf16 v[80:83], v[172:175], v[210:213], v[80:83]
	v_mfma_f32_16x16x32_bf16 v[68:71], v[148:151], v[218:221], v[68:71]
	v_mfma_f32_16x16x32_bf16 v[64:67], v[172:175], v[218:221], v[64:67]
	s_barrier
	s_setprio 0
	s_add_i32 s50, s43, s34
	v_lshl_add_u64 v[176:177], s[28:29], 0, v[154:155]
	s_mov_b32 m0, s50
	ds_read_b128 v[186:189], v183 offset:16384
	ds_read_b128 v[190:193], v183 offset:17408
	ds_read_b128 v[198:201], v183 offset:18432
	ds_read_b128 v[202:205], v183 offset:19456
	ds_read_b128 v[206:209], v183 offset:20480
	ds_read_b128 v[210:213], v183 offset:21504
	ds_read_b128 v[214:217], v183 offset:22528
	ds_read_b128 v[218:221], v183 offset:23552
	global_load_lds_dwordx4 v[176:177], off
	s_add_i32 m0, s50, 0x2000
	s_add_u32 s50, s28, 0x80000
	v_lshl_add_u64 v[194:195], s[28:29], 0, v[158:159]
	s_addc_u32 s51, s29, 0
	s_add_i32 s52, s44, s34
	global_load_lds_dwordx4 v[194:195], off
	s_mov_b32 m0, s52
	v_lshl_add_u64 v[224:225], s[30:31], 0, v[156:157]
	global_load_lds_dwordx4 v154, s[50:51]
	s_add_i32 m0, s52, 0x2000
	s_nop 0
	global_load_lds_dwordx4 v158, s[50:51]
	s_mov_b32 m0, s35
	v_lshl_add_u64 v[222:223], s[30:31], 0, v[152:153]
	global_load_lds_dwordx4 v[222:223], off
	s_mov_b32 m0, s33
	s_nop 0
	global_load_lds_dwordx4 v[224:225], off
	s_waitcnt lgkmcnt(0)
	s_setprio 1
	s_barrier
; #define PG8_STAGE(bufoff, gbase, voff) do { _Pragma("unroll") for (int _i = 0; _i < 2; ++_i) \
;         __builtin_amdgcn_global_load_lds((const unsigned*)((const char*)(gbase) + (voff)[_i]), (PG8_LAS unsigned*)(lds + (bufoff) + ldsw + _i * 8192), 16, 0, 0); } while (0)
; #define PG8_LDA(dst, b, h) do { _Pragma("unroll") for (int m = 0; m < 4; ++m) _Pragma("unroll") for (int k = 0; k < 2; ++k) dst[m][k] = *(const PG8_LAS bf16x8*)(lds + PG8_SA(b, h) + aoff + m * 2048 + k * 1024); } while (0)
; #define PG8_LDB(dst, b, h) do { _Pragma("unroll") for (int n = 0; n < 2; ++n) _Pragma("unroll") for (int k = 0; k < 2; ++k) dst[n][k] = *(const PG8_LAS bf16x8*)(lds + PG8_SB(b, h) + boff + n * 2048 + k * 1024); } while (0)
; #define PG8_MMA(ai, bj, At, Bt) do { __builtin_amdgcn_s_setprio(1); _Pragma("unroll") for (int m = 0; m < 4; ++m) _Pragma("unroll") for (int n = 0; n < 2; ++n) _Pragma("unroll") for (int k = 0; k < 2; ++k) \
;         acc[ai][bj][m][n] = __builtin_amdgcn_mfma_f32_16x16x32_bf16(Bt[n][k], At[m][k], acc[ai][bj][m][n], 0, 0, 0); __builtin_amdgcn_s_setprio(0); } while (0)
; #define PG8_WAIT_V(n) asm volatile("s_waitcnt vmcnt(" #n ")" ::: "memory")
; #define PG8_WAIT_L(n) asm volatile("s_waitcnt lgkmcnt(" #n ")" ::: "memory")
; #define PG8_BAR __builtin_amdgcn_s_barrier()
; #define PG8_SCHED __builtin_amdgcn_sched_barrier(0)
; template <class Epi, class Sched, bool ALIGN_EPI = false, bool SP2 = false>
; __device__ __forceinline__ void gemm_phase(PG8_LAS unsigned char* lds, const Gemm g, const Sched& S, const Epi& E) {
;     ...
;             PG8_WAIT_V(8); PG8_WAIT_L(0); PG8_BAR; PG8_MMA(1, 0, At, B0); PG8_MMA(1, 1, At, B1); PG8_BAR; PG8_SCHED;
;             PG8_LDB(B0, 1, 0); PG8_LDB(B1, 1, 1); PG8_SCHED; PG8_LDA(At, 1, 0); PG8_STAGE(PG8_SA(0, 1), a2 + hstep, voffA);
;             PG8_WAIT_V(8); PG8_WAIT_L(0); PG8_BAR; PG8_MMA(0, 0, At, B0); PG8_MMA(0, 1, At, B1); PG8_BAR; PG8_SCHED;
	v_mfma_f32_16x16x32_bf16 v[56:59], v[128:131], v[186:189], 0
	v_mfma_f32_16x16x32_bf16 v[60:63], v[136:139], v[186:189], 0
	v_mfma_f32_16x16x32_bf16 v[40:43], v[128:131], v[198:201], 0
	v_mfma_f32_16x16x32_bf16 v[44:47], v[136:139], v[198:201], 0
	v_mfma_f32_16x16x32_bf16 v[24:27], v[128:131], v[206:209], 0
	v_mfma_f32_16x16x32_bf16 v[28:31], v[136:139], v[206:209], 0
	v_mfma_f32_16x16x32_bf16 v[8:11], v[128:131], v[214:217], 0
	v_mfma_f32_16x16x32_bf16 v[12:15], v[136:139], v[214:217], 0
	v_mfma_f32_16x16x32_bf16 v[56:59], v[132:135], v[190:193], v[56:59]
	v_mfma_f32_16x16x32_bf16 v[60:63], v[140:143], v[190:193], v[60:63]
	v_mfma_f32_16x16x32_bf16 v[40:43], v[132:135], v[202:205], v[40:43]
	v_mfma_f32_16x16x32_bf16 v[44:47], v[140:143], v[202:205], v[44:47]
	v_mfma_f32_16x16x32_bf16 v[24:27], v[132:135], v[210:213], v[24:27]
	v_mfma_f32_16x16x32_bf16 v[28:31], v[140:143], v[210:213], v[28:31]
	v_mfma_f32_16x16x32_bf16 v[8:11], v[132:135], v[218:221], v[8:11]
	v_mfma_f32_16x16x32_bf16 v[12:15], v[140:143], v[218:221], v[12:15]
	v_mfma_f32_16x16x32_bf16 v[52:55], v[144:147], v[186:189], 0
	v_mfma_f32_16x16x32_bf16 v[48:51], v[168:171], v[186:189], 0
	v_mfma_f32_16x16x32_bf16 v[36:39], v[144:147], v[198:201], 0
	v_mfma_f32_16x16x32_bf16 v[32:35], v[168:171], v[198:201], 0
	v_mfma_f32_16x16x32_bf16 v[20:23], v[144:147], v[206:209], 0
	v_mfma_f32_16x16x32_bf16 v[16:19], v[168:171], v[206:209], 0
	v_mfma_f32_16x16x32_bf16 v[4:7], v[144:147], v[214:217], 0
	v_mfma_f32_16x16x32_bf16 v[0:3], v[168:171], v[214:217], 0
	v_mfma_f32_16x16x32_bf16 v[52:55], v[148:151], v[190:193], v[52:55]
	v_mfma_f32_16x16x32_bf16 v[48:51], v[172:175], v[190:193], v[48:51]
	v_mfma_f32_16x16x32_bf16 v[36:39], v[148:151], v[202:205], v[36:39]
	v_mfma_f32_16x16x32_bf16 v[32:35], v[172:175], v[202:205], v[32:35]
	v_mfma_f32_16x16x32_bf16 v[20:23], v[148:151], v[210:213], v[20:23]
	v_mfma_f32_16x16x32_bf16 v[16:19], v[172:175], v[210:213], v[16:19]
	v_mfma_f32_16x16x32_bf16 v[4:7], v[148:151], v[218:221], v[4:7]
	v_mfma_f32_16x16x32_bf16 v[0:3], v[172:175], v[218:221], v[0:3]
	s_barrier
	s_setprio 0
	s_add_i32 s50, 0, 0x18000
	s_add_i32 s51, 0, 0x1c000
	v_add_u32_e32 v140, s50, v179
	v_add_u32_e32 v172, s51, v179
	ds_read_b128 v[128:131], v140
	ds_read_b128 v[132:135], v140 offset:1024
	ds_read_b128 v[136:139], v140 offset:2048
	ds_read_b128 v[140:143], v140 offset:3072
	ds_read_b128 v[144:147], v172
	ds_read_b128 v[148:151], v172 offset:1024
	ds_read_b128 v[168:171], v172 offset:2048
	ds_read_b128 v[172:175], v172 offset:3072
	s_add_u32 s30, s30, 0x80000
	s_addc_u32 s31, s31, 0
	s_mov_b32 m0, s36
	ds_read_b128 v[186:189], v183 offset:32768
	ds_read_b128 v[190:193], v183 offset:33792
	ds_read_b128 v[198:201], v183 offset:34816
	ds_read_b128 v[202:205], v183 offset:35840
	ds_read_b128 v[206:209], v183 offset:36864
	ds_read_b128 v[210:213], v183 offset:37888
	ds_read_b128 v[214:217], v183 offset:38912
	ds_read_b128 v[218:221], v183 offset:39936
	global_load_lds_dwordx4 v152, s[30:31]
	s_mov_b32 m0, s37
	v_lshl_add_u64 v[226:227], s[30:31], 0, v[156:157]
	global_load_lds_dwordx4 v[226:227], off
	s_waitcnt vmcnt(8) lgkmcnt(0)
	s_setprio 1
	s_barrier
	v_mfma_f32_16x16x32_bf16 v[124:127], v[128:131], v[186:189], v[124:127]
	v_mfma_f32_16x16x32_bf16 v[120:123], v[136:139], v[186:189], v[120:123]
	v_mfma_f32_16x16x32_bf16 v[104:107], v[128:131], v[198:201], v[104:107]
	v_mfma_f32_16x16x32_bf16 v[108:111], v[136:139], v[198:201], v[108:111]
	v_mfma_f32_16x16x32_bf16 v[88:91], v[128:131], v[206:209], v[88:91]
	v_mfma_f32_16x16x32_bf16 v[92:95], v[136:139], v[206:209], v[92:95]
	v_mfma_f32_16x16x32_bf16 v[72:75], v[128:131], v[214:217], v[72:75]
	v_mfma_f32_16x16x32_bf16 v[76:79], v[136:139], v[214:217], v[76:79]
	v_mfma_f32_16x16x32_bf16 v[124:127], v[132:135], v[190:193], v[124:127]
	v_mfma_f32_16x16x32_bf16 v[120:123], v[140:143], v[190:193], v[120:123]
	v_mfma_f32_16x16x32_bf16 v[104:107], v[132:135], v[202:205], v[104:107]
	v_mfma_f32_16x16x32_bf16 v[108:111], v[140:143], v[202:205], v[108:111]
	v_mfma_f32_16x16x32_bf16 v[88:91], v[132:135], v[210:213], v[88:91]
	v_mfma_f32_16x16x32_bf16 v[92:95], v[140:143], v[210:213], v[92:95]
	v_mfma_f32_16x16x32_bf16 v[72:75], v[132:135], v[218:221], v[72:75]
	v_mfma_f32_16x16x32_bf16 v[76:79], v[140:143], v[218:221], v[76:79]
	v_mfma_f32_16x16x32_bf16 v[116:119], v[144:147], v[186:189], v[116:119]
	v_mfma_f32_16x16x32_bf16 v[112:115], v[168:171], v[186:189], v[112:115]
	v_mfma_f32_16x16x32_bf16 v[100:103], v[144:147], v[198:201], v[100:103]
	v_mfma_f32_16x16x32_bf16 v[96:99], v[168:171], v[198:201], v[96:99]
	v_mfma_f32_16x16x32_bf16 v[84:87], v[144:147], v[206:209], v[84:87]
	v_mfma_f32_16x16x32_bf16 v[80:83], v[168:171], v[206:209], v[80:83]
	v_mfma_f32_16x16x32_bf16 v[68:71], v[144:147], v[214:217], v[68:71]
	v_mfma_f32_16x16x32_bf16 v[64:67], v[168:171], v[214:217], v[64:67]
	v_mfma_f32_16x16x32_bf16 v[116:119], v[148:151], v[190:193], v[116:119]
	v_mfma_f32_16x16x32_bf16 v[112:115], v[172:175], v[190:193], v[112:115]
	v_mfma_f32_16x16x32_bf16 v[100:103], v[148:151], v[202:205], v[100:103]
	v_mfma_f32_16x16x32_bf16 v[96:99], v[172:175], v[202:205], v[96:99]
	v_mfma_f32_16x16x32_bf16 v[84:87], v[148:151], v[210:213], v[84:87]
	v_mfma_f32_16x16x32_bf16 v[80:83], v[172:175], v[210:213], v[80:83]
	v_mfma_f32_16x16x32_bf16 v[68:71], v[148:151], v[218:221], v[68:71]
	v_mfma_f32_16x16x32_bf16 v[64:67], v[172:175], v[218:221], v[64:67]
	s_barrier
; #define PG8_STAGE(bufoff, gbase, voff) do { _Pragma("unroll") for (int _i = 0; _i < 2; ++_i) \
;         __builtin_amdgcn_global_load_lds((const unsigned*)((const char*)(gbase) + (voff)[_i]), (PG8_LAS unsigned*)(lds + (bufoff) + ldsw + _i * 8192), 16, 0, 0); } while (0)
; #define PG8_LDA(dst, b, h) do { _Pragma("unroll") for (int m = 0; m < 4; ++m) _Pragma("unroll") for (int k = 0; k < 2; ++k) dst[m][k] = *(const PG8_LAS bf16x8*)(lds + PG8_SA(b, h) + aoff + m * 2048 + k * 1024); } while (0)
; #define PG8_LDB(dst, b, h) do { _Pragma("unroll") for (int n = 0; n < 2; ++n) _Pragma("unroll") for (int k = 0; k < 2; ++k) dst[n][k] = *(const PG8_LAS bf16x8*)(lds + PG8_SB(b, h) + boff + n * 2048 + k * 1024); } while (0)
; #define PG8_MMA(ai, bj, At, Bt) do { __builtin_amdgcn_s_setprio(1); _Pragma("unroll") for (int m = 0; m < 4; ++m) _Pragma("unroll") for (int n = 0; n < 2; ++n) _Pragma("unroll") for (int k = 0; k < 2; ++k) \
;         acc[ai][bj][m][n] = __builtin_amdgcn_mfma_f32_16x16x32_bf16(Bt[n][k], At[m][k], acc[ai][bj][m][n], 0, 0, 0); __builtin_amdgcn_s_setprio(0); } while (0)
; #define PG8_WAIT_V(n) asm volatile("s_waitcnt vmcnt(" #n ")" ::: "memory")
; template <class Epi, class Sched, bool ALIGN_EPI = false, bool SP2 = false>
; __device__ __forceinline__ void gemm_phase(PG8_LAS unsigned char* lds, const Gemm g, const Sched& S, const Epi& E) {
;     ...
;             PG8_LDB(B0, 0, 0); PG8_LDB(B1, 0, 1); PG8_SCHED; PG8_LDA(At, 0, 0); PG8_STAGE(PG8_SA(1, 1), a1 + hstep, voffA);
;             PG8_WAIT_V(8); PG8_WAIT_L(0); PG8_BAR; PG8_MMA(0, 0, At, B0); PG8_MMA(0, 1, At, B1); PG8_BAR; PG8_SCHED;
;             PG8_LDA(At, 0, 1); PG8_STAGE(PG8_SB(0, 0), b2, voffB); PG8_STAGE(PG8_SB(0, 1), b2 + hstep, voffB); PG8_STAGE(PG8_SA(0, 0), a2, voffA);
;             PG8_WAIT_V(8); PG8_WAIT_L(0); PG8_BAR; PG8_MMA(1, 0, At, B0); PG8_MMA(1, 1, At, B1); PG8_BAR; PG8_SCHED;
;             PG8_LDB(B0, 1, 0); PG8_LDB(B1, 1, 1); PG8_SCHED; PG8_LDA(At, 1, 0); PG8_STAGE(PG8_SA(0, 1), a2 + hstep, voffA);
;             PG8_WAIT_V(8); PG8_WAIT_L(0); PG8_BAR; PG8_MMA(0, 0, At, B0); PG8_MMA(0, 1, At, B1); PG8_BAR; PG8_SCHED;
;             PG8_LDA(At, 1, 1); PG8_STAGE(PG8_SB(1, 0), b3, voffB); PG8_STAGE(PG8_SB(1, 1), b3 + hstep, voffB); PG8_STAGE(PG8_SA(1, 0), a3, voffA);
;             PG8_WAIT_V(8); PG8_WAIT_L(0); PG8_BAR; PG8_MMA(1, 0, At, B0); PG8_MMA(1, 1, At, B1); PG8_BAR; PG8_SCHED;
	s_setprio 0
	s_add_i32 s30, s50, s34
	v_lshl_add_u64 v[176:177], v[176:177], 0, s[12:13]
	s_mov_b32 m0, s30
	ds_read_b128 v[186:189], v183 offset:49152
	ds_read_b128 v[190:193], v183 offset:50176
	ds_read_b128 v[198:201], v183 offset:51200
	ds_read_b128 v[202:205], v183 offset:52224
	ds_read_b128 v[206:209], v183 offset:53248
	ds_read_b128 v[210:213], v183 offset:54272
	ds_read_b128 v[214:217], v183 offset:55296
	ds_read_b128 v[218:221], v183 offset:56320
	global_load_lds_dwordx4 v[176:177], off
	s_add_i32 m0, s30, 0x2000
	s_add_u32 s28, s28, 0x80080
	v_lshl_add_u64 v[176:177], v[194:195], 0, s[12:13]
	s_addc_u32 s29, s29, 0
	s_add_i32 s30, s51, s34
	global_load_lds_dwordx4 v[176:177], off
	s_mov_b32 m0, s30
	s_nop 0
	global_load_lds_dwordx4 v154, s[28:29]
	s_add_i32 m0, s30, 0x2000
	v_lshl_add_u64 v[176:177], s[28:29], 0, v[158:159]
	global_load_lds_dwordx4 v[176:177], off
	s_mov_b32 m0, s39
	v_lshl_add_u64 v[176:177], v[222:223], 0, s[12:13]
	global_load_lds_dwordx4 v[176:177], off
	s_mov_b32 m0, s40
	v_lshl_add_u64 v[176:177], v[224:225], 0, s[12:13]
	global_load_lds_dwordx4 v[176:177], off
	s_waitcnt vmcnt(8) lgkmcnt(0)
	s_setprio 1
	s_barrier
	v_mfma_f32_16x16x32_bf16 v[56:59], v[128:131], v[186:189], v[56:59]
	v_mfma_f32_16x16x32_bf16 v[60:63], v[136:139], v[186:189], v[60:63]
	v_mfma_f32_16x16x32_bf16 v[40:43], v[128:131], v[198:201], v[40:43]
	v_mfma_f32_16x16x32_bf16 v[44:47], v[136:139], v[198:201], v[44:47]
	v_mfma_f32_16x16x32_bf16 v[24:27], v[128:131], v[206:209], v[24:27]
	v_mfma_f32_16x16x32_bf16 v[28:31], v[136:139], v[206:209], v[28:31]
	v_mfma_f32_16x16x32_bf16 v[8:11], v[128:131], v[214:217], v[8:11]
	v_mfma_f32_16x16x32_bf16 v[12:15], v[136:139], v[214:217], v[12:15]
	v_mfma_f32_16x16x32_bf16 v[56:59], v[132:135], v[190:193], v[56:59]
	v_mfma_f32_16x16x32_bf16 v[60:63], v[140:143], v[190:193], v[60:63]
	v_mfma_f32_16x16x32_bf16 v[40:43], v[132:135], v[202:205], v[40:43]
	v_mfma_f32_16x16x32_bf16 v[44:47], v[140:143], v[202:205], v[44:47]
	v_mfma_f32_16x16x32_bf16 v[24:27], v[132:135], v[210:213], v[24:27]
	v_mfma_f32_16x16x32_bf16 v[28:31], v[140:143], v[210:213], v[28:31]
	v_mfma_f32_16x16x32_bf16 v[8:11], v[132:135], v[218:221], v[8:11]
	v_mfma_f32_16x16x32_bf16 v[12:15], v[140:143], v[218:221], v[12:15]
	v_mfma_f32_16x16x32_bf16 v[52:55], v[144:147], v[186:189], v[52:55]
	v_mfma_f32_16x16x32_bf16 v[48:51], v[168:171], v[186:189], v[48:51]
	v_mfma_f32_16x16x32_bf16 v[36:39], v[144:147], v[198:201], v[36:39]
	v_mfma_f32_16x16x32_bf16 v[32:35], v[168:171], v[198:201], v[32:35]
	v_mfma_f32_16x16x32_bf16 v[20:23], v[144:147], v[206:209], v[20:23]
	v_mfma_f32_16x16x32_bf16 v[16:19], v[168:171], v[206:209], v[16:19]
	v_mfma_f32_16x16x32_bf16 v[4:7], v[144:147], v[214:217], v[4:7]
	v_mfma_f32_16x16x32_bf16 v[0:3], v[168:171], v[214:217], v[0:3]
	v_mfma_f32_16x16x32_bf16 v[52:55], v[148:151], v[190:193], v[52:55]
	v_mfma_f32_16x16x32_bf16 v[48:51], v[172:175], v[190:193], v[48:51]
	v_mfma_f32_16x16x32_bf16 v[36:39], v[148:151], v[202:205], v[36:39]
	v_mfma_f32_16x16x32_bf16 v[32:35], v[172:175], v[202:205], v[32:35]
	v_mfma_f32_16x16x32_bf16 v[20:23], v[148:151], v[210:213], v[20:23]
	v_mfma_f32_16x16x32_bf16 v[16:19], v[172:175], v[210:213], v[16:19]
	v_mfma_f32_16x16x32_bf16 v[4:7], v[148:151], v[218:221], v[4:7]
	v_mfma_f32_16x16x32_bf16 v[0:3], v[172:175], v[218:221], v[0:3]
	s_barrier
	s_setprio 0
	s_add_i32 s49, s49, 2
	s_add_u32 s26, s26, 0x100
	s_addc_u32 s27, s27, 0
	s_add_u32 s47, s47, 0x100
	s_addc_u32 s48, s48, 0
.LBB0_1180:
	ds_read_b128 v[128:131], v181
	ds_read_b128 v[132:135], v181 offset:1024
	ds_read_b128 v[136:139], v181 offset:2048
	ds_read_b128 v[140:143], v181 offset:3072
	ds_read_b128 v[144:147], v182
	ds_read_b128 v[148:151], v182 offset:1024
	ds_read_b128 v[168:171], v182 offset:2048
	ds_read_b128 v[172:175], v182 offset:3072
	s_add_u32 s28, s26, 0xfff80080
	s_addc_u32 s29, s27, -1
	s_cmp_eq_u32 s49, 28
	s_cselect_b32 s31, s7, s29
	s_cselect_b32 s30, s21, s28
	s_cselect_b32 s29, s19, s48
	s_cselect_b32 s28, s46, s47
	s_add_i32 m0, s35, 0xc000
	ds_read_b128 v[186:189], v183
	ds_read_b128 v[190:193], v183 offset:1024
	ds_read_b128 v[198:201], v183 offset:2048
	ds_read_b128 v[202:205], v183 offset:3072
	ds_read_b128 v[206:209], v183 offset:4096
	ds_read_b128 v[210:213], v183 offset:5120
	ds_read_b128 v[214:217], v183 offset:6144
	ds_read_b128 v[218:221], v183 offset:7168
	global_load_lds_dwordx4 v160, s[26:27]
	s_add_i32 m0, s35, 0xe000
	s_nop 0
	global_load_lds_dwordx4 v162, s[26:27]
	s_waitcnt vmcnt(8) lgkmcnt(0)
	s_setprio 1
	s_barrier
; #define PG8_STAGE(bufoff, gbase, voff) do { _Pragma("unroll") for (int _i = 0; _i < 2; ++_i) \
;         __builtin_amdgcn_global_load_lds((const unsigned*)((const char*)(gbase) + (voff)[_i]), (PG8_LAS unsigned*)(lds + (bufoff) + ldsw + _i * 8192), 16, 0, 0); } while (0)
; #define PG8_LDA(dst, b, h) do { _Pragma("unroll") for (int m = 0; m < 4; ++m) _Pragma("unroll") for (int k = 0; k < 2; ++k) dst[m][k] = *(const PG8_LAS bf16x8*)(lds + PG8_SA(b, h) + aoff + m * 2048 + k * 1024); } while (0)
; #define PG8_MMA(ai, bj, At, Bt) do { __builtin_amdgcn_s_setprio(1); _Pragma("unroll") for (int m = 0; m < 4; ++m) _Pragma("unroll") for (int n = 0; n < 2; ++n) _Pragma("unroll") for (int k = 0; k < 2; ++k) \
;         acc[ai][bj][m][n] = __builtin_amdgcn_mfma_f32_16x16x32_bf16(Bt[n][k], At[m][k], acc[ai][bj][m][n], 0, 0, 0); __builtin_amdgcn_s_setprio(0); } while (0)
; #define PG8_WAIT_V(n) asm volatile("s_waitcnt vmcnt(" #n ")" ::: "memory")
; #define PG8_WAIT_L(n) asm volatile("s_waitcnt lgkmcnt(" #n ")" ::: "memory")
; #define PG8_BAR __builtin_amdgcn_s_barrier()
; #define PG8_SCHED __builtin_amdgcn_sched_barrier(0)
; template <class Epi, class Sched, bool ALIGN_EPI = false, bool SP2 = false>
; __device__ __forceinline__ void gemm_phase(PG8_LAS unsigned char* lds, const Gemm g, const Sched& S, const Epi& E) {
;     ...
;             PG8_WAIT_V(8); PG8_WAIT_L(0); PG8_BAR; PG8_MMA(0, 0, At, B0); PG8_MMA(0, 1, At, B1); PG8_BAR; PG8_SCHED;
;             PG8_LDA(At, 0, 1); PG8_STAGE(PG8_SB(0, 0), b2, voffB); PG8_STAGE(PG8_SB(0, 1), b2 + hstep, voffB); PG8_STAGE(PG8_SA(0, 0), a2, voffA);
;             PG8_WAIT_V(8); PG8_WAIT_L(0); PG8_BAR; PG8_MMA(1, 0, At, B0); PG8_MMA(1, 1, At, B1); PG8_BAR; PG8_SCHED;
	v_mfma_f32_16x16x32_bf16 v[124:127], v[128:131], v[186:189], v[124:127]
	v_mfma_f32_16x16x32_bf16 v[120:123], v[136:139], v[186:189], v[120:123]
	v_mfma_f32_16x16x32_bf16 v[104:107], v[128:131], v[198:201], v[104:107]
	v_mfma_f32_16x16x32_bf16 v[108:111], v[136:139], v[198:201], v[108:111]
	v_mfma_f32_16x16x32_bf16 v[88:91], v[128:131], v[206:209], v[88:91]
	v_mfma_f32_16x16x32_bf16 v[92:95], v[136:139], v[206:209], v[92:95]
	v_mfma_f32_16x16x32_bf16 v[72:75], v[128:131], v[214:217], v[72:75]
	v_mfma_f32_16x16x32_bf16 v[76:79], v[136:139], v[214:217], v[76:79]
	v_mfma_f32_16x16x32_bf16 v[124:127], v[132:135], v[190:193], v[124:127]
	v_mfma_f32_16x16x32_bf16 v[120:123], v[140:143], v[190:193], v[120:123]
	v_mfma_f32_16x16x32_bf16 v[104:107], v[132:135], v[202:205], v[104:107]
	v_mfma_f32_16x16x32_bf16 v[108:111], v[140:143], v[202:205], v[108:111]
	v_mfma_f32_16x16x32_bf16 v[88:91], v[132:135], v[210:213], v[88:91]
	v_mfma_f32_16x16x32_bf16 v[92:95], v[140:143], v[210:213], v[92:95]
	v_mfma_f32_16x16x32_bf16 v[72:75], v[132:135], v[218:221], v[72:75]
	v_mfma_f32_16x16x32_bf16 v[76:79], v[140:143], v[218:221], v[76:79]
	v_mfma_f32_16x16x32_bf16 v[116:119], v[144:147], v[186:189], v[116:119]
	v_mfma_f32_16x16x32_bf16 v[112:115], v[168:171], v[186:189], v[112:115]
	v_mfma_f32_16x16x32_bf16 v[100:103], v[144:147], v[198:201], v[100:103]
	v_mfma_f32_16x16x32_bf16 v[96:99], v[168:171], v[198:201], v[96:99]
	v_mfma_f32_16x16x32_bf16 v[84:87], v[144:147], v[206:209], v[84:87]
	v_mfma_f32_16x16x32_bf16 v[80:83], v[168:171], v[206:209], v[80:83]
	v_mfma_f32_16x16x32_bf16 v[68:71], v[144:147], v[214:217], v[68:71]
	v_mfma_f32_16x16x32_bf16 v[64:67], v[168:171], v[214:217], v[64:67]
	v_mfma_f32_16x16x32_bf16 v[116:119], v[148:151], v[190:193], v[116:119]
	v_mfma_f32_16x16x32_bf16 v[112:115], v[172:175], v[190:193], v[112:115]
	v_mfma_f32_16x16x32_bf16 v[100:103], v[148:151], v[202:205], v[100:103]
	v_mfma_f32_16x16x32_bf16 v[96:99], v[172:175], v[202:205], v[96:99]
	v_mfma_f32_16x16x32_bf16 v[84:87], v[148:151], v[210:213], v[84:87]
	v_mfma_f32_16x16x32_bf16 v[80:83], v[172:175], v[210:213], v[80:83]
	v_mfma_f32_16x16x32_bf16 v[68:71], v[148:151], v[218:221], v[68:71]
	v_mfma_f32_16x16x32_bf16 v[64:67], v[172:175], v[218:221], v[64:67]
	s_barrier
	s_setprio 0
	s_add_i32 s50, s43, s34
	v_lshl_add_u64 v[176:177], s[28:29], 0, v[154:155]
	s_mov_b32 m0, s50
	ds_read_b128 v[186:189], v183 offset:16384
	ds_read_b128 v[190:193], v183 offset:17408
	ds_read_b128 v[198:201], v183 offset:18432
	ds_read_b128 v[202:205], v183 offset:19456
	ds_read_b128 v[206:209], v183 offset:20480
	ds_read_b128 v[210:213], v183 offset:21504
	ds_read_b128 v[214:217], v183 offset:22528
	ds_read_b128 v[218:221], v183 offset:23552
	global_load_lds_dwordx4 v[176:177], off
	s_add_i32 m0, s50, 0x2000
	s_add_u32 s50, s28, 0x80000
	v_lshl_add_u64 v[194:195], s[28:29], 0, v[158:159]
	s_addc_u32 s51, s29, 0
	s_add_i32 s52, s44, s34
	global_load_lds_dwordx4 v[194:195], off
	s_mov_b32 m0, s52
	v_lshl_add_u64 v[224:225], s[30:31], 0, v[156:157]
	global_load_lds_dwordx4 v154, s[50:51]
	s_add_i32 m0, s52, 0x2000
	s_nop 0
	global_load_lds_dwordx4 v158, s[50:51]
	s_mov_b32 m0, s35
	v_lshl_add_u64 v[222:223], s[30:31], 0, v[152:153]
	global_load_lds_dwordx4 v[222:223], off
	s_mov_b32 m0, s33
	s_nop 0
	global_load_lds_dwordx4 v[224:225], off
	s_waitcnt vmcnt(8) lgkmcnt(0)
	s_setprio 1
	s_barrier
	v_mfma_f32_16x16x32_bf16 v[56:59], v[128:131], v[186:189], v[56:59]
	v_mfma_f32_16x16x32_bf16 v[60:63], v[136:139], v[186:189], v[60:63]
	v_mfma_f32_16x16x32_bf16 v[40:43], v[128:131], v[198:201], v[40:43]
	v_mfma_f32_16x16x32_bf16 v[44:47], v[136:139], v[198:201], v[44:47]
	v_mfma_f32_16x16x32_bf16 v[24:27], v[128:131], v[206:209], v[24:27]
	v_mfma_f32_16x16x32_bf16 v[28:31], v[136:139], v[206:209], v[28:31]
	v_mfma_f32_16x16x32_bf16 v[8:11], v[128:131], v[214:217], v[8:11]
	v_mfma_f32_16x16x32_bf16 v[12:15], v[136:139], v[214:217], v[12:15]
	v_mfma_f32_16x16x32_bf16 v[56:59], v[132:135], v[190:193], v[56:59]
	v_mfma_f32_16x16x32_bf16 v[60:63], v[140:143], v[190:193], v[60:63]
	v_mfma_f32_16x16x32_bf16 v[40:43], v[132:135], v[202:205], v[40:43]
	v_mfma_f32_16x16x32_bf16 v[44:47], v[140:143], v[202:205], v[44:47]
	v_mfma_f32_16x16x32_bf16 v[24:27], v[132:135], v[210:213], v[24:27]
	v_mfma_f32_16x16x32_bf16 v[28:31], v[140:143], v[210:213], v[28:31]
	v_mfma_f32_16x16x32_bf16 v[8:11], v[132:135], v[218:221], v[8:11]
	v_mfma_f32_16x16x32_bf16 v[12:15], v[140:143], v[218:221], v[12:15]
	v_mfma_f32_16x16x32_bf16 v[52:55], v[144:147], v[186:189], v[52:55]
	v_mfma_f32_16x16x32_bf16 v[48:51], v[168:171], v[186:189], v[48:51]
	v_mfma_f32_16x16x32_bf16 v[36:39], v[144:147], v[198:201], v[36:39]
	v_mfma_f32_16x16x32_bf16 v[32:35], v[168:171], v[198:201], v[32:35]
	v_mfma_f32_16x16x32_bf16 v[20:23], v[144:147], v[206:209], v[20:23]
	v_mfma_f32_16x16x32_bf16 v[16:19], v[168:171], v[206:209], v[16:19]
	v_mfma_f32_16x16x32_bf16 v[4:7], v[144:147], v[214:217], v[4:7]
	v_mfma_f32_16x16x32_bf16 v[0:3], v[168:171], v[214:217], v[0:3]
	v_mfma_f32_16x16x32_bf16 v[52:55], v[148:151], v[190:193], v[52:55]
	v_mfma_f32_16x16x32_bf16 v[48:51], v[172:175], v[190:193], v[48:51]
	v_mfma_f32_16x16x32_bf16 v[36:39], v[148:151], v[202:205], v[36:39]
	v_mfma_f32_16x16x32_bf16 v[32:35], v[172:175], v[202:205], v[32:35]
	v_mfma_f32_16x16x32_bf16 v[20:23], v[148:151], v[210:213], v[20:23]
	v_mfma_f32_16x16x32_bf16 v[16:19], v[172:175], v[210:213], v[16:19]
	v_mfma_f32_16x16x32_bf16 v[4:7], v[148:151], v[218:221], v[4:7]
	v_mfma_f32_16x16x32_bf16 v[0:3], v[172:175], v[218:221], v[0:3]
	s_barrier
; #define PG8_STAGE(bufoff, gbase, voff) do { _Pragma("unroll") for (int _i = 0; _i < 2; ++_i) \
;         __builtin_amdgcn_global_load_lds((const unsigned*)((const char*)(gbase) + (voff)[_i]), (PG8_LAS unsigned*)(lds + (bufoff) + ldsw + _i * 8192), 16, 0, 0); } while (0)
; #define PG8_LDA(dst, b, h) do { _Pragma("unroll") for (int m = 0; m < 4; ++m) _Pragma("unroll") for (int k = 0; k < 2; ++k) dst[m][k] = *(const PG8_LAS bf16x8*)(lds + PG8_SA(b, h) + aoff + m * 2048 + k * 1024); } while (0)
; #define PG8_LDB(dst, b, h) do { _Pragma("unroll") for (int n = 0; n < 2; ++n) _Pragma("unroll") for (int k = 0; k < 2; ++k) dst[n][k] = *(const PG8_LAS bf16x8*)(lds + PG8_SB(b, h) + boff + n * 2048 + k * 1024); } while (0)
; #define PG8_MMA(ai, bj, At, Bt) do { __builtin_amdgcn_s_setprio(1); _Pragma("unroll") for (int m = 0; m < 4; ++m) _Pragma("unroll") for (int n = 0; n < 2; ++n) _Pragma("unroll") for (int k = 0; k < 2; ++k) \
;         acc[ai][bj][m][n] = __builtin_amdgcn_mfma_f32_16x16x32_bf16(Bt[n][k], At[m][k], acc[ai][bj][m][n], 0, 0, 0); __builtin_amdgcn_s_setprio(0); } while (0)
; #define PG8_WAIT_V(n) asm volatile("s_waitcnt vmcnt(" #n ")" ::: "memory")
; #define PG8_WAIT_L(n) asm volatile("s_waitcnt lgkmcnt(" #n ")" ::: "memory")
; #define PG8_BAR __builtin_amdgcn_s_barrier()
; #define PG8_SCHED __builtin_amdgcn_sched_barrier(0)
; template <class Epi, class Sched, bool ALIGN_EPI = false, bool SP2 = false>
; __device__ __forceinline__ void gemm_phase(PG8_LAS unsigned char* lds, const Gemm g, const Sched& S, const Epi& E) {
;     ...
;             PG8_LDB(B0, 1, 0); PG8_LDB(B1, 1, 1); PG8_SCHED; PG8_LDA(At, 1, 0); PG8_STAGE(PG8_SA(0, 1), a2 + hstep, voffA);
;             PG8_WAIT_V(8); PG8_WAIT_L(0); PG8_BAR; PG8_MMA(0, 0, At, B0); PG8_MMA(0, 1, At, B1); PG8_BAR; PG8_SCHED;
;             PG8_LDA(At, 1, 1); PG8_STAGE(PG8_SB(1, 0), b3, voffB); PG8_STAGE(PG8_SB(1, 1), b3 + hstep, voffB); PG8_STAGE(PG8_SA(1, 0), a3, voffA);
;             PG8_WAIT_V(8); PG8_WAIT_L(0); PG8_BAR; PG8_MMA(1, 0, At, B0); PG8_MMA(1, 1, At, B1); PG8_BAR; PG8_SCHED;
;     ...
;         if constexpr (ALIGN_EPI) { if (wr == 0) PG8_BAR; }
	s_setprio 0
	s_add_i32 s50, 0, 0x18000
	s_add_i32 s51, 0, 0x1c000
	v_add_u32_e32 v140, s50, v179
	v_add_u32_e32 v172, s51, v179
	ds_read_b128 v[128:131], v140
	ds_read_b128 v[132:135], v140 offset:1024
	ds_read_b128 v[136:139], v140 offset:2048
	ds_read_b128 v[140:143], v140 offset:3072
	ds_read_b128 v[144:147], v172
	ds_read_b128 v[148:151], v172 offset:1024
	ds_read_b128 v[168:171], v172 offset:2048
	ds_read_b128 v[172:175], v172 offset:3072
	s_add_u32 s30, s30, 0x80000
	s_addc_u32 s31, s31, 0
	s_mov_b32 m0, s36
	ds_read_b128 v[186:189], v183 offset:32768
	ds_read_b128 v[190:193], v183 offset:33792
	ds_read_b128 v[198:201], v183 offset:34816
	ds_read_b128 v[202:205], v183 offset:35840
	ds_read_b128 v[206:209], v183 offset:36864
	ds_read_b128 v[210:213], v183 offset:37888
	ds_read_b128 v[214:217], v183 offset:38912
	ds_read_b128 v[218:221], v183 offset:39936
	global_load_lds_dwordx4 v152, s[30:31]
	s_mov_b32 m0, s37
	s_nop 0
	global_load_lds_dwordx4 v156, s[30:31]
	s_waitcnt vmcnt(8) lgkmcnt(0)
	s_setprio 1
	s_barrier
	v_mfma_f32_16x16x32_bf16 v[124:127], v[128:131], v[186:189], v[124:127]
	v_mfma_f32_16x16x32_bf16 v[120:123], v[136:139], v[186:189], v[120:123]
	v_mfma_f32_16x16x32_bf16 v[104:107], v[128:131], v[198:201], v[104:107]
	v_mfma_f32_16x16x32_bf16 v[108:111], v[136:139], v[198:201], v[108:111]
	v_mfma_f32_16x16x32_bf16 v[88:91], v[128:131], v[206:209], v[88:91]
	v_mfma_f32_16x16x32_bf16 v[92:95], v[136:139], v[206:209], v[92:95]
	v_mfma_f32_16x16x32_bf16 v[72:75], v[128:131], v[214:217], v[72:75]
	v_mfma_f32_16x16x32_bf16 v[76:79], v[136:139], v[214:217], v[76:79]
	v_mfma_f32_16x16x32_bf16 v[124:127], v[132:135], v[190:193], v[124:127]
	v_mfma_f32_16x16x32_bf16 v[120:123], v[140:143], v[190:193], v[120:123]
	v_mfma_f32_16x16x32_bf16 v[104:107], v[132:135], v[202:205], v[104:107]
	v_mfma_f32_16x16x32_bf16 v[108:111], v[140:143], v[202:205], v[108:111]
	v_mfma_f32_16x16x32_bf16 v[88:91], v[132:135], v[210:213], v[88:91]
	v_mfma_f32_16x16x32_bf16 v[92:95], v[140:143], v[210:213], v[92:95]
	v_mfma_f32_16x16x32_bf16 v[72:75], v[132:135], v[218:221], v[72:75]
	v_mfma_f32_16x16x32_bf16 v[76:79], v[140:143], v[218:221], v[76:79]
	v_mfma_f32_16x16x32_bf16 v[116:119], v[144:147], v[186:189], v[116:119]
	v_mfma_f32_16x16x32_bf16 v[112:115], v[168:171], v[186:189], v[112:115]
	v_mfma_f32_16x16x32_bf16 v[100:103], v[144:147], v[198:201], v[100:103]
	v_mfma_f32_16x16x32_bf16 v[96:99], v[168:171], v[198:201], v[96:99]
	v_mfma_f32_16x16x32_bf16 v[84:87], v[144:147], v[206:209], v[84:87]
	v_mfma_f32_16x16x32_bf16 v[80:83], v[168:171], v[206:209], v[80:83]
	v_mfma_f32_16x16x32_bf16 v[68:71], v[144:147], v[214:217], v[68:71]
	v_mfma_f32_16x16x32_bf16 v[64:67], v[168:171], v[214:217], v[64:67]
	v_mfma_f32_16x16x32_bf16 v[116:119], v[148:151], v[190:193], v[116:119]
	v_mfma_f32_16x16x32_bf16 v[112:115], v[172:175], v[190:193], v[112:115]
	v_mfma_f32_16x16x32_bf16 v[100:103], v[148:151], v[202:205], v[100:103]
	v_mfma_f32_16x16x32_bf16 v[96:99], v[172:175], v[202:205], v[96:99]
	v_mfma_f32_16x16x32_bf16 v[84:87], v[148:151], v[210:213], v[84:87]
	v_mfma_f32_16x16x32_bf16 v[80:83], v[172:175], v[210:213], v[80:83]
	v_mfma_f32_16x16x32_bf16 v[68:71], v[148:151], v[218:221], v[68:71]
	v_mfma_f32_16x16x32_bf16 v[64:67], v[172:175], v[218:221], v[64:67]
	s_barrier
	s_setprio 0
	s_add_i32 s30, s50, s34
	v_lshl_add_u64 v[176:177], v[176:177], 0, s[12:13]
	s_mov_b32 m0, s30
	ds_read_b128 v[186:189], v183 offset:49152
	ds_read_b128 v[190:193], v183 offset:50176
	ds_read_b128 v[198:201], v183 offset:51200
	ds_read_b128 v[202:205], v183 offset:52224
	ds_read_b128 v[206:209], v183 offset:53248
	ds_read_b128 v[210:213], v183 offset:54272
	ds_read_b128 v[214:217], v183 offset:55296
	ds_read_b128 v[218:221], v183 offset:56320
	global_load_lds_dwordx4 v[176:177], off
	s_add_i32 m0, s30, 0x2000
	s_add_u32 s28, s28, 0x80080
	v_lshl_add_u64 v[176:177], v[194:195], 0, s[12:13]
	s_addc_u32 s29, s29, 0
	s_add_i32 s30, s51, s34
	global_load_lds_dwordx4 v[176:177], off
	s_mov_b32 m0, s30
	s_nop 0
	global_load_lds_dwordx4 v154, s[28:29]
	s_add_i32 m0, s30, 0x2000
	v_lshl_add_u64 v[176:177], s[28:29], 0, v[158:159]
	global_load_lds_dwordx4 v[176:177], off
	s_mov_b32 m0, s39
	v_lshl_add_u64 v[176:177], v[222:223], 0, s[12:13]
	global_load_lds_dwordx4 v[176:177], off
	s_mov_b32 m0, s40
	v_lshl_add_u64 v[176:177], v[224:225], 0, s[12:13]
	global_load_lds_dwordx4 v[176:177], off
	s_waitcnt vmcnt(8) lgkmcnt(0)
	s_setprio 1
	s_barrier
	v_mfma_f32_16x16x32_bf16 v[56:59], v[128:131], v[186:189], v[56:59]
	v_mfma_f32_16x16x32_bf16 v[60:63], v[136:139], v[186:189], v[60:63]
	v_mfma_f32_16x16x32_bf16 v[40:43], v[128:131], v[198:201], v[40:43]
	v_mfma_f32_16x16x32_bf16 v[44:47], v[136:139], v[198:201], v[44:47]
	v_mfma_f32_16x16x32_bf16 v[24:27], v[128:131], v[206:209], v[24:27]
	v_mfma_f32_16x16x32_bf16 v[28:31], v[136:139], v[206:209], v[28:31]
	v_mfma_f32_16x16x32_bf16 v[8:11], v[128:131], v[214:217], v[8:11]
	v_mfma_f32_16x16x32_bf16 v[12:15], v[136:139], v[214:217], v[12:15]
	v_mfma_f32_16x16x32_bf16 v[56:59], v[132:135], v[190:193], v[56:59]
	v_mfma_f32_16x16x32_bf16 v[60:63], v[140:143], v[190:193], v[60:63]
	v_mfma_f32_16x16x32_bf16 v[40:43], v[132:135], v[202:205], v[40:43]
	v_mfma_f32_16x16x32_bf16 v[44:47], v[140:143], v[202:205], v[44:47]
	v_mfma_f32_16x16x32_bf16 v[24:27], v[132:135], v[210:213], v[24:27]
	v_mfma_f32_16x16x32_bf16 v[28:31], v[140:143], v[210:213], v[28:31]
	v_mfma_f32_16x16x32_bf16 v[8:11], v[132:135], v[218:221], v[8:11]
	v_mfma_f32_16x16x32_bf16 v[12:15], v[140:143], v[218:221], v[12:15]
	v_mfma_f32_16x16x32_bf16 v[52:55], v[144:147], v[186:189], v[52:55]
	v_mfma_f32_16x16x32_bf16 v[48:51], v[168:171], v[186:189], v[48:51]
	v_mfma_f32_16x16x32_bf16 v[36:39], v[144:147], v[198:201], v[36:39]
	v_mfma_f32_16x16x32_bf16 v[32:35], v[168:171], v[198:201], v[32:35]
	v_mfma_f32_16x16x32_bf16 v[20:23], v[144:147], v[206:209], v[20:23]
	v_mfma_f32_16x16x32_bf16 v[16:19], v[168:171], v[206:209], v[16:19]
	v_mfma_f32_16x16x32_bf16 v[4:7], v[144:147], v[214:217], v[4:7]
	v_mfma_f32_16x16x32_bf16 v[0:3], v[168:171], v[214:217], v[0:3]
	v_mfma_f32_16x16x32_bf16 v[52:55], v[148:151], v[190:193], v[52:55]
	v_mfma_f32_16x16x32_bf16 v[48:51], v[172:175], v[190:193], v[48:51]
	v_mfma_f32_16x16x32_bf16 v[36:39], v[148:151], v[202:205], v[36:39]
	v_mfma_f32_16x16x32_bf16 v[32:35], v[172:175], v[202:205], v[32:35]
	v_mfma_f32_16x16x32_bf16 v[20:23], v[148:151], v[210:213], v[20:23]
	v_mfma_f32_16x16x32_bf16 v[16:19], v[172:175], v[210:213], v[16:19]
	v_mfma_f32_16x16x32_bf16 v[4:7], v[148:151], v[218:221], v[4:7]
	v_mfma_f32_16x16x32_bf16 v[0:3], v[172:175], v[218:221], v[0:3]
	s_barrier
	s_setprio 0
	s_add_i32 s49, s49, 2
	s_add_u32 s26, s26, 0x100
	s_addc_u32 s27, s27, 0
	s_add_u32 s47, s47, 0x100
	s_addc_u32 s48, s48, 0
	s_cmp_gt_u32 s49, 29
	s_cbranch_scc0 .LBB0_1180
	s_and_b64 vcc, exec, s[14:15]
	s_cbranch_vccz .LBB0_1183
	s_barrier

; #define PG8_STAGE(bufoff, gbase, voff) do { _Pragma("unroll") for (int _i = 0; _i < 2; ++_i) \
;         __builtin_amdgcn_global_load_lds((const unsigned*)((const char*)(gbase) + (voff)[_i]), (PG8_LAS unsigned*)(lds + (bufoff) + ldsw + _i * 8192), 16, 0, 0); } while (0)
; #define PG8_LDA(dst, b, h) do { _Pragma("unroll") for (int m = 0; m < 4; ++m) _Pragma("unroll") for (int k = 0; k < 2; ++k) dst[m][k] = *(const PG8_LAS bf16x8*)(lds + PG8_SA(b, h) + aoff + m * 2048 + k * 1024); } while (0)
; #define PG8_LDB(dst, b, h) do { _Pragma("unroll") for (int n = 0; n < 2; ++n) _Pragma("unroll") for (int k = 0; k < 2; ++k) dst[n][k] = *(const PG8_LAS bf16x8*)(lds + PG8_SB(b, h) + boff + n * 2048 + k * 1024); } while (0)
; #define PG8_MMA(ai, bj, At, Bt) do { __builtin_amdgcn_s_setprio(1); _Pragma("unroll") for (int m = 0; m < 4; ++m) _Pragma("unroll") for (int n = 0; n < 2; ++n) _Pragma("unroll") for (int k = 0; k < 2; ++k) \
;         acc[ai][bj][m][n] = __builtin_amdgcn_mfma_f32_16x16x32_bf16(Bt[n][k], At[m][k], acc[ai][bj][m][n], 0, 0, 0); __builtin_amdgcn_s_setprio(0); } while (0)
; #define PG8_WAIT_V(n) asm volatile("s_waitcnt vmcnt(" #n ")" ::: "memory")
; template <class Epi, class Sched, bool ALIGN_EPI = false, bool SP2 = false>
; __device__ __forceinline__ void gemm_phase(PG8_LAS unsigned char* lds, const Gemm g, const Sched& S, const Epi& E) {
;     ...
;         const char* nA = has_next ? (const char*)g.A + (size_t)nxt.pm * tstep : cA; const char* nB = has_next ? (const char*)g.Bt + (size_t)nxt.pn * tstep : cB;
;         for (int t = 0; t < nt; t += 2) {
;             const bool last = (t == nt - 2);
;             const char* a1 = cA + (size_t)(t + 1) * kstep;
;             const char* a2 = last ? nA : cA + (size_t)(t + 2) * kstep; const char* b2 = last ? nB : cB + (size_t)(t + 2) * kstep;
;             const char* a3 = a2 + kstep; const char* b3 = b2 + kstep;
;             if (last && has_next) S.a_ready(nxt);
;             if constexpr (SP2) {
;             PG8_LDB(B0, 0, 0); PG8_LDB(B1, 0, 1); PG8_SCHED; PG8_LDA(At, 0, 0); PG8_STAGE(PG8_SA(1, 1), a1 + hstep, voffA);
;             PG8_WAIT_V(8); PG8_WAIT_L(0); PG8_BAR; PG8_MMA(0, 0, At, B0); PG8_MMA(0, 1, At, B1); PG8_BAR; PG8_SCHED;
;             PG8_LDA(At, 0, 1); PG8_STAGE(PG8_SB(0, 0), b2, voffB); PG8_STAGE(PG8_SB(0, 1), b2 + hstep, voffB); PG8_STAGE(PG8_SA(0, 0), a2, voffA);
.LBB0_1372:
	s_ashr_i32 s29, s28, 31
	s_lshl_b64 s[34:35], s[28:29], 20
	s_add_u32 s34, s74, s34
	s_addc_u32 s35, s75, s35
	s_and_b64 s[36:37], s[30:31], exec
	s_cselect_b32 s29, s35, s9
	s_cselect_b32 s39, s34, s8
	s_ashr_i32 s27, s26, 31
	s_lshl_b64 s[36:37], s[26:27], 20
	v_readlane_b32 s44, v254, 22
	v_readlane_b32 s45, v254, 23
	s_add_u32 s36, s44, s36
	s_addc_u32 s37, s45, s37
	s_and_b64 s[44:45], s[30:31], exec
	s_cselect_b32 s27, s37, s43
	s_cselect_b32 s41, s36, s42
	s_add_u32 s8, s8, 0x80080
	s_addc_u32 s9, s9, 0
	s_add_u32 s48, s42, 0x100
	s_addc_u32 s49, s43, 0
	s_mov_b32 s66, -2
	ds_read_b128 v[108:111], v173
	ds_read_b128 v[112:115], v173 offset:1024
	ds_read_b128 v[116:119], v173 offset:2048
	ds_read_b128 v[120:123], v173 offset:3072
	ds_read_b128 v[178:181], v175
	ds_read_b128 v[182:185], v175 offset:1024
	ds_read_b128 v[186:189], v175 offset:2048
	ds_read_b128 v[190:193], v175 offset:3072
	s_add_u32 s42, s8, 0xfff80080
	s_addc_u32 s43, s9, -1
	s_cmp_eq_u32 s66, 28
	s_cselect_b32 s45, s29, s43
	s_cselect_b32 s44, s39, s42
	s_cselect_b32 s43, s27, s49
	s_cselect_b32 s42, s41, s48
	s_add_i32 m0, s50, 0xc000
	ds_read_b128 v[198:201], v177
	ds_read_b128 v[202:205], v177 offset:1024
	ds_read_b128 v[206:209], v177 offset:2048
	ds_read_b128 v[210:213], v177 offset:3072
	ds_read_b128 v[214:217], v177 offset:4096
	ds_read_b128 v[218:221], v177 offset:5120
	ds_read_b128 v[222:225], v177 offset:6144
	ds_read_b128 v[226:229], v177 offset:7168
	global_load_lds_dwordx4 v154, s[8:9]
	s_add_i32 m0, s50, 0xe000
	s_nop 0
	global_load_lds_dwordx4 v156, s[8:9]
	s_waitcnt lgkmcnt(0)
	s_setprio 1
	s_barrier
	v_mfma_f32_16x16x32_bf16 v[140:143], v[108:111], v[198:201], 0
	v_mfma_f32_16x16x32_bf16 v[136:139], v[116:119], v[198:201], 0
	v_mfma_f32_16x16x32_bf16 v[100:103], v[108:111], v[206:209], 0
	v_mfma_f32_16x16x32_bf16 v[124:127], v[116:119], v[206:209], 0
	v_mfma_f32_16x16x32_bf16 v[84:87], v[108:111], v[214:217], 0
	v_mfma_f32_16x16x32_bf16 v[92:95], v[116:119], v[214:217], 0
	v_mfma_f32_16x16x32_bf16 v[68:71], v[108:111], v[222:225], 0
	v_mfma_f32_16x16x32_bf16 v[76:79], v[116:119], v[222:225], 0
	v_mfma_f32_16x16x32_bf16 v[140:143], v[112:115], v[202:205], v[140:143]
	v_mfma_f32_16x16x32_bf16 v[136:139], v[120:123], v[202:205], v[136:139]
	v_mfma_f32_16x16x32_bf16 v[100:103], v[112:115], v[210:213], v[100:103]
	v_mfma_f32_16x16x32_bf16 v[124:127], v[120:123], v[210:213], v[124:127]
	v_mfma_f32_16x16x32_bf16 v[84:87], v[112:115], v[218:221], v[84:87]
	v_mfma_f32_16x16x32_bf16 v[92:95], v[120:123], v[218:221], v[92:95]
	v_mfma_f32_16x16x32_bf16 v[68:71], v[112:115], v[226:229], v[68:71]
	v_mfma_f32_16x16x32_bf16 v[76:79], v[120:123], v[226:229], v[76:79]
	v_mfma_f32_16x16x32_bf16 v[128:131], v[178:181], v[198:201], 0
	v_mfma_f32_16x16x32_bf16 v[132:135], v[186:189], v[198:201], 0
	v_mfma_f32_16x16x32_bf16 v[104:107], v[178:181], v[206:209], 0
	v_mfma_f32_16x16x32_bf16 v[96:99], v[186:189], v[206:209], 0
	v_mfma_f32_16x16x32_bf16 v[88:91], v[178:181], v[214:217], 0
	v_mfma_f32_16x16x32_bf16 v[80:83], v[186:189], v[214:217], 0
	v_mfma_f32_16x16x32_bf16 v[72:75], v[178:181], v[222:225], 0
	v_mfma_f32_16x16x32_bf16 v[64:67], v[186:189], v[222:225], 0
	v_mfma_f32_16x16x32_bf16 v[128:131], v[182:185], v[202:205], v[128:131]
	v_mfma_f32_16x16x32_bf16 v[132:135], v[190:193], v[202:205], v[132:135]
	v_mfma_f32_16x16x32_bf16 v[104:107], v[182:185], v[210:213], v[104:107]
	v_mfma_f32_16x16x32_bf16 v[96:99], v[190:193], v[210:213], v[96:99]
	v_mfma_f32_16x16x32_bf16 v[88:91], v[182:185], v[218:221], v[88:91]
	v_mfma_f32_16x16x32_bf16 v[80:83], v[190:193], v[218:221], v[80:83]
	v_mfma_f32_16x16x32_bf16 v[72:75], v[182:185], v[226:229], v[72:75]
	v_mfma_f32_16x16x32_bf16 v[64:67], v[190:193], v[226:229], v[64:67]
	s_barrier
	s_setprio 0
	s_add_i32 s67, s62, s47
	v_lshl_add_u64 v[160:161], s[42:43], 0, v[144:145]
	s_mov_b32 m0, s67
	ds_read_b128 v[198:201], v177 offset:16384
	ds_read_b128 v[202:205], v177 offset:17408
	ds_read_b128 v[206:209], v177 offset:18432
	ds_read_b128 v[210:213], v177 offset:19456
	ds_read_b128 v[214:217], v177 offset:20480
	ds_read_b128 v[218:221], v177 offset:21504
	ds_read_b128 v[222:225], v177 offset:22528
	ds_read_b128 v[226:229], v177 offset:23552
	global_load_lds_dwordx4 v[160:161], off
	s_add_i32 m0, s67, 0x2000
	s_add_u32 s68, s42, 0x80000
	v_lshl_add_u64 v[164:165], s[42:43], 0, v[146:147]
	s_addc_u32 s69, s43, 0
	s_add_i32 s67, s63, s47
	global_load_lds_dwordx4 v[164:165], off
	s_mov_b32 m0, s67
	v_lshl_add_u64 v[194:195], s[44:45], 0, v[146:147]
	global_load_lds_dwordx4 v144, s[68:69]
	s_add_i32 m0, s67, 0x2000
	s_nop 0
	global_load_lds_dwordx4 v146, s[68:69]
	s_mov_b32 m0, s50
	v_lshl_add_u64 v[170:171], s[44:45], 0, v[144:145]
	global_load_lds_dwordx4 v[170:171], off
	s_mov_b32 m0, s51
	s_nop 0
	global_load_lds_dwordx4 v[194:195], off
	s_waitcnt lgkmcnt(0)
	s_setprio 1
	s_barrier
; #define PG8_STAGE(bufoff, gbase, voff) do { _Pragma("unroll") for (int _i = 0; _i < 2; ++_i) \
;         __builtin_amdgcn_global_load_lds((const unsigned*)((const char*)(gbase) + (voff)[_i]), (PG8_LAS unsigned*)(lds + (bufoff) + ldsw + _i * 8192), 16, 0, 0); } while (0)
; #define PG8_LDA(dst, b, h) do { _Pragma("unroll") for (int m = 0; m < 4; ++m) _Pragma("unroll") for (int k = 0; k < 2; ++k) dst[m][k] = *(const PG8_LAS bf16x8*)(lds + PG8_SA(b, h) + aoff + m * 2048 + k * 1024); } while (0)
; #define PG8_LDB(dst, b, h) do { _Pragma("unroll") for (int n = 0; n < 2; ++n) _Pragma("unroll") for (int k = 0; k < 2; ++k) dst[n][k] = *(const PG8_LAS bf16x8*)(lds + PG8_SB(b, h) + boff + n * 2048 + k * 1024); } while (0)
; #define PG8_MMA(ai, bj, At, Bt) do { __builtin_amdgcn_s_setprio(1); _Pragma("unroll") for (int m = 0; m < 4; ++m) _Pragma("unroll") for (int n = 0; n < 2; ++n) _Pragma("unroll") for (int k = 0; k < 2; ++k) \
;         acc[ai][bj][m][n] = __builtin_amdgcn_mfma_f32_16x16x32_bf16(Bt[n][k], At[m][k], acc[ai][bj][m][n], 0, 0, 0); __builtin_amdgcn_s_setprio(0); } while (0)
; #define PG8_WAIT_V(n) asm volatile("s_waitcnt vmcnt(" #n ")" ::: "memory")
; #define PG8_WAIT_L(n) asm volatile("s_waitcnt lgkmcnt(" #n ")" ::: "memory")
; #define PG8_BAR __builtin_amdgcn_s_barrier()
; #define PG8_SCHED __builtin_amdgcn_sched_barrier(0)
; template <class Epi, class Sched, bool ALIGN_EPI = false, bool SP2 = false>
; __device__ __forceinline__ void gemm_phase(PG8_LAS unsigned char* lds, const Gemm g, const Sched& S, const Epi& E) {
;     ...
;             PG8_WAIT_V(8); PG8_WAIT_L(0); PG8_BAR; PG8_MMA(1, 0, At, B0); PG8_MMA(1, 1, At, B1); PG8_BAR; PG8_SCHED;
;             PG8_LDB(B0, 1, 0); PG8_LDB(B1, 1, 1); PG8_SCHED; PG8_LDA(At, 1, 0); PG8_STAGE(PG8_SA(0, 1), a2 + hstep, voffA);
;             PG8_WAIT_V(8); PG8_WAIT_L(0); PG8_BAR; PG8_MMA(0, 0, At, B0); PG8_MMA(0, 1, At, B1); PG8_BAR; PG8_SCHED;
	v_mfma_f32_16x16x32_bf16 v[60:63], v[108:111], v[198:201], 0
	v_mfma_f32_16x16x32_bf16 v[56:59], v[116:119], v[198:201], 0
	v_mfma_f32_16x16x32_bf16 v[36:39], v[108:111], v[206:209], 0
	v_mfma_f32_16x16x32_bf16 v[44:47], v[116:119], v[206:209], 0
	v_mfma_f32_16x16x32_bf16 v[20:23], v[108:111], v[214:217], 0
	v_mfma_f32_16x16x32_bf16 v[28:31], v[116:119], v[214:217], 0
	v_mfma_f32_16x16x32_bf16 v[4:7], v[108:111], v[222:225], 0
	v_mfma_f32_16x16x32_bf16 v[12:15], v[116:119], v[222:225], 0
	v_mfma_f32_16x16x32_bf16 v[60:63], v[112:115], v[202:205], v[60:63]
	v_mfma_f32_16x16x32_bf16 v[56:59], v[120:123], v[202:205], v[56:59]
	v_mfma_f32_16x16x32_bf16 v[36:39], v[112:115], v[210:213], v[36:39]
	v_mfma_f32_16x16x32_bf16 v[44:47], v[120:123], v[210:213], v[44:47]
	v_mfma_f32_16x16x32_bf16 v[20:23], v[112:115], v[218:221], v[20:23]
	v_mfma_f32_16x16x32_bf16 v[28:31], v[120:123], v[218:221], v[28:31]
	v_mfma_f32_16x16x32_bf16 v[4:7], v[112:115], v[226:229], v[4:7]
	v_mfma_f32_16x16x32_bf16 v[12:15], v[120:123], v[226:229], v[12:15]
	v_mfma_f32_16x16x32_bf16 v[48:51], v[178:181], v[198:201], 0
	v_mfma_f32_16x16x32_bf16 v[52:55], v[186:189], v[198:201], 0
	v_mfma_f32_16x16x32_bf16 v[40:43], v[178:181], v[206:209], 0
	v_mfma_f32_16x16x32_bf16 v[32:35], v[186:189], v[206:209], 0
	v_mfma_f32_16x16x32_bf16 v[24:27], v[178:181], v[214:217], 0
	v_mfma_f32_16x16x32_bf16 v[16:19], v[186:189], v[214:217], 0
	v_mfma_f32_16x16x32_bf16 v[8:11], v[178:181], v[222:225], 0
	v_mfma_f32_16x16x32_bf16 v[0:3], v[186:189], v[222:225], 0
	v_mfma_f32_16x16x32_bf16 v[48:51], v[182:185], v[202:205], v[48:51]
	v_mfma_f32_16x16x32_bf16 v[52:55], v[190:193], v[202:205], v[52:55]
	v_mfma_f32_16x16x32_bf16 v[40:43], v[182:185], v[210:213], v[40:43]
	v_mfma_f32_16x16x32_bf16 v[32:35], v[190:193], v[210:213], v[32:35]
	v_mfma_f32_16x16x32_bf16 v[24:27], v[182:185], v[218:221], v[24:27]
	v_mfma_f32_16x16x32_bf16 v[16:19], v[190:193], v[218:221], v[16:19]
	v_mfma_f32_16x16x32_bf16 v[8:11], v[182:185], v[226:229], v[8:11]
	v_mfma_f32_16x16x32_bf16 v[0:3], v[190:193], v[226:229], v[0:3]
	s_barrier
	s_setprio 0
	s_add_i32 s67, 0, 0x18000
	s_add_i32 s68, 0, 0x1c000
	v_add_u32_e32 v120, s67, v167
	v_add_u32_e32 v162, s68, v167
	ds_read_b128 v[108:111], v120
	ds_read_b128 v[112:115], v120 offset:1024
	ds_read_b128 v[116:119], v120 offset:2048
	ds_read_b128 v[120:123], v120 offset:3072
	ds_read_b128 v[178:181], v162
	ds_read_b128 v[182:185], v162 offset:1024
	ds_read_b128 v[186:189], v162 offset:2048
	ds_read_b128 v[190:193], v162 offset:3072
	s_add_u32 s44, s44, 0x80000
	s_addc_u32 s45, s45, 0
	s_mov_b32 m0, s52
	ds_read_b128 v[198:201], v177 offset:32768
	ds_read_b128 v[202:205], v177 offset:33792
	ds_read_b128 v[206:209], v177 offset:34816
	ds_read_b128 v[210:213], v177 offset:35840
	ds_read_b128 v[214:217], v177 offset:36864
	ds_read_b128 v[218:221], v177 offset:37888
	ds_read_b128 v[222:225], v177 offset:38912
	ds_read_b128 v[226:229], v177 offset:39936
	global_load_lds_dwordx4 v144, s[44:45]
	s_mov_b32 m0, s53
	v_lshl_add_u64 v[230:231], s[44:45], 0, v[146:147]
	global_load_lds_dwordx4 v[230:231], off
	s_waitcnt vmcnt(8) lgkmcnt(0)
	s_setprio 1
	s_barrier
	v_mfma_f32_16x16x32_bf16 v[140:143], v[108:111], v[198:201], v[140:143]
	v_mfma_f32_16x16x32_bf16 v[136:139], v[116:119], v[198:201], v[136:139]
	v_mfma_f32_16x16x32_bf16 v[100:103], v[108:111], v[206:209], v[100:103]
	v_mfma_f32_16x16x32_bf16 v[124:127], v[116:119], v[206:209], v[124:127]
	v_mfma_f32_16x16x32_bf16 v[84:87], v[108:111], v[214:217], v[84:87]
	v_mfma_f32_16x16x32_bf16 v[92:95], v[116:119], v[214:217], v[92:95]
	v_mfma_f32_16x16x32_bf16 v[68:71], v[108:111], v[222:225], v[68:71]
	v_mfma_f32_16x16x32_bf16 v[76:79], v[116:119], v[222:225], v[76:79]
	v_mfma_f32_16x16x32_bf16 v[140:143], v[112:115], v[202:205], v[140:143]
	v_mfma_f32_16x16x32_bf16 v[136:139], v[120:123], v[202:205], v[136:139]
	v_mfma_f32_16x16x32_bf16 v[100:103], v[112:115], v[210:213], v[100:103]
	v_mfma_f32_16x16x32_bf16 v[124:127], v[120:123], v[210:213], v[124:127]
	v_mfma_f32_16x16x32_bf16 v[84:87], v[112:115], v[218:221], v[84:87]
	v_mfma_f32_16x16x32_bf16 v[92:95], v[120:123], v[218:221], v[92:95]
	v_mfma_f32_16x16x32_bf16 v[68:71], v[112:115], v[226:229], v[68:71]
	v_mfma_f32_16x16x32_bf16 v[76:79], v[120:123], v[226:229], v[76:79]
	v_mfma_f32_16x16x32_bf16 v[128:131], v[178:181], v[198:201], v[128:131]
	v_mfma_f32_16x16x32_bf16 v[132:135], v[186:189], v[198:201], v[132:135]
	v_mfma_f32_16x16x32_bf16 v[104:107], v[178:181], v[206:209], v[104:107]
	v_mfma_f32_16x16x32_bf16 v[96:99], v[186:189], v[206:209], v[96:99]
	v_mfma_f32_16x16x32_bf16 v[88:91], v[178:181], v[214:217], v[88:91]
	v_mfma_f32_16x16x32_bf16 v[80:83], v[186:189], v[214:217], v[80:83]
	v_mfma_f32_16x16x32_bf16 v[72:75], v[178:181], v[222:225], v[72:75]
	v_mfma_f32_16x16x32_bf16 v[64:67], v[186:189], v[222:225], v[64:67]
	v_mfma_f32_16x16x32_bf16 v[128:131], v[182:185], v[202:205], v[128:131]
	v_mfma_f32_16x16x32_bf16 v[132:135], v[190:193], v[202:205], v[132:135]
	v_mfma_f32_16x16x32_bf16 v[104:107], v[182:185], v[210:213], v[104:107]
	v_mfma_f32_16x16x32_bf16 v[96:99], v[190:193], v[210:213], v[96:99]
	v_mfma_f32_16x16x32_bf16 v[88:91], v[182:185], v[218:221], v[88:91]
	v_mfma_f32_16x16x32_bf16 v[80:83], v[190:193], v[218:221], v[80:83]
	v_mfma_f32_16x16x32_bf16 v[72:75], v[182:185], v[226:229], v[72:75]
	v_mfma_f32_16x16x32_bf16 v[64:67], v[190:193], v[226:229], v[64:67]
	s_barrier
; #define PG8_STAGE(bufoff, gbase, voff) do { _Pragma("unroll") for (int _i = 0; _i < 2; ++_i) \
;         __builtin_amdgcn_global_load_lds((const unsigned*)((const char*)(gbase) + (voff)[_i]), (PG8_LAS unsigned*)(lds + (bufoff) + ldsw + _i * 8192), 16, 0, 0); } while (0)
; #define PG8_LDA(dst, b, h) do { _Pragma("unroll") for (int m = 0; m < 4; ++m) _Pragma("unroll") for (int k = 0; k < 2; ++k) dst[m][k] = *(const PG8_LAS bf16x8*)(lds + PG8_SA(b, h) + aoff + m * 2048 + k * 1024); } while (0)
; #define PG8_LDB(dst, b, h) do { _Pragma("unroll") for (int n = 0; n < 2; ++n) _Pragma("unroll") for (int k = 0; k < 2; ++k) dst[n][k] = *(const PG8_LAS bf16x8*)(lds + PG8_SB(b, h) + boff + n * 2048 + k * 1024); } while (0)
; #define PG8_MMA(ai, bj, At, Bt) do { __builtin_amdgcn_s_setprio(1); _Pragma("unroll") for (int m = 0; m < 4; ++m) _Pragma("unroll") for (int n = 0; n < 2; ++n) _Pragma("unroll") for (int k = 0; k < 2; ++k) \
;         acc[ai][bj][m][n] = __builtin_amdgcn_mfma_f32_16x16x32_bf16(Bt[n][k], At[m][k], acc[ai][bj][m][n], 0, 0, 0); __builtin_amdgcn_s_setprio(0); } while (0)
; #define PG8_WAIT_V(n) asm volatile("s_waitcnt vmcnt(" #n ")" ::: "memory")
; template <class Epi, class Sched, bool ALIGN_EPI = false, bool SP2 = false>
; __device__ __forceinline__ void gemm_phase(PG8_LAS unsigned char* lds, const Gemm g, const Sched& S, const Epi& E) {
;     ...
;             PG8_LDB(B0, 0, 0); PG8_LDB(B1, 0, 1); PG8_SCHED; PG8_LDA(At, 0, 0); PG8_STAGE(PG8_SA(1, 1), a1 + hstep, voffA);
;             PG8_WAIT_V(8); PG8_WAIT_L(0); PG8_BAR; PG8_MMA(0, 0, At, B0); PG8_MMA(0, 1, At, B1); PG8_BAR; PG8_SCHED;
;             PG8_LDA(At, 0, 1); PG8_STAGE(PG8_SB(0, 0), b2, voffB); PG8_STAGE(PG8_SB(0, 1), b2 + hstep, voffB); PG8_STAGE(PG8_SA(0, 0), a2, voffA);
;             PG8_WAIT_V(8); PG8_WAIT_L(0); PG8_BAR; PG8_MMA(1, 0, At, B0); PG8_MMA(1, 1, At, B1); PG8_BAR; PG8_SCHED;
;             PG8_LDB(B0, 1, 0); PG8_LDB(B1, 1, 1); PG8_SCHED; PG8_LDA(At, 1, 0); PG8_STAGE(PG8_SA(0, 1), a2 + hstep, voffA);
;             PG8_WAIT_V(8); PG8_WAIT_L(0); PG8_BAR; PG8_MMA(0, 0, At, B0); PG8_MMA(0, 1, At, B1); PG8_BAR; PG8_SCHED;
;             PG8_LDA(At, 1, 1); PG8_STAGE(PG8_SB(1, 0), b3, voffB); PG8_STAGE(PG8_SB(1, 1), b3 + hstep, voffB); PG8_STAGE(PG8_SA(1, 0), a3, voffA);
;             PG8_WAIT_V(8); PG8_WAIT_L(0); PG8_BAR; PG8_MMA(1, 0, At, B0); PG8_MMA(1, 1, At, B1); PG8_BAR; PG8_SCHED;
	s_setprio 0
	s_add_i32 s44, s67, s47
	v_lshl_add_u64 v[160:161], v[160:161], 0, s[16:17]
	s_mov_b32 m0, s44
	ds_read_b128 v[198:201], v177 offset:49152
	ds_read_b128 v[202:205], v177 offset:50176
	ds_read_b128 v[206:209], v177 offset:51200
	ds_read_b128 v[210:213], v177 offset:52224
	ds_read_b128 v[214:217], v177 offset:53248
	ds_read_b128 v[218:221], v177 offset:54272
	ds_read_b128 v[222:225], v177 offset:55296
	ds_read_b128 v[226:229], v177 offset:56320
	global_load_lds_dwordx4 v[160:161], off
	s_add_i32 m0, s44, 0x2000
	s_add_u32 s42, s42, 0x80080
	v_lshl_add_u64 v[160:161], v[164:165], 0, s[16:17]
	s_addc_u32 s43, s43, 0
	s_add_i32 s44, s68, s47
	global_load_lds_dwordx4 v[160:161], off
	s_mov_b32 m0, s44
	s_nop 0
	global_load_lds_dwordx4 v144, s[42:43]
	s_add_i32 m0, s44, 0x2000
	v_lshl_add_u64 v[160:161], s[42:43], 0, v[146:147]
	global_load_lds_dwordx4 v[160:161], off
	s_mov_b32 m0, s55
	v_lshl_add_u64 v[160:161], v[170:171], 0, s[16:17]
	global_load_lds_dwordx4 v[160:161], off
	s_mov_b32 m0, s56
	v_lshl_add_u64 v[160:161], v[194:195], 0, s[16:17]
	global_load_lds_dwordx4 v[160:161], off
	s_waitcnt vmcnt(8) lgkmcnt(0)
	s_setprio 1
	s_barrier
	v_mfma_f32_16x16x32_bf16 v[60:63], v[108:111], v[198:201], v[60:63]
	v_mfma_f32_16x16x32_bf16 v[56:59], v[116:119], v[198:201], v[56:59]
	v_mfma_f32_16x16x32_bf16 v[36:39], v[108:111], v[206:209], v[36:39]
	v_mfma_f32_16x16x32_bf16 v[44:47], v[116:119], v[206:209], v[44:47]
	v_mfma_f32_16x16x32_bf16 v[20:23], v[108:111], v[214:217], v[20:23]
	v_mfma_f32_16x16x32_bf16 v[28:31], v[116:119], v[214:217], v[28:31]
	v_mfma_f32_16x16x32_bf16 v[4:7], v[108:111], v[222:225], v[4:7]
	v_mfma_f32_16x16x32_bf16 v[12:15], v[116:119], v[222:225], v[12:15]
	v_mfma_f32_16x16x32_bf16 v[60:63], v[112:115], v[202:205], v[60:63]
	v_mfma_f32_16x16x32_bf16 v[56:59], v[120:123], v[202:205], v[56:59]
	v_mfma_f32_16x16x32_bf16 v[36:39], v[112:115], v[210:213], v[36:39]
	v_mfma_f32_16x16x32_bf16 v[44:47], v[120:123], v[210:213], v[44:47]
	v_mfma_f32_16x16x32_bf16 v[20:23], v[112:115], v[218:221], v[20:23]
	v_mfma_f32_16x16x32_bf16 v[28:31], v[120:123], v[218:221], v[28:31]
	v_mfma_f32_16x16x32_bf16 v[4:7], v[112:115], v[226:229], v[4:7]
	v_mfma_f32_16x16x32_bf16 v[12:15], v[120:123], v[226:229], v[12:15]
	v_mfma_f32_16x16x32_bf16 v[48:51], v[178:181], v[198:201], v[48:51]
	v_mfma_f32_16x16x32_bf16 v[52:55], v[186:189], v[198:201], v[52:55]
	v_mfma_f32_16x16x32_bf16 v[40:43], v[178:181], v[206:209], v[40:43]
	v_mfma_f32_16x16x32_bf16 v[32:35], v[186:189], v[206:209], v[32:35]
	v_mfma_f32_16x16x32_bf16 v[24:27], v[178:181], v[214:217], v[24:27]
	v_mfma_f32_16x16x32_bf16 v[16:19], v[186:189], v[214:217], v[16:19]
	v_mfma_f32_16x16x32_bf16 v[8:11], v[178:181], v[222:225], v[8:11]
	v_mfma_f32_16x16x32_bf16 v[0:3], v[186:189], v[222:225], v[0:3]
	v_mfma_f32_16x16x32_bf16 v[48:51], v[182:185], v[202:205], v[48:51]
	v_mfma_f32_16x16x32_bf16 v[52:55], v[190:193], v[202:205], v[52:55]
	v_mfma_f32_16x16x32_bf16 v[40:43], v[182:185], v[210:213], v[40:43]
	v_mfma_f32_16x16x32_bf16 v[32:35], v[190:193], v[210:213], v[32:35]
	v_mfma_f32_16x16x32_bf16 v[24:27], v[182:185], v[218:221], v[24:27]
	v_mfma_f32_16x16x32_bf16 v[16:19], v[190:193], v[218:221], v[16:19]
	v_mfma_f32_16x16x32_bf16 v[8:11], v[182:185], v[226:229], v[8:11]
	v_mfma_f32_16x16x32_bf16 v[0:3], v[190:193], v[226:229], v[0:3]
	s_barrier
	s_setprio 0
	s_add_i32 s66, s66, 2
	s_add_u32 s8, s8, 0x100
	s_addc_u32 s9, s9, 0
	s_add_u32 s48, s48, 0x100
	s_addc_u32 s49, s49, 0
.LBB0_1373:
	ds_read_b128 v[108:111], v173
	ds_read_b128 v[112:115], v173 offset:1024
	ds_read_b128 v[116:119], v173 offset:2048
	ds_read_b128 v[120:123], v173 offset:3072
	ds_read_b128 v[178:181], v175
	ds_read_b128 v[182:185], v175 offset:1024
	ds_read_b128 v[186:189], v175 offset:2048
	ds_read_b128 v[190:193], v175 offset:3072
	s_add_u32 s42, s8, 0xfff80080
	s_addc_u32 s43, s9, -1
	s_cmp_eq_u32 s66, 28
	s_cselect_b32 s45, s29, s43
	s_cselect_b32 s44, s39, s42
	s_cselect_b32 s43, s27, s49
	s_cselect_b32 s42, s41, s48
	s_add_i32 m0, s50, 0xc000
	ds_read_b128 v[198:201], v177
	ds_read_b128 v[202:205], v177 offset:1024
	ds_read_b128 v[206:209], v177 offset:2048
	ds_read_b128 v[210:213], v177 offset:3072
	ds_read_b128 v[214:217], v177 offset:4096
	ds_read_b128 v[218:221], v177 offset:5120
	ds_read_b128 v[222:225], v177 offset:6144
	ds_read_b128 v[226:229], v177 offset:7168
	global_load_lds_dwordx4 v154, s[8:9]
	s_add_i32 m0, s50, 0xe000
	s_nop 0
	global_load_lds_dwordx4 v156, s[8:9]
	s_waitcnt vmcnt(8) lgkmcnt(0)
	s_setprio 1
	s_barrier
; #define PG8_STAGE(bufoff, gbase, voff) do { _Pragma("unroll") for (int _i = 0; _i < 2; ++_i) \
;         __builtin_amdgcn_global_load_lds((const unsigned*)((const char*)(gbase) + (voff)[_i]), (PG8_LAS unsigned*)(lds + (bufoff) + ldsw + _i * 8192), 16, 0, 0); } while (0)
; #define PG8_LDA(dst, b, h) do { _Pragma("unroll") for (int m = 0; m < 4; ++m) _Pragma("unroll") for (int k = 0; k < 2; ++k) dst[m][k] = *(const PG8_LAS bf16x8*)(lds + PG8_SA(b, h) + aoff + m * 2048 + k * 1024); } while (0)
; #define PG8_MMA(ai, bj, At, Bt) do { __builtin_amdgcn_s_setprio(1); _Pragma("unroll") for (int m = 0; m < 4; ++m) _Pragma("unroll") for (int n = 0; n < 2; ++n) _Pragma("unroll") for (int k = 0; k < 2; ++k) \
;         acc[ai][bj][m][n] = __builtin_amdgcn_mfma_f32_16x16x32_bf16(Bt[n][k], At[m][k], acc[ai][bj][m][n], 0, 0, 0); __builtin_amdgcn_s_setprio(0); } while (0)
; #define PG8_WAIT_V(n) asm volatile("s_waitcnt vmcnt(" #n ")" ::: "memory")
; #define PG8_WAIT_L(n) asm volatile("s_waitcnt lgkmcnt(" #n ")" ::: "memory")
; #define PG8_BAR __builtin_amdgcn_s_barrier()
; #define PG8_SCHED __builtin_amdgcn_sched_barrier(0)
; template <class Epi, class Sched, bool ALIGN_EPI = false, bool SP2 = false>
; __device__ __forceinline__ void gemm_phase(PG8_LAS unsigned char* lds, const Gemm g, const Sched& S, const Epi& E) {
;     ...
;             PG8_WAIT_V(8); PG8_WAIT_L(0); PG8_BAR; PG8_MMA(0, 0, At, B0); PG8_MMA(0, 1, At, B1); PG8_BAR; PG8_SCHED;
;             PG8_LDA(At, 0, 1); PG8_STAGE(PG8_SB(0, 0), b2, voffB); PG8_STAGE(PG8_SB(0, 1), b2 + hstep, voffB); PG8_STAGE(PG8_SA(0, 0), a2, voffA);
;             PG8_WAIT_V(8); PG8_WAIT_L(0); PG8_BAR; PG8_MMA(1, 0, At, B0); PG8_MMA(1, 1, At, B1); PG8_BAR; PG8_SCHED;
	v_mfma_f32_16x16x32_bf16 v[140:143], v[108:111], v[198:201], v[140:143]
	v_mfma_f32_16x16x32_bf16 v[136:139], v[116:119], v[198:201], v[136:139]
	v_mfma_f32_16x16x32_bf16 v[100:103], v[108:111], v[206:209], v[100:103]
	v_mfma_f32_16x16x32_bf16 v[124:127], v[116:119], v[206:209], v[124:127]
	v_mfma_f32_16x16x32_bf16 v[84:87], v[108:111], v[214:217], v[84:87]
	v_mfma_f32_16x16x32_bf16 v[92:95], v[116:119], v[214:217], v[92:95]
	v_mfma_f32_16x16x32_bf16 v[68:71], v[108:111], v[222:225], v[68:71]
	v_mfma_f32_16x16x32_bf16 v[76:79], v[116:119], v[222:225], v[76:79]
	v_mfma_f32_16x16x32_bf16 v[140:143], v[112:115], v[202:205], v[140:143]
	v_mfma_f32_16x16x32_bf16 v[136:139], v[120:123], v[202:205], v[136:139]
	v_mfma_f32_16x16x32_bf16 v[100:103], v[112:115], v[210:213], v[100:103]
	v_mfma_f32_16x16x32_bf16 v[124:127], v[120:123], v[210:213], v[124:127]
	v_mfma_f32_16x16x32_bf16 v[84:87], v[112:115], v[218:221], v[84:87]
	v_mfma_f32_16x16x32_bf16 v[92:95], v[120:123], v[218:221], v[92:95]
	v_mfma_f32_16x16x32_bf16 v[68:71], v[112:115], v[226:229], v[68:71]
	v_mfma_f32_16x16x32_bf16 v[76:79], v[120:123], v[226:229], v[76:79]
	v_mfma_f32_16x16x32_bf16 v[128:131], v[178:181], v[198:201], v[128:131]
	v_mfma_f32_16x16x32_bf16 v[132:135], v[186:189], v[198:201], v[132:135]
	v_mfma_f32_16x16x32_bf16 v[104:107], v[178:181], v[206:209], v[104:107]
	v_mfma_f32_16x16x32_bf16 v[96:99], v[186:189], v[206:209], v[96:99]
	v_mfma_f32_16x16x32_bf16 v[88:91], v[178:181], v[214:217], v[88:91]
	v_mfma_f32_16x16x32_bf16 v[80:83], v[186:189], v[214:217], v[80:83]
	v_mfma_f32_16x16x32_bf16 v[72:75], v[178:181], v[222:225], v[72:75]
	v_mfma_f32_16x16x32_bf16 v[64:67], v[186:189], v[222:225], v[64:67]
	v_mfma_f32_16x16x32_bf16 v[128:131], v[182:185], v[202:205], v[128:131]
	v_mfma_f32_16x16x32_bf16 v[132:135], v[190:193], v[202:205], v[132:135]
	v_mfma_f32_16x16x32_bf16 v[104:107], v[182:185], v[210:213], v[104:107]
	v_mfma_f32_16x16x32_bf16 v[96:99], v[190:193], v[210:213], v[96:99]
	v_mfma_f32_16x16x32_bf16 v[88:91], v[182:185], v[218:221], v[88:91]
	v_mfma_f32_16x16x32_bf16 v[80:83], v[190:193], v[218:221], v[80:83]
	v_mfma_f32_16x16x32_bf16 v[72:75], v[182:185], v[226:229], v[72:75]
	v_mfma_f32_16x16x32_bf16 v[64:67], v[190:193], v[226:229], v[64:67]
	s_barrier
	s_setprio 0
	s_add_i32 s67, s62, s47
	v_lshl_add_u64 v[160:161], s[42:43], 0, v[144:145]
	s_mov_b32 m0, s67
	ds_read_b128 v[198:201], v177 offset:16384
	ds_read_b128 v[202:205], v177 offset:17408
	ds_read_b128 v[206:209], v177 offset:18432
	ds_read_b128 v[210:213], v177 offset:19456
	ds_read_b128 v[214:217], v177 offset:20480
	ds_read_b128 v[218:221], v177 offset:21504
	ds_read_b128 v[222:225], v177 offset:22528
	ds_read_b128 v[226:229], v177 offset:23552
	global_load_lds_dwordx4 v[160:161], off
	s_add_i32 m0, s67, 0x2000
	s_add_u32 s68, s42, 0x80000
	v_lshl_add_u64 v[164:165], s[42:43], 0, v[146:147]
	s_addc_u32 s69, s43, 0
	s_add_i32 s67, s63, s47
	global_load_lds_dwordx4 v[164:165], off
	s_mov_b32 m0, s67
	v_lshl_add_u64 v[194:195], s[44:45], 0, v[146:147]
	global_load_lds_dwordx4 v144, s[68:69]
	s_add_i32 m0, s67, 0x2000
	s_nop 0
	global_load_lds_dwordx4 v146, s[68:69]
	s_mov_b32 m0, s50
	v_lshl_add_u64 v[170:171], s[44:45], 0, v[144:145]
	global_load_lds_dwordx4 v[170:171], off
	s_mov_b32 m0, s51
	s_nop 0
	global_load_lds_dwordx4 v[194:195], off
	s_waitcnt vmcnt(8) lgkmcnt(0)
	s_setprio 1
	s_barrier
	v_mfma_f32_16x16x32_bf16 v[60:63], v[108:111], v[198:201], v[60:63]
	v_mfma_f32_16x16x32_bf16 v[56:59], v[116:119], v[198:201], v[56:59]
	v_mfma_f32_16x16x32_bf16 v[36:39], v[108:111], v[206:209], v[36:39]
	v_mfma_f32_16x16x32_bf16 v[44:47], v[116:119], v[206:209], v[44:47]
	v_mfma_f32_16x16x32_bf16 v[20:23], v[108:111], v[214:217], v[20:23]
	v_mfma_f32_16x16x32_bf16 v[28:31], v[116:119], v[214:217], v[28:31]
	v_mfma_f32_16x16x32_bf16 v[4:7], v[108:111], v[222:225], v[4:7]
	v_mfma_f32_16x16x32_bf16 v[12:15], v[116:119], v[222:225], v[12:15]
	v_mfma_f32_16x16x32_bf16 v[60:63], v[112:115], v[202:205], v[60:63]
	v_mfma_f32_16x16x32_bf16 v[56:59], v[120:123], v[202:205], v[56:59]
	v_mfma_f32_16x16x32_bf16 v[36:39], v[112:115], v[210:213], v[36:39]
	v_mfma_f32_16x16x32_bf16 v[44:47], v[120:123], v[210:213], v[44:47]
	v_mfma_f32_16x16x32_bf16 v[20:23], v[112:115], v[218:221], v[20:23]
	v_mfma_f32_16x16x32_bf16 v[28:31], v[120:123], v[218:221], v[28:31]
	v_mfma_f32_16x16x32_bf16 v[4:7], v[112:115], v[226:229], v[4:7]
	v_mfma_f32_16x16x32_bf16 v[12:15], v[120:123], v[226:229], v[12:15]
	v_mfma_f32_16x16x32_bf16 v[48:51], v[178:181], v[198:201], v[48:51]
	v_mfma_f32_16x16x32_bf16 v[52:55], v[186:189], v[198:201], v[52:55]
	v_mfma_f32_16x16x32_bf16 v[40:43], v[178:181], v[206:209], v[40:43]
	v_mfma_f32_16x16x32_bf16 v[32:35], v[186:189], v[206:209], v[32:35]
	v_mfma_f32_16x16x32_bf16 v[24:27], v[178:181], v[214:217], v[24:27]
	v_mfma_f32_16x16x32_bf16 v[16:19], v[186:189], v[214:217], v[16:19]
	v_mfma_f32_16x16x32_bf16 v[8:11], v[178:181], v[222:225], v[8:11]
	v_mfma_f32_16x16x32_bf16 v[0:3], v[186:189], v[222:225], v[0:3]
	v_mfma_f32_16x16x32_bf16 v[48:51], v[182:185], v[202:205], v[48:51]
	v_mfma_f32_16x16x32_bf16 v[52:55], v[190:193], v[202:205], v[52:55]
	v_mfma_f32_16x16x32_bf16 v[40:43], v[182:185], v[210:213], v[40:43]
	v_mfma_f32_16x16x32_bf16 v[32:35], v[190:193], v[210:213], v[32:35]
	v_mfma_f32_16x16x32_bf16 v[24:27], v[182:185], v[218:221], v[24:27]
	v_mfma_f32_16x16x32_bf16 v[16:19], v[190:193], v[218:221], v[16:19]
	v_mfma_f32_16x16x32_bf16 v[8:11], v[182:185], v[226:229], v[8:11]
	v_mfma_f32_16x16x32_bf16 v[0:3], v[190:193], v[226:229], v[0:3]
	s_barrier
; #define PG8_STAGE(bufoff, gbase, voff) do { _Pragma("unroll") for (int _i = 0; _i < 2; ++_i) \
;         __builtin_amdgcn_global_load_lds((const unsigned*)((const char*)(gbase) + (voff)[_i]), (PG8_LAS unsigned*)(lds + (bufoff) + ldsw + _i * 8192), 16, 0, 0); } while (0)
; #define PG8_LDA(dst, b, h) do { _Pragma("unroll") for (int m = 0; m < 4; ++m) _Pragma("unroll") for (int k = 0; k < 2; ++k) dst[m][k] = *(const PG8_LAS bf16x8*)(lds + PG8_SA(b, h) + aoff + m * 2048 + k * 1024); } while (0)
; #define PG8_LDB(dst, b, h) do { _Pragma("unroll") for (int n = 0; n < 2; ++n) _Pragma("unroll") for (int k = 0; k < 2; ++k) dst[n][k] = *(const PG8_LAS bf16x8*)(lds + PG8_SB(b, h) + boff + n * 2048 + k * 1024); } while (0)
; #define PG8_MMA(ai, bj, At, Bt) do { __builtin_amdgcn_s_setprio(1); _Pragma("unroll") for (int m = 0; m < 4; ++m) _Pragma("unroll") for (int n = 0; n < 2; ++n) _Pragma("unroll") for (int k = 0; k < 2; ++k) \
;         acc[ai][bj][m][n] = __builtin_amdgcn_mfma_f32_16x16x32_bf16(Bt[n][k], At[m][k], acc[ai][bj][m][n], 0, 0, 0); __builtin_amdgcn_s_setprio(0); } while (0)
; #define PG8_WAIT_V(n) asm volatile("s_waitcnt vmcnt(" #n ")" ::: "memory")
; #define PG8_WAIT_L(n) asm volatile("s_waitcnt lgkmcnt(" #n ")" ::: "memory")
; #define PG8_BAR __builtin_amdgcn_s_barrier()
; #define PG8_SCHED __builtin_amdgcn_sched_barrier(0)
; template <class Epi, class Sched, bool ALIGN_EPI = false, bool SP2 = false>
; __device__ __forceinline__ void gemm_phase(PG8_LAS unsigned char* lds, const Gemm g, const Sched& S, const Epi& E) {
;     ...
;             PG8_LDB(B0, 1, 0); PG8_LDB(B1, 1, 1); PG8_SCHED; PG8_LDA(At, 1, 0); PG8_STAGE(PG8_SA(0, 1), a2 + hstep, voffA);
;             PG8_WAIT_V(8); PG8_WAIT_L(0); PG8_BAR; PG8_MMA(0, 0, At, B0); PG8_MMA(0, 1, At, B1); PG8_BAR; PG8_SCHED;
;             PG8_LDA(At, 1, 1); PG8_STAGE(PG8_SB(1, 0), b3, voffB); PG8_STAGE(PG8_SB(1, 1), b3 + hstep, voffB); PG8_STAGE(PG8_SA(1, 0), a3, voffA);
;             PG8_WAIT_V(8); PG8_WAIT_L(0); PG8_BAR; PG8_MMA(1, 0, At, B0); PG8_MMA(1, 1, At, B1); PG8_BAR; PG8_SCHED;
;     ...
;         if constexpr (ALIGN_EPI) { if (wr == 0) PG8_BAR; }
	s_setprio 0
	s_add_i32 s67, 0, 0x18000
	s_add_i32 s68, 0, 0x1c000
	v_add_u32_e32 v120, s67, v167
	v_add_u32_e32 v162, s68, v167
	ds_read_b128 v[108:111], v120
	ds_read_b128 v[112:115], v120 offset:1024
	ds_read_b128 v[116:119], v120 offset:2048
	ds_read_b128 v[120:123], v120 offset:3072
	ds_read_b128 v[178:181], v162
	ds_read_b128 v[182:185], v162 offset:1024
	ds_read_b128 v[186:189], v162 offset:2048
	ds_read_b128 v[190:193], v162 offset:3072
	s_add_u32 s44, s44, 0x80000
	s_addc_u32 s45, s45, 0
	s_mov_b32 m0, s52
	ds_read_b128 v[198:201], v177 offset:32768
	ds_read_b128 v[202:205], v177 offset:33792
	ds_read_b128 v[206:209], v177 offset:34816
	ds_read_b128 v[210:213], v177 offset:35840
	ds_read_b128 v[214:217], v177 offset:36864
	ds_read_b128 v[218:221], v177 offset:37888
	ds_read_b128 v[222:225], v177 offset:38912
	ds_read_b128 v[226:229], v177 offset:39936
	global_load_lds_dwordx4 v144, s[44:45]
	s_mov_b32 m0, s53
	s_nop 0
	global_load_lds_dwordx4 v146, s[44:45]
	s_waitcnt vmcnt(8) lgkmcnt(0)
	s_setprio 1
	s_barrier
	v_mfma_f32_16x16x32_bf16 v[140:143], v[108:111], v[198:201], v[140:143]
	v_mfma_f32_16x16x32_bf16 v[136:139], v[116:119], v[198:201], v[136:139]
	v_mfma_f32_16x16x32_bf16 v[100:103], v[108:111], v[206:209], v[100:103]
	v_mfma_f32_16x16x32_bf16 v[124:127], v[116:119], v[206:209], v[124:127]
	v_mfma_f32_16x16x32_bf16 v[84:87], v[108:111], v[214:217], v[84:87]
	v_mfma_f32_16x16x32_bf16 v[92:95], v[116:119], v[214:217], v[92:95]
	v_mfma_f32_16x16x32_bf16 v[68:71], v[108:111], v[222:225], v[68:71]
	v_mfma_f32_16x16x32_bf16 v[76:79], v[116:119], v[222:225], v[76:79]
	v_mfma_f32_16x16x32_bf16 v[140:143], v[112:115], v[202:205], v[140:143]
	v_mfma_f32_16x16x32_bf16 v[136:139], v[120:123], v[202:205], v[136:139]
	v_mfma_f32_16x16x32_bf16 v[100:103], v[112:115], v[210:213], v[100:103]
	v_mfma_f32_16x16x32_bf16 v[124:127], v[120:123], v[210:213], v[124:127]
	v_mfma_f32_16x16x32_bf16 v[84:87], v[112:115], v[218:221], v[84:87]
	v_mfma_f32_16x16x32_bf16 v[92:95], v[120:123], v[218:221], v[92:95]
	v_mfma_f32_16x16x32_bf16 v[68:71], v[112:115], v[226:229], v[68:71]
	v_mfma_f32_16x16x32_bf16 v[76:79], v[120:123], v[226:229], v[76:79]
	v_mfma_f32_16x16x32_bf16 v[128:131], v[178:181], v[198:201], v[128:131]
	v_mfma_f32_16x16x32_bf16 v[132:135], v[186:189], v[198:201], v[132:135]
	v_mfma_f32_16x16x32_bf16 v[104:107], v[178:181], v[206:209], v[104:107]
	v_mfma_f32_16x16x32_bf16 v[96:99], v[186:189], v[206:209], v[96:99]
	v_mfma_f32_16x16x32_bf16 v[88:91], v[178:181], v[214:217], v[88:91]
	v_mfma_f32_16x16x32_bf16 v[80:83], v[186:189], v[214:217], v[80:83]
	v_mfma_f32_16x16x32_bf16 v[72:75], v[178:181], v[222:225], v[72:75]
	v_mfma_f32_16x16x32_bf16 v[64:67], v[186:189], v[222:225], v[64:67]
	v_mfma_f32_16x16x32_bf16 v[128:131], v[182:185], v[202:205], v[128:131]
	v_mfma_f32_16x16x32_bf16 v[132:135], v[190:193], v[202:205], v[132:135]
	v_mfma_f32_16x16x32_bf16 v[104:107], v[182:185], v[210:213], v[104:107]
	v_mfma_f32_16x16x32_bf16 v[96:99], v[190:193], v[210:213], v[96:99]
	v_mfma_f32_16x16x32_bf16 v[88:91], v[182:185], v[218:221], v[88:91]
	v_mfma_f32_16x16x32_bf16 v[80:83], v[190:193], v[218:221], v[80:83]
	v_mfma_f32_16x16x32_bf16 v[72:75], v[182:185], v[226:229], v[72:75]
	v_mfma_f32_16x16x32_bf16 v[64:67], v[190:193], v[226:229], v[64:67]
	s_barrier
	s_setprio 0
	s_add_i32 s44, s67, s47
	v_lshl_add_u64 v[160:161], v[160:161], 0, s[16:17]
	s_mov_b32 m0, s44
	ds_read_b128 v[198:201], v177 offset:49152
	ds_read_b128 v[202:205], v177 offset:50176
	ds_read_b128 v[206:209], v177 offset:51200
	ds_read_b128 v[210:213], v177 offset:52224
	ds_read_b128 v[214:217], v177 offset:53248
	ds_read_b128 v[218:221], v177 offset:54272
	ds_read_b128 v[222:225], v177 offset:55296
	ds_read_b128 v[226:229], v177 offset:56320
	global_load_lds_dwordx4 v[160:161], off
	s_add_i32 m0, s44, 0x2000
	s_add_u32 s42, s42, 0x80080
	v_lshl_add_u64 v[160:161], v[164:165], 0, s[16:17]
	s_addc_u32 s43, s43, 0
	s_add_i32 s44, s68, s47
	global_load_lds_dwordx4 v[160:161], off
	s_mov_b32 m0, s44
	s_nop 0
	global_load_lds_dwordx4 v144, s[42:43]
	s_add_i32 m0, s44, 0x2000
	v_lshl_add_u64 v[160:161], s[42:43], 0, v[146:147]
	global_load_lds_dwordx4 v[160:161], off
	s_mov_b32 m0, s55
	v_lshl_add_u64 v[160:161], v[170:171], 0, s[16:17]
	global_load_lds_dwordx4 v[160:161], off
	s_mov_b32 m0, s56
	v_lshl_add_u64 v[160:161], v[194:195], 0, s[16:17]
	global_load_lds_dwordx4 v[160:161], off
	s_waitcnt vmcnt(8) lgkmcnt(0)
	s_setprio 1
	s_barrier
	v_mfma_f32_16x16x32_bf16 v[60:63], v[108:111], v[198:201], v[60:63]
	v_mfma_f32_16x16x32_bf16 v[56:59], v[116:119], v[198:201], v[56:59]
	v_mfma_f32_16x16x32_bf16 v[36:39], v[108:111], v[206:209], v[36:39]
	v_mfma_f32_16x16x32_bf16 v[44:47], v[116:119], v[206:209], v[44:47]
	v_mfma_f32_16x16x32_bf16 v[20:23], v[108:111], v[214:217], v[20:23]
	v_mfma_f32_16x16x32_bf16 v[28:31], v[116:119], v[214:217], v[28:31]
	v_mfma_f32_16x16x32_bf16 v[4:7], v[108:111], v[222:225], v[4:7]
	v_mfma_f32_16x16x32_bf16 v[12:15], v[116:119], v[222:225], v[12:15]
	v_mfma_f32_16x16x32_bf16 v[60:63], v[112:115], v[202:205], v[60:63]
	v_mfma_f32_16x16x32_bf16 v[56:59], v[120:123], v[202:205], v[56:59]
	v_mfma_f32_16x16x32_bf16 v[36:39], v[112:115], v[210:213], v[36:39]
	v_mfma_f32_16x16x32_bf16 v[44:47], v[120:123], v[210:213], v[44:47]
	v_mfma_f32_16x16x32_bf16 v[20:23], v[112:115], v[218:221], v[20:23]
	v_mfma_f32_16x16x32_bf16 v[28:31], v[120:123], v[218:221], v[28:31]
	v_mfma_f32_16x16x32_bf16 v[4:7], v[112:115], v[226:229], v[4:7]
	v_mfma_f32_16x16x32_bf16 v[12:15], v[120:123], v[226:229], v[12:15]
	v_mfma_f32_16x16x32_bf16 v[48:51], v[178:181], v[198:201], v[48:51]
	v_mfma_f32_16x16x32_bf16 v[52:55], v[186:189], v[198:201], v[52:55]
	v_mfma_f32_16x16x32_bf16 v[40:43], v[178:181], v[206:209], v[40:43]
	v_mfma_f32_16x16x32_bf16 v[32:35], v[186:189], v[206:209], v[32:35]
	v_mfma_f32_16x16x32_bf16 v[24:27], v[178:181], v[214:217], v[24:27]
	v_mfma_f32_16x16x32_bf16 v[16:19], v[186:189], v[214:217], v[16:19]
	v_mfma_f32_16x16x32_bf16 v[8:11], v[178:181], v[222:225], v[8:11]
	v_mfma_f32_16x16x32_bf16 v[0:3], v[186:189], v[222:225], v[0:3]
	v_mfma_f32_16x16x32_bf16 v[48:51], v[182:185], v[202:205], v[48:51]
	v_mfma_f32_16x16x32_bf16 v[52:55], v[190:193], v[202:205], v[52:55]
	v_mfma_f32_16x16x32_bf16 v[40:43], v[182:185], v[210:213], v[40:43]
	v_mfma_f32_16x16x32_bf16 v[32:35], v[190:193], v[210:213], v[32:35]
	v_mfma_f32_16x16x32_bf16 v[24:27], v[182:185], v[218:221], v[24:27]
	v_mfma_f32_16x16x32_bf16 v[16:19], v[190:193], v[218:221], v[16:19]
	v_mfma_f32_16x16x32_bf16 v[8:11], v[182:185], v[226:229], v[8:11]
	v_mfma_f32_16x16x32_bf16 v[0:3], v[190:193], v[226:229], v[0:3]
	s_barrier
	s_setprio 0
	s_add_i32 s66, s66, 2
	s_add_u32 s8, s8, 0x100
	s_addc_u32 s9, s9, 0
	s_add_u32 s48, s48, 0x100
	s_addc_u32 s49, s49, 0
	s_cmp_gt_u32 s66, 29
	s_cbranch_scc0 .LBB0_1373
	s_and_b64 vcc, exec, s[18:19]
	s_cbranch_vccz .LBB0_1376
	s_barrier

; #define PG8_STAGE(bufoff, gbase, voff) do { _Pragma("unroll") for (int _i = 0; _i < 2; ++_i) \
;         __builtin_amdgcn_global_load_lds((const unsigned*)((const char*)(gbase) + (voff)[_i]), (PG8_LAS unsigned*)(lds + (bufoff) + ldsw + _i * 8192), 16, 0, 0); } while (0)
; #define PG8_LDA(dst, b, h) do { _Pragma("unroll") for (int m = 0; m < 4; ++m) _Pragma("unroll") for (int k = 0; k < 2; ++k) dst[m][k] = *(const PG8_LAS bf16x8*)(lds + PG8_SA(b, h) + aoff + m * 2048 + k * 1024); } while (0)
; #define PG8_LDB(dst, b, h) do { _Pragma("unroll") for (int n = 0; n < 2; ++n) _Pragma("unroll") for (int k = 0; k < 2; ++k) dst[n][k] = *(const PG8_LAS bf16x8*)(lds + PG8_SB(b, h) + boff + n * 2048 + k * 1024); } while (0)
; #define PG8_MMA(ai, bj, At, Bt) do { __builtin_amdgcn_s_setprio(1); _Pragma("unroll") for (int m = 0; m < 4; ++m) _Pragma("unroll") for (int n = 0; n < 2; ++n) _Pragma("unroll") for (int k = 0; k < 2; ++k) \
;         acc[ai][bj][m][n] = __builtin_amdgcn_mfma_f32_16x16x32_bf16(Bt[n][k], At[m][k], acc[ai][bj][m][n], 0, 0, 0); __builtin_amdgcn_s_setprio(0); } while (0)
; #define PG8_WAIT_V(n) asm volatile("s_waitcnt vmcnt(" #n ")" ::: "memory")
; template <class Epi, class Sched, bool ALIGN_EPI = false, bool SP2 = false>
; __device__ __forceinline__ void gemm_phase(PG8_LAS unsigned char* lds, const Gemm g, const Sched& S, const Epi& E) {
;     ...
;         const char* nA = has_next ? (const char*)g.A + (size_t)nxt.pm * tstep : cA; const char* nB = has_next ? (const char*)g.Bt + (size_t)nxt.pn * tstep : cB;
;         for (int t = 0; t < nt; t += 2) {
;             const bool last = (t == nt - 2);
;             const char* a1 = cA + (size_t)(t + 1) * kstep;
;             const char* a2 = last ? nA : cA + (size_t)(t + 2) * kstep; const char* b2 = last ? nB : cB + (size_t)(t + 2) * kstep;
;             const char* a3 = a2 + kstep; const char* b3 = b2 + kstep;
;             if (last && has_next) S.a_ready(nxt);
;             if constexpr (SP2) {
;             PG8_LDB(B0, 0, 0); PG8_LDB(B1, 0, 1); PG8_SCHED; PG8_LDA(At, 0, 0); PG8_STAGE(PG8_SA(1, 1), a1 + hstep, voffA);
;             PG8_WAIT_V(8); PG8_WAIT_L(0); PG8_BAR; PG8_MMA(0, 0, At, B0); PG8_MMA(0, 1, At, B1); PG8_BAR; PG8_SCHED;
;             PG8_LDA(At, 0, 1); PG8_STAGE(PG8_SB(0, 0), b2, voffB); PG8_STAGE(PG8_SB(0, 1), b2 + hstep, voffB); PG8_STAGE(PG8_SA(0, 0), a2, voffA);
.LBB0_1548:
	s_ashr_i32 s13, s12, 31
	s_lshl_b64 s[14:15], s[12:13], 20
	s_add_u32 s14, s60, s14
	s_addc_u32 s15, s61, s15
	s_and_b64 s[16:17], s[0:1], exec
	s_cselect_b32 s13, s15, s21
	s_cselect_b32 s39, s14, s20
	s_ashr_i32 s11, s10, 31
	s_lshl_b64 s[16:17], s[10:11], 20
	s_add_u32 s16, s72, s16
	s_addc_u32 s17, s73, s17
	s_and_b64 s[24:25], s[0:1], exec
	s_cselect_b32 s11, s17, s23
	s_cselect_b32 s40, s16, s22
	s_add_u32 s20, s20, 0x80080
	s_addc_u32 s21, s21, 0
	s_add_u32 s41, s22, 0x100
	s_addc_u32 s42, s23, 0
	s_mov_b32 s43, -2
	ds_read_b128 v[144:147], v155
	ds_read_b128 v[148:151], v155 offset:1024
	ds_read_b128 v[158:161], v155 offset:2048
	ds_read_b128 v[162:165], v155 offset:3072
	ds_read_b128 v[166:169], v156
	ds_read_b128 v[170:173], v156 offset:1024
	ds_read_b128 v[174:177], v156 offset:2048
	ds_read_b128 v[178:181], v156 offset:3072
	s_add_u32 s22, s20, 0xfff80080
	s_addc_u32 s23, s21, -1
	s_cmp_eq_u32 s43, 28
	s_cselect_b32 s25, s13, s23
	s_cselect_b32 s24, s39, s22
	s_cselect_b32 s23, s11, s42
	s_cselect_b32 s22, s40, s41
	s_add_i32 m0, s19, 0xc000
	ds_read_b128 v[182:185], v157
	ds_read_b128 v[186:189], v157 offset:1024
	ds_read_b128 v[190:193], v157 offset:2048
	ds_read_b128 v[194:197], v157 offset:3072
	ds_read_b128 v[198:201], v157 offset:4096
	ds_read_b128 v[202:205], v157 offset:5120
	ds_read_b128 v[206:209], v157 offset:6144
	ds_read_b128 v[210:213], v157 offset:7168
	global_load_lds_dwordx4 v136, s[20:21]
	s_add_i32 m0, s19, 0xe000
	s_nop 0
	global_load_lds_dwordx4 v138, s[20:21]
	s_waitcnt lgkmcnt(0)
	s_setprio 1
	s_barrier
	v_mfma_f32_16x16x32_bf16 v[124:127], v[144:147], v[182:185], 0
	v_mfma_f32_16x16x32_bf16 v[120:123], v[158:161], v[182:185], 0
	v_mfma_f32_16x16x32_bf16 v[108:111], v[144:147], v[190:193], 0
	v_mfma_f32_16x16x32_bf16 v[104:107], v[158:161], v[190:193], 0
	v_mfma_f32_16x16x32_bf16 v[88:91], v[144:147], v[198:201], 0
	v_mfma_f32_16x16x32_bf16 v[92:95], v[158:161], v[198:201], 0
	v_mfma_f32_16x16x32_bf16 v[72:75], v[144:147], v[206:209], 0
	v_mfma_f32_16x16x32_bf16 v[76:79], v[158:161], v[206:209], 0
	v_mfma_f32_16x16x32_bf16 v[124:127], v[148:151], v[186:189], v[124:127]
	v_mfma_f32_16x16x32_bf16 v[120:123], v[162:165], v[186:189], v[120:123]
	v_mfma_f32_16x16x32_bf16 v[108:111], v[148:151], v[194:197], v[108:111]
	v_mfma_f32_16x16x32_bf16 v[104:107], v[162:165], v[194:197], v[104:107]
	v_mfma_f32_16x16x32_bf16 v[88:91], v[148:151], v[202:205], v[88:91]
	v_mfma_f32_16x16x32_bf16 v[92:95], v[162:165], v[202:205], v[92:95]
	v_mfma_f32_16x16x32_bf16 v[72:75], v[148:151], v[210:213], v[72:75]
	v_mfma_f32_16x16x32_bf16 v[76:79], v[162:165], v[210:213], v[76:79]
	v_mfma_f32_16x16x32_bf16 v[116:119], v[166:169], v[182:185], 0
	v_mfma_f32_16x16x32_bf16 v[112:115], v[174:177], v[182:185], 0
	v_mfma_f32_16x16x32_bf16 v[96:99], v[166:169], v[190:193], 0
	v_mfma_f32_16x16x32_bf16 v[100:103], v[174:177], v[190:193], 0
	v_mfma_f32_16x16x32_bf16 v[80:83], v[166:169], v[198:201], 0
	v_mfma_f32_16x16x32_bf16 v[84:87], v[174:177], v[198:201], 0
	v_mfma_f32_16x16x32_bf16 v[64:67], v[166:169], v[206:209], 0
	v_mfma_f32_16x16x32_bf16 v[68:71], v[174:177], v[206:209], 0
	v_mfma_f32_16x16x32_bf16 v[116:119], v[170:173], v[186:189], v[116:119]
	v_mfma_f32_16x16x32_bf16 v[112:115], v[178:181], v[186:189], v[112:115]
	v_mfma_f32_16x16x32_bf16 v[96:99], v[170:173], v[194:197], v[96:99]
	v_mfma_f32_16x16x32_bf16 v[100:103], v[178:181], v[194:197], v[100:103]
	v_mfma_f32_16x16x32_bf16 v[80:83], v[170:173], v[202:205], v[80:83]
	v_mfma_f32_16x16x32_bf16 v[84:87], v[178:181], v[202:205], v[84:87]
	v_mfma_f32_16x16x32_bf16 v[64:67], v[170:173], v[210:213], v[64:67]
	v_mfma_f32_16x16x32_bf16 v[68:71], v[178:181], v[210:213], v[68:71]
	s_barrier
	s_setprio 0
	s_add_i32 s44, s36, s27
	v_lshl_add_u64 v[214:215], s[22:23], 0, v[130:131]
	s_mov_b32 m0, s44
	ds_read_b128 v[182:185], v157 offset:16384
	ds_read_b128 v[186:189], v157 offset:17408
	ds_read_b128 v[190:193], v157 offset:18432
	ds_read_b128 v[194:197], v157 offset:19456
	ds_read_b128 v[198:201], v157 offset:20480
	ds_read_b128 v[202:205], v157 offset:21504
	ds_read_b128 v[206:209], v157 offset:22528
	ds_read_b128 v[210:213], v157 offset:23552
	global_load_lds_dwordx4 v[214:215], off
	s_add_i32 m0, s44, 0x2000
	s_add_u32 s44, s22, 0x80000
	v_lshl_add_u64 v[216:217], s[22:23], 0, v[134:135]
	s_addc_u32 s45, s23, 0
	s_add_i32 s46, s37, s27
	global_load_lds_dwordx4 v[216:217], off
	s_mov_b32 m0, s46
	v_lshl_add_u64 v[220:221], s[24:25], 0, v[132:133]
	global_load_lds_dwordx4 v130, s[44:45]
	s_add_i32 m0, s46, 0x2000
	s_nop 0
	global_load_lds_dwordx4 v134, s[44:45]
	s_mov_b32 m0, s19
	v_lshl_add_u64 v[218:219], s[24:25], 0, v[128:129]
	global_load_lds_dwordx4 v[218:219], off
	s_mov_b32 m0, s28
	s_nop 0
	global_load_lds_dwordx4 v[220:221], off
	s_waitcnt lgkmcnt(0)
	s_setprio 1
	s_barrier
; #define PG8_STAGE(bufoff, gbase, voff) do { _Pragma("unroll") for (int _i = 0; _i < 2; ++_i) \
;         __builtin_amdgcn_global_load_lds((const unsigned*)((const char*)(gbase) + (voff)[_i]), (PG8_LAS unsigned*)(lds + (bufoff) + ldsw + _i * 8192), 16, 0, 0); } while (0)
; #define PG8_LDA(dst, b, h) do { _Pragma("unroll") for (int m = 0; m < 4; ++m) _Pragma("unroll") for (int k = 0; k < 2; ++k) dst[m][k] = *(const PG8_LAS bf16x8*)(lds + PG8_SA(b, h) + aoff + m * 2048 + k * 1024); } while (0)
; #define PG8_LDB(dst, b, h) do { _Pragma("unroll") for (int n = 0; n < 2; ++n) _Pragma("unroll") for (int k = 0; k < 2; ++k) dst[n][k] = *(const PG8_LAS bf16x8*)(lds + PG8_SB(b, h) + boff + n * 2048 + k * 1024); } while (0)
; #define PG8_MMA(ai, bj, At, Bt) do { __builtin_amdgcn_s_setprio(1); _Pragma("unroll") for (int m = 0; m < 4; ++m) _Pragma("unroll") for (int n = 0; n < 2; ++n) _Pragma("unroll") for (int k = 0; k < 2; ++k) \
;         acc[ai][bj][m][n] = __builtin_amdgcn_mfma_f32_16x16x32_bf16(Bt[n][k], At[m][k], acc[ai][bj][m][n], 0, 0, 0); __builtin_amdgcn_s_setprio(0); } while (0)
; #define PG8_WAIT_V(n) asm volatile("s_waitcnt vmcnt(" #n ")" ::: "memory")
; #define PG8_WAIT_L(n) asm volatile("s_waitcnt lgkmcnt(" #n ")" ::: "memory")
; #define PG8_BAR __builtin_amdgcn_s_barrier()
; #define PG8_SCHED __builtin_amdgcn_sched_barrier(0)
; template <class Epi, class Sched, bool ALIGN_EPI = false, bool SP2 = false>
; __device__ __forceinline__ void gemm_phase(PG8_LAS unsigned char* lds, const Gemm g, const Sched& S, const Epi& E) {
;     ...
;             PG8_WAIT_V(8); PG8_WAIT_L(0); PG8_BAR; PG8_MMA(1, 0, At, B0); PG8_MMA(1, 1, At, B1); PG8_BAR; PG8_SCHED;
;             PG8_LDB(B0, 1, 0); PG8_LDB(B1, 1, 1); PG8_SCHED; PG8_LDA(At, 1, 0); PG8_STAGE(PG8_SA(0, 1), a2 + hstep, voffA);
;             PG8_WAIT_V(8); PG8_WAIT_L(0); PG8_BAR; PG8_MMA(0, 0, At, B0); PG8_MMA(0, 1, At, B1); PG8_BAR; PG8_SCHED;
	v_mfma_f32_16x16x32_bf16 v[56:59], v[144:147], v[182:185], 0
	v_mfma_f32_16x16x32_bf16 v[60:63], v[158:161], v[182:185], 0
	v_mfma_f32_16x16x32_bf16 v[40:43], v[144:147], v[190:193], 0
	v_mfma_f32_16x16x32_bf16 v[44:47], v[158:161], v[190:193], 0
	v_mfma_f32_16x16x32_bf16 v[24:27], v[144:147], v[198:201], 0
	v_mfma_f32_16x16x32_bf16 v[28:31], v[158:161], v[198:201], 0
	v_mfma_f32_16x16x32_bf16 v[8:11], v[144:147], v[206:209], 0
	v_mfma_f32_16x16x32_bf16 v[12:15], v[158:161], v[206:209], 0
	v_mfma_f32_16x16x32_bf16 v[56:59], v[148:151], v[186:189], v[56:59]
	v_mfma_f32_16x16x32_bf16 v[60:63], v[162:165], v[186:189], v[60:63]
	v_mfma_f32_16x16x32_bf16 v[40:43], v[148:151], v[194:197], v[40:43]
	v_mfma_f32_16x16x32_bf16 v[44:47], v[162:165], v[194:197], v[44:47]
	v_mfma_f32_16x16x32_bf16 v[24:27], v[148:151], v[202:205], v[24:27]
	v_mfma_f32_16x16x32_bf16 v[28:31], v[162:165], v[202:205], v[28:31]
	v_mfma_f32_16x16x32_bf16 v[8:11], v[148:151], v[210:213], v[8:11]
	v_mfma_f32_16x16x32_bf16 v[12:15], v[162:165], v[210:213], v[12:15]
	v_mfma_f32_16x16x32_bf16 v[48:51], v[166:169], v[182:185], 0
	v_mfma_f32_16x16x32_bf16 v[52:55], v[174:177], v[182:185], 0
	v_mfma_f32_16x16x32_bf16 v[32:35], v[166:169], v[190:193], 0
	v_mfma_f32_16x16x32_bf16 v[36:39], v[174:177], v[190:193], 0
	v_mfma_f32_16x16x32_bf16 v[16:19], v[166:169], v[198:201], 0
	v_mfma_f32_16x16x32_bf16 v[20:23], v[174:177], v[198:201], 0
	v_mfma_f32_16x16x32_bf16 v[0:3], v[166:169], v[206:209], 0
	v_mfma_f32_16x16x32_bf16 v[4:7], v[174:177], v[206:209], 0
	v_mfma_f32_16x16x32_bf16 v[48:51], v[170:173], v[186:189], v[48:51]
	v_mfma_f32_16x16x32_bf16 v[52:55], v[178:181], v[186:189], v[52:55]
	v_mfma_f32_16x16x32_bf16 v[32:35], v[170:173], v[194:197], v[32:35]
	v_mfma_f32_16x16x32_bf16 v[36:39], v[178:181], v[194:197], v[36:39]
	v_mfma_f32_16x16x32_bf16 v[16:19], v[170:173], v[202:205], v[16:19]
	v_mfma_f32_16x16x32_bf16 v[20:23], v[178:181], v[202:205], v[20:23]
	v_mfma_f32_16x16x32_bf16 v[0:3], v[170:173], v[210:213], v[0:3]
	v_mfma_f32_16x16x32_bf16 v[4:7], v[178:181], v[210:213], v[4:7]
	s_barrier
	s_setprio 0
	s_add_i32 s44, 0, 0x18000
	s_add_i32 s45, 0, 0x1c000
	v_add_u32_e32 v162, s44, v153
	v_add_u32_e32 v178, s45, v153
	ds_read_b128 v[144:147], v162
	ds_read_b128 v[148:151], v162 offset:1024
	ds_read_b128 v[158:161], v162 offset:2048
	ds_read_b128 v[162:165], v162 offset:3072
	ds_read_b128 v[166:169], v178
	ds_read_b128 v[170:173], v178 offset:1024
	ds_read_b128 v[174:177], v178 offset:2048
	ds_read_b128 v[178:181], v178 offset:3072
	s_add_u32 s24, s24, 0x80000
	s_addc_u32 s25, s25, 0
	s_mov_b32 m0, s29
	ds_read_b128 v[182:185], v157 offset:32768
	ds_read_b128 v[186:189], v157 offset:33792
	ds_read_b128 v[190:193], v157 offset:34816
	ds_read_b128 v[194:197], v157 offset:35840
	ds_read_b128 v[198:201], v157 offset:36864
	ds_read_b128 v[202:205], v157 offset:37888
	ds_read_b128 v[206:209], v157 offset:38912
	ds_read_b128 v[210:213], v157 offset:39936
	global_load_lds_dwordx4 v128, s[24:25]
	s_mov_b32 m0, s30
	v_lshl_add_u64 v[222:223], s[24:25], 0, v[132:133]
	global_load_lds_dwordx4 v[222:223], off
	s_waitcnt vmcnt(8) lgkmcnt(0)
	s_setprio 1
	s_barrier
	v_mfma_f32_16x16x32_bf16 v[124:127], v[144:147], v[182:185], v[124:127]
	v_mfma_f32_16x16x32_bf16 v[120:123], v[158:161], v[182:185], v[120:123]
	v_mfma_f32_16x16x32_bf16 v[108:111], v[144:147], v[190:193], v[108:111]
	v_mfma_f32_16x16x32_bf16 v[104:107], v[158:161], v[190:193], v[104:107]
	v_mfma_f32_16x16x32_bf16 v[88:91], v[144:147], v[198:201], v[88:91]
	v_mfma_f32_16x16x32_bf16 v[92:95], v[158:161], v[198:201], v[92:95]
	v_mfma_f32_16x16x32_bf16 v[72:75], v[144:147], v[206:209], v[72:75]
	v_mfma_f32_16x16x32_bf16 v[76:79], v[158:161], v[206:209], v[76:79]
	v_mfma_f32_16x16x32_bf16 v[124:127], v[148:151], v[186:189], v[124:127]
	v_mfma_f32_16x16x32_bf16 v[120:123], v[162:165], v[186:189], v[120:123]
	v_mfma_f32_16x16x32_bf16 v[108:111], v[148:151], v[194:197], v[108:111]
	v_mfma_f32_16x16x32_bf16 v[104:107], v[162:165], v[194:197], v[104:107]
	v_mfma_f32_16x16x32_bf16 v[88:91], v[148:151], v[202:205], v[88:91]
	v_mfma_f32_16x16x32_bf16 v[92:95], v[162:165], v[202:205], v[92:95]
	v_mfma_f32_16x16x32_bf16 v[72:75], v[148:151], v[210:213], v[72:75]
	v_mfma_f32_16x16x32_bf16 v[76:79], v[162:165], v[210:213], v[76:79]
	v_mfma_f32_16x16x32_bf16 v[116:119], v[166:169], v[182:185], v[116:119]
	v_mfma_f32_16x16x32_bf16 v[112:115], v[174:177], v[182:185], v[112:115]
	v_mfma_f32_16x16x32_bf16 v[96:99], v[166:169], v[190:193], v[96:99]
	v_mfma_f32_16x16x32_bf16 v[100:103], v[174:177], v[190:193], v[100:103]
	v_mfma_f32_16x16x32_bf16 v[80:83], v[166:169], v[198:201], v[80:83]
	v_mfma_f32_16x16x32_bf16 v[84:87], v[174:177], v[198:201], v[84:87]
	v_mfma_f32_16x16x32_bf16 v[64:67], v[166:169], v[206:209], v[64:67]
	v_mfma_f32_16x16x32_bf16 v[68:71], v[174:177], v[206:209], v[68:71]
	v_mfma_f32_16x16x32_bf16 v[116:119], v[170:173], v[186:189], v[116:119]
	v_mfma_f32_16x16x32_bf16 v[112:115], v[178:181], v[186:189], v[112:115]
	v_mfma_f32_16x16x32_bf16 v[96:99], v[170:173], v[194:197], v[96:99]
	v_mfma_f32_16x16x32_bf16 v[100:103], v[178:181], v[194:197], v[100:103]
	v_mfma_f32_16x16x32_bf16 v[80:83], v[170:173], v[202:205], v[80:83]
	v_mfma_f32_16x16x32_bf16 v[84:87], v[178:181], v[202:205], v[84:87]
	v_mfma_f32_16x16x32_bf16 v[64:67], v[170:173], v[210:213], v[64:67]
	v_mfma_f32_16x16x32_bf16 v[68:71], v[178:181], v[210:213], v[68:71]
	s_barrier
; #define PG8_STAGE(bufoff, gbase, voff) do { _Pragma("unroll") for (int _i = 0; _i < 2; ++_i) \
;         __builtin_amdgcn_global_load_lds((const unsigned*)((const char*)(gbase) + (voff)[_i]), (PG8_LAS unsigned*)(lds + (bufoff) + ldsw + _i * 8192), 16, 0, 0); } while (0)
; #define PG8_LDA(dst, b, h) do { _Pragma("unroll") for (int m = 0; m < 4; ++m) _Pragma("unroll") for (int k = 0; k < 2; ++k) dst[m][k] = *(const PG8_LAS bf16x8*)(lds + PG8_SA(b, h) + aoff + m * 2048 + k * 1024); } while (0)
; #define PG8_LDB(dst, b, h) do { _Pragma("unroll") for (int n = 0; n < 2; ++n) _Pragma("unroll") for (int k = 0; k < 2; ++k) dst[n][k] = *(const PG8_LAS bf16x8*)(lds + PG8_SB(b, h) + boff + n * 2048 + k * 1024); } while (0)
; #define PG8_MMA(ai, bj, At, Bt) do { __builtin_amdgcn_s_setprio(1); _Pragma("unroll") for (int m = 0; m < 4; ++m) _Pragma("unroll") for (int n = 0; n < 2; ++n) _Pragma("unroll") for (int k = 0; k < 2; ++k) \
;         acc[ai][bj][m][n] = __builtin_amdgcn_mfma_f32_16x16x32_bf16(Bt[n][k], At[m][k], acc[ai][bj][m][n], 0, 0, 0); __builtin_amdgcn_s_setprio(0); } while (0)
; #define PG8_WAIT_V(n) asm volatile("s_waitcnt vmcnt(" #n ")" ::: "memory")
; #define PG8_WAIT_L(n) asm volatile("s_waitcnt lgkmcnt(" #n ")" ::: "memory")
; #define PG8_BAR __builtin_amdgcn_s_barrier()
; #define PG8_SCHED __builtin_amdgcn_sched_barrier(0)
; template <class Epi, class Sched, bool ALIGN_EPI = false, bool SP2 = false>
; __device__ __forceinline__ void gemm_phase(PG8_LAS unsigned char* lds, const Gemm g, const Sched& S, const Epi& E) {
;     ...
;             const bool last = (t == nt - 2);
;             const char* a1 = cA + (size_t)(t + 1) * kstep;
;             const char* a2 = last ? nA : cA + (size_t)(t + 2) * kstep; const char* b2 = last ? nB : cB + (size_t)(t + 2) * kstep;
;             const char* a3 = a2 + kstep; const char* b3 = b2 + kstep;
;             if (last && has_next) S.a_ready(nxt);
;             if constexpr (SP2) {
;             PG8_LDB(B0, 0, 0); PG8_LDB(B1, 0, 1); PG8_SCHED; PG8_LDA(At, 0, 0); PG8_STAGE(PG8_SA(1, 1), a1 + hstep, voffA);
;     ...
;             PG8_LDA(At, 1, 1); PG8_STAGE(PG8_SB(1, 0), b3, voffB); PG8_STAGE(PG8_SB(1, 1), b3 + hstep, voffB); PG8_STAGE(PG8_SA(1, 0), a3, voffA);
;             PG8_WAIT_V(8); PG8_WAIT_L(0); PG8_BAR; PG8_MMA(1, 0, At, B0); PG8_MMA(1, 1, At, B1); PG8_BAR; PG8_SCHED;
	s_setprio 0
	s_add_i32 s24, s44, s27
	v_lshl_add_u64 v[214:215], v[214:215], 0, s[4:5]
	s_mov_b32 m0, s24
	ds_read_b128 v[182:185], v157 offset:49152
	ds_read_b128 v[186:189], v157 offset:50176
	ds_read_b128 v[190:193], v157 offset:51200
	ds_read_b128 v[194:197], v157 offset:52224
	ds_read_b128 v[198:201], v157 offset:53248
	ds_read_b128 v[202:205], v157 offset:54272
	ds_read_b128 v[206:209], v157 offset:55296
	ds_read_b128 v[210:213], v157 offset:56320
	global_load_lds_dwordx4 v[214:215], off
	s_add_i32 m0, s24, 0x2000
	s_add_u32 s22, s22, 0x80080
	v_lshl_add_u64 v[214:215], v[216:217], 0, s[4:5]
	s_addc_u32 s23, s23, 0
	s_add_i32 s24, s45, s27
	global_load_lds_dwordx4 v[214:215], off
	s_mov_b32 m0, s24
	s_nop 0
	global_load_lds_dwordx4 v130, s[22:23]
	s_add_i32 m0, s24, 0x2000
	v_lshl_add_u64 v[214:215], s[22:23], 0, v[134:135]
	global_load_lds_dwordx4 v[214:215], off
	s_mov_b32 m0, s33
	v_lshl_add_u64 v[214:215], v[218:219], 0, s[4:5]
	global_load_lds_dwordx4 v[214:215], off
	s_mov_b32 m0, s34
	v_lshl_add_u64 v[214:215], v[220:221], 0, s[4:5]
	global_load_lds_dwordx4 v[214:215], off
	s_waitcnt vmcnt(8) lgkmcnt(0)
	s_setprio 1
	s_barrier
	v_mfma_f32_16x16x32_bf16 v[56:59], v[144:147], v[182:185], v[56:59]
	v_mfma_f32_16x16x32_bf16 v[60:63], v[158:161], v[182:185], v[60:63]
	v_mfma_f32_16x16x32_bf16 v[40:43], v[144:147], v[190:193], v[40:43]
	v_mfma_f32_16x16x32_bf16 v[44:47], v[158:161], v[190:193], v[44:47]
	v_mfma_f32_16x16x32_bf16 v[24:27], v[144:147], v[198:201], v[24:27]
	v_mfma_f32_16x16x32_bf16 v[28:31], v[158:161], v[198:201], v[28:31]
	v_mfma_f32_16x16x32_bf16 v[8:11], v[144:147], v[206:209], v[8:11]
	v_mfma_f32_16x16x32_bf16 v[12:15], v[158:161], v[206:209], v[12:15]
	v_mfma_f32_16x16x32_bf16 v[56:59], v[148:151], v[186:189], v[56:59]
	v_mfma_f32_16x16x32_bf16 v[60:63], v[162:165], v[186:189], v[60:63]
	v_mfma_f32_16x16x32_bf16 v[40:43], v[148:151], v[194:197], v[40:43]
	v_mfma_f32_16x16x32_bf16 v[44:47], v[162:165], v[194:197], v[44:47]
	v_mfma_f32_16x16x32_bf16 v[24:27], v[148:151], v[202:205], v[24:27]
	v_mfma_f32_16x16x32_bf16 v[28:31], v[162:165], v[202:205], v[28:31]
	v_mfma_f32_16x16x32_bf16 v[8:11], v[148:151], v[210:213], v[8:11]
	v_mfma_f32_16x16x32_bf16 v[12:15], v[162:165], v[210:213], v[12:15]
	v_mfma_f32_16x16x32_bf16 v[48:51], v[166:169], v[182:185], v[48:51]
	v_mfma_f32_16x16x32_bf16 v[52:55], v[174:177], v[182:185], v[52:55]
	v_mfma_f32_16x16x32_bf16 v[32:35], v[166:169], v[190:193], v[32:35]
	v_mfma_f32_16x16x32_bf16 v[36:39], v[174:177], v[190:193], v[36:39]
	v_mfma_f32_16x16x32_bf16 v[16:19], v[166:169], v[198:201], v[16:19]
	v_mfma_f32_16x16x32_bf16 v[20:23], v[174:177], v[198:201], v[20:23]
	v_mfma_f32_16x16x32_bf16 v[0:3], v[166:169], v[206:209], v[0:3]
	v_mfma_f32_16x16x32_bf16 v[4:7], v[174:177], v[206:209], v[4:7]
	v_mfma_f32_16x16x32_bf16 v[48:51], v[170:173], v[186:189], v[48:51]
	v_mfma_f32_16x16x32_bf16 v[52:55], v[178:181], v[186:189], v[52:55]
	v_mfma_f32_16x16x32_bf16 v[32:35], v[170:173], v[194:197], v[32:35]
	v_mfma_f32_16x16x32_bf16 v[36:39], v[178:181], v[194:197], v[36:39]
	v_mfma_f32_16x16x32_bf16 v[16:19], v[170:173], v[202:205], v[16:19]
	v_mfma_f32_16x16x32_bf16 v[20:23], v[178:181], v[202:205], v[20:23]
	v_mfma_f32_16x16x32_bf16 v[0:3], v[170:173], v[210:213], v[0:3]
	v_mfma_f32_16x16x32_bf16 v[4:7], v[178:181], v[210:213], v[4:7]
	s_barrier
	s_setprio 0
	s_add_i32 s43, s43, 2
	s_add_u32 s20, s20, 0x100
	s_addc_u32 s21, s21, 0
	s_add_u32 s41, s41, 0x100
	s_addc_u32 s42, s42, 0
.LBB0_1549:
	ds_read_b128 v[144:147], v155
	ds_read_b128 v[148:151], v155 offset:1024
	ds_read_b128 v[158:161], v155 offset:2048
	ds_read_b128 v[162:165], v155 offset:3072
	ds_read_b128 v[166:169], v156
	ds_read_b128 v[170:173], v156 offset:1024
	ds_read_b128 v[174:177], v156 offset:2048
	ds_read_b128 v[178:181], v156 offset:3072
	s_add_u32 s22, s20, 0xfff80080
	s_addc_u32 s23, s21, -1
	s_cmp_eq_u32 s43, 28
	s_cselect_b32 s25, s13, s23
	s_cselect_b32 s24, s39, s22
	s_cselect_b32 s23, s11, s42
	s_cselect_b32 s22, s40, s41
	s_add_i32 m0, s19, 0xc000
	ds_read_b128 v[182:185], v157
	ds_read_b128 v[186:189], v157 offset:1024
	ds_read_b128 v[190:193], v157 offset:2048
	ds_read_b128 v[194:197], v157 offset:3072
	ds_read_b128 v[198:201], v157 offset:4096
	ds_read_b128 v[202:205], v157 offset:5120
	ds_read_b128 v[206:209], v157 offset:6144
	ds_read_b128 v[210:213], v157 offset:7168
	global_load_lds_dwordx4 v136, s[20:21]
	s_add_i32 m0, s19, 0xe000
	s_nop 0
	global_load_lds_dwordx4 v138, s[20:21]
	s_waitcnt vmcnt(8) lgkmcnt(0)
	s_setprio 1
	s_barrier
; #define PG8_STAGE(bufoff, gbase, voff) do { _Pragma("unroll") for (int _i = 0; _i < 2; ++_i) \
;         __builtin_amdgcn_global_load_lds((const unsigned*)((const char*)(gbase) + (voff)[_i]), (PG8_LAS unsigned*)(lds + (bufoff) + ldsw + _i * 8192), 16, 0, 0); } while (0)
; #define PG8_LDA(dst, b, h) do { _Pragma("unroll") for (int m = 0; m < 4; ++m) _Pragma("unroll") for (int k = 0; k < 2; ++k) dst[m][k] = *(const PG8_LAS bf16x8*)(lds + PG8_SA(b, h) + aoff + m * 2048 + k * 1024); } while (0)
; #define PG8_MMA(ai, bj, At, Bt) do { __builtin_amdgcn_s_setprio(1); _Pragma("unroll") for (int m = 0; m < 4; ++m) _Pragma("unroll") for (int n = 0; n < 2; ++n) _Pragma("unroll") for (int k = 0; k < 2; ++k) \
;         acc[ai][bj][m][n] = __builtin_amdgcn_mfma_f32_16x16x32_bf16(Bt[n][k], At[m][k], acc[ai][bj][m][n], 0, 0, 0); __builtin_amdgcn_s_setprio(0); } while (0)
; #define PG8_WAIT_V(n) asm volatile("s_waitcnt vmcnt(" #n ")" ::: "memory")
; #define PG8_WAIT_L(n) asm volatile("s_waitcnt lgkmcnt(" #n ")" ::: "memory")
; #define PG8_BAR __builtin_amdgcn_s_barrier()
; #define PG8_SCHED __builtin_amdgcn_sched_barrier(0)
; template <class Epi, class Sched, bool ALIGN_EPI = false, bool SP2 = false>
; __device__ __forceinline__ void gemm_phase(PG8_LAS unsigned char* lds, const Gemm g, const Sched& S, const Epi& E) {
;     ...
;             PG8_WAIT_V(8); PG8_WAIT_L(0); PG8_BAR; PG8_MMA(0, 0, At, B0); PG8_MMA(0, 1, At, B1); PG8_BAR; PG8_SCHED;
;             PG8_LDA(At, 0, 1); PG8_STAGE(PG8_SB(0, 0), b2, voffB); PG8_STAGE(PG8_SB(0, 1), b2 + hstep, voffB); PG8_STAGE(PG8_SA(0, 0), a2, voffA);
;             PG8_WAIT_V(8); PG8_WAIT_L(0); PG8_BAR; PG8_MMA(1, 0, At, B0); PG8_MMA(1, 1, At, B1); PG8_BAR; PG8_SCHED;
	v_mfma_f32_16x16x32_bf16 v[124:127], v[144:147], v[182:185], v[124:127]
	v_mfma_f32_16x16x32_bf16 v[120:123], v[158:161], v[182:185], v[120:123]
	v_mfma_f32_16x16x32_bf16 v[108:111], v[144:147], v[190:193], v[108:111]
	v_mfma_f32_16x16x32_bf16 v[104:107], v[158:161], v[190:193], v[104:107]
	v_mfma_f32_16x16x32_bf16 v[88:91], v[144:147], v[198:201], v[88:91]
	v_mfma_f32_16x16x32_bf16 v[92:95], v[158:161], v[198:201], v[92:95]
	v_mfma_f32_16x16x32_bf16 v[72:75], v[144:147], v[206:209], v[72:75]
	v_mfma_f32_16x16x32_bf16 v[76:79], v[158:161], v[206:209], v[76:79]
	v_mfma_f32_16x16x32_bf16 v[124:127], v[148:151], v[186:189], v[124:127]
	v_mfma_f32_16x16x32_bf16 v[120:123], v[162:165], v[186:189], v[120:123]
	v_mfma_f32_16x16x32_bf16 v[108:111], v[148:151], v[194:197], v[108:111]
	v_mfma_f32_16x16x32_bf16 v[104:107], v[162:165], v[194:197], v[104:107]
	v_mfma_f32_16x16x32_bf16 v[88:91], v[148:151], v[202:205], v[88:91]
	v_mfma_f32_16x16x32_bf16 v[92:95], v[162:165], v[202:205], v[92:95]
	v_mfma_f32_16x16x32_bf16 v[72:75], v[148:151], v[210:213], v[72:75]
	v_mfma_f32_16x16x32_bf16 v[76:79], v[162:165], v[210:213], v[76:79]
	v_mfma_f32_16x16x32_bf16 v[116:119], v[166:169], v[182:185], v[116:119]
	v_mfma_f32_16x16x32_bf16 v[112:115], v[174:177], v[182:185], v[112:115]
	v_mfma_f32_16x16x32_bf16 v[96:99], v[166:169], v[190:193], v[96:99]
	v_mfma_f32_16x16x32_bf16 v[100:103], v[174:177], v[190:193], v[100:103]
	v_mfma_f32_16x16x32_bf16 v[80:83], v[166:169], v[198:201], v[80:83]
	v_mfma_f32_16x16x32_bf16 v[84:87], v[174:177], v[198:201], v[84:87]
	v_mfma_f32_16x16x32_bf16 v[64:67], v[166:169], v[206:209], v[64:67]
	v_mfma_f32_16x16x32_bf16 v[68:71], v[174:177], v[206:209], v[68:71]
	v_mfma_f32_16x16x32_bf16 v[116:119], v[170:173], v[186:189], v[116:119]
	v_mfma_f32_16x16x32_bf16 v[112:115], v[178:181], v[186:189], v[112:115]
	v_mfma_f32_16x16x32_bf16 v[96:99], v[170:173], v[194:197], v[96:99]
	v_mfma_f32_16x16x32_bf16 v[100:103], v[178:181], v[194:197], v[100:103]
	v_mfma_f32_16x16x32_bf16 v[80:83], v[170:173], v[202:205], v[80:83]
	v_mfma_f32_16x16x32_bf16 v[84:87], v[178:181], v[202:205], v[84:87]
	v_mfma_f32_16x16x32_bf16 v[64:67], v[170:173], v[210:213], v[64:67]
	v_mfma_f32_16x16x32_bf16 v[68:71], v[178:181], v[210:213], v[68:71]
	s_barrier
	s_setprio 0
	s_add_i32 s44, s36, s27
	v_lshl_add_u64 v[214:215], s[22:23], 0, v[130:131]
	s_mov_b32 m0, s44
	ds_read_b128 v[182:185], v157 offset:16384
	ds_read_b128 v[186:189], v157 offset:17408
	ds_read_b128 v[190:193], v157 offset:18432
	ds_read_b128 v[194:197], v157 offset:19456
	ds_read_b128 v[198:201], v157 offset:20480
	ds_read_b128 v[202:205], v157 offset:21504
	ds_read_b128 v[206:209], v157 offset:22528
	ds_read_b128 v[210:213], v157 offset:23552
	global_load_lds_dwordx4 v[214:215], off
	s_add_i32 m0, s44, 0x2000
	s_add_u32 s44, s22, 0x80000
	v_lshl_add_u64 v[216:217], s[22:23], 0, v[134:135]
	s_addc_u32 s45, s23, 0
	s_add_i32 s46, s37, s27
	global_load_lds_dwordx4 v[216:217], off
	s_mov_b32 m0, s46
	v_lshl_add_u64 v[220:221], s[24:25], 0, v[132:133]
	global_load_lds_dwordx4 v130, s[44:45]
	s_add_i32 m0, s46, 0x2000
	s_nop 0
	global_load_lds_dwordx4 v134, s[44:45]
	s_mov_b32 m0, s19
	v_lshl_add_u64 v[218:219], s[24:25], 0, v[128:129]
	global_load_lds_dwordx4 v[218:219], off
	s_mov_b32 m0, s28
	s_nop 0
	global_load_lds_dwordx4 v[220:221], off
	s_waitcnt vmcnt(8) lgkmcnt(0)
	s_setprio 1
	s_barrier
	v_mfma_f32_16x16x32_bf16 v[56:59], v[144:147], v[182:185], v[56:59]
	v_mfma_f32_16x16x32_bf16 v[60:63], v[158:161], v[182:185], v[60:63]
	v_mfma_f32_16x16x32_bf16 v[40:43], v[144:147], v[190:193], v[40:43]
	v_mfma_f32_16x16x32_bf16 v[44:47], v[158:161], v[190:193], v[44:47]
	v_mfma_f32_16x16x32_bf16 v[24:27], v[144:147], v[198:201], v[24:27]
	v_mfma_f32_16x16x32_bf16 v[28:31], v[158:161], v[198:201], v[28:31]
	v_mfma_f32_16x16x32_bf16 v[8:11], v[144:147], v[206:209], v[8:11]
	v_mfma_f32_16x16x32_bf16 v[12:15], v[158:161], v[206:209], v[12:15]
	v_mfma_f32_16x16x32_bf16 v[56:59], v[148:151], v[186:189], v[56:59]
	v_mfma_f32_16x16x32_bf16 v[60:63], v[162:165], v[186:189], v[60:63]
	v_mfma_f32_16x16x32_bf16 v[40:43], v[148:151], v[194:197], v[40:43]
	v_mfma_f32_16x16x32_bf16 v[44:47], v[162:165], v[194:197], v[44:47]
	v_mfma_f32_16x16x32_bf16 v[24:27], v[148:151], v[202:205], v[24:27]
	v_mfma_f32_16x16x32_bf16 v[28:31], v[162:165], v[202:205], v[28:31]
	v_mfma_f32_16x16x32_bf16 v[8:11], v[148:151], v[210:213], v[8:11]
	v_mfma_f32_16x16x32_bf16 v[12:15], v[162:165], v[210:213], v[12:15]
	v_mfma_f32_16x16x32_bf16 v[48:51], v[166:169], v[182:185], v[48:51]
	v_mfma_f32_16x16x32_bf16 v[52:55], v[174:177], v[182:185], v[52:55]
	v_mfma_f32_16x16x32_bf16 v[32:35], v[166:169], v[190:193], v[32:35]
	v_mfma_f32_16x16x32_bf16 v[36:39], v[174:177], v[190:193], v[36:39]
	v_mfma_f32_16x16x32_bf16 v[16:19], v[166:169], v[198:201], v[16:19]
	v_mfma_f32_16x16x32_bf16 v[20:23], v[174:177], v[198:201], v[20:23]
	v_mfma_f32_16x16x32_bf16 v[0:3], v[166:169], v[206:209], v[0:3]
	v_mfma_f32_16x16x32_bf16 v[4:7], v[174:177], v[206:209], v[4:7]
	v_mfma_f32_16x16x32_bf16 v[48:51], v[170:173], v[186:189], v[48:51]
	v_mfma_f32_16x16x32_bf16 v[52:55], v[178:181], v[186:189], v[52:55]
	v_mfma_f32_16x16x32_bf16 v[32:35], v[170:173], v[194:197], v[32:35]
	v_mfma_f32_16x16x32_bf16 v[36:39], v[178:181], v[194:197], v[36:39]
	v_mfma_f32_16x16x32_bf16 v[16:19], v[170:173], v[202:205], v[16:19]
	v_mfma_f32_16x16x32_bf16 v[20:23], v[178:181], v[202:205], v[20:23]
	v_mfma_f32_16x16x32_bf16 v[0:3], v[170:173], v[210:213], v[0:3]
	v_mfma_f32_16x16x32_bf16 v[4:7], v[178:181], v[210:213], v[4:7]
	s_barrier
; #define PG8_STAGE(bufoff, gbase, voff) do { _Pragma("unroll") for (int _i = 0; _i < 2; ++_i) \
;         __builtin_amdgcn_global_load_lds((const unsigned*)((const char*)(gbase) + (voff)[_i]), (PG8_LAS unsigned*)(lds + (bufoff) + ldsw + _i * 8192), 16, 0, 0); } while (0)
; #define PG8_LDA(dst, b, h) do { _Pragma("unroll") for (int m = 0; m < 4; ++m) _Pragma("unroll") for (int k = 0; k < 2; ++k) dst[m][k] = *(const PG8_LAS bf16x8*)(lds + PG8_SA(b, h) + aoff + m * 2048 + k * 1024); } while (0)
; #define PG8_LDB(dst, b, h) do { _Pragma("unroll") for (int n = 0; n < 2; ++n) _Pragma("unroll") for (int k = 0; k < 2; ++k) dst[n][k] = *(const PG8_LAS bf16x8*)(lds + PG8_SB(b, h) + boff + n * 2048 + k * 1024); } while (0)
; #define PG8_MMA(ai, bj, At, Bt) do { __builtin_amdgcn_s_setprio(1); _Pragma("unroll") for (int m = 0; m < 4; ++m) _Pragma("unroll") for (int n = 0; n < 2; ++n) _Pragma("unroll") for (int k = 0; k < 2; ++k) \
;         acc[ai][bj][m][n] = __builtin_amdgcn_mfma_f32_16x16x32_bf16(Bt[n][k], At[m][k], acc[ai][bj][m][n], 0, 0, 0); __builtin_amdgcn_s_setprio(0); } while (0)
; #define PG8_WAIT_V(n) asm volatile("s_waitcnt vmcnt(" #n ")" ::: "memory")
; #define PG8_WAIT_L(n) asm volatile("s_waitcnt lgkmcnt(" #n ")" ::: "memory")
; #define PG8_BAR __builtin_amdgcn_s_barrier()
; #define PG8_SCHED __builtin_amdgcn_sched_barrier(0)
; template <class Epi, class Sched, bool ALIGN_EPI = false, bool SP2 = false>
; __device__ __forceinline__ void gemm_phase(PG8_LAS unsigned char* lds, const Gemm g, const Sched& S, const Epi& E) {
;     ...
;             PG8_LDB(B0, 1, 0); PG8_LDB(B1, 1, 1); PG8_SCHED; PG8_LDA(At, 1, 0); PG8_STAGE(PG8_SA(0, 1), a2 + hstep, voffA);
;             PG8_WAIT_V(8); PG8_WAIT_L(0); PG8_BAR; PG8_MMA(0, 0, At, B0); PG8_MMA(0, 1, At, B1); PG8_BAR; PG8_SCHED;
;             PG8_LDA(At, 1, 1); PG8_STAGE(PG8_SB(1, 0), b3, voffB); PG8_STAGE(PG8_SB(1, 1), b3 + hstep, voffB); PG8_STAGE(PG8_SA(1, 0), a3, voffA);
;             PG8_WAIT_V(8); PG8_WAIT_L(0); PG8_BAR; PG8_MMA(1, 0, At, B0); PG8_MMA(1, 1, At, B1); PG8_BAR; PG8_SCHED;
;     ...
;         if constexpr (ALIGN_EPI) { if (wr == 0) PG8_BAR; }
	s_setprio 0
	s_add_i32 s44, 0, 0x18000
	s_add_i32 s45, 0, 0x1c000
	v_add_u32_e32 v162, s44, v153
	v_add_u32_e32 v178, s45, v153
	ds_read_b128 v[144:147], v162
	ds_read_b128 v[148:151], v162 offset:1024
	ds_read_b128 v[158:161], v162 offset:2048
	ds_read_b128 v[162:165], v162 offset:3072
	ds_read_b128 v[166:169], v178
	ds_read_b128 v[170:173], v178 offset:1024
	ds_read_b128 v[174:177], v178 offset:2048
	ds_read_b128 v[178:181], v178 offset:3072
	s_add_u32 s24, s24, 0x80000
	s_addc_u32 s25, s25, 0
	s_mov_b32 m0, s29
	ds_read_b128 v[182:185], v157 offset:32768
	ds_read_b128 v[186:189], v157 offset:33792
	ds_read_b128 v[190:193], v157 offset:34816
	ds_read_b128 v[194:197], v157 offset:35840
	ds_read_b128 v[198:201], v157 offset:36864
	ds_read_b128 v[202:205], v157 offset:37888
	ds_read_b128 v[206:209], v157 offset:38912
	ds_read_b128 v[210:213], v157 offset:39936
	global_load_lds_dwordx4 v128, s[24:25]
	s_mov_b32 m0, s30
	s_nop 0
	global_load_lds_dwordx4 v132, s[24:25]
	s_waitcnt vmcnt(8) lgkmcnt(0)
	s_setprio 1
	s_barrier
	v_mfma_f32_16x16x32_bf16 v[124:127], v[144:147], v[182:185], v[124:127]
	v_mfma_f32_16x16x32_bf16 v[120:123], v[158:161], v[182:185], v[120:123]
	v_mfma_f32_16x16x32_bf16 v[108:111], v[144:147], v[190:193], v[108:111]
	v_mfma_f32_16x16x32_bf16 v[104:107], v[158:161], v[190:193], v[104:107]
	v_mfma_f32_16x16x32_bf16 v[88:91], v[144:147], v[198:201], v[88:91]
	v_mfma_f32_16x16x32_bf16 v[92:95], v[158:161], v[198:201], v[92:95]
	v_mfma_f32_16x16x32_bf16 v[72:75], v[144:147], v[206:209], v[72:75]
	v_mfma_f32_16x16x32_bf16 v[76:79], v[158:161], v[206:209], v[76:79]
	v_mfma_f32_16x16x32_bf16 v[124:127], v[148:151], v[186:189], v[124:127]
	v_mfma_f32_16x16x32_bf16 v[120:123], v[162:165], v[186:189], v[120:123]
	v_mfma_f32_16x16x32_bf16 v[108:111], v[148:151], v[194:197], v[108:111]
	v_mfma_f32_16x16x32_bf16 v[104:107], v[162:165], v[194:197], v[104:107]
	v_mfma_f32_16x16x32_bf16 v[88:91], v[148:151], v[202:205], v[88:91]
	v_mfma_f32_16x16x32_bf16 v[92:95], v[162:165], v[202:205], v[92:95]
	v_mfma_f32_16x16x32_bf16 v[72:75], v[148:151], v[210:213], v[72:75]
	v_mfma_f32_16x16x32_bf16 v[76:79], v[162:165], v[210:213], v[76:79]
	v_mfma_f32_16x16x32_bf16 v[116:119], v[166:169], v[182:185], v[116:119]
	v_mfma_f32_16x16x32_bf16 v[112:115], v[174:177], v[182:185], v[112:115]
	v_mfma_f32_16x16x32_bf16 v[96:99], v[166:169], v[190:193], v[96:99]
	v_mfma_f32_16x16x32_bf16 v[100:103], v[174:177], v[190:193], v[100:103]
	v_mfma_f32_16x16x32_bf16 v[80:83], v[166:169], v[198:201], v[80:83]
	v_mfma_f32_16x16x32_bf16 v[84:87], v[174:177], v[198:201], v[84:87]
	v_mfma_f32_16x16x32_bf16 v[64:67], v[166:169], v[206:209], v[64:67]
	v_mfma_f32_16x16x32_bf16 v[68:71], v[174:177], v[206:209], v[68:71]
	v_mfma_f32_16x16x32_bf16 v[116:119], v[170:173], v[186:189], v[116:119]
	v_mfma_f32_16x16x32_bf16 v[112:115], v[178:181], v[186:189], v[112:115]
	v_mfma_f32_16x16x32_bf16 v[96:99], v[170:173], v[194:197], v[96:99]
	v_mfma_f32_16x16x32_bf16 v[100:103], v[178:181], v[194:197], v[100:103]
	v_mfma_f32_16x16x32_bf16 v[80:83], v[170:173], v[202:205], v[80:83]
	v_mfma_f32_16x16x32_bf16 v[84:87], v[178:181], v[202:205], v[84:87]
	v_mfma_f32_16x16x32_bf16 v[64:67], v[170:173], v[210:213], v[64:67]
	v_mfma_f32_16x16x32_bf16 v[68:71], v[178:181], v[210:213], v[68:71]
	s_barrier
	s_setprio 0
	s_add_i32 s24, s44, s27
	v_lshl_add_u64 v[214:215], v[214:215], 0, s[4:5]
	s_mov_b32 m0, s24
	ds_read_b128 v[182:185], v157 offset:49152
	ds_read_b128 v[186:189], v157 offset:50176
	ds_read_b128 v[190:193], v157 offset:51200
	ds_read_b128 v[194:197], v157 offset:52224
	ds_read_b128 v[198:201], v157 offset:53248
	ds_read_b128 v[202:205], v157 offset:54272
	ds_read_b128 v[206:209], v157 offset:55296
	ds_read_b128 v[210:213], v157 offset:56320
	global_load_lds_dwordx4 v[214:215], off
	s_add_i32 m0, s24, 0x2000
	s_add_u32 s22, s22, 0x80080
	v_lshl_add_u64 v[214:215], v[216:217], 0, s[4:5]
	s_addc_u32 s23, s23, 0
	s_add_i32 s24, s45, s27
	global_load_lds_dwordx4 v[214:215], off
	s_mov_b32 m0, s24
	s_nop 0
	global_load_lds_dwordx4 v130, s[22:23]
	s_add_i32 m0, s24, 0x2000
	v_lshl_add_u64 v[214:215], s[22:23], 0, v[134:135]
	global_load_lds_dwordx4 v[214:215], off
	s_mov_b32 m0, s33
	v_lshl_add_u64 v[214:215], v[218:219], 0, s[4:5]
	global_load_lds_dwordx4 v[214:215], off
	s_mov_b32 m0, s34
	v_lshl_add_u64 v[214:215], v[220:221], 0, s[4:5]
	global_load_lds_dwordx4 v[214:215], off
	s_waitcnt vmcnt(8) lgkmcnt(0)
	s_setprio 1
	s_barrier
	v_mfma_f32_16x16x32_bf16 v[56:59], v[144:147], v[182:185], v[56:59]
	v_mfma_f32_16x16x32_bf16 v[60:63], v[158:161], v[182:185], v[60:63]
	v_mfma_f32_16x16x32_bf16 v[40:43], v[144:147], v[190:193], v[40:43]
	v_mfma_f32_16x16x32_bf16 v[44:47], v[158:161], v[190:193], v[44:47]
	v_mfma_f32_16x16x32_bf16 v[24:27], v[144:147], v[198:201], v[24:27]
	v_mfma_f32_16x16x32_bf16 v[28:31], v[158:161], v[198:201], v[28:31]
	v_mfma_f32_16x16x32_bf16 v[8:11], v[144:147], v[206:209], v[8:11]
	v_mfma_f32_16x16x32_bf16 v[12:15], v[158:161], v[206:209], v[12:15]
	v_mfma_f32_16x16x32_bf16 v[56:59], v[148:151], v[186:189], v[56:59]
	v_mfma_f32_16x16x32_bf16 v[60:63], v[162:165], v[186:189], v[60:63]
	v_mfma_f32_16x16x32_bf16 v[40:43], v[148:151], v[194:197], v[40:43]
	v_mfma_f32_16x16x32_bf16 v[44:47], v[162:165], v[194:197], v[44:47]
	v_mfma_f32_16x16x32_bf16 v[24:27], v[148:151], v[202:205], v[24:27]
	v_mfma_f32_16x16x32_bf16 v[28:31], v[162:165], v[202:205], v[28:31]
	v_mfma_f32_16x16x32_bf16 v[8:11], v[148:151], v[210:213], v[8:11]
	v_mfma_f32_16x16x32_bf16 v[12:15], v[162:165], v[210:213], v[12:15]
	v_mfma_f32_16x16x32_bf16 v[48:51], v[166:169], v[182:185], v[48:51]
	v_mfma_f32_16x16x32_bf16 v[52:55], v[174:177], v[182:185], v[52:55]
	v_mfma_f32_16x16x32_bf16 v[32:35], v[166:169], v[190:193], v[32:35]
	v_mfma_f32_16x16x32_bf16 v[36:39], v[174:177], v[190:193], v[36:39]
	v_mfma_f32_16x16x32_bf16 v[16:19], v[166:169], v[198:201], v[16:19]
	v_mfma_f32_16x16x32_bf16 v[20:23], v[174:177], v[198:201], v[20:23]
	v_mfma_f32_16x16x32_bf16 v[0:3], v[166:169], v[206:209], v[0:3]
	v_mfma_f32_16x16x32_bf16 v[4:7], v[174:177], v[206:209], v[4:7]
	v_mfma_f32_16x16x32_bf16 v[48:51], v[170:173], v[186:189], v[48:51]
	v_mfma_f32_16x16x32_bf16 v[52:55], v[178:181], v[186:189], v[52:55]
	v_mfma_f32_16x16x32_bf16 v[32:35], v[170:173], v[194:197], v[32:35]
	v_mfma_f32_16x16x32_bf16 v[36:39], v[178:181], v[194:197], v[36:39]
	v_mfma_f32_16x16x32_bf16 v[16:19], v[170:173], v[202:205], v[16:19]
	v_mfma_f32_16x16x32_bf16 v[20:23], v[178:181], v[202:205], v[20:23]
	v_mfma_f32_16x16x32_bf16 v[0:3], v[170:173], v[210:213], v[0:3]
	v_mfma_f32_16x16x32_bf16 v[4:7], v[178:181], v[210:213], v[4:7]
	s_barrier
	s_setprio 0
	s_add_i32 s43, s43, 2
	s_add_u32 s20, s20, 0x100
	s_addc_u32 s21, s21, 0
	s_add_u32 s41, s41, 0x100
	s_addc_u32 s42, s42, 0
	s_cmp_gt_u32 s43, 29
	s_cbranch_scc0 .LBB0_1549
	s_and_b64 vcc, exec, s[6:7]
	s_cbranch_vccz .LBB0_1552
	s_barrier
